# flat_load/flat_store replaced by global_load/global_store for all global-memory accesses (stores always, loads where the covering wait carries vmcnt): no LDS-aperture path, no lgkmcnt traffic
# speedup vs baseline: 1.0094x; 1.0094x over previous
; __device__ __forceinline__ float bf_lo(unsigned w) { return __uint_as_float(w << 16); }
; __global__ void __launch_bounds__(512, 2) mk_fwd(Args a) {
;     ...
;                 for (int lb = l0; lb < l1; lb += 4) {
;                     u32x4 x[6][2];
; #pragma unroll
;                     for (int i = 0; i < 6; ++i) { const int lg = lb - 1 + i; const bool ok = lg >= 0 && lg < LSEQ; const bf16_t* p = U + (size_t)(ok ? phys_of(lg) : 0) * NUP + c;
;                         x[i][0] = *(const u32x4*)p; x[i][1] = *(const u32x4*)(p + DFF);
;                         if (!ok) { x[i][0] = (u32x4){0u, 0u, 0u, 0u}; x[i][1] = (u32x4){0u, 0u, 0u, 0u}; } }
; #pragma unroll
;                     for (int i = 0; i < 4; ++i) { const int lg = lb + i; if (lg < l1) {
;                         f32x4 av[2], bv[2];
; #pragma unroll
;                         for (int hh = 0; hh < 2; ++hh) {
;                             f32x4 x0, x1, x2, y0, y1, y2;
;                             const unsigned a0 = hh ? x[i][0].z : x[i][0].x, a1 = hh ? x[i][0].w : x[i][0].y, b0 = hh ? x[i + 1][0].z : x[i + 1][0].x, b1 = hh ? x[i + 1][0].w : x[i + 1][0].y, c0 = hh ? x[i + 2][0].z : x[i + 2][0].x, c1 = hh ? x[i + 2][0].w : x[i + 2][0].y;
;                             x0 = (f32x4){bf_lo(a0), bf_hi(a0), bf_lo(a1), bf_hi(a1)}; x1 = (f32x4){bf_lo(b0), bf_hi(b0), bf_lo(b1), bf_hi(b1)}; x2 = (f32x4){bf_lo(c0), bf_hi(c0), bf_lo(c1), bf_hi(c1)};
;                             const unsigned d0 = hh ? x[i][1].z : x[i][1].x, d1 = hh ? x[i][1].w : x[i][1].y, e0 = hh ? x[i + 1][1].z : x[i + 1][1].x, e1 = hh ? x[i + 1][1].w : x[i + 1][1].y, f0 = hh ? x[i + 2][1].z : x[i + 2][1].x, f1 = hh ? x[i + 2][1].w : x[i + 2][1].y;
;                             y0 = (f32x4){bf_lo(d0), bf_hi(d0), bf_lo(d1), bf_hi(d1)}; y1 = (f32x4){bf_lo(e0), bf_hi(e0), bf_lo(e1), bf_hi(e1)}; y2 = (f32x4){bf_lo(f0), bf_hi(f0), bf_lo(f1), bf_hi(f1)};
;                             av[hh] = wt[0][0][hh] * x0 + wt[1][0][hh] * x1 + wt[2][0][hh] * x2;
;                             bv[hh] = wt[0][1][hh] * y0 + wt[1][1][hh] * y1 + wt[2][1][hh] * y2; }
;                         u32x4 o;
;                         o.x = cvt_pk_bf16(av[0][0] * sigm(av[0][0]) * bv[0][0], av[0][1] * sigm(av[0][1]) * bv[0][1]); o.y = cvt_pk_bf16(av[0][2] * sigm(av[0][2]) * bv[0][2], av[0][3] * sigm(av[0][3]) * bv[0][3]);
.LBB0_98:
	s_waitcnt vmcnt(0) lgkmcnt(0)
	v_cndmask_b32_e64 v122, 0, v86, s[0:1]
	v_cndmask_b32_e64 v86, 0, v75, s[0:1]
	v_cndmask_b32_e64 v75, 0, v68, s[0:1]
	v_cndmask_b32_e64 v92, 0, v67, s[0:1]
	v_cndmask_b32_e64 v68, 0, v65, s[0:1]
	v_cndmask_b32_e64 v67, 0, v49, s[38:39]
	v_cndmask_b32_e64 v65, 0, v48, s[38:39]
	v_lshl_add_u64 v[48:49], s[48:49], 1, v[88:89]
	v_cndmask_b32_e64 v115, 0, v71, s[0:1]
	v_cndmask_b32_e64 v113, 0, v70, s[0:1]
	v_cndmask_b32_e64 v97, 0, v55, s[38:39]
	v_cndmask_b32_e64 v96, 0, v54, s[38:39]
	v_cndmask_b32_e64 v71, 0, v53, s[38:39]
	v_cndmask_b32_e64 v70, 0, v52, s[38:39]
	v_cndmask_b32_e64 v94, 0, v51, s[38:39]
	v_cndmask_b32_e64 v95, 0, v50, s[38:39]
	v_add_co_u32_e64 v52, s[38:39], s19, v48
	v_cndmask_b32_e64 v117, 0, v87, s[0:1]
	s_nop 0
	v_addc_co_u32_e64 v53, s[38:39], 0, v49, s[38:39]
	flat_load_dwordx4 v[48:51], v[48:49]
	s_nop 0
	flat_load_dwordx4 v[52:55], v[52:53] offset:3072
	v_cndmask_b32_e64 v87, 0, v74, s[0:1]
	v_cndmask_b32_e64 v74, 0, v69, s[0:1]
	v_cndmask_b32_e64 v69, 0, v64, s[0:1]
	v_lshlrev_b32_e32 v100, 16, v69
	v_and_b32_e32 v101, 0xffff0000, v69
	v_cndmask_b32_e64 v125, 0, v83, s[0:1]
	v_cndmask_b32_e64 v126, 0, v82, s[0:1]
	v_lshlrev_b32_e32 v64, 16, v65
	v_and_b32_e32 v65, 0xffff0000, v65
	v_lshlrev_b32_e32 v104, 16, v75
	v_and_b32_e32 v105, 0xffff0000, v75
	v_pk_mul_f32 v[82:83], v[16:17], v[100:101]
	v_cndmask_b32_e64 v72, 0, v72, s[0:1]
	v_lshlrev_b32_e32 v102, 16, v68
	v_and_b32_e32 v103, 0xffff0000, v68
	v_lshlrev_b32_e32 v68, 16, v70
	v_and_b32_e32 v69, 0xffff0000, v70
	v_pk_fma_f32 v[64:65], v[4:5], v[64:65], v[82:83]
	v_pk_mul_f32 v[82:83], v[24:25], v[104:105]
	v_lshlrev_b32_e32 v110, 16, v92
	v_and_b32_e32 v111, 0xffff0000, v92
	v_cndmask_b32_e64 v123, 0, v85, s[0:1]
	v_cndmask_b32_e64 v124, 0, v84, s[0:1]
	v_cndmask_b32_e64 v85, 0, v79, s[0:1]
	v_cndmask_b32_e64 v84, 0, v78, s[0:1]
	v_cndmask_b32_e64 v93, 0, v66, s[0:1]
	v_lshlrev_b32_e32 v78, 16, v72
	v_and_b32_e32 v79, 0xffff0000, v72
	v_pk_fma_f32 v[68:69], v[8:9], v[68:69], v[82:83]
	v_lshlrev_b32_e32 v82, 16, v94
	v_and_b32_e32 v83, 0xffff0000, v94
	v_lshlrev_b32_e32 v114, 16, v115
	v_and_b32_e32 v115, 0xffff0000, v115
	v_pk_mul_f32 v[118:119], v[22:23], v[110:111]
	v_pk_fma_f32 v[64:65], v[32:33], v[78:79], v[64:65]
	v_lshlrev_b32_e32 v108, 16, v93
	v_and_b32_e32 v109, 0xffff0000, v93
	v_lshlrev_b32_e32 v92, 16, v96
	v_and_b32_e32 v93, 0xffff0000, v96
	v_lshlrev_b32_e32 v96, 16, v97
	v_and_b32_e32 v97, 0xffff0000, v97
	v_pk_fma_f32 v[82:83], v[2:3], v[82:83], v[118:119]
	v_pk_mul_f32 v[118:119], v[30:31], v[114:115]
	v_cndmask_b32_e64 v127, 0, v81, s[0:1]
	v_pk_fma_f32 v[96:97], v[14:15], v[96:97], v[118:119]
	v_mul_f32_e32 v118, 0xbfb8aa3b, v64
	v_exp_f32_e32 v118, v118
	v_mul_f32_e32 v119, 0xbfb8aa3b, v65
	v_exp_f32_e32 v119, v119
	v_cndmask_b32_e64 v128, 0, v80, s[0:1]
	v_add_f32_e32 v118, 1.0, v118
	v_rcp_f32_e32 v118, v118
	v_cndmask_b32_e64 v80, 0, v77, s[0:1]
	v_cndmask_b32_e64 v81, 0, v76, s[0:1]
	v_cndmask_b32_e64 v73, 0, v73, s[0:1]
	v_lshlrev_b32_e32 v66, 16, v67
	v_and_b32_e32 v67, 0xffff0000, v67
	v_lshlrev_b32_e32 v76, 16, v73
	v_and_b32_e32 v77, 0xffff0000, v73
	v_lshlrev_b32_e32 v106, 16, v74
	v_and_b32_e32 v107, 0xffff0000, v74
	v_lshlrev_b32_e32 v74, 16, v81
	v_and_b32_e32 v75, 0xffff0000, v81
	v_lshlrev_b32_e32 v72, 16, v80
	v_and_b32_e32 v73, 0xffff0000, v80
	v_pk_mul_f32 v[80:81], v[18:19], v[102:103]
	v_pk_fma_f32 v[68:69], v[40:41], v[74:75], v[68:69]
	v_pk_fma_f32 v[66:67], v[6:7], v[66:67], v[80:81]
	v_add_f32_e32 v119, 1.0, v119
	v_pk_fma_f32 v[66:67], v[34:35], v[76:77], v[66:67]
	v_mul_f32_e32 v64, v64, v118
	v_rcp_f32_e32 v119, v119
	v_mul_f32_e32 v64, v68, v64
	v_mul_f32_e32 v68, 0xbfb8aa3b, v66
	v_mul_f32_e32 v118, 0xbfb8aa3b, v67
	v_exp_f32_e32 v68, v68
	v_exp_f32_e32 v118, v118
	v_mul_f32_e32 v65, v65, v119
	v_mul_f32_e32 v65, v69, v65
	v_add_f32_e32 v68, 1.0, v68
	v_add_f32_e32 v69, 1.0, v118
	v_lshlrev_b32_e32 v70, 16, v71
	v_and_b32_e32 v71, 0xffff0000, v71
	v_pk_mul_f32 v[80:81], v[26:27], v[106:107]
	v_rcp_f32_e32 v68, v68
	v_rcp_f32_e32 v69, v69
	v_pk_fma_f32 v[70:71], v[10:11], v[70:71], v[80:81]
	v_lshlrev_b32_e32 v80, 16, v95
	v_and_b32_e32 v81, 0xffff0000, v95
	v_pk_mul_f32 v[120:121], v[20:21], v[108:109]
	v_lshlrev_b32_e32 v98, 16, v87
	v_and_b32_e32 v99, 0xffff0000, v87
	v_pk_fma_f32 v[80:81], v[0:1], v[80:81], v[120:121]
	v_cvt_pk_bf16_f32 v64, v64, v65
	v_mul_f32_e32 v65, v66, v68
	v_pk_fma_f32 v[80:81], v[36:37], v[98:99], v[80:81]
	v_mul_f32_e32 v66, v67, v69
	v_mul_f32_e32 v67, 0xbfb8aa3b, v80
	v_mul_f32_e32 v68, 0xbfb8aa3b, v81
	v_exp_f32_e32 v67, v67
	v_exp_f32_e32 v68, v68
	v_pk_fma_f32 v[70:71], v[42:43], v[72:73], v[70:71]
	v_lshlrev_b32_e32 v94, 16, v86
	v_add_f32_e32 v67, 1.0, v67
	v_add_f32_e32 v68, 1.0, v68
	v_rcp_f32_e32 v67, v67
	v_rcp_f32_e32 v68, v68
	v_and_b32_e32 v95, 0xffff0000, v86
	v_pk_fma_f32 v[82:83], v[38:39], v[94:95], v[82:83]
	v_mul_f32_e32 v65, v70, v65
	v_mul_f32_e32 v66, v71, v66
	v_cvt_pk_bf16_f32 v65, v65, v66
	v_mul_f32_e32 v66, v80, v67
	v_mul_f32_e32 v67, v81, v68
	v_mul_f32_e32 v68, 0xbfb8aa3b, v82
	v_mul_f32_e32 v69, 0xbfb8aa3b, v83
	v_exp_f32_e32 v68, v68
	v_exp_f32_e32 v69, v69
	v_lshlrev_b32_e32 v112, 16, v113
	v_and_b32_e32 v113, 0xffff0000, v113
	v_add_f32_e32 v68, 1.0, v68
	v_add_f32_e32 v69, 1.0, v69
	v_pk_mul_f32 v[120:121], v[28:29], v[112:113]
	v_rcp_f32_e32 v68, v68
	v_rcp_f32_e32 v69, v69
	v_lshlrev_b32_e32 v86, 16, v84
	v_and_b32_e32 v87, 0xffff0000, v84
	v_pk_fma_f32 v[92:93], v[12:13], v[92:93], v[120:121]
	s_cmp_gt_i32 s8, 15
	v_pk_fma_f32 v[92:93], v[44:45], v[86:87], v[92:93]
	v_lshlrev_b32_e32 v84, 16, v85
	v_and_b32_e32 v85, 0xffff0000, v85
	v_mul_f32_e32 v66, v92, v66
	v_mul_f32_e32 v67, v93, v67
	s_cselect_b32 s18, -16, 0x2000
	v_pk_fma_f32 v[96:97], v[46:47], v[84:85], v[96:97]
	v_cvt_pk_bf16_f32 v66, v66, v67
	v_mul_f32_e32 v67, v82, v68
	v_mul_f32_e32 v68, v83, v69
	s_cselect_b32 s13, -1, 0
	s_add_u32 s18, s8, s18
	v_mul_f32_e32 v67, v96, v67
	v_mul_f32_e32 v68, v97, v68
	s_addc_u32 s13, s9, s13
	v_cvt_pk_bf16_f32 v67, v67, v68
	s_mulk_i32 s13, 0x2c00
	v_mad_u64_u32 v[68:69], s[28:29], s18, v204, v[90:91]
	v_add_u32_e32 v69, s13, v69
	s_add_i32 s13, s8, 1
	global_store_dwordx4 v[68:69], v[64:67], off
	s_cmp_ge_i32 s13, s7
	v_lshlrev_b32_e32 v96, 16, v128
	v_and_b32_e32 v97, 0xffff0000, v128
	v_lshlrev_b32_e32 v92, 16, v127
	v_and_b32_e32 v93, 0xffff0000, v127
	v_lshlrev_b32_e32 v82, 16, v124
	v_and_b32_e32 v83, 0xffff0000, v124
	v_lshlrev_b32_e32 v80, 16, v123
	v_and_b32_e32 v81, 0xffff0000, v123
	v_lshlrev_b32_e32 v70, 16, v126
	v_and_b32_e32 v71, 0xffff0000, v126
	v_lshlrev_b32_e32 v68, 16, v125
	v_and_b32_e32 v69, 0xffff0000, v125
	v_lshlrev_b32_e32 v66, 16, v122
	v_and_b32_e32 v67, 0xffff0000, v122
	v_lshlrev_b32_e32 v64, 16, v117
	v_and_b32_e32 v65, 0xffff0000, v117
	s_cbranch_scc1 .LBB0_100
; __device__ __forceinline__ float bf_lo(unsigned w) { return __uint_as_float(w << 16); }
; __global__ void __launch_bounds__(512, 2) mk_fwd(Args a) {
;     ...
;                 for (int lb = l0; lb < l1; lb += 4) {
;                     u32x4 x[6][2];
; #pragma unroll
;                     for (int i = 0; i < 6; ++i) { const int lg = lb - 1 + i; const bool ok = lg >= 0 && lg < LSEQ; const bf16_t* p = U + (size_t)(ok ? phys_of(lg) : 0) * NUP + c;
;                         x[i][0] = *(const u32x4*)p; x[i][1] = *(const u32x4*)(p + DFF);
;                         if (!ok) { x[i][0] = (u32x4){0u, 0u, 0u, 0u}; x[i][1] = (u32x4){0u, 0u, 0u, 0u}; } }
; #pragma unroll
;                     for (int i = 0; i < 4; ++i) { const int lg = lb + i; if (lg < l1) {
;                         f32x4 av[2], bv[2];
; #pragma unroll
;                         for (int hh = 0; hh < 2; ++hh) {
;                             f32x4 x0, x1, x2, y0, y1, y2;
;                             const unsigned a0 = hh ? x[i][0].z : x[i][0].x, a1 = hh ? x[i][0].w : x[i][0].y, b0 = hh ? x[i + 1][0].z : x[i + 1][0].x, b1 = hh ? x[i + 1][0].w : x[i + 1][0].y, c0 = hh ? x[i + 2][0].z : x[i + 2][0].x, c1 = hh ? x[i + 2][0].w : x[i + 2][0].y;
;                             x0 = (f32x4){bf_lo(a0), bf_hi(a0), bf_lo(a1), bf_hi(a1)}; x1 = (f32x4){bf_lo(b0), bf_hi(b0), bf_lo(b1), bf_hi(b1)}; x2 = (f32x4){bf_lo(c0), bf_hi(c0), bf_lo(c1), bf_hi(c1)};
;                             const unsigned d0 = hh ? x[i][1].z : x[i][1].x, d1 = hh ? x[i][1].w : x[i][1].y, e0 = hh ? x[i + 1][1].z : x[i + 1][1].x, e1 = hh ? x[i + 1][1].w : x[i + 1][1].y, f0 = hh ? x[i + 2][1].z : x[i + 2][1].x, f1 = hh ? x[i + 2][1].w : x[i + 2][1].y;
;                             y0 = (f32x4){bf_lo(d0), bf_hi(d0), bf_lo(d1), bf_hi(d1)}; y1 = (f32x4){bf_lo(e0), bf_hi(e0), bf_lo(e1), bf_hi(e1)}; y2 = (f32x4){bf_lo(f0), bf_hi(f0), bf_lo(f1), bf_hi(f1)};
;                             av[hh] = wt[0][0][hh] * x0 + wt[1][0][hh] * x1 + wt[2][0][hh] * x2;
;                             bv[hh] = wt[0][1][hh] * y0 + wt[1][1][hh] * y1 + wt[2][1][hh] * y2; }
;                         u32x4 o;
;                         o.x = cvt_pk_bf16(av[0][0] * sigm(av[0][0]) * bv[0][0], av[0][1] * sigm(av[0][1]) * bv[0][1]); o.y = cvt_pk_bf16(av[0][2] * sigm(av[0][2]) * bv[0][2], av[0][3] * sigm(av[0][3]) * bv[0][3]);
	v_pk_mul_f32 v[120:121], v[16:17], v[78:79]
	v_pk_mul_f32 v[118:119], v[18:19], v[76:77]
	v_pk_fma_f32 v[100:101], v[4:5], v[100:101], v[120:121]
	v_pk_fma_f32 v[102:103], v[6:7], v[102:103], v[118:119]
	v_pk_fma_f32 v[100:101], v[32:33], v[96:97], v[100:101]
	v_pk_mul_f32 v[118:119], v[26:27], v[72:73]
	v_mul_f32_e32 v117, 0xbfb8aa3b, v100
	v_exp_f32_e32 v117, v117
	v_pk_fma_f32 v[106:107], v[10:11], v[106:107], v[118:119]
	v_pk_mul_f32 v[118:119], v[22:23], v[94:95]
	v_pk_mul_f32 v[120:121], v[24:25], v[74:75]
	v_pk_fma_f32 v[110:111], v[2:3], v[110:111], v[118:119]
	v_pk_mul_f32 v[118:119], v[30:31], v[84:85]
	v_add_f32_e32 v117, 1.0, v117
	v_pk_fma_f32 v[114:115], v[14:15], v[114:115], v[118:119]
	v_mul_f32_e32 v118, 0xbfb8aa3b, v101
	v_exp_f32_e32 v118, v118
	v_rcp_f32_e32 v117, v117
	v_pk_fma_f32 v[104:105], v[8:9], v[104:105], v[120:121]
	v_pk_fma_f32 v[102:103], v[34:35], v[92:93], v[102:103]
	v_pk_fma_f32 v[104:105], v[40:41], v[82:83], v[104:105]
	v_add_f32_e32 v118, 1.0, v118
	v_mul_f32_e32 v100, v100, v117
	v_rcp_f32_e32 v118, v118
	v_mul_f32_e32 v100, v104, v100
	v_mul_f32_e32 v104, 0xbfb8aa3b, v102
	v_mul_f32_e32 v117, 0xbfb8aa3b, v103
	v_exp_f32_e32 v104, v104
	v_exp_f32_e32 v117, v117
	v_mul_f32_e32 v101, v101, v118
	v_mul_f32_e32 v101, v105, v101
	v_add_f32_e32 v104, 1.0, v104
	v_add_f32_e32 v105, 1.0, v117
	v_rcp_f32_e32 v104, v104
	v_rcp_f32_e32 v105, v105
	v_pk_mul_f32 v[120:121], v[20:21], v[98:99]
	v_cvt_pk_bf16_f32 v100, v100, v101
	v_mul_f32_e32 v101, v102, v104
	v_pk_fma_f32 v[108:109], v[0:1], v[108:109], v[120:121]
	v_mul_f32_e32 v102, v103, v105
	v_pk_fma_f32 v[108:109], v[36:37], v[70:71], v[108:109]
	v_pk_fma_f32 v[106:107], v[42:43], v[80:81], v[106:107]
	v_mul_f32_e32 v103, 0xbfb8aa3b, v108
	v_mul_f32_e32 v104, 0xbfb8aa3b, v109
	v_exp_f32_e32 v103, v103
	v_exp_f32_e32 v104, v104
	v_pk_fma_f32 v[110:111], v[38:39], v[68:69], v[110:111]
	v_mul_f32_e32 v101, v106, v101
	v_add_f32_e32 v103, 1.0, v103
	v_add_f32_e32 v104, 1.0, v104
	v_rcp_f32_e32 v103, v103
	v_rcp_f32_e32 v104, v104
	v_mul_f32_e32 v102, v107, v102
	v_cvt_pk_bf16_f32 v101, v101, v102
	v_mul_f32_e32 v102, v108, v103
	v_mul_f32_e32 v103, v109, v104
	v_mul_f32_e32 v104, 0xbfb8aa3b, v110
	v_mul_f32_e32 v105, 0xbfb8aa3b, v111
	v_exp_f32_e32 v104, v104
	v_exp_f32_e32 v105, v105
	v_pk_mul_f32 v[120:121], v[28:29], v[86:87]
	s_cmp_gt_i32 s8, 14
	v_add_f32_e32 v104, 1.0, v104
	v_add_f32_e32 v105, 1.0, v105
	v_rcp_f32_e32 v104, v104
	v_rcp_f32_e32 v105, v105
	v_pk_fma_f32 v[112:113], v[12:13], v[112:113], v[120:121]
	s_cselect_b32 s18, -16, 0x2000
	v_pk_fma_f32 v[112:113], v[44:45], v[66:67], v[112:113]
	s_cselect_b32 s13, -1, 0
	s_add_u32 s18, s8, s18
	v_mul_f32_e32 v102, v112, v102
	v_mul_f32_e32 v103, v113, v103
	s_addc_u32 s13, s9, s13
	v_pk_fma_f32 v[114:115], v[46:47], v[64:65], v[114:115]
	v_cvt_pk_bf16_f32 v102, v102, v103
	v_mul_f32_e32 v103, v110, v104
	v_mul_f32_e32 v104, v111, v105
	s_add_u32 s18, s18, 1
	v_mul_f32_e32 v103, v114, v103
	v_mul_f32_e32 v104, v115, v104
	s_addc_u32 s13, s13, 0
	v_cvt_pk_bf16_f32 v103, v103, v104
	s_mulk_i32 s13, 0x2c00
	v_mad_u64_u32 v[104:105], s[28:29], s18, v204, v[90:91]
	v_add_u32_e32 v105, s13, v105
	global_store_dwordx4 v[104:105], v[100:103], off

; __device__ __forceinline__ float bf_lo(unsigned w) { return __uint_as_float(w << 16); }
; __global__ void __launch_bounds__(512, 2) mk_fwd(Args a) {
;     ...
;                 for (int lb = l0; lb < l1; lb += 4) {
;                     u32x4 x[6][2];
; #pragma unroll
;                     for (int i = 0; i < 6; ++i) { const int lg = lb - 1 + i; const bool ok = lg >= 0 && lg < LSEQ; const bf16_t* p = U + (size_t)(ok ? phys_of(lg) : 0) * NUP + c;
;                         x[i][0] = *(const u32x4*)p; x[i][1] = *(const u32x4*)(p + DFF);
;                         if (!ok) { x[i][0] = (u32x4){0u, 0u, 0u, 0u}; x[i][1] = (u32x4){0u, 0u, 0u, 0u}; } }
; #pragma unroll
;                     for (int i = 0; i < 4; ++i) { const int lg = lb + i; if (lg < l1) {
;                         f32x4 av[2], bv[2];
; #pragma unroll
;                         for (int hh = 0; hh < 2; ++hh) {
;                             f32x4 x0, x1, x2, y0, y1, y2;
;                             const unsigned a0 = hh ? x[i][0].z : x[i][0].x, a1 = hh ? x[i][0].w : x[i][0].y, b0 = hh ? x[i + 1][0].z : x[i + 1][0].x, b1 = hh ? x[i + 1][0].w : x[i + 1][0].y, c0 = hh ? x[i + 2][0].z : x[i + 2][0].x, c1 = hh ? x[i + 2][0].w : x[i + 2][0].y;
;                             x0 = (f32x4){bf_lo(a0), bf_hi(a0), bf_lo(a1), bf_hi(a1)}; x1 = (f32x4){bf_lo(b0), bf_hi(b0), bf_lo(b1), bf_hi(b1)}; x2 = (f32x4){bf_lo(c0), bf_hi(c0), bf_lo(c1), bf_hi(c1)};
;                             const unsigned d0 = hh ? x[i][1].z : x[i][1].x, d1 = hh ? x[i][1].w : x[i][1].y, e0 = hh ? x[i + 1][1].z : x[i + 1][1].x, e1 = hh ? x[i + 1][1].w : x[i + 1][1].y, f0 = hh ? x[i + 2][1].z : x[i + 2][1].x, f1 = hh ? x[i + 2][1].w : x[i + 2][1].y;
;                             y0 = (f32x4){bf_lo(d0), bf_hi(d0), bf_lo(d1), bf_hi(d1)}; y1 = (f32x4){bf_lo(e0), bf_hi(e0), bf_lo(e1), bf_hi(e1)}; y2 = (f32x4){bf_lo(f0), bf_hi(f0), bf_lo(f1), bf_hi(f1)};
;                             av[hh] = wt[0][0][hh] * x0 + wt[1][0][hh] * x1 + wt[2][0][hh] * x2;
;                             bv[hh] = wt[0][1][hh] * y0 + wt[1][1][hh] * y1 + wt[2][1][hh] * y2; }
;                         u32x4 o;
;                         o.x = cvt_pk_bf16(av[0][0] * sigm(av[0][0]) * bv[0][0], av[0][1] * sigm(av[0][1]) * bv[0][1]); o.y = cvt_pk_bf16(av[0][2] * sigm(av[0][2]) * bv[0][2], av[0][3] * sigm(av[0][3]) * bv[0][3]);
.LBB0_102:
	v_pk_mul_f32 v[108:109], v[18:19], v[92:93]
	v_pk_mul_f32 v[110:111], v[16:17], v[96:97]
	v_pk_fma_f32 v[76:77], v[6:7], v[76:77], v[108:109]
	v_pk_fma_f32 v[78:79], v[4:5], v[78:79], v[110:111]
	v_pk_mul_f32 v[108:109], v[26:27], v[80:81]
	v_pk_mul_f32 v[110:111], v[24:25], v[82:83]
	v_pk_fma_f32 v[72:73], v[10:11], v[72:73], v[108:109]
	v_pk_fma_f32 v[74:75], v[8:9], v[74:75], v[110:111]
	v_pk_fma_f32 v[108:109], v[42:43], v[102:103], v[72:73]
	v_pk_fma_f32 v[72:73], v[40:41], v[100:101], v[74:75]
	v_pk_mul_f32 v[74:75], v[22:23], v[68:69]
	v_pk_mul_f32 v[110:111], v[20:21], v[70:71]
	v_pk_fma_f32 v[74:75], v[2:3], v[94:95], v[74:75]
	v_pk_fma_f32 v[98:99], v[0:1], v[98:99], v[110:111]
	v_pk_fma_f32 v[78:79], v[32:33], v[104:105], v[78:79]
	v_pk_fma_f32 v[94:95], v[38:39], v[62:63], v[74:75]
	v_pk_fma_f32 v[74:75], v[36:37], v[60:61], v[98:99]
	v_pk_mul_f32 v[98:99], v[30:31], v[64:65]
	v_pk_fma_f32 v[76:77], v[34:35], v[106:107], v[76:77]
	v_pk_fma_f32 v[84:85], v[14:15], v[84:85], v[98:99]
	v_mul_f32_e32 v98, 0xbfb8aa3b, v78
	v_exp_f32_e32 v98, v98
	v_mul_f32_e32 v99, 0xbfb8aa3b, v79
	v_exp_f32_e32 v99, v99
	v_pk_mul_f32 v[110:111], v[28:29], v[66:67]
	v_add_f32_e32 v98, 1.0, v98
	v_rcp_f32_e32 v98, v98
	v_add_f32_e32 v99, 1.0, v99
	v_rcp_f32_e32 v99, v99
	s_cmp_gt_i32 s0, 15
	v_mul_f32_e32 v78, v78, v98
	v_mul_f32_e32 v72, v72, v78
	v_mul_f32_e32 v78, v79, v99
	v_mul_f32_e32 v79, 0xbfb8aa3b, v76
	v_mul_f32_e32 v98, 0xbfb8aa3b, v77
	v_exp_f32_e32 v79, v79
	v_exp_f32_e32 v98, v98
	v_mul_f32_e32 v73, v73, v78
	v_cvt_pk_bf16_f32 v72, v72, v73
	v_add_f32_e32 v78, 1.0, v79
	v_add_f32_e32 v79, 1.0, v98
	v_rcp_f32_e32 v78, v78
	v_rcp_f32_e32 v79, v79
	v_pk_fma_f32 v[86:87], v[12:13], v[86:87], v[110:111]
	s_cselect_b32 s1, -16, 0x2000
	v_mul_f32_e32 v73, v76, v78
	v_mul_f32_e32 v76, v77, v79
	v_mul_f32_e32 v77, 0xbfb8aa3b, v74
	v_exp_f32_e32 v77, v77
	v_mul_f32_e32 v78, 0xbfb8aa3b, v75
	v_mul_f32_e32 v73, v108, v73
	v_exp_f32_e32 v78, v78
	v_add_f32_e32 v77, 1.0, v77
	v_rcp_f32_e32 v77, v77
	v_mul_f32_e32 v76, v109, v76
	v_cvt_pk_bf16_f32 v73, v73, v76
	v_mul_f32_e32 v76, 0xbfb8aa3b, v94
	v_mul_f32_e32 v74, v74, v77
	v_mul_f32_e32 v77, 0xbfb8aa3b, v95
	v_exp_f32_e32 v76, v76
	v_exp_f32_e32 v77, v77
	v_add_f32_e32 v78, 1.0, v78
	v_rcp_f32_e32 v78, v78
	v_add_f32_e32 v76, 1.0, v76
	v_add_f32_e32 v77, 1.0, v77
	v_rcp_f32_e32 v76, v76
	v_rcp_f32_e32 v77, v77
	v_pk_fma_f32 v[86:87], v[44:45], v[56:57], v[86:87]
	v_mul_f32_e32 v75, v75, v78
	s_cselect_b32 s0, -1, 0
	s_add_u32 s1, s8, s1
	v_mul_f32_e32 v74, v86, v74
	v_mul_f32_e32 v75, v87, v75
	s_addc_u32 s0, s9, s0
	v_pk_fma_f32 v[84:85], v[46:47], v[58:59], v[84:85]
	v_cvt_pk_bf16_f32 v74, v74, v75
	v_mul_f32_e32 v75, v94, v76
	v_mul_f32_e32 v76, v95, v77
	s_add_u32 s1, s1, 2
	v_mul_f32_e32 v75, v84, v75
	v_mul_f32_e32 v76, v85, v76
	s_addc_u32 s0, s0, 0
	v_cvt_pk_bf16_f32 v75, v75, v76
	s_mul_i32 s13, s0, 0x2c00
	v_mad_u64_u32 v[76:77], s[0:1], s1, v204, v[90:91]
	v_add_u32_e32 v77, s13, v77
	global_store_dwordx4 v[76:77], v[72:75], off
	s_add_i32 s0, s8, 3
	s_cmp_ge_i32 s0, s7
	s_cbranch_scc1 .LBB0_85
.LBB0_103:
	s_waitcnt vmcnt(0) lgkmcnt(0)
	v_cndmask_b32_e32 v76, 0, v51, vcc
	v_cndmask_b32_e32 v51, 0, v49, vcc
	v_cndmask_b32_e32 v49, 0, v48, vcc
	v_pk_mul_f32 v[74:75], v[16:17], v[104:105]
	v_lshlrev_b32_e32 v48, 16, v49
	v_and_b32_e32 v49, 0xffff0000, v49
	v_pk_fma_f32 v[74:75], v[4:5], v[96:97], v[74:75]
	v_pk_mul_f32 v[58:59], v[30:31], v[58:59]
	v_pk_fma_f32 v[48:49], v[32:33], v[48:49], v[74:75]
	v_pk_fma_f32 v[58:59], v[14:15], v[64:65], v[58:59]
	v_mul_f32_e32 v64, 0xbfb8aa3b, v48
	v_exp_f32_e32 v64, v64
	v_mul_f32_e32 v65, 0xbfb8aa3b, v49
	v_exp_f32_e32 v65, v65
	v_cndmask_b32_e32 v79, 0, v55, vcc
	v_add_f32_e32 v64, 1.0, v64
	v_rcp_f32_e32 v64, v64
	v_cndmask_b32_e32 v55, 0, v53, vcc
	v_cndmask_b32_e32 v53, 0, v52, vcc
	v_pk_mul_f32 v[72:73], v[18:19], v[106:107]
	v_pk_mul_f32 v[74:75], v[24:25], v[100:101]
	v_cndmask_b32_e32 v78, 0, v50, vcc
	v_lshlrev_b32_e32 v50, 16, v51
	v_and_b32_e32 v51, 0xffff0000, v51
	v_lshlrev_b32_e32 v52, 16, v53
	v_and_b32_e32 v53, 0xffff0000, v53
	v_pk_fma_f32 v[72:73], v[6:7], v[92:93], v[72:73]
	v_pk_fma_f32 v[74:75], v[8:9], v[82:83], v[74:75]
	v_pk_fma_f32 v[50:51], v[34:35], v[50:51], v[72:73]
	v_pk_fma_f32 v[52:53], v[40:41], v[52:53], v[74:75]
	v_add_f32_e32 v65, 1.0, v65
	v_mul_f32_e32 v48, v48, v64
	v_rcp_f32_e32 v65, v65
	v_mul_f32_e32 v48, v52, v48
	v_mul_f32_e32 v52, 0xbfb8aa3b, v50
	v_mul_f32_e32 v64, 0xbfb8aa3b, v51
	v_exp_f32_e32 v52, v52
	v_exp_f32_e32 v64, v64
	v_mul_f32_e32 v49, v49, v65
	v_mul_f32_e32 v49, v53, v49
	v_add_f32_e32 v52, 1.0, v52
	v_add_f32_e32 v53, 1.0, v64
	v_pk_mul_f32 v[72:73], v[26:27], v[102:103]
	v_rcp_f32_e32 v52, v52
	v_rcp_f32_e32 v53, v53
	v_cndmask_b32_e32 v77, 0, v54, vcc
	v_lshlrev_b32_e32 v54, 16, v55
	v_and_b32_e32 v55, 0xffff0000, v55
	v_pk_fma_f32 v[72:73], v[10:11], v[80:81], v[72:73]
	v_pk_mul_f32 v[60:61], v[20:21], v[60:61]
	v_pk_fma_f32 v[54:55], v[42:43], v[54:55], v[72:73]
	v_lshlrev_b32_e32 v72, 16, v78
	v_and_b32_e32 v73, 0xffff0000, v78
	v_pk_fma_f32 v[60:61], v[0:1], v[70:71], v[60:61]
	v_cvt_pk_bf16_f32 v48, v48, v49
	v_mul_f32_e32 v49, v50, v52
	v_pk_fma_f32 v[60:61], v[36:37], v[72:73], v[60:61]
	v_mul_f32_e32 v50, v51, v53
	v_mul_f32_e32 v51, 0xbfb8aa3b, v60
	v_mul_f32_e32 v52, 0xbfb8aa3b, v61
	v_exp_f32_e32 v51, v51
	v_exp_f32_e32 v52, v52
	v_pk_mul_f32 v[62:63], v[22:23], v[62:63]
	v_lshlrev_b32_e32 v74, 16, v76
	v_add_f32_e32 v51, 1.0, v51
	v_add_f32_e32 v52, 1.0, v52
	v_rcp_f32_e32 v51, v51
	v_rcp_f32_e32 v52, v52
	v_and_b32_e32 v75, 0xffff0000, v76
	v_pk_fma_f32 v[62:63], v[2:3], v[68:69], v[62:63]
	v_mul_f32_e32 v49, v54, v49
	v_pk_fma_f32 v[62:63], v[38:39], v[74:75], v[62:63]
	v_mul_f32_e32 v50, v55, v50
	v_cvt_pk_bf16_f32 v49, v49, v50
	v_mul_f32_e32 v50, v60, v51
	v_mul_f32_e32 v51, v61, v52
	v_mul_f32_e32 v52, 0xbfb8aa3b, v62
	v_mul_f32_e32 v53, 0xbfb8aa3b, v63
	v_exp_f32_e32 v52, v52
	v_exp_f32_e32 v53, v53
	v_pk_mul_f32 v[56:57], v[28:29], v[56:57]
	s_cmp_gt_i32 s0, 15
	v_add_f32_e32 v52, 1.0, v52
	v_add_f32_e32 v53, 1.0, v53
	v_rcp_f32_e32 v52, v52
	v_rcp_f32_e32 v53, v53
	v_lshlrev_b32_e32 v76, 16, v77
	v_and_b32_e32 v77, 0xffff0000, v77
	v_pk_fma_f32 v[56:57], v[12:13], v[66:67], v[56:57]
	s_cselect_b32 s1, -16, 0x2000
	v_pk_fma_f32 v[56:57], v[44:45], v[76:77], v[56:57]
	s_cselect_b32 s0, -1, 0
	s_add_u32 s1, s8, s1
	v_lshlrev_b32_e32 v78, 16, v79
	v_and_b32_e32 v79, 0xffff0000, v79
	v_mul_f32_e32 v50, v56, v50
	v_mul_f32_e32 v51, v57, v51
	s_addc_u32 s0, s9, s0
	v_pk_fma_f32 v[58:59], v[46:47], v[78:79], v[58:59]
	v_cvt_pk_bf16_f32 v50, v50, v51
	v_mul_f32_e32 v51, v62, v52
	v_mul_f32_e32 v52, v63, v53
	s_add_u32 s1, s1, 3
	v_mul_f32_e32 v51, v58, v51
	v_mul_f32_e32 v52, v59, v52
	s_addc_u32 s0, s0, 0
	v_cvt_pk_bf16_f32 v51, v51, v52
	s_mul_i32 s8, s0, 0x2c00
	v_mad_u64_u32 v[52:53], s[0:1], s1, v204, v[90:91]
	v_add_u32_e32 v53, s8, v53
	global_store_dwordx4 v[52:53], v[48:51], off
	s_branch .LBB0_85

; __device__ __forceinline__ u32x4 pack8(f32x4 v0, f32x4 v1) { u32x4 w; w.x = cvt_pk_bf16(v0[0], v0[1]); w.y = cvt_pk_bf16(v0[2], v0[3]); w.z = cvt_pk_bf16(v1[0], v1[1]); w.w = cvt_pk_bf16(v1[2], v1[3]); return w; }
; __global__ void __launch_bounds__(512, 2) mk_fwd(Args a) {
;     ...
;                 for (int r = gw; r < LSEQ; r += NGW) {
;                     f32x4 v[8]; float s = 0.f; const float* hr = H + (size_t)r * DM;
; #pragma unroll
;                     for (int j = 0; j < 8; ++j) { v[j] = *(const f32x4*)(hr + (lane + 64 * (j >> 1)) * 8 + (j & 1) * 4); s += (v[j].x * v[j].x + v[j].y * v[j].y) + (v[j].z * v[j].z + v[j].w * v[j].w); }
;                     const float rs = __builtin_amdgcn_rsqf(wave_sum(s, lane) * (1.f / DM) + EPS);
; #pragma unroll
;                     for (int j = 0; j < 4; ++j) { const int c = (lane + 64 * j) * 8; const f32x4 g0 = *(const f32x4*)(gm + c), g1 = *(const f32x4*)(gm + c + 4);
;                         *(u32x4*)(X + (size_t)r * DM + c) = pg8::pack8(v[2 * j] * rs * g0, v[2 * j + 1] * rs * g1); }
;                 }
.LBB0_110:
	s_nop 0
	v_lshl_add_u64 v[0:1], s[64:65], 0, v[44:45]
	v_add_co_u32_e32 v0, vcc, 0x9901000, v0
	s_add_i32 s0, s0, s72
	s_nop 0
	v_addc_co_u32_e32 v1, vcc, 0, v1, vcc
	global_load_dwordx4 v[28:31], v[0:1], off
	global_load_dwordx4 v[24:27], v[0:1], off offset:16
	v_lshl_add_u64 v[44:45], v[44:45], 0, s[4:5]
	s_cmpk_gt_i32 s0, 0x200f
	s_waitcnt vmcnt(0) lgkmcnt(0)
	v_mov_b32_e32 v4, v29
	v_mov_b32_e32 v5, v25
	v_mov_b32_e32 v2, v28
	v_mov_b32_e32 v3, v24
	v_pk_mul_f32 v[4:5], v[4:5], v[4:5]
	v_mov_b32_e32 v6, v31
	v_mov_b32_e32 v7, v27
	v_pk_fma_f32 v[2:3], v[2:3], v[2:3], v[4:5]
	v_mov_b32_e32 v4, v30
	v_mov_b32_e32 v5, v26
	v_pk_mul_f32 v[6:7], v[6:7], v[6:7]
	s_nop 0
	v_pk_fma_f32 v[4:5], v[4:5], v[4:5], v[6:7]
	s_nop 0
	v_pk_add_f32 v[12:13], v[2:3], v[4:5]
	global_load_dwordx4 v[4:7], v[0:1], off offset:2048
	v_pk_add_f32 v[12:13], v[12:13], v[12:13] op_sel:[0,1] op_sel_hi:[1,0]
	s_waitcnt vmcnt(0) lgkmcnt(0)
	v_pk_mul_f32 v[2:3], v[6:7], v[6:7]
	v_pk_mul_f32 v[8:9], v[4:5], v[4:5]
	s_nop 0
	v_pk_mov_b32 v[10:11], v[8:9], v[2:3] op_sel:[1,0]
	v_mov_b32_e32 v9, v3
	v_pk_add_f32 v[14:15], v[10:11], v[8:9]
	v_lshl_add_u64 v[8:9], s[64:65], 0, v[42:43]
	v_add_co_u32_e32 v16, vcc, s6, v8
	global_load_dwordx4 v[0:3], v[0:1], off offset:2064
	s_nop 0
	v_addc_co_u32_e32 v17, vcc, 0, v9, vcc
	global_load_dwordx4 v[8:11], v[16:17], off
	v_pk_add_f32 v[14:15], v[14:15], v[14:15] op_sel:[0,1] op_sel_hi:[1,0]
	v_lshl_add_u64 v[42:43], v[42:43], 0, s[4:5]
	s_waitcnt vmcnt(0) lgkmcnt(0)
	v_mul_f32_e32 v18, v8, v8
	v_mul_f32_e32 v19, v9, v9
	v_mov_b32_e32 v13, v18
	v_mov_b32_e32 v15, v19
	v_pk_add_f32 v[12:13], v[12:13], v[14:15]
	v_mul_f32_e32 v14, v1, v1
	v_mul_f32_e32 v18, v3, v3
	v_mul_f32_e32 v20, v10, v10
	v_mul_f32_e32 v21, v11, v11
	v_pk_fma_f32 v[14:15], v[0:1], v[0:1], v[14:15] op_sel_hi:[1,1,0]
	v_pk_fma_f32 v[18:19], v[2:3], v[2:3], v[18:19] op_sel_hi:[1,1,0]
	v_mov_b32_e32 v15, v20
	v_mov_b32_e32 v19, v21
	v_pk_add_f32 v[14:15], v[14:15], v[18:19]
	s_nop 0
	v_pk_add_f32 v[54:55], v[12:13], v[14:15]
	global_load_dwordx4 v[12:15], v[16:17], off offset:16
	v_pk_add_f32 v[54:55], v[54:55], v[54:55] op_sel:[0,1] op_sel_hi:[1,0]
	s_waitcnt vmcnt(0) lgkmcnt(0)
	v_pk_mul_f32 v[16:17], v[14:15], v[14:15]
	v_pk_mul_f32 v[18:19], v[12:13], v[12:13]
	s_nop 0
	v_pk_mov_b32 v[20:21], v[18:19], v[16:17] op_sel:[1,0]
	v_mov_b32_e32 v19, v17
	v_lshl_add_u64 v[16:17], s[64:65], 0, v[40:41]
	v_add_co_u32_e32 v16, vcc, s6, v16
	v_pk_add_f32 v[56:57], v[20:21], v[18:19]
	s_nop 0
	v_addc_co_u32_e32 v17, vcc, 0, v17, vcc
	global_load_dwordx4 v[20:23], v[16:17], off
	s_nop 0
	global_load_dwordx4 v[16:19], v[16:17], off offset:16
	v_pk_add_f32 v[56:57], v[56:57], v[56:57] op_sel:[0,1] op_sel_hi:[1,0]
	v_lshl_add_u64 v[40:41], v[40:41], 0, s[4:5]
	s_waitcnt vmcnt(0) lgkmcnt(0)
	v_mul_f32_e32 v46, v16, v16
	v_mul_f32_e32 v53, v17, v17
	v_mov_b32_e32 v55, v46
	v_mov_b32_e32 v57, v53
	v_mul_f32_e32 v46, v21, v21
	v_mul_f32_e32 v58, v18, v18
	v_pk_add_f32 v[54:55], v[54:55], v[56:57]
	v_pk_fma_f32 v[56:57], v[20:21], v[20:21], v[46:47] op_sel_hi:[1,1,0]
	v_mul_f32_e32 v46, v23, v23
	v_mul_f32_e32 v60, v19, v19
	v_mov_b32_e32 v57, v58
	v_pk_fma_f32 v[58:59], v[22:23], v[22:23], v[46:47] op_sel_hi:[1,1,0]
	s_nop 0
	v_mov_b32_e32 v59, v60
	v_pk_add_f32 v[56:57], v[56:57], v[58:59]
	s_nop 0
	v_pk_add_f32 v[54:55], v[54:55], v[56:57]
	s_nop 0
	v_add_f32_e32 v46, v54, v55
	global_load_dwordx4 v[54:57], v[32:33], off offset:16
	global_load_dwordx4 v[58:61], v[32:33], off
	ds_bpermute_b32 v53, v47, v46
	s_waitcnt lgkmcnt(0)
	v_add_f32_e32 v46, v46, v53
	ds_bpermute_b32 v53, v48, v46
	s_waitcnt lgkmcnt(0)
	v_add_f32_e32 v46, v46, v53
	ds_bpermute_b32 v53, v49, v46
	s_waitcnt lgkmcnt(0)
	v_add_f32_e32 v46, v46, v53
	ds_bpermute_b32 v53, v50, v46
	s_waitcnt lgkmcnt(0)
	v_add_f32_e32 v46, v46, v53
	ds_bpermute_b32 v53, v51, v46
	s_waitcnt lgkmcnt(0)
	v_add_f32_e32 v46, v46, v53
	ds_bpermute_b32 v53, v52, v46
	s_waitcnt lgkmcnt(0)
	v_add_f32_e32 v46, v46, v53
	v_fmamk_f32 v46, v46, 0x3a000000, v202
	v_rsq_f32_e32 v46, v46
	s_nop 0
	v_pk_mul_f32 v[28:29], v[46:47], v[28:29] op_sel_hi:[0,1]
	v_pk_mul_f32 v[24:25], v[46:47], v[24:25] op_sel_hi:[0,1]
	v_pk_mul_f32 v[26:27], v[46:47], v[26:27] op_sel_hi:[0,1]
	v_pk_mul_f32 v[30:31], v[46:47], v[30:31] op_sel_hi:[0,1]
	v_pk_mul_f32 v[0:1], v[46:47], v[0:1] op_sel_hi:[0,1]
	v_pk_mul_f32 v[2:3], v[46:47], v[2:3] op_sel_hi:[0,1]
	v_pk_mul_f32 v[4:5], v[46:47], v[4:5] op_sel_hi:[0,1]
	v_pk_mul_f32 v[6:7], v[46:47], v[6:7] op_sel_hi:[0,1]
	v_pk_mul_f32 v[8:9], v[46:47], v[8:9] op_sel_hi:[0,1]
	v_pk_mul_f32 v[10:11], v[46:47], v[10:11] op_sel_hi:[0,1]
	s_waitcnt vmcnt(1)
	v_pk_mul_f32 v[56:57], v[56:57], v[26:27]
	s_waitcnt vmcnt(0)
	v_pk_mul_f32 v[28:29], v[58:59], v[28:29]
	v_pk_mul_f32 v[26:27], v[54:55], v[24:25]
	v_cvt_pk_bf16_f32 v24, v28, v29
	v_lshl_add_u64 v[28:29], s[64:65], 0, v[38:39]
	v_add_co_u32_e32 v28, vcc, s7, v28
	v_pk_mul_f32 v[30:31], v[60:61], v[30:31]
	s_nop 0
	v_addc_co_u32_e32 v29, vcc, 0, v29, vcc
	v_cvt_pk_bf16_f32 v25, v30, v31
	v_cvt_pk_bf16_f32 v26, v26, v27
	v_cvt_pk_bf16_f32 v27, v56, v57
	global_store_dwordx4 v[28:29], v[24:27], off
	global_load_dwordx4 v[24:27], v[32:33], off offset:2064
	s_nop 0
	global_load_dwordx4 v[54:57], v[32:33], off offset:2048
	v_lshl_add_u64 v[38:39], v[38:39], 0, s[2:3]
	s_waitcnt vmcnt(0)
	v_pk_mul_f32 v[26:27], v[26:27], v[2:3]
	v_pk_mul_f32 v[2:3], v[24:25], v[0:1]
	v_pk_mul_f32 v[6:7], v[56:57], v[6:7]
	v_pk_mul_f32 v[4:5], v[54:55], v[4:5]
	s_nop 0
	v_cvt_pk_bf16_f32 v0, v4, v5
	v_cvt_pk_bf16_f32 v1, v6, v7
	v_cvt_pk_bf16_f32 v2, v2, v3
	v_cvt_pk_bf16_f32 v3, v26, v27
	global_store_dwordx4 v[28:29], v[0:3], off offset:1024
	global_load_dwordx4 v[0:3], v[34:35], off offset:16
	s_nop 0
	global_load_dwordx4 v[4:7], v[34:35], off
	s_waitcnt vmcnt(0)
	v_pk_mul_f32 v[6:7], v[6:7], v[10:11]
	v_pk_mul_f32 v[4:5], v[4:5], v[8:9]
	v_pk_mul_f32 v[8:9], v[46:47], v[12:13] op_sel_hi:[0,1]
	v_pk_mul_f32 v[10:11], v[46:47], v[14:15] op_sel_hi:[0,1]
	v_pk_mul_f32 v[10:11], v[2:3], v[10:11]
	v_pk_mul_f32 v[2:3], v[0:1], v[8:9]
	v_cvt_pk_bf16_f32 v0, v4, v5
	v_cvt_pk_bf16_f32 v1, v6, v7
	v_pk_mul_f32 v[8:9], v[46:47], v[20:21] op_sel_hi:[0,1]
	v_cvt_pk_bf16_f32 v2, v2, v3
	v_cvt_pk_bf16_f32 v3, v10, v11
	global_store_dwordx4 v[28:29], v[0:3], off offset:2048
	global_load_dwordx4 v[0:3], v[36:37], off offset:16
	s_nop 0
	global_load_dwordx4 v[4:7], v[36:37], off
	v_pk_mul_f32 v[10:11], v[46:47], v[22:23] op_sel_hi:[0,1]
	s_waitcnt vmcnt(0)
	v_pk_mul_f32 v[6:7], v[6:7], v[10:11]
	v_pk_mul_f32 v[4:5], v[4:5], v[8:9]
	v_pk_mul_f32 v[8:9], v[46:47], v[16:17] op_sel_hi:[0,1]
	v_pk_mul_f32 v[10:11], v[46:47], v[18:19] op_sel_hi:[0,1]
	v_pk_mul_f32 v[10:11], v[2:3], v[10:11]
	v_pk_mul_f32 v[2:3], v[0:1], v[8:9]
	v_cvt_pk_bf16_f32 v0, v4, v5
	v_cvt_pk_bf16_f32 v1, v6, v7
	s_nop 0
	v_cvt_pk_bf16_f32 v2, v2, v3
	v_cvt_pk_bf16_f32 v3, v10, v11
	global_store_dwordx4 v[28:29], v[0:3], off offset:3072
	s_cbranch_scc0 .LBB0_110

; __device__ __forceinline__ bf16_t to_bf1(float f) { return (bf16_t)(cvt_pk_bf16(f, 0.f) & 0xffffu); }
; __global__ void __launch_bounds__(512, 2) mk_fwd(Args a) {
;     ...
;             { const float* PM = (const float*)(ws + O_PM);
;               for (int it = gw; it < 16 * 16; it += NGW) { const int h = it >> 4, row = it & 15; float s0 = 0.f, s1 = 0.f, ls = 0.f;
; #pragma unroll
;                   for (int p = 0; p < NMP; ++p) { const float* pp = PM + ((size_t)(h * NMP + p) * 16 + row) * 128; s0 += pp[lane]; s1 += pp[64 + lane]; ls += PM[PM_L + (h * NMP + p) * 16 + row]; }
;                   const float rl = 1.f / ls; bf16_t* op = AO + (size_t)(LREAL + row) * DM + h * 128;
;                   op[lane] = to_bf1(s0 * rl); op[64 + lane] = to_bf1(s1 * rl); } }
.LBB0_118:
	s_ashr_i32 s7, s6, 4
	s_and_b32 s13, s6, 15
	s_mul_i32 s8, s7, 7
	s_lshl_b32 s28, s13, 9
	s_mov_b32 s29, s12
	s_ashr_i32 s9, s8, 31
	s_waitcnt lgkmcnt(0)
	v_lshl_add_u64 v[2:3], v[0:1], 0, s[28:29]
	s_lshl_b64 s[28:29], s[8:9], 13
	v_lshl_add_u64 v[4:5], v[2:3], 0, s[28:29]
	global_load_dword v6, v[4:5], off
	s_mul_i32 s28, s7, 0x70
	global_load_dword v4, v[4:5], off offset:256
	s_ashr_i32 s29, s28, 31
	s_lshl_b64 s[28:29], s[28:29], 2
	s_add_u32 s18, s0, s28
	s_addc_u32 s24, s1, s29
	s_lshl_b32 s9, s13, 2
	s_add_u32 s18, s18, s9
	s_addc_u32 s24, s24, 0
	v_mov_b32_e32 v5, s24
	s_add_i32 s28, s8, 1
	s_ashr_i32 s29, s28, 31
	s_lshl_b64 s[36:37], s[28:29], 13
	s_lshl_b32 s28, s28, 4
	s_ashr_i32 s29, s28, 31
	s_lshl_b64 s[28:29], s[28:29], 2
	s_waitcnt vmcnt(0) lgkmcnt(0)
	v_add_f32_e32 v6, 0, v6
	v_add_f32_e32 v7, 0, v4
	v_mov_b32_e32 v4, s18
	v_add_co_u32_e32 v4, vcc, s26, v4
	s_add_u32 s18, s0, s28
	s_nop 0
	v_addc_co_u32_e32 v5, vcc, 0, v5, vcc
	global_load_dword v4, v[4:5], off
	s_addc_u32 s24, s1, s29
	s_add_u32 s18, s18, s9
	s_addc_u32 s24, s24, 0
	s_add_i32 s28, s8, 2
	s_ashr_i32 s29, s28, 31
	s_waitcnt vmcnt(0) lgkmcnt(0)
	v_add_f32_e32 v8, 0, v4
	v_lshl_add_u64 v[4:5], v[2:3], 0, s[36:37]
	global_load_dword v9, v[4:5], off
	s_lshl_b64 s[36:37], s[28:29], 13
	global_load_dword v4, v[4:5], off offset:256
	v_mov_b32_e32 v5, s24
	s_lshl_b32 s28, s28, 4
	s_ashr_i32 s29, s28, 31
	s_lshl_b64 s[28:29], s[28:29], 2
	s_waitcnt vmcnt(0) lgkmcnt(0)
	v_add_f32_e32 v6, v6, v9
	v_add_f32_e32 v7, v7, v4
	v_mov_b32_e32 v4, s18
	v_add_co_u32_e32 v4, vcc, s26, v4
	s_add_u32 s18, s0, s28
	s_nop 0
	v_addc_co_u32_e32 v5, vcc, 0, v5, vcc
	global_load_dword v4, v[4:5], off
	s_addc_u32 s24, s1, s29
	s_add_u32 s18, s18, s9
	s_addc_u32 s24, s24, 0
	s_add_i32 s28, s8, 3
	s_ashr_i32 s29, s28, 31
	s_waitcnt vmcnt(0) lgkmcnt(0)
	v_add_f32_e32 v8, v8, v4
	v_lshl_add_u64 v[4:5], v[2:3], 0, s[36:37]
	global_load_dword v9, v[4:5], off
	s_lshl_b64 s[36:37], s[28:29], 13
	global_load_dword v4, v[4:5], off offset:256
	v_mov_b32_e32 v5, s24
	s_lshl_b32 s28, s28, 4
	s_ashr_i32 s29, s28, 31
	s_lshl_b64 s[28:29], s[28:29], 2
	s_waitcnt vmcnt(0) lgkmcnt(0)
	v_add_f32_e32 v6, v6, v9
	v_add_f32_e32 v7, v7, v4
	v_mov_b32_e32 v4, s18
	v_add_co_u32_e32 v4, vcc, s26, v4
	s_add_u32 s18, s0, s28
	s_nop 0
	v_addc_co_u32_e32 v5, vcc, 0, v5, vcc
	global_load_dword v4, v[4:5], off
	s_addc_u32 s24, s1, s29
	s_add_u32 s18, s18, s9
	s_addc_u32 s24, s24, 0
	s_add_i32 s28, s8, 4
	s_ashr_i32 s29, s28, 31
	s_waitcnt vmcnt(0) lgkmcnt(0)
	v_add_f32_e32 v8, v8, v4
	v_lshl_add_u64 v[4:5], v[2:3], 0, s[36:37]
	global_load_dword v9, v[4:5], off
	s_lshl_b64 s[36:37], s[28:29], 13
	global_load_dword v4, v[4:5], off offset:256
	v_mov_b32_e32 v5, s24
	s_lshl_b32 s28, s28, 4
	s_ashr_i32 s29, s28, 31
	s_lshl_b64 s[28:29], s[28:29], 2
	s_waitcnt vmcnt(0) lgkmcnt(0)
	v_add_f32_e32 v6, v6, v9
	v_add_f32_e32 v7, v7, v4
	v_mov_b32_e32 v4, s18
	v_add_co_u32_e32 v4, vcc, s26, v4
	s_add_u32 s18, s0, s28
	s_nop 0
	v_addc_co_u32_e32 v5, vcc, 0, v5, vcc
	global_load_dword v4, v[4:5], off
	s_addc_u32 s24, s1, s29
	s_add_u32 s18, s18, s9
	s_addc_u32 s24, s24, 0
	s_add_i32 s28, s8, 5
	s_ashr_i32 s29, s28, 31
	s_waitcnt vmcnt(0) lgkmcnt(0)
	v_add_f32_e32 v8, v8, v4
	v_lshl_add_u64 v[4:5], v[2:3], 0, s[36:37]
	global_load_dword v9, v[4:5], off
	s_lshl_b64 s[36:37], s[28:29], 13
	global_load_dword v4, v[4:5], off offset:256
	v_mov_b32_e32 v5, s24
	s_lshl_b32 s28, s28, 4
	s_ashr_i32 s29, s28, 31
	s_lshl_b64 s[28:29], s[28:29], 2
	s_waitcnt vmcnt(0) lgkmcnt(0)
	v_add_f32_e32 v6, v6, v9
	v_add_f32_e32 v7, v7, v4
	v_mov_b32_e32 v4, s18
	v_add_co_u32_e32 v4, vcc, s26, v4
	s_add_u32 s18, s0, s28
	s_nop 0
	v_addc_co_u32_e32 v5, vcc, 0, v5, vcc
	global_load_dword v4, v[4:5], off
	s_addc_u32 s24, s1, s29
	s_add_u32 s18, s18, s9
	s_addc_u32 s24, s24, 0
	s_add_i32 s28, s8, 6
	s_ashr_i32 s29, s28, 31
	s_waitcnt vmcnt(0) lgkmcnt(0)
	v_add_f32_e32 v8, v8, v4
	v_lshl_add_u64 v[4:5], v[2:3], 0, s[36:37]
	global_load_dword v9, v[4:5], off
	s_lshl_b64 s[36:37], s[28:29], 13
	global_load_dword v4, v[4:5], off offset:256
	v_mov_b32_e32 v5, s24
	v_lshl_add_u64 v[2:3], v[2:3], 0, s[36:37]
	s_lshl_b32 s28, s28, 4
	s_ashr_i32 s29, s28, 31
	s_lshl_b64 s[28:29], s[28:29], 2
	s_add_u32 s8, s0, s28
	s_waitcnt vmcnt(0) lgkmcnt(0)
	v_add_f32_e32 v6, v6, v9
	v_add_f32_e32 v7, v7, v4
	v_mov_b32_e32 v4, s18
	v_add_co_u32_e32 v4, vcc, s26, v4
	s_addc_u32 s18, s1, s29
	s_nop 0
	v_addc_co_u32_e32 v5, vcc, 0, v5, vcc
	global_load_dword v4, v[4:5], off
	s_add_u32 s8, s8, s9
	global_load_dword v5, v[2:3], off
	s_addc_u32 s9, s18, 0
	global_load_dword v2, v[2:3], off offset:256
	v_mov_b32_e32 v3, s9
	s_waitcnt vmcnt(0) lgkmcnt(0)
	v_add_f32_e32 v4, v8, v4
	v_add_f32_e32 v5, v6, v5
	v_add_f32_e32 v6, v7, v2
	v_mov_b32_e32 v2, s8
	v_add_co_u32_e32 v2, vcc, s26, v2
	s_nop 1
	v_addc_co_u32_e32 v3, vcc, 0, v3, vcc
	global_load_dword v2, v[2:3], off
	s_waitcnt vmcnt(0) lgkmcnt(0)
	v_add_f32_e32 v2, v4, v2
	v_div_scale_f32 v3, s[8:9], v2, v2, 1.0
	v_rcp_f32_e32 v4, v3
	s_lshl_b32 s8, s13, 12
	s_add_u32 s13, s82, s8
	s_addc_u32 s18, s83, 0
	v_fma_f32 v7, -v3, v4, 1.0
	v_fmac_f32_e32 v4, v7, v4
	v_div_scale_f32 v7, vcc, 1.0, v2, 1.0
	v_mul_f32_e32 v8, v7, v4
	v_fma_f32 v9, -v3, v8, v7
	v_fmac_f32_e32 v8, v9, v4
	s_lshl_b32 s8, s7, 7
	v_fma_f32 v3, -v3, v8, v7
	s_ashr_i32 s9, s8, 31
	v_div_fmas_f32 v3, v3, v4, v8
	s_lshl_b64 s[8:9], s[8:9], 1
	v_div_fixup_f32 v7, v3, v2, 1.0
	s_add_u32 s8, s13, s8
	s_addc_u32 s9, s18, s9
	v_mul_f32_e32 v2, v7, v5
	v_cvt_pk_bf16_f32 v8, v2, v145
	v_lshl_add_u64 v[2:3], v[150:151], 1, s[8:9]
	s_mov_b64 s[8:9], 0x2000000
	v_lshl_add_u64 v[4:5], v[2:3], 0, s[8:9]
	v_add_co_u32_e32 v2, vcc, 0x2000000, v2
	s_add_i32 s6, s6, s72
	s_nop 0
	v_addc_co_u32_e32 v3, vcc, 0, v3, vcc
	global_store_short v[2:3], v8, off
	v_mul_f32_e32 v2, v6, v7
	s_cmpk_gt_i32 s6, 0xff
	v_cvt_pk_bf16_f32 v2, v2, v145
	global_store_short v[4:5], v2, off offset:128
	s_cbranch_scc0 .LBB0_118

; __device__ __forceinline__ unsigned addpair(unsigned x, unsigned y, float sg) { return cvt_pk_bf16(bf_lo(x) + sg * bf_lo(y), bf_hi(x) + sg * bf_hi(y)); }
; __global__ void __launch_bounds__(512, 2) mk_fwd(Args a) {
;     ...
;             for (int r = gw; r < LSEQ; r += NGW) {
;                 const bool v = r < LSEQ; const int kk = v ? pos_of(r) : 0; const bool up = kk > HF; const int kf = up ? LSEQ - kk : kk;
;                 const bf16_t* u = UW + (size_t)kf * 1024; const bf16_t* w = UW + (size_t)MH * 1024 + (size_t)kf * 1024;
; #pragma unroll
;                 for (int j = 0; j < 2; ++j) { const int c = (lane + 64 * j) * 8; u32x4 o = {0u, 0u, 0u, 0u};
;                     if (v) { const u32x4 x = *(const u32x4*)(u + c), y = *(const u32x4*)(w + c); const float sg = up ? 1.f : -1.f;
;                         o.x = addpair(x.x, y.x, sg); o.y = addpair(x.y, y.y, sg); o.z = addpair(x.z, y.z, sg); o.w = addpair(x.w, y.w, sg); }
;                     *(u32x4*)(CC + (size_t)r * 1024 + c) = o; }
.LBB0_121:
	s_cmpk_lt_i32 s1, 0x2000
	s_cselect_b32 s6, 16, 0xffffe000
	s_add_i32 s8, s6, s1
	s_sub_i32 s9, s0, s6
	s_cmpk_gt_i32 s8, 0x1008
	s_cselect_b64 s[6:7], -1, 0
	v_cndmask_b32_e64 v18, -1.0, 1.0, s[6:7]
	s_and_b64 s[6:7], s[6:7], exec
	s_cselect_b32 s6, s9, s8
	s_ashr_i32 s7, s6, 31
	s_lshl_b64 s[6:7], s[6:7], 11
	v_lshl_add_u64 v[14:15], v[0:1], 0, s[6:7]
	v_lshl_add_u64 v[16:17], v[2:3], 0, s[6:7]
	global_load_dwordx4 v[6:9], v[14:15], off
	global_load_dwordx4 v[10:13], v[16:17], off
	s_add_i32 s1, s1, s72
	s_sub_i32 s0, s0, s72
	s_cmpk_gt_i32 s1, 0x200f
	s_waitcnt vmcnt(0) lgkmcnt(0)
	v_lshlrev_b32_e32 v19, 16, v6
	v_lshlrev_b32_e32 v20, 16, v10
	v_and_b32_e32 v6, 0xffff0000, v6
	v_and_b32_e32 v10, 0xffff0000, v10
	v_lshlrev_b32_e32 v21, 16, v7
	v_lshlrev_b32_e32 v22, 16, v11
	v_and_b32_e32 v7, 0xffff0000, v7
	v_and_b32_e32 v11, 0xffff0000, v11
	v_lshlrev_b32_e32 v23, 16, v8
	v_lshlrev_b32_e32 v24, 16, v12
	v_and_b32_e32 v8, 0xffff0000, v8
	v_and_b32_e32 v12, 0xffff0000, v12
	v_lshlrev_b32_e32 v25, 16, v9
	v_lshlrev_b32_e32 v26, 16, v13
	v_and_b32_e32 v9, 0xffff0000, v9
	v_and_b32_e32 v13, 0xffff0000, v13
	v_fmac_f32_e32 v6, v18, v10
	v_fmac_f32_e32 v7, v18, v11
	v_fmac_f32_e32 v8, v18, v12
	v_fmac_f32_e32 v9, v18, v13
	v_fmac_f32_e32 v19, v18, v20
	v_fmac_f32_e32 v21, v18, v22
	v_fmac_f32_e32 v23, v18, v24
	v_fmac_f32_e32 v25, v18, v26
	v_cvt_pk_bf16_f32 v6, v19, v6
	v_cvt_pk_bf16_f32 v7, v21, v7
	v_cvt_pk_bf16_f32 v8, v23, v8
	v_cvt_pk_bf16_f32 v9, v25, v9
	global_store_dwordx4 v[4:5], v[6:9], off
	global_load_dwordx4 v[6:9], v[14:15], off offset:1024
	s_nop 0
	global_load_dwordx4 v[10:13], v[16:17], off offset:1024
	s_waitcnt vmcnt(0) lgkmcnt(0)
	v_lshlrev_b32_e32 v14, 16, v6
	v_lshlrev_b32_e32 v15, 16, v10
	v_and_b32_e32 v6, 0xffff0000, v6
	v_and_b32_e32 v10, 0xffff0000, v10
	v_lshlrev_b32_e32 v16, 16, v7
	v_lshlrev_b32_e32 v17, 16, v11
	v_and_b32_e32 v7, 0xffff0000, v7
	v_and_b32_e32 v11, 0xffff0000, v11
	v_lshlrev_b32_e32 v19, 16, v8
	v_lshlrev_b32_e32 v20, 16, v12
	v_and_b32_e32 v8, 0xffff0000, v8
	v_and_b32_e32 v12, 0xffff0000, v12
	v_lshlrev_b32_e32 v21, 16, v9
	v_lshlrev_b32_e32 v22, 16, v13
	v_and_b32_e32 v9, 0xffff0000, v9
	v_and_b32_e32 v13, 0xffff0000, v13
	v_fmac_f32_e32 v6, v18, v10
	v_fmac_f32_e32 v7, v18, v11
	v_fmac_f32_e32 v8, v18, v12
	v_fmac_f32_e32 v9, v18, v13
	v_fmac_f32_e32 v14, v18, v15
	v_fmac_f32_e32 v16, v18, v17
	v_fmac_f32_e32 v19, v18, v20
	v_fmac_f32_e32 v21, v18, v22
	v_cvt_pk_bf16_f32 v6, v14, v6
	v_cvt_pk_bf16_f32 v7, v16, v7
	v_cvt_pk_bf16_f32 v8, v19, v8
	v_cvt_pk_bf16_f32 v9, v21, v9
	global_store_dwordx4 v[4:5], v[6:9], off offset:1024
	v_lshl_add_u64 v[4:5], v[4:5], 0, s[80:81]
	s_cbranch_scc0 .LBB0_121

; __device__ __forceinline__ float shx(float v, int o, int lane) { return __int_as_float(__builtin_amdgcn_ds_bpermute((lane ^ o) << 2, __float_as_int(v))); }
; __device__ __forceinline__ int crow(int r, int hi) { return (r & 3) + 8 * (r >> 2) + 4 * hi; }
; __device__ __forceinline__ void attn_unit(const bf16_t* __restrict__ Qb, const bf16_t* __restrict__ Kh, const bf16_t* __restrict__ Vh, bf16_t* __restrict__ Ob,
;                                           LAS unsigned char* lds, float MB, int tid, int nrows, int t0, int t1, float* part, float* partl) {
;     ...
;     if (act && part) {
;         l_reg += shx(l_reg, 32, lane);
;         if (hi == 0 && r32 < 16) partl[r32] = l_reg;
; #pragma unroll
;         for (int r = 0; r < 8; ++r) {
; #pragma unroll
;             for (int d0 = 0; d0 < 4; ++d0) part[crow(r, hi) * 128 + d0 * 32 + r32] = o[d0][r]; }
.LBB0_127:
	s_or_b64 exec, exec, s[48:49]
	s_lshl_b64 s[28:29], s[36:37], 13
	s_add_u32 s26, s6, s28
	s_addc_u32 s28, s7, s29
	s_and_b64 s[8:9], s[8:9], exec
	s_cselect_b32 s8, s28, 0
	s_cselect_b32 s9, s26, 0
	s_waitcnt lgkmcnt(0)
	v_mov_b32_e32 v40, s9
	v_mov_b32_e32 v41, s8
	v_lshl_add_u64 v[40:41], v[200:201], 2, v[40:41]
	s_movk_i32 s8, 0x1000
	global_store_dword v[40:41], v0, off
	global_store_dword v[40:41], v1, off offset:512
	global_store_dword v[40:41], v2, off offset:1024
	global_store_dword v[40:41], v3, off offset:1536
	global_store_dword v[40:41], v4, off offset:64
	global_store_dword v[40:41], v5, off offset:576
	global_store_dword v[40:41], v6, off offset:1088
	global_store_dword v[40:41], v7, off offset:1600
	global_store_dword v[40:41], v8, off offset:128
	global_store_dword v[40:41], v9, off offset:640
	global_store_dword v[40:41], v10, off offset:1152
	global_store_dword v[40:41], v11, off offset:1664
	global_store_dword v[40:41], v12, off offset:192
	global_store_dword v[40:41], v13, off offset:704
	global_store_dword v[40:41], v14, off offset:1216
	global_store_dword v[40:41], v15, off offset:1728
	global_store_dword v[40:41], v16, off offset:256
	global_store_dword v[40:41], v17, off offset:768
	global_store_dword v[40:41], v18, off offset:1280
	global_store_dword v[40:41], v19, off offset:1792
	global_store_dword v[40:41], v20, off offset:320
	global_store_dword v[40:41], v21, off offset:832
	global_store_dword v[40:41], v22, off offset:1344
	global_store_dword v[40:41], v23, off offset:1856
	global_store_dword v[40:41], v24, off offset:384
	global_store_dword v[40:41], v25, off offset:896
	global_store_dword v[40:41], v26, off offset:1408
	global_store_dword v[40:41], v27, off offset:1920
	global_store_dword v[40:41], v28, off offset:448
	global_store_dword v[40:41], v29, off offset:960
	global_store_dword v[40:41], v30, off offset:1472
	global_store_dword v[40:41], v31, off offset:1984

; __device__ __forceinline__ bf16_t to_bf1(float f) { return (bf16_t)(cvt_pk_bf16(f, 0.f) & 0xffffu); }
; __device__ __forceinline__ float shx(float v, int o, int lane) { return __int_as_float(__builtin_amdgcn_ds_bpermute((lane ^ o) << 2, __float_as_int(v))); }
; __device__ __forceinline__ int crow(int r, int hi) { return (r & 3) + 8 * (r >> 2) + 4 * hi; }
; __device__ __forceinline__ void attn_unit(const bf16_t* __restrict__ Qb, const bf16_t* __restrict__ Kh, const bf16_t* __restrict__ Vh, bf16_t* __restrict__ Ob,
;                                           LAS unsigned char* lds, float MB, int tid, int nrows, int t0, int t1, float* part, float* partl) {
;     ...
;     } else if (act) {
;     l_reg += shx(l_reg, 32, lane);
;     if (hi == 0) li_l[r32] = l_reg;
;     asm volatile("s_waitcnt lgkmcnt(0)" ::: "memory");
;     float rli[16];
; #pragma unroll
;     for (int r = 0; r < 16; ++r) rli[r] = __builtin_amdgcn_rcpf(li_l[crow(r, hi)]);
;     int r32e = r32; asm volatile("" : "+v"(r32e));
;     const unsigned ob = (unsigned)((wid * 32) * LDO + r32e) * 2u;
; #pragma unroll
;     for (int r = 0; r < 16; ++r) { const int orow = crow(r, hi);
;         if (wid * 32 + orow < nrows) {
; #pragma unroll
;         for (int d0 = 0; d0 < 4; ++d0) *(bf16_t*)((char*)Ob + ob + (unsigned)(orow * LDO + d0 * 32) * 2u) = to_bf1(o[d0][r] * rli[r]); } }
.LBB0_143:
	s_andn2_b64 vcc, exec, s[50:51]
	s_cbranch_vccnz .LBB0_179
	ds_bpermute_b32 v64, v222, v155
	ds_bpermute_b32 v65, v222, v149
	s_and_b32 s37, s37, 0x3fffffc0
	s_lshl_b32 s37, s37, 2
	s_add_i32 s37, s37, 0x14000
	v_xor_b32_e32 v66, 0xc0, v222
	s_waitcnt lgkmcnt(0)
	v_add_f32_e32 v64, v155, v64
	v_add_f32_e32 v65, v149, v65
	s_nop 0
	ds_bpermute_b32 v67, v66, v64
	ds_bpermute_b32 v68, v66, v65
	s_waitcnt lgkmcnt(0)
	v_add_f32_e32 v64, v64, v67
	v_add_f32_e32 v65, v65, v68
	s_and_saveexec_b64 s[50:51], s[0:1]
	v_lshl_add_u32 v66, v151, 2, s37
	ds_write_b32 v66, v64
	ds_write_b32 v66, v65 offset:64
	s_or_b64 exec, exec, s[50:51]
	s_waitcnt lgkmcnt(0)
	v_and_b32_e32 v66, 0x30, v150
	v_add_u32_e32 v66, s37, v66
	ds_read_b128 v[68:71], v66
	ds_read_b128 v[72:75], v66 offset:64
	s_lshl_b64 s[46:47], s[48:49], 12
	s_add_u32 s42, s82, s46
	s_addc_u32 s43, s83, s47
	s_lshl_b32 s46, s29, 7
	s_ashr_i32 s47, s46, 31
	s_lshl_b64 s[46:47], s[46:47], 1
	s_add_u32 s46, s42, s46
	s_addc_u32 s47, s43, s47
	s_lshl_b32 s29, s33, 17
	v_and_b32_e32 v76, 15, v150
	v_bfe_u32 v77, v150, 4, 2
	v_lshl_add_u32 v76, v76, 1, s29
	v_lshl_add_u32 v144, v77, 14, v76
	v_lshl_add_u64 v[80:81], s[46:47], 0, v[144:145]
	s_mov_b64 s[42:43], 0x1000
	s_waitcnt lgkmcnt(0)
	v_rcp_f32_e32 v68, v68
	v_rcp_f32_e32 v69, v69
	v_rcp_f32_e32 v70, v70
	v_rcp_f32_e32 v71, v71
	v_rcp_f32_e32 v72, v72
	v_rcp_f32_e32 v73, v73
	v_rcp_f32_e32 v74, v74
	v_rcp_f32_e32 v75, v75
	s_nop 0
	v_mul_f32_e32 v82, v0, v68
	v_cvt_pk_bf16_f32 v82, v82, v145
	global_store_short v[80:81], v82, off
	v_mul_f32_e32 v83, v4, v68
	v_cvt_pk_bf16_f32 v83, v83, v145
	global_store_short v[80:81], v83, off offset:32
	v_mul_f32_e32 v84, v8, v68
	v_cvt_pk_bf16_f32 v84, v84, v145
	global_store_short v[80:81], v84, off offset:64
	v_mul_f32_e32 v85, v12, v68
	v_cvt_pk_bf16_f32 v85, v85, v145
	global_store_short v[80:81], v85, off offset:96
	v_mul_f32_e32 v86, v16, v68
	v_cvt_pk_bf16_f32 v86, v86, v145
	global_store_short v[80:81], v86, off offset:128
	v_mul_f32_e32 v87, v20, v68
	v_cvt_pk_bf16_f32 v87, v87, v145
	global_store_short v[80:81], v87, off offset:160
	v_mul_f32_e32 v88, v24, v68
	v_cvt_pk_bf16_f32 v88, v88, v145
	global_store_short v[80:81], v88, off offset:192
	v_mul_f32_e32 v89, v28, v68
	v_cvt_pk_bf16_f32 v89, v89, v145
	global_store_short v[80:81], v89, off offset:224
	v_lshl_add_u64 v[80:81], v[80:81], 0, s[42:43]
	v_mul_f32_e32 v82, v1, v69
	v_cvt_pk_bf16_f32 v82, v82, v145
	global_store_short v[80:81], v82, off
	v_mul_f32_e32 v83, v5, v69
	v_cvt_pk_bf16_f32 v83, v83, v145
	global_store_short v[80:81], v83, off offset:32
	v_mul_f32_e32 v84, v9, v69
	v_cvt_pk_bf16_f32 v84, v84, v145
	global_store_short v[80:81], v84, off offset:64
	v_mul_f32_e32 v85, v13, v69
	v_cvt_pk_bf16_f32 v85, v85, v145
	global_store_short v[80:81], v85, off offset:96
	v_mul_f32_e32 v86, v17, v69
	v_cvt_pk_bf16_f32 v86, v86, v145
	global_store_short v[80:81], v86, off offset:128
	v_mul_f32_e32 v87, v21, v69
	v_cvt_pk_bf16_f32 v87, v87, v145
	global_store_short v[80:81], v87, off offset:160
	v_mul_f32_e32 v88, v25, v69
	v_cvt_pk_bf16_f32 v88, v88, v145
	global_store_short v[80:81], v88, off offset:192
	v_mul_f32_e32 v89, v29, v69
	v_cvt_pk_bf16_f32 v89, v89, v145
	global_store_short v[80:81], v89, off offset:224
	v_lshl_add_u64 v[80:81], v[80:81], 0, s[42:43]
	v_mul_f32_e32 v82, v2, v70
	v_cvt_pk_bf16_f32 v82, v82, v145
	global_store_short v[80:81], v82, off
	v_mul_f32_e32 v83, v6, v70
	v_cvt_pk_bf16_f32 v83, v83, v145
	global_store_short v[80:81], v83, off offset:32
	v_mul_f32_e32 v84, v10, v70
	v_cvt_pk_bf16_f32 v84, v84, v145
	global_store_short v[80:81], v84, off offset:64
	v_mul_f32_e32 v85, v14, v70
	v_cvt_pk_bf16_f32 v85, v85, v145
	global_store_short v[80:81], v85, off offset:96
	v_mul_f32_e32 v86, v18, v70
	v_cvt_pk_bf16_f32 v86, v86, v145
	global_store_short v[80:81], v86, off offset:128
	v_mul_f32_e32 v87, v22, v70
	v_cvt_pk_bf16_f32 v87, v87, v145
	global_store_short v[80:81], v87, off offset:160
	v_mul_f32_e32 v88, v26, v70
	v_cvt_pk_bf16_f32 v88, v88, v145
	global_store_short v[80:81], v88, off offset:192
	v_mul_f32_e32 v89, v30, v70
	v_cvt_pk_bf16_f32 v89, v89, v145
	global_store_short v[80:81], v89, off offset:224
	v_lshl_add_u64 v[80:81], v[80:81], 0, s[42:43]
	v_mul_f32_e32 v82, v3, v71
	v_cvt_pk_bf16_f32 v82, v82, v145
	global_store_short v[80:81], v82, off
	v_mul_f32_e32 v83, v7, v71
	v_cvt_pk_bf16_f32 v83, v83, v145
	global_store_short v[80:81], v83, off offset:32
; __device__ __forceinline__ bf16_t to_bf1(float f) { return (bf16_t)(cvt_pk_bf16(f, 0.f) & 0xffffu); }
; __device__ __forceinline__ float shx(float v, int o, int lane) { return __int_as_float(__builtin_amdgcn_ds_bpermute((lane ^ o) << 2, __float_as_int(v))); }
; __device__ __forceinline__ int crow(int r, int hi) { return (r & 3) + 8 * (r >> 2) + 4 * hi; }
; __device__ __forceinline__ void attn_unit(const bf16_t* __restrict__ Qb, const bf16_t* __restrict__ Kh, const bf16_t* __restrict__ Vh, bf16_t* __restrict__ Ob,
;                                           LAS unsigned char* lds, float MB, int tid, int nrows, int t0, int t1, float* part, float* partl) {
;     ...
;     } else if (act) {
;     l_reg += shx(l_reg, 32, lane);
;     if (hi == 0) li_l[r32] = l_reg;
;     asm volatile("s_waitcnt lgkmcnt(0)" ::: "memory");
;     float rli[16];
; #pragma unroll
;     for (int r = 0; r < 16; ++r) rli[r] = __builtin_amdgcn_rcpf(li_l[crow(r, hi)]);
;     int r32e = r32; asm volatile("" : "+v"(r32e));
;     const unsigned ob = (unsigned)((wid * 32) * LDO + r32e) * 2u;
; #pragma unroll
;     for (int r = 0; r < 16; ++r) { const int orow = crow(r, hi);
;         if (wid * 32 + orow < nrows) {
; #pragma unroll
;         for (int d0 = 0; d0 < 4; ++d0) *(bf16_t*)((char*)Ob + ob + (unsigned)(orow * LDO + d0 * 32) * 2u) = to_bf1(o[d0][r] * rli[r]); } }
	v_mul_f32_e32 v84, v11, v71
	v_cvt_pk_bf16_f32 v84, v84, v145
	global_store_short v[80:81], v84, off offset:64
	v_mul_f32_e32 v85, v15, v71
	v_cvt_pk_bf16_f32 v85, v85, v145
	global_store_short v[80:81], v85, off offset:96
	v_mul_f32_e32 v86, v19, v71
	v_cvt_pk_bf16_f32 v86, v86, v145
	global_store_short v[80:81], v86, off offset:128
	v_mul_f32_e32 v87, v23, v71
	v_cvt_pk_bf16_f32 v87, v87, v145
	global_store_short v[80:81], v87, off offset:160
	v_mul_f32_e32 v88, v27, v71
	v_cvt_pk_bf16_f32 v88, v88, v145
	global_store_short v[80:81], v88, off offset:192
	v_mul_f32_e32 v89, v31, v71
	v_cvt_pk_bf16_f32 v89, v89, v145
	global_store_short v[80:81], v89, off offset:224
	s_mov_b64 s[42:43], 0xd000
	v_lshl_add_u64 v[80:81], v[80:81], 0, s[42:43]
	s_mov_b64 s[42:43], 0x1000
	v_mul_f32_e32 v82, v32, v72
	v_cvt_pk_bf16_f32 v82, v82, v145
	global_store_short v[80:81], v82, off
	v_mul_f32_e32 v83, v36, v72
	v_cvt_pk_bf16_f32 v83, v83, v145
	global_store_short v[80:81], v83, off offset:32
	v_mul_f32_e32 v84, v40, v72
	v_cvt_pk_bf16_f32 v84, v84, v145
	global_store_short v[80:81], v84, off offset:64
	v_mul_f32_e32 v85, v44, v72
	v_cvt_pk_bf16_f32 v85, v85, v145
	global_store_short v[80:81], v85, off offset:96
	v_mul_f32_e32 v86, v48, v72
	v_cvt_pk_bf16_f32 v86, v86, v145
	global_store_short v[80:81], v86, off offset:128
	v_mul_f32_e32 v87, v52, v72
	v_cvt_pk_bf16_f32 v87, v87, v145
	global_store_short v[80:81], v87, off offset:160
	v_mul_f32_e32 v88, v56, v72
	v_cvt_pk_bf16_f32 v88, v88, v145
	global_store_short v[80:81], v88, off offset:192
	v_mul_f32_e32 v89, v60, v72
	v_cvt_pk_bf16_f32 v89, v89, v145
	global_store_short v[80:81], v89, off offset:224
	v_lshl_add_u64 v[80:81], v[80:81], 0, s[42:43]
	v_mul_f32_e32 v82, v33, v73
	v_cvt_pk_bf16_f32 v82, v82, v145
	global_store_short v[80:81], v82, off
	v_mul_f32_e32 v83, v37, v73
	v_cvt_pk_bf16_f32 v83, v83, v145
	global_store_short v[80:81], v83, off offset:32
	v_mul_f32_e32 v84, v41, v73
	v_cvt_pk_bf16_f32 v84, v84, v145
	global_store_short v[80:81], v84, off offset:64
	v_mul_f32_e32 v85, v45, v73
	v_cvt_pk_bf16_f32 v85, v85, v145
	global_store_short v[80:81], v85, off offset:96
	v_mul_f32_e32 v86, v49, v73
	v_cvt_pk_bf16_f32 v86, v86, v145
	global_store_short v[80:81], v86, off offset:128
	v_mul_f32_e32 v87, v53, v73
	v_cvt_pk_bf16_f32 v87, v87, v145
	global_store_short v[80:81], v87, off offset:160
	v_mul_f32_e32 v88, v57, v73
	v_cvt_pk_bf16_f32 v88, v88, v145
	global_store_short v[80:81], v88, off offset:192
	v_mul_f32_e32 v89, v61, v73
	v_cvt_pk_bf16_f32 v89, v89, v145
	global_store_short v[80:81], v89, off offset:224
	v_lshl_add_u64 v[80:81], v[80:81], 0, s[42:43]
	v_mul_f32_e32 v82, v34, v74
	v_cvt_pk_bf16_f32 v82, v82, v145
	global_store_short v[80:81], v82, off
	v_mul_f32_e32 v83, v38, v74
	v_cvt_pk_bf16_f32 v83, v83, v145
	global_store_short v[80:81], v83, off offset:32
	v_mul_f32_e32 v84, v42, v74
	v_cvt_pk_bf16_f32 v84, v84, v145
	global_store_short v[80:81], v84, off offset:64
	v_mul_f32_e32 v85, v46, v74
	v_cvt_pk_bf16_f32 v85, v85, v145
	global_store_short v[80:81], v85, off offset:96
	v_mul_f32_e32 v86, v50, v74
	v_cvt_pk_bf16_f32 v86, v86, v145
	global_store_short v[80:81], v86, off offset:128
	v_mul_f32_e32 v87, v54, v74
	v_cvt_pk_bf16_f32 v87, v87, v145
	global_store_short v[80:81], v87, off offset:160
	v_mul_f32_e32 v88, v58, v74
	v_cvt_pk_bf16_f32 v88, v88, v145
	global_store_short v[80:81], v88, off offset:192
	v_mul_f32_e32 v89, v62, v74
	v_cvt_pk_bf16_f32 v89, v89, v145
	global_store_short v[80:81], v89, off offset:224
	v_lshl_add_u64 v[80:81], v[80:81], 0, s[42:43]
	v_mul_f32_e32 v82, v35, v75
	v_cvt_pk_bf16_f32 v82, v82, v145
	global_store_short v[80:81], v82, off
	v_mul_f32_e32 v83, v39, v75
	v_cvt_pk_bf16_f32 v83, v83, v145
	global_store_short v[80:81], v83, off offset:32
	v_mul_f32_e32 v84, v43, v75
	v_cvt_pk_bf16_f32 v84, v84, v145
	global_store_short v[80:81], v84, off offset:64
	v_mul_f32_e32 v85, v47, v75
	v_cvt_pk_bf16_f32 v85, v85, v145
	global_store_short v[80:81], v85, off offset:96
	v_mul_f32_e32 v86, v51, v75
	v_cvt_pk_bf16_f32 v86, v86, v145
	global_store_short v[80:81], v86, off offset:128
	v_mul_f32_e32 v87, v55, v75
	v_cvt_pk_bf16_f32 v87, v87, v145
	global_store_short v[80:81], v87, off offset:160
	v_mul_f32_e32 v88, v59, v75
	v_cvt_pk_bf16_f32 v88, v88, v145
	global_store_short v[80:81], v88, off offset:192
	v_mul_f32_e32 v89, v63, v75
	v_cvt_pk_bf16_f32 v89, v89, v145
	global_store_short v[80:81], v89, off offset:224

; __device__ __forceinline__ float shx(float v, int o, int lane) { return __int_as_float(__builtin_amdgcn_ds_bpermute((lane ^ o) << 2, __float_as_int(v))); }
; __device__ __forceinline__ void attn_unit(const bf16_t* __restrict__ Qb, const bf16_t* __restrict__ Kh, const bf16_t* __restrict__ Vh, bf16_t* __restrict__ Ob,
;                                           LAS unsigned char* lds, float MB, int tid, int nrows, int t0, int t1, float* part, float* partl) {
;     ...
;     if (act && part) {
;         l_reg += shx(l_reg, 32, lane);
;         if (hi == 0 && r32 < 16) partl[r32] = l_reg;
.LBB0_180:
	ds_bpermute_b32 v40, v222, v155
	s_ashr_i32 s37, s36, 31
	v_xor_b32_e32 v43, 0xc0, v222
	s_waitcnt lgkmcnt(0)
	v_add_f32_e32 v42, v155, v40
	s_nop 0
	ds_bpermute_b32 v40, v43, v42
	s_waitcnt lgkmcnt(0)
	v_add_f32_e32 v42, v42, v40
	s_and_saveexec_b64 s[48:49], s[0:1]
	s_cbranch_execz .LBB0_127
	s_lshl_b64 s[28:29], s[36:37], 6
	v_lshl_add_u64 v[40:41], v[198:199], 0, s[28:29]
	global_store_dword v[40:41], v42, off
	s_branch .LBB0_127

; __device__ __forceinline__ u32x4 pack8(f32x4 v0, f32x4 v1) { u32x4 w; w.x = cvt_pk_bf16(v0[0], v0[1]); w.y = cvt_pk_bf16(v0[2], v0[3]); w.z = cvt_pk_bf16(v1[0], v1[1]); w.w = cvt_pk_bf16(v1[2], v1[3]); return w; }
; __device__ __forceinline__ void epi8(const Desc& d, int pb, int row, int col, f32x4 v0, f32x4 v1) {
;     ...
;     } else if (d.epi == EPI_BF16) {
;         *(u32x4*)((bf16_t*)d.o0 + (size_t)pb * d.sO + (size_t)row * d.ldc + col) = pack8(v0 * d.scale, v1 * d.scale);
; __device__ __forceinline__ void epilogue(const Desc& d, const f32x4 (&acc)[2][2][4][2], const Unit& u, int wr, int wc, int fr, int fq) {
;     const int row0 = u.pm * BM + wr * 64 + fr, col0 = u.pn * BM + wc * 32 + 8 * fq;
; #pragma unroll
;     for (int ai = 0; ai < 2; ++ai)
; #pragma unroll
;         for (int m = 0; m < 4; ++m) {
; #pragma unroll
;             for (int bj = 0; bj < 2; ++bj) epi8(d, u.pb, row0 + ai * HALF + m * 16, col0 + bj * HALF, acc[ai][bj][m][0], acc[ai][bj][m][1]);
;             asm volatile("" ::: "memory"); }
; }
.LBB0_202:
	v_lshl_add_u32 v142, s60, 8, v138
	s_mov_b32 s52, 0x3a34d738
	s_mul_i32 s43, s54, 0x880000
	v_lshl_or_b32 v146, s55, 8, v140
	v_ashrrev_i32_e32 v143, 31, v142
	v_pk_mul_f32 v[124:125], v[124:125], s[52:53] op_sel_hi:[1,0]
	v_pk_mul_f32 v[120:121], v[120:121], s[52:53] op_sel_hi:[1,0]
	s_mul_hi_i32 s42, s54, 0x880000
	s_add_u32 s50, s2, s43
	v_pk_mul_f32 v[126:127], v[126:127], s[52:53] op_sel_hi:[1,0]
	v_pk_mul_f32 v[148:149], v[122:123], s[52:53] op_sel_hi:[1,0]
	v_cvt_pk_bf16_f32 v122, v124, v125
	v_cvt_pk_bf16_f32 v123, v126, v127
	v_cvt_pk_bf16_f32 v124, v120, v121
	s_addc_u32 s51, s3, s42
	v_lshlrev_b64 v[120:121], 11, v[142:143]
	v_ashrrev_i32_e32 v147, 31, v146
	v_lshl_add_u64 v[120:121], s[50:51], 0, v[120:121]
	v_lshlrev_b64 v[126:127], 1, v[146:147]
	v_lshl_add_u64 v[120:121], v[120:121], 0, v[126:127]
	v_cvt_pk_bf16_f32 v125, v148, v149
	global_store_dwordx4 v[120:121], v[122:125], off
	v_pk_mul_f32 v[116:117], v[116:117], s[52:53] op_sel_hi:[1,0]
	v_pk_mul_f32 v[118:119], v[118:119], s[52:53] op_sel_hi:[1,0]
	v_pk_mul_f32 v[122:123], v[114:115], s[52:53] op_sel_hi:[1,0]
	v_pk_mul_f32 v[114:115], v[112:113], s[52:53] op_sel_hi:[1,0]
	v_cvt_pk_bf16_f32 v112, v116, v117
	v_cvt_pk_bf16_f32 v113, v118, v119
	v_pk_mul_f32 v[108:109], v[108:109], s[52:53] op_sel_hi:[1,0]
	v_cvt_pk_bf16_f32 v114, v114, v115
	v_cvt_pk_bf16_f32 v115, v122, v123
	global_store_dwordx4 v[120:121], v[112:115], off offset:256
	v_pk_mul_f32 v[110:111], v[110:111], s[52:53] op_sel_hi:[1,0]
	v_pk_mul_f32 v[100:101], v[100:101], s[52:53] op_sel_hi:[1,0]
	v_or_b32_e32 v112, 16, v142
	v_ashrrev_i32_e32 v113, 31, v112
	v_pk_mul_f32 v[114:115], v[106:107], s[52:53] op_sel_hi:[1,0]
	v_pk_mul_f32 v[106:107], v[104:105], s[52:53] op_sel_hi:[1,0]
	v_cvt_pk_bf16_f32 v104, v108, v109
	v_lshlrev_b64 v[108:109], 11, v[112:113]
	v_lshl_add_u64 v[108:109], s[50:51], 0, v[108:109]
	v_cvt_pk_bf16_f32 v105, v110, v111
	v_lshl_add_u64 v[108:109], v[108:109], 0, v[126:127]
	v_cvt_pk_bf16_f32 v106, v106, v107
	v_cvt_pk_bf16_f32 v107, v114, v115
	global_store_dwordx4 v[108:109], v[104:107], off
	v_pk_mul_f32 v[102:103], v[102:103], s[52:53] op_sel_hi:[1,0]
	v_pk_mul_f32 v[92:93], v[92:93], s[52:53] op_sel_hi:[1,0]
	v_pk_mul_f32 v[104:105], v[98:99], s[52:53] op_sel_hi:[1,0]
	v_pk_mul_f32 v[98:99], v[96:97], s[52:53] op_sel_hi:[1,0]
	v_cvt_pk_bf16_f32 v96, v100, v101
	v_cvt_pk_bf16_f32 v97, v102, v103
	v_pk_mul_f32 v[94:95], v[94:95], s[52:53] op_sel_hi:[1,0]
	v_cvt_pk_bf16_f32 v98, v98, v99
	v_cvt_pk_bf16_f32 v99, v104, v105
	global_store_dwordx4 v[108:109], v[96:99], off offset:256
	v_pk_mul_f32 v[84:85], v[84:85], s[52:53] op_sel_hi:[1,0]
	v_pk_mul_f32 v[86:87], v[86:87], s[52:53] op_sel_hi:[1,0]
	v_or_b32_e32 v96, 32, v142
	v_ashrrev_i32_e32 v97, 31, v96
	v_pk_mul_f32 v[98:99], v[90:91], s[52:53] op_sel_hi:[1,0]
	v_pk_mul_f32 v[90:91], v[88:89], s[52:53] op_sel_hi:[1,0]
	v_cvt_pk_bf16_f32 v88, v92, v93
	v_lshlrev_b64 v[92:93], 11, v[96:97]
	v_lshl_add_u64 v[92:93], s[50:51], 0, v[92:93]
	v_cvt_pk_bf16_f32 v89, v94, v95
	v_lshl_add_u64 v[92:93], v[92:93], 0, v[126:127]
	v_cvt_pk_bf16_f32 v90, v90, v91
	v_cvt_pk_bf16_f32 v91, v98, v99
	global_store_dwordx4 v[92:93], v[88:91], off
	v_pk_mul_f32 v[76:77], v[76:77], s[52:53] op_sel_hi:[1,0]
	v_pk_mul_f32 v[78:79], v[78:79], s[52:53] op_sel_hi:[1,0]
	v_pk_mul_f32 v[88:89], v[82:83], s[52:53] op_sel_hi:[1,0]
	v_pk_mul_f32 v[82:83], v[80:81], s[52:53] op_sel_hi:[1,0]
	v_cvt_pk_bf16_f32 v80, v84, v85
	v_cvt_pk_bf16_f32 v81, v86, v87
	v_pk_mul_f32 v[70:71], v[70:71], s[52:53] op_sel_hi:[1,0]
	v_cvt_pk_bf16_f32 v82, v82, v83
	v_cvt_pk_bf16_f32 v83, v88, v89
	global_store_dwordx4 v[92:93], v[80:83], off offset:256
	v_pk_mul_f32 v[68:69], v[68:69], s[52:53] op_sel_hi:[1,0]
	v_pk_mul_f32 v[62:63], v[62:63], s[52:53] op_sel_hi:[1,0]
	v_or_b32_e32 v80, 48, v142
	v_ashrrev_i32_e32 v81, 31, v80
	v_pk_mul_f32 v[82:83], v[74:75], s[52:53] op_sel_hi:[1,0]
	v_pk_mul_f32 v[74:75], v[72:73], s[52:53] op_sel_hi:[1,0]
	v_cvt_pk_bf16_f32 v72, v76, v77
	v_lshlrev_b64 v[76:77], 11, v[80:81]
	v_lshl_add_u64 v[76:77], s[50:51], 0, v[76:77]
	v_cvt_pk_bf16_f32 v73, v78, v79
	v_lshl_add_u64 v[76:77], v[76:77], 0, v[126:127]
	v_cvt_pk_bf16_f32 v74, v74, v75
	v_cvt_pk_bf16_f32 v75, v82, v83
	global_store_dwordx4 v[76:77], v[72:75], off
	s_mov_b32 s4, 0x40000
	v_pk_mul_f32 v[60:61], v[60:61], s[52:53] op_sel_hi:[1,0]
	v_pk_mul_f32 v[72:73], v[66:67], s[52:53] op_sel_hi:[1,0]
	v_pk_mul_f32 v[66:67], v[64:65], s[52:53] op_sel_hi:[1,0]
	v_cvt_pk_bf16_f32 v64, v68, v69
	v_cvt_pk_bf16_f32 v65, v70, v71
	s_mov_b64 s[50:51], 0x40000
	v_cvt_pk_bf16_f32 v66, v66, v67
	v_cvt_pk_bf16_f32 v67, v72, v73
	global_store_dwordx4 v[76:77], v[64:67], off offset:256
	v_pk_mul_f32 v[54:55], v[54:55], s[52:53] op_sel_hi:[1,0]
	v_pk_mul_f32 v[52:53], v[52:53], s[52:53] op_sel_hi:[1,0]
	v_pk_mul_f32 v[64:65], v[58:59], s[52:53] op_sel_hi:[1,0]
	v_pk_mul_f32 v[58:59], v[56:57], s[52:53] op_sel_hi:[1,0]
	v_cvt_pk_bf16_f32 v56, v60, v61
	v_cvt_pk_bf16_f32 v57, v62, v63
	v_add_co_u32_e32 v62, vcc, s4, v120
	v_cvt_pk_bf16_f32 v58, v58, v59
	v_cvt_pk_bf16_f32 v59, v64, v65
	v_lshl_add_u64 v[60:61], v[120:121], 0, s[50:51]
	s_nop 0
	v_addc_co_u32_e32 v63, vcc, 0, v121, vcc
	global_store_dwordx4 v[62:63], v[56:59], off
	v_pk_mul_f32 v[46:47], v[46:47], s[52:53] op_sel_hi:[1,0]
	s_mov_b32 s4, 0x48000
	v_pk_mul_f32 v[56:57], v[50:51], s[52:53] op_sel_hi:[1,0]
	v_pk_mul_f32 v[50:51], v[48:49], s[52:53] op_sel_hi:[1,0]
	v_cvt_pk_bf16_f32 v48, v52, v53
	v_cvt_pk_bf16_f32 v49, v54, v55
; __device__ __forceinline__ f32x4 zero4() { float a, b, c, e; asm volatile("v_mov_b32 %0, 0\n\tv_mov_b32 %1, 0\n\tv_mov_b32 %2, 0\n\tv_mov_b32 %3, 0" : "=v"(a), "=v"(b), "=v"(c), "=v"(e)); return (f32x4){a, b, c, e}; }
; #define PG8_BAR __builtin_amdgcn_s_barrier()
; __device__ __forceinline__ void epilogue(const Desc& d, const f32x4 (&acc)[2][2][4][2], const Unit& u, int wr, int wc, int fr, int fq) {
;     const int row0 = u.pm * BM + wr * 64 + fr, col0 = u.pn * BM + wc * 32 + 8 * fq;
; #pragma unroll
;     for (int ai = 0; ai < 2; ++ai)
; #pragma unroll
;         for (int m = 0; m < 4; ++m) {
; #pragma unroll
;             for (int bj = 0; bj < 2; ++bj) epi8(d, u.pb, row0 + ai * HALF + m * 16, col0 + bj * HALF, acc[ai][bj][m][0], acc[ai][bj][m][1]);
;             asm volatile("" ::: "memory"); }
; }
; __device__ __forceinline__ void gemm_phase(LAS unsigned char* lds, const Desc& g, int G, int cidx, int tid) {
;     ...
; #pragma unroll
;         for (int a = 0; a < 2; ++a)
; #pragma unroll
;             for (int b = 0; b < 2; ++b)
; #pragma unroll
;                 for (int m = 0; m < 4; ++m)
; #pragma unroll
;                     for (int n = 0; n < 2; ++n) acc[a][b][m][n] = zero4();
;         cur = nxt; cA = nA; cB = nB; ++ui;
;         if (wr == 1) PG8_BAR;
	v_pk_mul_f32 v[44:45], v[44:45], s[52:53] op_sel_hi:[1,0]
	v_cvt_pk_bf16_f32 v50, v50, v51
	v_cvt_pk_bf16_f32 v51, v56, v57
	global_store_dwordx4 v[60:61], v[48:51], off offset:256
	s_mov_b64 s[50:51], 0x48000
	v_pk_mul_f32 v[38:39], v[38:39], s[52:53] op_sel_hi:[1,0]
	v_pk_mul_f32 v[48:49], v[42:43], s[52:53] op_sel_hi:[1,0]
	v_pk_mul_f32 v[42:43], v[40:41], s[52:53] op_sel_hi:[1,0]
	v_cvt_pk_bf16_f32 v40, v44, v45
	v_cvt_pk_bf16_f32 v41, v46, v47
	v_add_co_u32_e32 v46, vcc, s4, v120
	v_cvt_pk_bf16_f32 v42, v42, v43
	v_cvt_pk_bf16_f32 v43, v48, v49
	v_lshl_add_u64 v[44:45], v[120:121], 0, s[50:51]
	s_nop 0
	v_addc_co_u32_e32 v47, vcc, 0, v121, vcc
	global_store_dwordx4 v[46:47], v[40:43], off
	v_pk_mul_f32 v[36:37], v[36:37], s[52:53] op_sel_hi:[1,0]
	v_pk_mul_f32 v[30:31], v[30:31], s[52:53] op_sel_hi:[1,0]
	v_pk_mul_f32 v[40:41], v[34:35], s[52:53] op_sel_hi:[1,0]
	v_pk_mul_f32 v[34:35], v[32:33], s[52:53] op_sel_hi:[1,0]
	v_cvt_pk_bf16_f32 v32, v36, v37
	v_cvt_pk_bf16_f32 v33, v38, v39
	s_mov_b32 s4, 0x50000
	v_cvt_pk_bf16_f32 v34, v34, v35
	v_cvt_pk_bf16_f32 v35, v40, v41
	global_store_dwordx4 v[44:45], v[32:35], off offset:256
	v_pk_mul_f32 v[28:29], v[28:29], s[52:53] op_sel_hi:[1,0]
	s_mov_b64 s[50:51], 0x50000
	v_pk_mul_f32 v[32:33], v[26:27], s[52:53] op_sel_hi:[1,0]
	v_pk_mul_f32 v[26:27], v[24:25], s[52:53] op_sel_hi:[1,0]
	v_cvt_pk_bf16_f32 v24, v28, v29
	v_cvt_pk_bf16_f32 v25, v30, v31
	v_add_co_u32_e32 v30, vcc, s4, v120
	v_cvt_pk_bf16_f32 v26, v26, v27
	v_cvt_pk_bf16_f32 v27, v32, v33
	v_lshl_add_u64 v[28:29], v[120:121], 0, s[50:51]
	s_nop 0
	v_addc_co_u32_e32 v31, vcc, 0, v121, vcc
	global_store_dwordx4 v[30:31], v[24:27], off
	v_pk_mul_f32 v[22:23], v[22:23], s[52:53] op_sel_hi:[1,0]
	v_pk_mul_f32 v[20:21], v[20:21], s[52:53] op_sel_hi:[1,0]
	v_pk_mul_f32 v[24:25], v[18:19], s[52:53] op_sel_hi:[1,0]
	v_pk_mul_f32 v[18:19], v[16:17], s[52:53] op_sel_hi:[1,0]
	v_cvt_pk_bf16_f32 v16, v20, v21
	v_cvt_pk_bf16_f32 v17, v22, v23
	v_pk_mul_f32 v[14:15], v[14:15], s[52:53] op_sel_hi:[1,0]
	v_cvt_pk_bf16_f32 v18, v18, v19
	v_cvt_pk_bf16_f32 v19, v24, v25
	global_store_dwordx4 v[28:29], v[16:19], off offset:256
	s_mov_b32 s4, 0x58000
	v_pk_mul_f32 v[12:13], v[12:13], s[52:53] op_sel_hi:[1,0]
	v_pk_mul_f32 v[16:17], v[10:11], s[52:53] op_sel_hi:[1,0]
	v_pk_mul_f32 v[10:11], v[8:9], s[52:53] op_sel_hi:[1,0]
	v_cvt_pk_bf16_f32 v8, v12, v13
	v_cvt_pk_bf16_f32 v9, v14, v15
	s_mov_b64 s[50:51], 0x58000
	v_add_co_u32_e32 v14, vcc, s4, v120
	v_lshl_add_u64 v[12:13], v[120:121], 0, s[50:51]
	s_nop 0
	v_addc_co_u32_e32 v15, vcc, 0, v121, vcc
	v_pk_mul_f32 v[2:3], v[2:3], s[52:53] op_sel_hi:[1,0]
	v_pk_mul_f32 v[0:1], v[0:1], s[52:53] op_sel_hi:[1,0]
	v_cvt_pk_bf16_f32 v10, v10, v11
	v_cvt_pk_bf16_f32 v11, v16, v17
	global_store_dwordx4 v[14:15], v[8:11], off
	v_pk_mul_f32 v[6:7], v[6:7], s[52:53] op_sel_hi:[1,0]
	v_pk_mul_f32 v[4:5], v[4:5], s[52:53] op_sel_hi:[1,0]
	v_cvt_pk_bf16_f32 v0, v0, v1
	v_cvt_pk_bf16_f32 v1, v2, v3
	s_and_b64 vcc, exec, s[38:39]
	v_cvt_pk_bf16_f32 v2, v4, v5
	v_cvt_pk_bf16_f32 v3, v6, v7
	global_store_dwordx4 v[12:13], v[0:3], off offset:256
	s_mov_b64 s[38:39], -1
	s_cbranch_vccnz .LBB0_187
	s_andn2_b64 vcc, exec, s[8:9]
	v_mov_b32 v124, 0
	v_mov_b32 v125, 0
	v_mov_b32 v126, 0
	v_mov_b32 v127, 0
	v_mov_b32 v120, 0
	v_mov_b32 v121, 0
	v_mov_b32 v122, 0
	v_mov_b32 v123, 0
	v_mov_b32 v108, 0
	v_mov_b32 v109, 0
	v_mov_b32 v110, 0
	v_mov_b32 v111, 0
	v_mov_b32 v104, 0
	v_mov_b32 v105, 0
	v_mov_b32 v106, 0
	v_mov_b32 v107, 0
	v_mov_b32 v92, 0
	v_mov_b32 v93, 0
	v_mov_b32 v94, 0
	v_mov_b32 v95, 0
	v_mov_b32 v88, 0
	v_mov_b32 v89, 0
	v_mov_b32 v90, 0
	v_mov_b32 v91, 0
	v_mov_b32 v76, 0
	v_mov_b32 v77, 0
	v_mov_b32 v78, 0
	v_mov_b32 v79, 0
	v_mov_b32 v72, 0
	v_mov_b32 v73, 0
	v_mov_b32 v74, 0
	v_mov_b32 v75, 0
	v_mov_b32 v116, 0
	v_mov_b32 v117, 0
	v_mov_b32 v118, 0
	v_mov_b32 v119, 0
	v_mov_b32 v112, 0
	v_mov_b32 v113, 0
	v_mov_b32 v114, 0
	v_mov_b32 v115, 0
	v_mov_b32 v100, 0
	v_mov_b32 v101, 0
	v_mov_b32 v102, 0
	v_mov_b32 v103, 0
	v_mov_b32 v96, 0
	v_mov_b32 v97, 0
	v_mov_b32 v98, 0
	v_mov_b32 v99, 0
	v_mov_b32 v84, 0
	v_mov_b32 v85, 0
	v_mov_b32 v86, 0
	v_mov_b32 v87, 0
	v_mov_b32 v80, 0
	v_mov_b32 v81, 0
	v_mov_b32 v82, 0
	v_mov_b32 v83, 0
	v_mov_b32 v68, 0
	v_mov_b32 v69, 0
	v_mov_b32 v70, 0
	v_mov_b32 v71, 0
	v_mov_b32 v64, 0
	v_mov_b32 v65, 0
	v_mov_b32 v66, 0
	v_mov_b32 v67, 0
	v_mov_b32 v60, 0
	v_mov_b32 v61, 0
	v_mov_b32 v62, 0
	v_mov_b32 v63, 0
	v_mov_b32 v56, 0
	v_mov_b32 v57, 0
	v_mov_b32 v58, 0
	v_mov_b32 v59, 0
	v_mov_b32 v44, 0
	v_mov_b32 v45, 0
	v_mov_b32 v46, 0
	v_mov_b32 v47, 0
	v_mov_b32 v40, 0
	v_mov_b32 v41, 0
	v_mov_b32 v42, 0
	v_mov_b32 v43, 0
	v_mov_b32 v28, 0
	v_mov_b32 v29, 0
	v_mov_b32 v30, 0
	v_mov_b32 v31, 0
	v_mov_b32 v24, 0
	v_mov_b32 v25, 0
	v_mov_b32 v26, 0
	v_mov_b32 v27, 0
	v_mov_b32 v12, 0
	v_mov_b32 v13, 0
	v_mov_b32 v14, 0
	v_mov_b32 v15, 0
	v_mov_b32 v8, 0
	v_mov_b32 v9, 0
	v_mov_b32 v10, 0
	v_mov_b32 v11, 0
	v_mov_b32 v52, 0
	v_mov_b32 v53, 0
	v_mov_b32 v54, 0
	v_mov_b32 v55, 0
	v_mov_b32 v48, 0
	v_mov_b32 v49, 0
	v_mov_b32 v50, 0
	v_mov_b32 v51, 0
	v_mov_b32 v36, 0
	v_mov_b32 v37, 0
	v_mov_b32 v38, 0
	v_mov_b32 v39, 0
	v_mov_b32 v32, 0
	v_mov_b32 v33, 0
	v_mov_b32 v34, 0
	v_mov_b32 v35, 0
	v_mov_b32 v20, 0
	v_mov_b32 v21, 0
	v_mov_b32 v22, 0
	v_mov_b32 v23, 0
	v_mov_b32 v16, 0
	v_mov_b32 v17, 0
	v_mov_b32 v18, 0
	v_mov_b32 v19, 0
	v_mov_b32 v0, 0
	v_mov_b32 v1, 0
	v_mov_b32 v2, 0
	v_mov_b32 v3, 0
	v_mov_b32 v4, 0
	v_mov_b32 v5, 0
	v_mov_b32 v6, 0
	v_mov_b32 v7, 0
	s_cbranch_vccnz .LBB0_186
	s_barrier
	s_branch .LBB0_186

; __global__ void __launch_bounds__(512, 2) mk_fwd(Args a) {
;     ...
;             for (int r = gw; r < LSEQ; r += NGW) {
;                 const int pos = pos_of(r);
;                 const f32x4 cs0 = *(const f32x4*)(ROPE + pos * 64 + 8 * qq), cs1 = *(const f32x4*)(ROPE + pos * 64 + 8 * qq + 4);
;                 const f32x4 sn0 = *(const f32x4*)(ROPE + pos * 64 + 32 + 8 * qq), sn1 = *(const f32x4*)(ROPE + pos * 64 + 32 + 8 * qq + 4);
;                 bf16_t* qp = Q + (size_t)r * NQ + hh * 192 + 8 * qq;
;                 const bf16_t* kvp = KV + (size_t)r * NKV + hh * 256 + 8 * qq;
;                 bf16_t* kp = KP + (size_t)r * NQ + hh * 192 + 8 * qq;
;                 u32x4 xq[6], xk[6];
; #pragma unroll
;                 for (int m = 0; m < 6; ++m) xq[m] = *(const u32x4*)(qp + 32 * m);
; #pragma unroll
;                 for (int m = 0; m < 4; ++m) xk[m] = *(const u32x4*)(kvp + 32 * m);
;                 xk[4] = *(const u32x4*)(KR + (size_t)r * NKR + 8 * qq); xk[5] = *(const u32x4*)(KR + (size_t)r * NKR + 32 + 8 * qq);
; #pragma unroll
;                 for (int which = 0; which < 2; ++which) {
;                     f32x4 v[6][2]; float ss = 0.f;
; #pragma unroll
;                     for (int m = 0; m < 6; ++m) { const u32x4 w = which ? xk[m] : xq[m];
;                         v[m][0] = (f32x4){bf_lo(w.x), bf_hi(w.x), bf_lo(w.y), bf_hi(w.y)}; v[m][1] = (f32x4){bf_lo(w.z), bf_hi(w.z), bf_lo(w.w), bf_hi(w.w)};
;                         const f32x4 sq = v[m][0] * v[m][0] + v[m][1] * v[m][1]; ss += (sq[0] + sq[1]) + (sq[2] + sq[3]); }
;                     ss += shx(ss, 1, lane); ss += shx(ss, 2, lane);
;                     const float rs = __builtin_amdgcn_rsqf(ss * (1.f / 192.f) + EPS) * (which ? 1.f : C2);
; #pragma unroll
;                     for (int m = 0; m < 6; ++m) { v[m][0] = v[m][0] * rs * (which ? gkv[m][0] : gqv[m][0]); v[m][1] = v[m][1] * rs * (which ? gkv[m][1] : gqv[m][1]); }
;                     const f32x4 a0 = v[4][0], a1 = v[4][1], b0 = v[5][0], b1 = v[5][1];
;                     v[4][0] = a0 * cs0 - b0 * sn0; v[4][1] = a1 * cs1 - b1 * sn1; v[5][0] = b0 * cs0 + a0 * sn0; v[5][1] = b1 * cs1 + a1 * sn1;
;                     bf16_t* op = which ? kp : qp;
; #pragma unroll
;                     for (int m = 0; m < 6; ++m) *(u32x4*)(op + 32 * m) = pg8::pack8(v[m][0], v[m][1]);
.LBB0_233:
	s_cmpk_lt_i32 s2, 0x2000
	s_cselect_b32 s3, 16, 0xffffe000
	s_add_i32 s3, s3, s2
	s_lshl_b32 s6, s3, 6
	v_lshl_add_u64 v[138:139], v[136:137], 0, v[144:145]
	s_mov_b32 s3, 0xfc01000
	s_ashr_i32 s7, s6, 31
	v_add_co_u32_e32 v140, vcc, s3, v138
	v_lshl_add_u64 v[100:101], s[6:7], 2, v[132:133]
	s_nop 0
	v_addc_co_u32_e32 v141, vcc, 0, v139, vcc
	global_load_dwordx4 v[104:107], v[100:101], off
	global_load_dwordx4 v[96:99], v[100:101], off offset:16
	global_load_dwordx4 v[108:111], v[100:101], off offset:128
	s_nop 0
	global_load_dwordx4 v[100:103], v[100:101], off offset:144
	s_nop 0
	global_load_dwordx4 v[154:157], v[140:141], off
	global_load_dwordx4 v[158:161], v[140:141], off offset:64
	global_load_dwordx4 v[164:167], v[140:141], off offset:128
	global_load_dwordx4 v[168:171], v[140:141], off offset:192
	global_load_dwordx4 v[172:175], v[140:141], off offset:256
	global_load_dwordx4 v[176:179], v[140:141], off offset:320
	v_lshl_add_u64 v[112:113], v[134:135], 0, v[144:145]
	s_mov_b32 s3, 0x1b9c1000
	v_add_co_u32_e32 v112, vcc, s3, v112
	v_lshl_add_u64 v[116:117], s[0:1], 0, v[144:145]
	s_nop 0
	v_addc_co_u32_e32 v113, vcc, 0, v113, vcc
	global_load_dwordx4 v[180:183], v[112:113], off
	global_load_dwordx4 v[128:131], v[112:113], off offset:64
	global_load_dwordx4 v[124:127], v[112:113], off offset:128
	s_nop 0
	global_load_dwordx4 v[112:115], v[112:113], off offset:192
	s_mov_b32 s3, 0x1b5a1000
	v_add_co_u32_e32 v116, vcc, s3, v116
	s_mov_b32 s3, 0x1fbc1000
	s_nop 0
	v_addc_co_u32_e32 v117, vcc, 0, v117, vcc
	global_load_dwordx4 v[120:123], v[116:117], off
	s_nop 0
	global_load_dwordx4 v[116:119], v[116:117], off offset:64
	s_add_i32 s2, s2, s72
	s_add_u32 s0, s0, s38
	s_addc_u32 s1, s1, s39
	v_lshl_add_u64 v[134:135], v[134:135], 0, s[36:37]
	v_lshl_add_u64 v[136:137], v[136:137], 0, s[8:9]
	s_cmpk_gt_i32 s2, 0x200f
	s_waitcnt vmcnt(0) lgkmcnt(0)
	v_lshlrev_b32_e32 v142, 16, v154
	v_and_b32_e32 v143, 0xffff0000, v154
	v_lshlrev_b32_e32 v146, 16, v155
	v_and_b32_e32 v147, 0xffff0000, v155
	v_lshlrev_b32_e32 v148, 16, v156
	v_and_b32_e32 v149, 0xffff0000, v156
	v_lshlrev_b32_e32 v154, 16, v157
	v_and_b32_e32 v155, 0xffff0000, v157
	v_lshlrev_b32_e32 v188, 16, v160
	v_and_b32_e32 v189, 0xffff0000, v160
	v_lshlrev_b32_e32 v160, 16, v161
	v_and_b32_e32 v161, 0xffff0000, v161
	v_lshlrev_b32_e32 v196, 16, v166
	v_and_b32_e32 v197, 0xffff0000, v166
	v_lshlrev_b32_e32 v166, 16, v167
	v_and_b32_e32 v167, 0xffff0000, v167
	v_pk_mul_f32 v[156:157], v[148:149], v[148:149]
	v_pk_mul_f32 v[184:185], v[154:155], v[154:155]
	v_lshlrev_b32_e32 v186, 16, v158
	v_and_b32_e32 v187, 0xffff0000, v158
	v_lshlrev_b32_e32 v158, 16, v159
	v_and_b32_e32 v159, 0xffff0000, v159
	v_pk_mul_f32 v[190:191], v[188:189], v[188:189]
	v_pk_mul_f32 v[192:193], v[160:161], v[160:161]
	v_lshlrev_b32_e32 v194, 16, v164
	v_and_b32_e32 v195, 0xffff0000, v164
	v_lshlrev_b32_e32 v164, 16, v165
	v_and_b32_e32 v165, 0xffff0000, v165
	v_pk_mul_f32 v[198:199], v[196:197], v[196:197]
	v_pk_mul_f32 v[200:201], v[166:167], v[166:167]
	v_pk_fma_f32 v[184:185], v[146:147], v[146:147], v[184:185]
	v_pk_fma_f32 v[156:157], v[142:143], v[142:143], v[156:157]
	v_pk_fma_f32 v[192:193], v[158:159], v[158:159], v[192:193]
	v_pk_fma_f32 v[190:191], v[186:187], v[186:187], v[190:191]
	v_pk_fma_f32 v[200:201], v[164:165], v[164:165], v[200:201]
	v_pk_fma_f32 v[198:199], v[194:195], v[194:195], v[198:199]
	v_add_f32_e32 v156, v156, v157
	v_add_f32_e32 v184, v184, v185
	v_add_f32_e32 v190, v190, v191
	v_add_f32_e32 v192, v192, v193
	v_mov_b32_e32 v157, v198
	v_mov_b32_e32 v185, v199
	v_mov_b32_e32 v191, v200
	v_mov_b32_e32 v193, v201
	v_pk_add_f32 v[156:157], v[156:157], v[184:185]
	v_pk_add_f32 v[184:185], v[190:191], v[192:193]
	v_lshlrev_b32_e32 v190, 16, v170
	v_and_b32_e32 v191, 0xffff0000, v170
	v_lshlrev_b32_e32 v170, 16, v171
	v_and_b32_e32 v171, 0xffff0000, v171
	v_pk_add_f32 v[156:157], v[156:157], v[184:185]
	v_lshlrev_b32_e32 v184, 16, v168
	v_and_b32_e32 v185, 0xffff0000, v168
	v_lshlrev_b32_e32 v168, 16, v169
	v_and_b32_e32 v169, 0xffff0000, v169
	v_pk_mul_f32 v[192:193], v[190:191], v[190:191]
	v_pk_mul_f32 v[198:199], v[170:171], v[170:171]
	v_pk_fma_f32 v[192:193], v[184:185], v[184:185], v[192:193]
	v_pk_fma_f32 v[198:199], v[168:169], v[168:169], v[198:199]
	v_lshlrev_b32_e32 v212, 16, v178
	v_pk_mov_b32 v[200:201], v[192:193], v[198:199] op_sel:[1,0]
	v_mov_b32_e32 v193, v199
	v_pk_add_f32 v[192:193], v[200:201], v[192:193]
	v_lshlrev_b32_e32 v200, 16, v174
	v_and_b32_e32 v201, 0xffff0000, v174
	v_lshlrev_b32_e32 v174, 16, v175
	v_and_b32_e32 v175, 0xffff0000, v175
	v_and_b32_e32 v213, 0xffff0000, v178
	v_lshlrev_b32_e32 v178, 16, v179
	v_and_b32_e32 v179, 0xffff0000, v179
	v_lshlrev_b32_e32 v198, 16, v172
	v_and_b32_e32 v199, 0xffff0000, v172
	v_lshlrev_b32_e32 v172, 16, v173
	v_and_b32_e32 v173, 0xffff0000, v173
	v_pk_mul_f32 v[206:207], v[200:201], v[200:201]
	v_pk_mul_f32 v[208:209], v[174:175], v[174:175]
	v_lshlrev_b32_e32 v210, 16, v176
	v_and_b32_e32 v211, 0xffff0000, v176
	v_lshlrev_b32_e32 v176, 16, v177
	v_and_b32_e32 v177, 0xffff0000, v177
	v_pk_mul_f32 v[214:215], v[212:213], v[212:213]
	v_pk_mul_f32 v[216:217], v[178:179], v[178:179]
	v_pk_add_f32 v[156:157], v[156:157], v[156:157] op_sel:[0,1] op_sel_hi:[1,0]
	v_pk_add_f32 v[192:193], v[192:193], v[192:193] op_sel:[0,1] op_sel_hi:[1,0]
	v_pk_fma_f32 v[208:209], v[172:173], v[172:173], v[208:209]
	v_pk_fma_f32 v[206:207], v[198:199], v[198:199], v[206:207]
	v_pk_fma_f32 v[216:217], v[176:177], v[176:177], v[216:217]
	v_pk_fma_f32 v[214:215], v[210:211], v[210:211], v[214:215]
	v_add_f32_e32 v206, v206, v207
	v_add_f32_e32 v208, v208, v209
	v_mov_b32_e32 v157, v214
	v_mov_b32_e32 v193, v215
	v_mov_b32_e32 v207, v216
	v_mov_b32_e32 v209, v217
	v_pk_add_f32 v[156:157], v[156:157], v[192:193]
	v_pk_add_f32 v[192:193], v[206:207], v[208:209]
	s_nop 0
	v_pk_add_f32 v[156:157], v[156:157], v[192:193]
	s_nop 0
	v_add_f32_e32 v156, v156, v157
	ds_bpermute_b32 v157, v151, v156
	s_waitcnt lgkmcnt(0)
; __device__ __forceinline__ float bf_lo(unsigned w) { return __uint_as_float(w << 16); }
; __device__ __forceinline__ float bf_hi(unsigned w) { return __uint_as_float(w & 0xffff0000u); }
; __device__ __forceinline__ float shx(float v, int o, int lane) { return __int_as_float(__builtin_amdgcn_ds_bpermute((lane ^ o) << 2, __float_as_int(v))); }
; __device__ __forceinline__ u32x4 pack8(f32x4 v0, f32x4 v1) { u32x4 w; w.x = cvt_pk_bf16(v0[0], v0[1]); w.y = cvt_pk_bf16(v0[2], v0[3]); w.z = cvt_pk_bf16(v1[0], v1[1]); w.w = cvt_pk_bf16(v1[2], v1[3]); return w; }
; __global__ void __launch_bounds__(512, 2) mk_fwd(Args a) {
;     ...
;                 for (int which = 0; which < 2; ++which) {
;                     f32x4 v[6][2]; float ss = 0.f;
; #pragma unroll
;                     for (int m = 0; m < 6; ++m) { const u32x4 w = which ? xk[m] : xq[m];
;                         v[m][0] = (f32x4){bf_lo(w.x), bf_hi(w.x), bf_lo(w.y), bf_hi(w.y)}; v[m][1] = (f32x4){bf_lo(w.z), bf_hi(w.z), bf_lo(w.w), bf_hi(w.w)};
;                         const f32x4 sq = v[m][0] * v[m][0] + v[m][1] * v[m][1]; ss += (sq[0] + sq[1]) + (sq[2] + sq[3]); }
;                     ss += shx(ss, 1, lane); ss += shx(ss, 2, lane);
;                     const float rs = __builtin_amdgcn_rsqf(ss * (1.f / 192.f) + EPS) * (which ? 1.f : C2);
; #pragma unroll
;                     for (int m = 0; m < 6; ++m) { v[m][0] = v[m][0] * rs * (which ? gkv[m][0] : gqv[m][0]); v[m][1] = v[m][1] * rs * (which ? gkv[m][1] : gqv[m][1]); }
;                     const f32x4 a0 = v[4][0], a1 = v[4][1], b0 = v[5][0], b1 = v[5][1];
;                     v[4][0] = a0 * cs0 - b0 * sn0; v[4][1] = a1 * cs1 - b1 * sn1; v[5][0] = b0 * cs0 + a0 * sn0; v[5][1] = b1 * cs1 + a1 * sn1;
;                     bf16_t* op = which ? kp : qp;
; #pragma unroll
;                     for (int m = 0; m < 6; ++m) *(u32x4*)(op + 32 * m) = pg8::pack8(v[m][0], v[m][1]);
	v_add_f32_e32 v156, v156, v157
	ds_bpermute_b32 v157, v162, v156
	s_waitcnt lgkmcnt(0)
	v_add_f32_e32 v156, v156, v157
	v_fmamk_f32 v156, v156, 0x3baaaaab, v202
	v_rsq_f32_e32 v156, v156
	s_nop 0
	v_mul_f32_e32 v156, 0x3dd53b94, v156
	v_pk_mul_f32 v[154:155], v[156:157], v[154:155] op_sel_hi:[0,1]
	v_pk_mul_f32 v[192:193], v[154:155], v[2:3]
	v_pk_mul_f32 v[154:155], v[156:157], v[186:187] op_sel_hi:[0,1]
	v_pk_mul_f32 v[186:187], v[154:155], v[20:21]
	v_pk_mul_f32 v[154:155], v[156:157], v[188:189] op_sel_hi:[0,1]
	v_pk_mul_f32 v[188:189], v[154:155], v[16:17]
	v_pk_mul_f32 v[154:155], v[156:157], v[194:195] op_sel_hi:[0,1]
	v_pk_mul_f32 v[194:195], v[154:155], v[36:37]
	v_pk_mul_f32 v[154:155], v[156:157], v[196:197] op_sel_hi:[0,1]
	v_pk_mul_f32 v[196:197], v[154:155], v[32:33]
	v_pk_mul_f32 v[154:155], v[156:157], v[184:185] op_sel_hi:[0,1]
	v_pk_mul_f32 v[184:185], v[154:155], v[52:53]
	v_pk_mul_f32 v[154:155], v[156:157], v[190:191] op_sel_hi:[0,1]
	v_pk_mul_f32 v[176:177], v[156:157], v[176:177] op_sel_hi:[0,1]
	v_pk_mul_f32 v[142:143], v[156:157], v[142:143] op_sel_hi:[0,1]
	v_pk_mul_f32 v[146:147], v[156:157], v[146:147] op_sel_hi:[0,1]
	v_pk_mul_f32 v[148:149], v[156:157], v[148:149] op_sel_hi:[0,1]
	v_pk_mul_f32 v[158:159], v[156:157], v[158:159] op_sel_hi:[0,1]
	v_pk_mul_f32 v[160:161], v[156:157], v[160:161] op_sel_hi:[0,1]
	v_pk_mul_f32 v[164:165], v[156:157], v[164:165] op_sel_hi:[0,1]
	v_pk_mul_f32 v[166:167], v[156:157], v[166:167] op_sel_hi:[0,1]
	v_pk_mul_f32 v[168:169], v[156:157], v[168:169] op_sel_hi:[0,1]
	v_pk_mul_f32 v[170:171], v[156:157], v[170:171] op_sel_hi:[0,1]
	v_pk_mul_f32 v[190:191], v[154:155], v[48:49]
	v_pk_mul_f32 v[154:155], v[156:157], v[172:173] op_sel_hi:[0,1]
	v_pk_mul_f32 v[172:173], v[156:157], v[198:199] op_sel_hi:[0,1]
	v_pk_mul_f32 v[174:175], v[156:157], v[174:175] op_sel_hi:[0,1]
	v_pk_mul_f32 v[198:199], v[156:157], v[200:201] op_sel_hi:[0,1]
	v_pk_mul_f32 v[200:201], v[156:157], v[210:211] op_sel_hi:[0,1]
	v_pk_mul_f32 v[176:177], v[176:177], v[86:87]
	v_pk_mul_f32 v[206:207], v[156:157], v[212:213] op_sel_hi:[0,1]
	v_pk_mul_f32 v[156:157], v[156:157], v[178:179] op_sel_hi:[0,1]
	v_pk_mul_f32 v[154:155], v[154:155], v[70:71]
	v_pk_mul_f32 v[156:157], v[156:157], v[82:83]
	v_pk_mul_f32 v[178:179], v[206:207], v[80:81]
	v_pk_mul_f32 v[208:209], v[110:111], v[176:177]
	v_pk_mul_f32 v[176:177], v[106:107], v[176:177]
	v_pk_mul_f32 v[198:199], v[198:199], v[64:65]
	v_pk_mul_f32 v[174:175], v[174:175], v[66:67]
	v_pk_fma_f32 v[208:209], v[106:107], v[154:155], v[208:209] neg_lo:[0,0,1] neg_hi:[0,0,1]
	v_pk_mul_f32 v[212:213], v[102:103], v[156:157]
	v_pk_fma_f32 v[176:177], v[110:111], v[154:155], v[176:177]
	v_pk_mul_f32 v[154:155], v[96:97], v[178:179]
	v_pk_mul_f32 v[156:157], v[98:99], v[156:157]
	v_pk_mul_f32 v[146:147], v[146:147], v[6:7]
	v_pk_mul_f32 v[142:143], v[142:143], v[4:5]
	v_pk_mul_f32 v[148:149], v[148:149], v[0:1]
	v_pk_mul_f32 v[210:211], v[100:101], v[178:179]
	v_pk_fma_f32 v[212:213], v[98:99], v[174:175], v[212:213] neg_lo:[0,0,1] neg_hi:[0,0,1]
	v_pk_fma_f32 v[174:175], v[102:103], v[174:175], v[156:157]
	v_pk_fma_f32 v[178:179], v[100:101], v[198:199], v[154:155]
	v_cvt_pk_bf16_f32 v154, v142, v143
	v_cvt_pk_bf16_f32 v155, v146, v147
	v_cvt_pk_bf16_f32 v156, v148, v149
	v_cvt_pk_bf16_f32 v157, v192, v193
	v_pk_mul_f32 v[158:159], v[158:159], v[22:23]
	v_pk_mul_f32 v[160:161], v[160:161], v[18:19]
	global_store_dwordx4 v[140:141], v[154:157], off
	v_pk_mul_f32 v[164:165], v[164:165], v[38:39]
	v_pk_mul_f32 v[166:167], v[166:167], v[34:35]
	v_cvt_pk_bf16_f32 v154, v186, v187
	v_cvt_pk_bf16_f32 v155, v158, v159
	v_cvt_pk_bf16_f32 v156, v188, v189
	v_cvt_pk_bf16_f32 v157, v160, v161
	v_pk_mul_f32 v[200:201], v[200:201], v[84:85]
	global_store_dwordx4 v[140:141], v[154:157], off offset:64
	v_pk_mul_f32 v[168:169], v[168:169], v[54:55]
	v_pk_mul_f32 v[170:171], v[170:171], v[50:51]
	v_cvt_pk_bf16_f32 v154, v194, v195
	v_cvt_pk_bf16_f32 v155, v164, v165
	v_cvt_pk_bf16_f32 v156, v196, v197
	v_cvt_pk_bf16_f32 v157, v166, v167
	v_pk_mul_f32 v[172:173], v[172:173], v[68:69]
	v_pk_mul_f32 v[206:207], v[108:109], v[200:201]
	global_store_dwordx4 v[140:141], v[154:157], off offset:128
	v_pk_fma_f32 v[206:207], v[104:105], v[172:173], v[206:207] neg_lo:[0,0,1] neg_hi:[0,0,1]
	v_pk_fma_f32 v[210:211], v[96:97], v[198:199], v[210:211] neg_lo:[0,0,1] neg_hi:[0,0,1]
	v_cvt_pk_bf16_f32 v154, v184, v185
	v_cvt_pk_bf16_f32 v155, v168, v169
	v_cvt_pk_bf16_f32 v156, v190, v191
	v_cvt_pk_bf16_f32 v157, v170, v171
	v_pk_mul_f32 v[200:201], v[104:105], v[200:201]
	global_store_dwordx4 v[140:141], v[154:157], off offset:192
	v_pk_fma_f32 v[172:173], v[108:109], v[172:173], v[200:201]
	v_lshlrev_b32_e32 v146, 16, v182
	v_cvt_pk_bf16_f32 v154, v206, v207
	v_cvt_pk_bf16_f32 v155, v208, v209
	v_cvt_pk_bf16_f32 v156, v210, v211
	v_cvt_pk_bf16_f32 v157, v212, v213
	global_store_dwordx4 v[140:141], v[154:157], off offset:256
	v_and_b32_e32 v147, 0xffff0000, v182
	v_lshlrev_b32_e32 v148, 16, v183
	v_cvt_pk_bf16_f32 v154, v172, v173
	v_cvt_pk_bf16_f32 v155, v176, v177
	v_cvt_pk_bf16_f32 v156, v178, v179
	v_cvt_pk_bf16_f32 v157, v174, v175
	v_and_b32_e32 v149, 0xffff0000, v183
	v_lshlrev_b32_e32 v160, 16, v130
	v_and_b32_e32 v161, 0xffff0000, v130
	v_lshlrev_b32_e32 v130, 16, v131
	v_and_b32_e32 v131, 0xffff0000, v131
	v_lshlrev_b32_e32 v170, 16, v126
	v_and_b32_e32 v171, 0xffff0000, v126
	v_lshlrev_b32_e32 v126, 16, v127
	v_and_b32_e32 v127, 0xffff0000, v127
	global_store_dwordx4 v[140:141], v[154:157], off offset:320
	v_lshlrev_b32_e32 v140, 16, v180
	v_and_b32_e32 v141, 0xffff0000, v180
; __device__ __forceinline__ float bf_lo(unsigned w) { return __uint_as_float(w << 16); }
; __device__ __forceinline__ float bf_hi(unsigned w) { return __uint_as_float(w & 0xffff0000u); }
; __device__ __forceinline__ float shx(float v, int o, int lane) { return __int_as_float(__builtin_amdgcn_ds_bpermute((lane ^ o) << 2, __float_as_int(v))); }
; __global__ void __launch_bounds__(512, 2) mk_fwd(Args a) {
;     ...
;                 for (int which = 0; which < 2; ++which) {
;                     f32x4 v[6][2]; float ss = 0.f;
; #pragma unroll
;                     for (int m = 0; m < 6; ++m) { const u32x4 w = which ? xk[m] : xq[m];
;                         v[m][0] = (f32x4){bf_lo(w.x), bf_hi(w.x), bf_lo(w.y), bf_hi(w.y)}; v[m][1] = (f32x4){bf_lo(w.z), bf_hi(w.z), bf_lo(w.w), bf_hi(w.w)};
;                         const f32x4 sq = v[m][0] * v[m][0] + v[m][1] * v[m][1]; ss += (sq[0] + sq[1]) + (sq[2] + sq[3]); }
;                     ss += shx(ss, 1, lane); ss += shx(ss, 2, lane);
;                     const float rs = __builtin_amdgcn_rsqf(ss * (1.f / 192.f) + EPS) * (which ? 1.f : C2);
	v_lshlrev_b32_e32 v142, 16, v181
	v_and_b32_e32 v143, 0xffff0000, v181
	v_pk_mul_f32 v[154:155], v[146:147], v[146:147]
	v_pk_mul_f32 v[156:157], v[148:149], v[148:149]
	v_lshlrev_b32_e32 v158, 16, v128
	v_and_b32_e32 v159, 0xffff0000, v128
	v_lshlrev_b32_e32 v128, 16, v129
	v_and_b32_e32 v129, 0xffff0000, v129
	v_pk_mul_f32 v[164:165], v[160:161], v[160:161]
	v_pk_mul_f32 v[166:167], v[130:131], v[130:131]
	v_lshlrev_b32_e32 v168, 16, v124
	v_and_b32_e32 v169, 0xffff0000, v124
	v_lshlrev_b32_e32 v124, 16, v125
	v_and_b32_e32 v125, 0xffff0000, v125
	v_pk_mul_f32 v[172:173], v[170:171], v[170:171]
	v_pk_mul_f32 v[174:175], v[126:127], v[126:127]
	v_pk_fma_f32 v[156:157], v[142:143], v[142:143], v[156:157]
	v_pk_fma_f32 v[154:155], v[140:141], v[140:141], v[154:155]
	v_pk_fma_f32 v[166:167], v[128:129], v[128:129], v[166:167]
	v_pk_fma_f32 v[164:165], v[158:159], v[158:159], v[164:165]
	v_pk_fma_f32 v[174:175], v[124:125], v[124:125], v[174:175]
	v_pk_fma_f32 v[172:173], v[168:169], v[168:169], v[172:173]
	v_add_f32_e32 v154, v154, v155
	v_add_f32_e32 v156, v156, v157
	v_add_f32_e32 v164, v164, v165
	v_add_f32_e32 v166, v166, v167
	v_mov_b32_e32 v155, v172
	v_mov_b32_e32 v157, v173
	v_mov_b32_e32 v165, v174
	v_mov_b32_e32 v167, v175
	v_pk_add_f32 v[154:155], v[154:155], v[156:157]
	v_pk_add_f32 v[156:157], v[164:165], v[166:167]
	v_lshlrev_b32_e32 v166, 16, v114
	v_and_b32_e32 v167, 0xffff0000, v114
	v_lshlrev_b32_e32 v172, 16, v115
	v_and_b32_e32 v173, 0xffff0000, v115
	v_pk_add_f32 v[154:155], v[154:155], v[156:157]
	v_lshlrev_b32_e32 v156, 16, v112
	v_and_b32_e32 v157, 0xffff0000, v112
	v_lshlrev_b32_e32 v164, 16, v113
	v_and_b32_e32 v165, 0xffff0000, v113
	v_pk_mul_f32 v[112:113], v[166:167], v[166:167]
	v_pk_mul_f32 v[114:115], v[172:173], v[172:173]
	v_pk_fma_f32 v[112:113], v[156:157], v[156:157], v[112:113]
	v_pk_fma_f32 v[114:115], v[164:165], v[164:165], v[114:115]
	v_lshlrev_b32_e32 v178, 16, v122
	v_pk_mov_b32 v[174:175], v[112:113], v[114:115] op_sel:[1,0]
	v_mov_b32_e32 v113, v115
	v_and_b32_e32 v179, 0xffff0000, v122
	v_lshlrev_b32_e32 v180, 16, v123
	v_and_b32_e32 v181, 0xffff0000, v123
	v_lshlrev_b32_e32 v186, 16, v118
	v_and_b32_e32 v187, 0xffff0000, v118
	v_lshlrev_b32_e32 v188, 16, v119
	v_and_b32_e32 v189, 0xffff0000, v119
	v_pk_add_f32 v[112:113], v[174:175], v[112:113]
	v_lshlrev_b32_e32 v174, 16, v120
	v_and_b32_e32 v175, 0xffff0000, v120
	v_lshlrev_b32_e32 v176, 16, v121
	v_and_b32_e32 v177, 0xffff0000, v121
	v_pk_mul_f32 v[114:115], v[178:179], v[178:179]
	v_pk_mul_f32 v[120:121], v[180:181], v[180:181]
	v_lshlrev_b32_e32 v182, 16, v116
	v_and_b32_e32 v183, 0xffff0000, v116
	v_lshlrev_b32_e32 v184, 16, v117
	v_and_b32_e32 v185, 0xffff0000, v117
	v_pk_mul_f32 v[116:117], v[186:187], v[186:187]
	v_pk_mul_f32 v[118:119], v[188:189], v[188:189]
	v_pk_add_f32 v[154:155], v[154:155], v[154:155] op_sel:[0,1] op_sel_hi:[1,0]
	v_pk_add_f32 v[112:113], v[112:113], v[112:113] op_sel:[0,1] op_sel_hi:[1,0]
	v_pk_fma_f32 v[120:121], v[176:177], v[176:177], v[120:121]
	v_pk_fma_f32 v[114:115], v[174:175], v[174:175], v[114:115]
	v_pk_fma_f32 v[118:119], v[184:185], v[184:185], v[118:119]
	v_pk_fma_f32 v[116:117], v[182:183], v[182:183], v[116:117]
	v_add_f32_e32 v114, v114, v115
	v_add_f32_e32 v120, v120, v121
	v_mov_b32_e32 v155, v116
	v_mov_b32_e32 v113, v117
	v_mov_b32_e32 v115, v118
	v_mov_b32_e32 v121, v119
	v_pk_add_f32 v[112:113], v[154:155], v[112:113]
	v_pk_add_f32 v[114:115], v[114:115], v[120:121]
	s_nop 0
	v_pk_add_f32 v[112:113], v[112:113], v[114:115]
	s_nop 0
	v_add_f32_e32 v112, v112, v113
	ds_bpermute_b32 v113, v151, v112
	s_waitcnt lgkmcnt(0)
	v_add_f32_e32 v112, v112, v113
	ds_bpermute_b32 v113, v162, v112
	s_waitcnt lgkmcnt(0)
; __device__ __forceinline__ float bf_lo(unsigned w) { return __uint_as_float(w << 16); }
; __device__ __forceinline__ float bf_hi(unsigned w) { return __uint_as_float(w & 0xffff0000u); }
; __device__ __forceinline__ float shx(float v, int o, int lane) { return __int_as_float(__builtin_amdgcn_ds_bpermute((lane ^ o) << 2, __float_as_int(v))); }
; __device__ __forceinline__ u32x4 pack8(f32x4 v0, f32x4 v1) { u32x4 w; w.x = cvt_pk_bf16(v0[0], v0[1]); w.y = cvt_pk_bf16(v0[2], v0[3]); w.z = cvt_pk_bf16(v1[0], v1[1]); w.w = cvt_pk_bf16(v1[2], v1[3]); return w; }
; __global__ void __launch_bounds__(512, 2) mk_fwd(Args a) {
;     ...
;                 for (int which = 0; which < 2; ++which) {
;                     f32x4 v[6][2]; float ss = 0.f;
; #pragma unroll
;                     for (int m = 0; m < 6; ++m) { const u32x4 w = which ? xk[m] : xq[m];
;                         v[m][0] = (f32x4){bf_lo(w.x), bf_hi(w.x), bf_lo(w.y), bf_hi(w.y)}; v[m][1] = (f32x4){bf_lo(w.z), bf_hi(w.z), bf_lo(w.w), bf_hi(w.w)};
;                         const f32x4 sq = v[m][0] * v[m][0] + v[m][1] * v[m][1]; ss += (sq[0] + sq[1]) + (sq[2] + sq[3]); }
;                     ss += shx(ss, 1, lane); ss += shx(ss, 2, lane);
;                     const float rs = __builtin_amdgcn_rsqf(ss * (1.f / 192.f) + EPS) * (which ? 1.f : C2);
; #pragma unroll
;                     for (int m = 0; m < 6; ++m) { v[m][0] = v[m][0] * rs * (which ? gkv[m][0] : gqv[m][0]); v[m][1] = v[m][1] * rs * (which ? gkv[m][1] : gqv[m][1]); }
;                     const f32x4 a0 = v[4][0], a1 = v[4][1], b0 = v[5][0], b1 = v[5][1];
;                     v[4][0] = a0 * cs0 - b0 * sn0; v[4][1] = a1 * cs1 - b1 * sn1; v[5][0] = b0 * cs0 + a0 * sn0; v[5][1] = b1 * cs1 + a1 * sn1;
;                     bf16_t* op = which ? kp : qp;
; #pragma unroll
;                     for (int m = 0; m < 6; ++m) *(u32x4*)(op + 32 * m) = pg8::pack8(v[m][0], v[m][1]);
;                 }
	v_add_f32_e32 v112, v112, v113
	v_fmamk_f32 v112, v112, 0x3baaaaab, v202
	v_rsq_f32_e32 v154, v112
	s_nop 0
	v_pk_mul_f32 v[114:115], v[154:155], v[142:143] op_sel_hi:[0,1]
	v_pk_mul_f32 v[112:113], v[154:155], v[140:141] op_sel_hi:[0,1]
	v_pk_mul_f32 v[190:191], v[114:115], v[14:15]
	v_pk_mul_f32 v[114:115], v[154:155], v[148:149] op_sel_hi:[0,1]
	v_pk_mul_f32 v[116:117], v[154:155], v[130:131] op_sel_hi:[0,1]
	v_pk_mul_f32 v[130:131], v[154:155], v[156:157] op_sel_hi:[0,1]
	v_pk_mul_f32 v[156:157], v[154:155], v[176:177] op_sel_hi:[0,1]
	v_pk_mul_f32 v[192:193], v[112:113], v[12:13]
	v_pk_mul_f32 v[112:113], v[154:155], v[146:147] op_sel_hi:[0,1]
	v_pk_mul_f32 v[146:147], v[114:115], v[10:11]
	v_pk_mul_f32 v[114:115], v[154:155], v[158:159] op_sel_hi:[0,1]
	v_pk_mul_f32 v[118:119], v[154:155], v[160:161] op_sel_hi:[0,1]
	v_pk_mul_f32 v[142:143], v[154:155], v[166:167] op_sel_hi:[0,1]
	v_pk_mul_f32 v[158:159], v[154:155], v[174:175] op_sel_hi:[0,1]
	v_pk_mul_f32 v[166:167], v[156:157], v[78:79]
	v_pk_mul_f32 v[156:157], v[154:155], v[180:181] op_sel_hi:[0,1]
	v_pk_mul_f32 v[148:149], v[112:113], v[8:9]
	v_pk_mul_f32 v[112:113], v[154:155], v[128:129] op_sel_hi:[0,1]
	v_pk_mul_f32 v[120:121], v[118:119], v[24:25]
	v_pk_mul_f32 v[118:119], v[154:155], v[124:125] op_sel_hi:[0,1]
	v_pk_mul_f32 v[128:129], v[154:155], v[170:171] op_sel_hi:[0,1]
	v_pk_mul_f32 v[124:125], v[154:155], v[126:127] op_sel_hi:[0,1]
	v_pk_mul_f32 v[126:127], v[154:155], v[164:165] op_sel_hi:[0,1]
	v_pk_mul_f32 v[164:165], v[158:159], v[76:77]
	v_pk_mul_f32 v[158:159], v[154:155], v[178:179] op_sel_hi:[0,1]
	v_pk_mul_f32 v[170:171], v[156:157], v[74:75]
	v_pk_mul_f32 v[156:157], v[154:155], v[182:183] op_sel_hi:[0,1]
	v_pk_mul_f32 v[122:123], v[154:155], v[168:169] op_sel_hi:[0,1]
	v_pk_mul_f32 v[140:141], v[154:155], v[172:173] op_sel_hi:[0,1]
	v_pk_mul_f32 v[168:169], v[158:159], v[72:73]
	v_pk_mul_f32 v[158:159], v[154:155], v[184:185] op_sel_hi:[0,1]
	v_pk_mul_f32 v[174:175], v[156:157], v[92:93]
	v_pk_mul_f32 v[156:157], v[154:155], v[186:187] op_sel_hi:[0,1]
	v_pk_mul_f32 v[154:155], v[154:155], v[188:189] op_sel_hi:[0,1]
	v_pk_mul_f32 v[172:173], v[158:159], v[94:95]
	v_pk_mul_f32 v[176:177], v[154:155], v[90:91]
	v_pk_mul_f32 v[178:179], v[156:157], v[88:89]
	v_pk_mul_f32 v[156:157], v[108:109], v[174:175]
	v_pk_mul_f32 v[154:155], v[110:111], v[172:173]
	v_pk_mul_f32 v[160:161], v[100:101], v[178:179]
	v_pk_mul_f32 v[158:159], v[102:103], v[176:177]
	v_pk_mul_f32 v[174:175], v[104:105], v[174:175]
	v_pk_fma_f32 v[154:155], v[106:107], v[166:167], v[154:155] neg_lo:[0,0,1] neg_hi:[0,0,1]
	v_pk_fma_f32 v[156:157], v[104:105], v[164:165], v[156:157] neg_lo:[0,0,1] neg_hi:[0,0,1]
	v_pk_fma_f32 v[158:159], v[98:99], v[170:171], v[158:159] neg_lo:[0,0,1] neg_hi:[0,0,1]
	v_pk_fma_f32 v[160:161], v[96:97], v[168:169], v[160:161] neg_lo:[0,0,1] neg_hi:[0,0,1]
	v_pk_mul_f32 v[104:105], v[106:107], v[172:173]
	v_pk_fma_f32 v[106:107], v[108:109], v[164:165], v[174:175]
	v_pk_mul_f32 v[96:97], v[96:97], v[178:179]
	v_pk_mul_f32 v[98:99], v[98:99], v[176:177]
	v_add_co_u32_e32 v108, vcc, s3, v138
	v_pk_fma_f32 v[102:103], v[102:103], v[170:171], v[98:99]
	v_pk_fma_f32 v[100:101], v[100:101], v[168:169], v[96:97]
	v_cvt_pk_bf16_f32 v96, v192, v193
	v_cvt_pk_bf16_f32 v97, v190, v191
	v_cvt_pk_bf16_f32 v98, v148, v149
	v_cvt_pk_bf16_f32 v99, v146, v147
	v_addc_co_u32_e32 v109, vcc, 0, v139, vcc
	v_pk_mul_f32 v[112:113], v[112:113], v[30:31]
	v_pk_mul_f32 v[114:115], v[114:115], v[28:29]
	v_pk_mul_f32 v[116:117], v[116:117], v[26:27]
	global_store_dwordx4 v[108:109], v[96:99], off
	v_pk_mul_f32 v[118:119], v[118:119], v[46:47]
	v_pk_mul_f32 v[122:123], v[122:123], v[44:45]
	v_cvt_pk_bf16_f32 v96, v114, v115
	v_cvt_pk_bf16_f32 v97, v112, v113
	v_cvt_pk_bf16_f32 v98, v120, v121
	v_cvt_pk_bf16_f32 v99, v116, v117
	v_pk_mul_f32 v[124:125], v[124:125], v[42:43]
	v_pk_mul_f32 v[128:129], v[128:129], v[40:41]
	global_store_dwordx4 v[108:109], v[96:99], off offset:64
	v_pk_mul_f32 v[126:127], v[126:127], v[62:63]
	v_pk_mul_f32 v[130:131], v[130:131], v[60:61]
	v_cvt_pk_bf16_f32 v96, v122, v123
	v_cvt_pk_bf16_f32 v97, v118, v119
	v_cvt_pk_bf16_f32 v98, v128, v129
	v_cvt_pk_bf16_f32 v99, v124, v125
	v_pk_mul_f32 v[140:141], v[140:141], v[58:59]
	v_pk_mul_f32 v[142:143], v[142:143], v[56:57]
	global_store_dwordx4 v[108:109], v[96:99], off offset:128
	v_pk_fma_f32 v[104:105], v[110:111], v[166:167], v[104:105]
	s_nop 0
	v_cvt_pk_bf16_f32 v96, v130, v131
	v_cvt_pk_bf16_f32 v97, v126, v127
	v_cvt_pk_bf16_f32 v98, v142, v143
	v_cvt_pk_bf16_f32 v99, v140, v141
	global_store_dwordx4 v[108:109], v[96:99], off offset:192
	s_nop 1
	v_cvt_pk_bf16_f32 v96, v156, v157
	v_cvt_pk_bf16_f32 v97, v154, v155
	v_cvt_pk_bf16_f32 v98, v160, v161
	v_cvt_pk_bf16_f32 v99, v158, v159
	global_store_dwordx4 v[108:109], v[96:99], off offset:256
	s_nop 1
	v_cvt_pk_bf16_f32 v96, v106, v107
	v_cvt_pk_bf16_f32 v97, v104, v105
	v_cvt_pk_bf16_f32 v98, v100, v101
	v_cvt_pk_bf16_f32 v99, v102, v103
	global_store_dwordx4 v[108:109], v[96:99], off offset:320
	s_cbranch_scc0 .LBB0_233

; __device__ __forceinline__ unsigned cvt_pk_bf16(float lo, float hi) { unsigned r; asm volatile("v_cvt_pk_bf16_f32 %0, %1, %2" : "=v"(r) : "v"(lo), "v"(hi)); return r; }
; __device__ __forceinline__ float bf_lo(unsigned w) { return __uint_as_float(w << 16); }
; __global__ void __launch_bounds__(512, 2) mk_fwd(Args a) {
;     ...
;             for (int r = gw; r < LSEQ; r += NGW) {
;                 const bf16_t* pr = PA + (size_t)r * NPA;
;                 { u32x2 w[3]; float s = 0.f;
; #pragma unroll
;                   for (int j = 0; j < 3; ++j) { w[j] = *(const u32x2*)(pr + 1024 + (lane + 64 * j) * 4); const float a0 = bf_lo(w[j].x), a1 = bf_hi(w[j].x), a2 = bf_lo(w[j].y), a3 = bf_hi(w[j].y); s += (a0 * a0 + a1 * a1) + (a2 * a2 + a3 * a3); }
;                   const float rs = __builtin_amdgcn_rsqf(wave_sum(s, lane) * (1.f / QL) + EPS);
; #pragma unroll
;                   for (int j = 0; j < 3; ++j) { const f32x4 g = *(const f32x4*)(gqa + (lane + 64 * j) * 4); u32x2 o;
;                       o.x = cvt_pk_bf16(bf_lo(w[j].x) * rs * g.x, bf_hi(w[j].x) * rs * g.y); o.y = cvt_pk_bf16(bf_lo(w[j].y) * rs * g.z, bf_hi(w[j].y) * rs * g.w);
;                       *(u32x2*)(CQN + (size_t)r * QL + (lane + 64 * j) * 4) = o; } }
;                 { u32x2 w[2]; float s = 0.f;
; #pragma unroll
;                   for (int j = 0; j < 2; ++j) { w[j] = *(const u32x2*)(pr + 1792 + (lane + 64 * j) * 4); const float a0 = bf_lo(w[j].x), a1 = bf_hi(w[j].x), a2 = bf_lo(w[j].y), a3 = bf_hi(w[j].y); s += (a0 * a0 + a1 * a1) + (a2 * a2 + a3 * a3); }
;                   const float rs = __builtin_amdgcn_rsqf(wave_sum(s, lane) * (1.f / KVL) + EPS);
; #pragma unroll
;                   for (int j = 0; j < 2; ++j) { const f32x4 g = *(const f32x4*)(gkva + (lane + 64 * j) * 4); u32x2 o;
;                       o.x = cvt_pk_bf16(bf_lo(w[j].x) * rs * g.x, bf_hi(w[j].x) * rs * g.y); o.y = cvt_pk_bf16(bf_lo(w[j].y) * rs * g.z, bf_hi(w[j].y) * rs * g.w);
;                       *(u32x2*)(CKVN + (size_t)r * KVL + (lane + 64 * j) * 4) = o; } }
;                 { const int rl = row_left(r), rr = row_right(r);
;                   const bf16_t* pl = PA + (size_t)(rl < 0 ? r : rl) * NPA; const bf16_t* pq = PA + (size_t)(rr < 0 ? r : rr) * NPA;
;                   const float ml = rl < 0 ? 0.f : 1.f, mr = rr < 0 ? 0.f : 1.f;
.LBB0_239:
	v_lshl_add_u64 v[38:39], s[64:65], 0, v[26:27]
	v_add_co_u32_e32 v62, vcc, 0xfc01000, v38
	global_load_dwordx4 v[0:3], v[4:5], off
	s_nop 0
	v_addc_co_u32_e32 v63, vcc, 0, v39, vcc
	global_load_dwordx2 v[68:69], v[62:63], off offset:2048
	global_load_dwordx2 v[70:71], v[62:63], off offset:2560
	global_load_dwordx2 v[72:73], v[62:63], off offset:3072
	v_lshl_add_u64 v[40:41], s[64:65], 0, v[18:19]
	v_add_co_u32_e64 v64, s[0:1], s13, v40
	v_lshl_add_u64 v[42:43], s[64:65], 0, v[20:21]
	s_nop 0
	v_addc_co_u32_e64 v65, s[0:1], 0, v41, s[0:1]
	s_mov_b32 s0, 0xe761000
	s_nop 0
	v_add_co_u32_e64 v66, s[0:1], s0, v42
	v_lshl_add_u64 v[44:45], s[64:65], 0, v[32:33]
	s_nop 0
	v_addc_co_u32_e64 v67, s[0:1], 0, v43, s[0:1]
	v_add_co_u32_e64 v78, s[0:1], s18, v44
	v_lshl_add_u64 v[46:47], s[64:65], 0, v[24:25]
	s_nop 0
	v_addc_co_u32_e64 v79, s[0:1], 0, v45, s[0:1]
	v_add_co_u32_e64 v82, s[0:1], s24, v44
	v_lshl_add_u64 v[36:37], s[64:65], 0, v[28:29]
	s_nop 0
	v_addc_co_u32_e64 v83, s[0:1], 0, v45, s[0:1]
	s_mov_b32 s0, 0x22d41000
	s_nop 0
	v_add_co_u32_e64 v40, s[0:1], s0, v46
	s_waitcnt vmcnt(0)
	v_lshl_add_u64 v[50:51], s[64:65], 0, v[30:31]
	v_addc_co_u32_e64 v41, s[0:1], 0, v47, s[0:1]
	v_add_co_u32_e64 v42, s[0:1], s18, v50
	v_sub_co_u32_e64 v48, s[2:3], s6, 1
	s_nop 0
	v_addc_co_u32_e64 v43, s[0:1], 0, v51, s[0:1]
	s_cmpk_lg_i32 s6, 0x2000
	v_readfirstlane_b32 s7, v48
	v_add_co_u32_e64 v44, s[0:1], s24, v50
	s_cselect_b32 s7, s7, -1
	s_nop 0
	v_addc_co_u32_e64 v45, s[0:1], 0, v51, s[0:1]
	s_and_b64 s[0:1], s[2:3], exec
	s_cselect_b32 s2, 0x200f, s7
	s_add_i32 s0, s6, 1
	s_cmpk_lg_i32 s6, 0x200f
	s_cselect_b32 s0, s0, 0
	s_cmpk_lg_i32 s6, 0x1fff
	s_cselect_b32 s3, s0, -1
	s_cmp_lt_i32 s2, 0
	s_cselect_b64 s[0:1], -1, 0
	v_cndmask_b32_e64 v38, 1.0, 0, s[0:1]
	s_and_b64 s[0:1], s[0:1], exec
	s_cselect_b32 s0, s6, s2
	s_mul_hi_i32 s1, s0, 0x2a00
	s_mulk_i32 s0, 0x2a00
	s_add_u32 s2, s84, s0
	s_addc_u32 s7, s85, s1
	s_cmp_lt_i32 s3, 0
	s_cselect_b64 s[0:1], -1, 0
	v_cndmask_b32_e64 v46, 1.0, 0, s[0:1]
	s_and_b64 s[0:1], s[0:1], exec
	s_cselect_b32 s0, s6, s3
	s_mul_hi_i32 s1, s0, 0x2a00
	s_mulk_i32 s0, 0x2a00
	s_add_u32 s8, s84, s0
	s_addc_u32 s9, s85, s1
	s_add_u32 s0, s2, 0x1a00
	s_addc_u32 s1, s7, 0
	s_add_u32 s2, s2, 0x2200
	s_addc_u32 s3, s7, 0
	v_lshl_add_u64 v[74:75], s[0:1], 0, v[22:23]
	v_lshl_add_u64 v[48:49], s[0:1], 0, v[34:35]
	s_add_u32 s0, s8, 0x1a00
	s_addc_u32 s1, s9, 0
	v_lshl_add_u64 v[76:77], s[2:3], 0, v[22:23]
	v_lshl_add_u64 v[50:51], s[2:3], 0, v[34:35]
	s_add_u32 s2, s8, 0x2200
	s_waitcnt lgkmcnt(0)
	v_lshlrev_b32_e32 v39, 16, v68
	v_and_b32_e32 v47, 0xffff0000, v68
	v_lshlrev_b32_e32 v68, 16, v69
	v_and_b32_e32 v69, 0xffff0000, v69
	v_lshlrev_b32_e32 v86, 16, v70
	v_and_b32_e32 v70, 0xffff0000, v70
	v_lshlrev_b32_e32 v87, 16, v71
	v_and_b32_e32 v71, 0xffff0000, v71
	v_lshlrev_b32_e32 v88, 16, v72
	v_and_b32_e32 v72, 0xffff0000, v72
	v_lshlrev_b32_e32 v89, 16, v73
	v_and_b32_e32 v73, 0xffff0000, v73
	v_mul_f32_e32 v90, v47, v47
	v_mul_f32_e32 v91, v69, v69
	v_mul_f32_e32 v92, v70, v70
	v_mul_f32_e32 v93, v71, v71
	v_mul_f32_e32 v94, v72, v72
	v_mul_f32_e32 v95, v73, v73
	v_fmac_f32_e32 v90, v39, v39
	v_fmac_f32_e32 v91, v68, v68
	v_fmac_f32_e32 v92, v86, v86
	v_fmac_f32_e32 v93, v87, v87
	v_fmac_f32_e32 v94, v88, v88
	v_fmac_f32_e32 v95, v89, v89
	v_add_f32_e32 v90, v90, v91
	v_add_f32_e32 v91, v92, v93
	v_add_f32_e32 v92, v94, v95
	v_add_f32_e32 v90, v90, v91
	v_add_f32_e32 v90, v90, v92
	ds_bpermute_b32 v91, v56, v90
	s_addc_u32 s3, s9, 0
	v_lshl_add_u64 v[80:81], s[0:1], 0, v[22:23]
	v_lshl_add_u64 v[84:85], s[2:3], 0, v[22:23]
	v_lshl_add_u64 v[52:53], s[0:1], 0, v[34:35]
	s_waitcnt lgkmcnt(0)
	v_add_f32_e32 v90, v90, v91
	ds_bpermute_b32 v91, v57, v90
	v_lshl_add_u64 v[54:55], s[2:3], 0, v[34:35]
	s_add_i32 s6, s6, s72
	v_lshl_add_u64 v[18:19], v[18:19], 0, s[28:29]
	v_lshl_add_u64 v[20:21], v[20:21], 0, s[4:5]
	s_waitcnt lgkmcnt(0)
	v_add_f32_e32 v90, v90, v91
	ds_bpermute_b32 v91, v58, v90
	v_lshl_add_u64 v[24:25], v[24:25], 0, s[80:81]
	v_lshl_add_u64 v[26:27], v[26:27], 0, s[34:35]
	v_lshl_add_u64 v[28:29], v[28:29], 0, s[34:35]
	v_lshl_add_u64 v[30:31], v[30:31], 0, s[34:35]
	s_waitcnt lgkmcnt(0)
	v_add_f32_e32 v90, v90, v91
	ds_bpermute_b32 v91, v59, v90
	v_lshl_add_u64 v[32:33], v[32:33], 0, s[34:35]
	s_cmpk_gt_i32 s6, 0x200f
	s_waitcnt lgkmcnt(0)
	v_add_f32_e32 v90, v90, v91
	ds_bpermute_b32 v91, v60, v90
	s_waitcnt lgkmcnt(0)
	v_add_f32_e32 v90, v90, v91
	ds_bpermute_b32 v91, v61, v90
	s_waitcnt lgkmcnt(0)
	v_add_f32_e32 v90, v90, v91
	v_fmamk_f32 v90, v90, 0x3aaaaaab, v202
	v_rsq_f32_e32 v90, v90
	s_nop 0
	v_mul_f32_e32 v39, v90, v39
	v_mul_f32_e32 v47, v90, v47
	v_mul_f32_e32 v68, v90, v68
	v_mul_f32_e32 v69, v90, v69
	v_mul_f32_e32 v0, v0, v39
	v_mul_f32_e32 v1, v1, v47
	v_mul_f32_e32 v2, v2, v68
	v_mul_f32_e32 v3, v3, v69
	v_cvt_pk_bf16_f32 v0, v0, v1
	v_cvt_pk_bf16_f32 v1, v2, v3
	global_store_dwordx2 v[64:65], v[0:1], off
	global_load_dwordx4 v[0:3], v[4:5], off offset:1024
	v_mul_f32_e32 v86, v90, v86
	v_mul_f32_e32 v70, v90, v70
	v_mul_f32_e32 v87, v90, v87
	v_mul_f32_e32 v71, v90, v71
	v_mul_f32_e32 v88, v90, v88
	v_mul_f32_e32 v72, v90, v72
	v_mul_f32_e32 v89, v90, v89
	v_mul_f32_e32 v73, v90, v73
	s_waitcnt vmcnt(0)
	v_mul_f32_e32 v0, v0, v86
	v_mul_f32_e32 v1, v1, v70
	v_mul_f32_e32 v2, v2, v87
	v_mul_f32_e32 v3, v3, v71
	v_cvt_pk_bf16_f32 v0, v0, v1
	v_cvt_pk_bf16_f32 v1, v2, v3
	global_store_dwordx2 v[64:65], v[0:1], off offset:512
	global_load_dwordx4 v[0:3], v[4:5], off offset:2048
	s_waitcnt vmcnt(0)
; __global__ void __launch_bounds__(512, 2) mk_fwd(Args a) {
;     ...
;                   for (int j = 0; j < 3; ++j) { const f32x4 g = *(const f32x4*)(gqa + (lane + 64 * j) * 4); u32x2 o;
;                       o.x = cvt_pk_bf16(bf_lo(w[j].x) * rs * g.x, bf_hi(w[j].x) * rs * g.y); o.y = cvt_pk_bf16(bf_lo(w[j].y) * rs * g.z, bf_hi(w[j].y) * rs * g.w);
;                       *(u32x2*)(CQN + (size_t)r * QL + (lane + 64 * j) * 4) = o; } }
;                 { u32x2 w[2]; float s = 0.f;
; #pragma unroll
;                   for (int j = 0; j < 2; ++j) { w[j] = *(const u32x2*)(pr + 1792 + (lane + 64 * j) * 4); const float a0 = bf_lo(w[j].x), a1 = bf_hi(w[j].x), a2 = bf_lo(w[j].y), a3 = bf_hi(w[j].y); s += (a0 * a0 + a1 * a1) + (a2 * a2 + a3 * a3); }
;                   const float rs = __builtin_amdgcn_rsqf(wave_sum(s, lane) * (1.f / KVL) + EPS);
; #pragma unroll
;                   for (int j = 0; j < 2; ++j) { const f32x4 g = *(const f32x4*)(gkva + (lane + 64 * j) * 4); u32x2 o;
;                       o.x = cvt_pk_bf16(bf_lo(w[j].x) * rs * g.x, bf_hi(w[j].x) * rs * g.y); o.y = cvt_pk_bf16(bf_lo(w[j].y) * rs * g.z, bf_hi(w[j].y) * rs * g.w);
;                       *(u32x2*)(CKVN + (size_t)r * KVL + (lane + 64 * j) * 4) = o; } }
;                 { const int rl = row_left(r), rr = row_right(r);
;                   const bf16_t* pl = PA + (size_t)(rl < 0 ? r : rl) * NPA; const bf16_t* pq = PA + (size_t)(rr < 0 ? r : rr) * NPA;
;                   const float ml = rl < 0 ? 0.f : 1.f, mr = rr < 0 ? 0.f : 1.f;
; #pragma unroll
;                   for (int j = 0; j < 2; ++j) { const int c = (lane + 64 * j) * 8;
;                       const u32x4 b = *(const u32x4*)(pr + 2304 + c);
;                       const u32x4 c0 = *(const u32x4*)(pl + 3328 + c), h0 = *(const u32x4*)(pl + 4352 + c);
;                       const u32x4 c1 = *(const u32x4*)(pr + 3328 + c), h1 = *(const u32x4*)(pr + 4352 + c);
;                       const u32x4 c2 = *(const u32x4*)(pq + 3328 + c), h2 = *(const u32x4*)(pq + 4352 + c);
;                       const f32x4 w0 = *(const f32x4*)(cw + c) * ml, w0b = *(const f32x4*)(cw + c + 4) * ml, w1 = *(const f32x4*)(cw + 1024 + c), w1b = *(const f32x4*)(cw + 1024 + c + 4);
;                       const f32x4 w2 = *(const f32x4*)(cw + 2048 + c) * mr, w2b = *(const f32x4*)(cw + 2048 + c + 4) * mr;
	v_mul_f32_e32 v0, v0, v88
	v_mul_f32_e32 v1, v1, v72
	v_mul_f32_e32 v2, v2, v89
	v_mul_f32_e32 v3, v3, v73
	v_cvt_pk_bf16_f32 v0, v0, v1
	v_cvt_pk_bf16_f32 v1, v2, v3
	global_store_dwordx2 v[64:65], v[0:1], off offset:1024
	global_load_dwordx2 v[62:63], v[62:63], off offset:3584
	s_nop 0
	global_load_dwordx2 v[36:37], v[36:37], off
	s_nop 0
	global_load_dwordx4 v[0:3], v[6:7], off
	s_waitcnt vmcnt(0) lgkmcnt(0)
	v_lshlrev_b32_e32 v39, 16, v62
	v_and_b32_e32 v47, 0xffff0000, v62
	v_lshlrev_b32_e32 v62, 16, v63
	v_and_b32_e32 v63, 0xffff0000, v63
	v_lshlrev_b32_e32 v64, 16, v36
	v_and_b32_e32 v36, 0xffff0000, v36
	v_lshlrev_b32_e32 v65, 16, v37
	v_and_b32_e32 v37, 0xffff0000, v37
	v_mul_f32_e32 v68, v47, v47
	v_mul_f32_e32 v69, v63, v63
	v_mul_f32_e32 v70, v36, v36
	v_mul_f32_e32 v71, v37, v37
	v_fmac_f32_e32 v68, v39, v39
	v_fmac_f32_e32 v69, v62, v62
	v_fmac_f32_e32 v70, v64, v64
	v_fmac_f32_e32 v71, v65, v65
	v_add_f32_e32 v68, v68, v69
	v_add_f32_e32 v69, v70, v71
	v_add_f32_e32 v68, v68, v69
	ds_bpermute_b32 v69, v56, v68
	s_waitcnt lgkmcnt(0)
	v_add_f32_e32 v68, v68, v69
	ds_bpermute_b32 v69, v57, v68
	s_waitcnt lgkmcnt(0)
	v_add_f32_e32 v68, v68, v69
	ds_bpermute_b32 v69, v58, v68
	s_waitcnt lgkmcnt(0)
	v_add_f32_e32 v68, v68, v69
	ds_bpermute_b32 v69, v59, v68
	s_waitcnt lgkmcnt(0)
	v_add_f32_e32 v68, v68, v69
	ds_bpermute_b32 v69, v60, v68
	s_waitcnt lgkmcnt(0)
	v_add_f32_e32 v68, v68, v69
	ds_bpermute_b32 v69, v61, v68
	s_waitcnt lgkmcnt(0)
	v_add_f32_e32 v68, v68, v69
	v_fmamk_f32 v68, v68, 0x3b000000, v202
	v_rsq_f32_e32 v68, v68
	s_nop 0
	v_mul_f32_e32 v39, v68, v39
	v_mul_f32_e32 v47, v68, v47
	v_mul_f32_e32 v62, v68, v62
	v_mul_f32_e32 v63, v68, v63
	v_mul_f32_e32 v0, v0, v39
	v_mul_f32_e32 v1, v1, v47
	v_mul_f32_e32 v2, v2, v62
	v_mul_f32_e32 v3, v3, v63
	v_cvt_pk_bf16_f32 v0, v0, v1
	v_cvt_pk_bf16_f32 v1, v2, v3
	global_store_dwordx2 v[66:67], v[0:1], off
	global_load_dwordx4 v[0:3], v[6:7], off offset:1024
	v_mul_f32_e32 v64, v68, v64
	v_mul_f32_e32 v36, v68, v36
	v_mul_f32_e32 v65, v68, v65
	v_mul_f32_e32 v37, v68, v37
	s_waitcnt vmcnt(0)
	v_mul_f32_e32 v0, v0, v64
	v_mul_f32_e32 v1, v1, v36
	v_mul_f32_e32 v2, v2, v65
	v_mul_f32_e32 v3, v3, v37
	v_cvt_pk_bf16_f32 v0, v0, v1
	v_cvt_pk_bf16_f32 v1, v2, v3
	global_store_dwordx2 v[66:67], v[0:1], off offset:512
	global_load_dwordx4 v[0:3], v[78:79], off offset:2560
	s_nop 0
	global_load_dwordx4 v[62:65], v[80:81], off
	global_load_dwordx4 v[66:69], v[74:75], off
	global_load_dwordx4 v[70:73], v[84:85], off
	s_nop 0
	global_load_dwordx4 v[74:77], v[76:77], off
	s_nop 0
	global_load_dwordx4 v[78:81], v[78:79], off offset:512
	s_nop 0
	global_load_dwordx4 v[82:85], v[82:83], off offset:512
	s_nop 0
	global_load_dwordx4 v[86:89], v[8:9], off
	global_load_dwordx4 v[90:93], v[8:9], off offset:16
	global_load_dwordx4 v[94:97], v[12:13], off
	global_load_dwordx4 v[98:101], v[12:13], off offset:16
	global_load_dwordx4 v[102:105], v[10:11], off
	global_load_dwordx4 v[106:109], v[10:11], off offset:16
	s_waitcnt vmcnt(0) lgkmcnt(0)
	v_lshlrev_b32_e32 v39, 16, v0
	v_and_b32_e32 v47, 0xffff0000, v0
	v_lshlrev_b32_e32 v37, 16, v62
	v_lshlrev_b32_e32 v36, 16, v66
	v_lshlrev_b32_e32 v111, 16, v70
	v_and_b32_e32 v113, 0xffff0000, v62
	v_and_b32_e32 v112, 0xffff0000, v66
	v_and_b32_e32 v115, 0xffff0000, v70
	v_lshlrev_b32_e32 v124, 16, v1
	v_lshlrev_b32_e32 v117, 16, v63
	v_lshlrev_b32_e32 v116, 16, v67
	v_and_b32_e32 v125, 0xffff0000, v1
	v_and_b32_e32 v1, 0xffff0000, v63
	v_and_b32_e32 v0, 0xffff0000, v67
	v_lshlrev_b32_e32 v63, 16, v64
	v_and_b32_e32 v67, 0xffff0000, v64
	v_lshlrev_b32_e32 v126, 16, v2
	v_lshlrev_b32_e32 v62, 16, v68
	v_and_b32_e32 v66, 0xffff0000, v68
	v_lshlrev_b32_e32 v120, 16, v69
	v_and_b32_e32 v64, 0xffff0000, v69
	v_lshlrev_b32_e32 v69, 16, v72
	v_and_b32_e32 v127, 0xffff0000, v2
	v_lshlrev_b32_e32 v128, 16, v3
	v_and_b32_e32 v129, 0xffff0000, v3
	v_and_b32_e32 v3, 0xffff0000, v72
	v_lshlrev_b32_e32 v110, 16, v74
	v_and_b32_e32 v114, 0xffff0000, v74
	v_lshlrev_b32_e32 v118, 16, v75
	v_and_b32_e32 v70, 0xffff0000, v75
	v_lshlrev_b32_e32 v68, 16, v76
	v_and_b32_e32 v2, 0xffff0000, v76
	v_lshlrev_b32_e32 v122, 16, v77
	v_and_b32_e32 v72, 0xffff0000, v77
	v_lshlrev_b32_e32 v130, 16, v78
	v_and_b32_e32 v131, 0xffff0000, v78
	v_lshlrev_b32_e32 v132, 16, v79
	v_and_b32_e32 v133, 0xffff0000, v79
	v_lshlrev_b32_e32 v134, 16, v80
	v_and_b32_e32 v135, 0xffff0000, v80
	v_lshlrev_b32_e32 v136, 16, v81
	v_and_b32_e32 v137, 0xffff0000, v81
	v_lshlrev_b32_e32 v138, 16, v82
	v_and_b32_e32 v139, 0xffff0000, v82
	v_lshlrev_b32_e32 v140, 16, v83
	v_and_b32_e32 v141, 0xffff0000, v83
	v_lshlrev_b32_e32 v142, 16, v84
	v_and_b32_e32 v143, 0xffff0000, v84
	v_lshlrev_b32_e32 v144, 16, v85
	v_and_b32_e32 v146, 0xffff0000, v85
	v_pk_mul_f32 v[74:75], v[38:39], v[88:89] op_sel_hi:[0,1]
	v_pk_mul_f32 v[76:77], v[38:39], v[86:87] op_sel_hi:[0,1]
	v_pk_mul_f32 v[78:79], v[38:39], v[92:93] op_sel_hi:[0,1]
	v_pk_mul_f32 v[80:81], v[38:39], v[90:91] op_sel_hi:[0,1]
	v_pk_mul_f32 v[82:83], v[46:47], v[96:97] op_sel_hi:[0,1]
	v_pk_mul_f32 v[84:85], v[46:47], v[94:95] op_sel_hi:[0,1]
	v_pk_mul_f32 v[86:87], v[46:47], v[100:101] op_sel_hi:[0,1]
	v_pk_mul_f32 v[88:89], v[46:47], v[98:99] op_sel_hi:[0,1]
	v_lshlrev_b32_e32 v121, 16, v65
	v_mov_b32_e32 v90, v76
	v_mov_b32_e32 v91, v84
	v_mov_b32_e32 v84, v77
	v_mov_b32_e32 v76, v74
	v_mov_b32_e32 v77, v82
	v_mov_b32_e32 v82, v75
	v_mov_b32_e32 v74, v80
	v_mov_b32_e32 v75, v88
	v_mov_b32_e32 v88, v81
	v_mov_b32_e32 v80, v78
	v_mov_b32_e32 v81, v86
	v_and_b32_e32 v65, 0xffff0000, v65
	v_lshlrev_b32_e32 v123, 16, v73
	v_mov_b32_e32 v86, v79
; __global__ void __launch_bounds__(512, 2) mk_fwd(Args a) {
;     ...
;                   for (int j = 0; j < 2; ++j) { const int c = (lane + 64 * j) * 8;
;                       const u32x4 b = *(const u32x4*)(pr + 2304 + c);
;                       const u32x4 c0 = *(const u32x4*)(pl + 3328 + c), h0 = *(const u32x4*)(pl + 4352 + c);
;                       const u32x4 c1 = *(const u32x4*)(pr + 3328 + c), h1 = *(const u32x4*)(pr + 4352 + c);
;                       const u32x4 c2 = *(const u32x4*)(pq + 3328 + c), h2 = *(const u32x4*)(pq + 4352 + c);
;                       const f32x4 w0 = *(const f32x4*)(cw + c) * ml, w0b = *(const f32x4*)(cw + c + 4) * ml, w1 = *(const f32x4*)(cw + 1024 + c), w1b = *(const f32x4*)(cw + 1024 + c + 4);
;                       const f32x4 w2 = *(const f32x4*)(cw + 2048 + c) * mr, w2b = *(const f32x4*)(cw + 2048 + c + 4) * mr;
;                       u32x4 o;
;                       o.x = convpair(b.x, c0.x, h0.x, c1.x, h1.x, c2.x, h2.x, w0.x, w0.y, w1.x, w1.y, w2.x, w2.y);
;                       o.y = convpair(b.y, c0.y, h0.y, c1.y, h1.y, c2.y, h2.y, w0.z, w0.w, w1.z, w1.w, w2.z, w2.w);
;                       o.z = convpair(b.z, c0.z, h0.z, c1.z, h1.z, c2.z, h2.z, w0b.x, w0b.y, w1b.x, w1b.y, w2b.x, w2b.y);
;                       o.w = convpair(b.w, c0.w, h0.w, c1.w, h1.w, c2.w, h2.w, w0b.z, w0b.w, w1b.z, w1b.w, w2b.z, w2b.w);
;                       *(u32x4*)(CC + (size_t)r * 1024 + c) = o; } }
	v_pk_mul_f32 v[62:63], v[74:75], v[62:63]
	v_pk_mul_f32 v[66:67], v[88:89], v[66:67]
	v_pk_mul_f32 v[74:75], v[80:81], v[120:121]
	v_lshlrev_b32_e32 v119, 16, v71
	v_and_b32_e32 v71, 0xffff0000, v71
	v_and_b32_e32 v73, 0xffff0000, v73
	v_mul_f32_e32 v95, v107, v127
	v_mul_f32_e32 v96, v108, v128
	v_pk_mul_f32 v[36:37], v[90:91], v[36:37]
	v_pk_mul_f32 v[78:79], v[84:85], v[112:113]
	v_pk_mul_f32 v[76:77], v[76:77], v[116:117]
	v_pk_mul_f32 v[0:1], v[82:83], v[0:1]
	v_pk_mul_f32 v[64:65], v[86:87], v[64:65]
	v_pk_mul_f32 v[2:3], v[66:67], v[2:3]
	v_pk_mul_f32 v[66:67], v[74:75], v[122:123]
	v_mul_f32_e32 v39, v102, v39
	v_mul_f32_e32 v47, v103, v47
	v_mul_f32_e32 v92, v104, v124
	v_mul_f32_e32 v93, v105, v125
	v_mul_f32_e32 v94, v106, v126
	v_mul_f32_e32 v97, v109, v129
	v_pk_mul_f32 v[36:37], v[36:37], v[110:111]
	v_pk_mul_f32 v[78:79], v[78:79], v[114:115]
	v_pk_mul_f32 v[76:77], v[76:77], v[118:119]
	v_pk_mul_f32 v[0:1], v[0:1], v[70:71]
	v_pk_mul_f32 v[62:63], v[62:63], v[68:69]
	v_pk_mul_f32 v[64:65], v[64:65], v[72:73]
	v_fma_f32 v2, v95, v143, v2
	v_fma_f32 v66, v96, v144, v66
	v_fma_f32 v36, v39, v138, v36
	v_fma_f32 v39, v47, v139, v78
	v_fma_f32 v47, v92, v140, v76
	v_fma_f32 v0, v93, v141, v0
	v_fma_f32 v62, v94, v142, v62
	v_fma_f32 v64, v97, v146, v64
	v_add_f32_e32 v2, v2, v3
	v_add_f32_e32 v3, v66, v67
	v_add_f32_e32 v36, v36, v37
	v_add_f32_e32 v37, v39, v79
	v_add_f32_e32 v39, v47, v77
	v_add_f32_e32 v0, v0, v1
	v_add_f32_e32 v1, v62, v63
	v_add_f32_e32 v47, v64, v65
	v_mul_f32_e32 v2, v2, v135
	v_mul_f32_e32 v3, v3, v136
	v_mul_f32_e32 v36, v36, v130
	v_mul_f32_e32 v37, v37, v131
	v_mul_f32_e32 v39, v39, v132
	v_mul_f32_e32 v62, v0, v133
	v_mul_f32_e32 v63, v1, v134
	v_mul_f32_e32 v47, v47, v137
	v_cvt_pk_bf16_f32 v0, v36, v37
	v_cvt_pk_bf16_f32 v1, v39, v62
	v_cvt_pk_bf16_f32 v2, v63, v2
	v_cvt_pk_bf16_f32 v3, v3, v47
	global_store_dwordx4 v[40:41], v[0:3], off
	global_load_dwordx4 v[0:3], v[8:9], off offset:2048
	s_nop 0
	global_load_dwordx4 v[62:65], v[8:9], off offset:2064
	global_load_dwordx4 v[66:69], v[16:17], off
	global_load_dwordx4 v[70:73], v[16:17], off offset:16
	global_load_dwordx4 v[74:77], v[52:53], off
	global_load_dwordx4 v[78:81], v[48:49], off
	s_nop 0
	global_load_dwordx4 v[52:55], v[54:55], off
	s_nop 0
	global_load_dwordx4 v[48:51], v[50:51], off
	s_nop 0
	global_load_dwordx4 v[82:85], v[42:43], off offset:2560
	global_load_dwordx4 v[86:89], v[42:43], off offset:512
	s_nop 0
	global_load_dwordx4 v[42:45], v[44:45], off offset:512
	s_nop 0
	global_load_dwordx4 v[90:93], v[14:15], off
	global_load_dwordx4 v[94:97], v[14:15], off offset:16
	s_waitcnt vmcnt(0)
	v_pk_mul_f32 v[2:3], v[38:39], v[2:3] op_sel_hi:[0,1]
	v_pk_mul_f32 v[0:1], v[38:39], v[0:1] op_sel_hi:[0,1]
	v_pk_mul_f32 v[36:37], v[38:39], v[64:65] op_sel_hi:[0,1]
	v_pk_mul_f32 v[38:39], v[38:39], v[62:63] op_sel_hi:[0,1]
	v_pk_mul_f32 v[62:63], v[46:47], v[68:69] op_sel_hi:[0,1]
	v_pk_mul_f32 v[64:65], v[46:47], v[66:67] op_sel_hi:[0,1]
	v_pk_mul_f32 v[66:67], v[46:47], v[72:73] op_sel_hi:[0,1]
	v_pk_mul_f32 v[46:47], v[46:47], v[70:71] op_sel_hi:[0,1]
	s_waitcnt lgkmcnt(0)
; __global__ void __launch_bounds__(512, 2) mk_fwd(Args a) {
;     ...
;                   for (int j = 0; j < 2; ++j) { const int c = (lane + 64 * j) * 8;
;                       const u32x4 b = *(const u32x4*)(pr + 2304 + c);
;                       const u32x4 c0 = *(const u32x4*)(pl + 3328 + c), h0 = *(const u32x4*)(pl + 4352 + c);
;                       const u32x4 c1 = *(const u32x4*)(pr + 3328 + c), h1 = *(const u32x4*)(pr + 4352 + c);
;                       const u32x4 c2 = *(const u32x4*)(pq + 3328 + c), h2 = *(const u32x4*)(pq + 4352 + c);
;                       const f32x4 w0 = *(const f32x4*)(cw + c) * ml, w0b = *(const f32x4*)(cw + c + 4) * ml, w1 = *(const f32x4*)(cw + 1024 + c), w1b = *(const f32x4*)(cw + 1024 + c + 4);
;                       const f32x4 w2 = *(const f32x4*)(cw + 2048 + c) * mr, w2b = *(const f32x4*)(cw + 2048 + c + 4) * mr;
;                       u32x4 o;
;                       o.x = convpair(b.x, c0.x, h0.x, c1.x, h1.x, c2.x, h2.x, w0.x, w0.y, w1.x, w1.y, w2.x, w2.y);
;                       o.y = convpair(b.y, c0.y, h0.y, c1.y, h1.y, c2.y, h2.y, w0.z, w0.w, w1.z, w1.w, w2.z, w2.w);
;                       o.z = convpair(b.z, c0.z, h0.z, c1.z, h1.z, c2.z, h2.z, w0b.x, w0b.y, w1b.x, w1b.y, w2b.x, w2b.y);
;                       o.w = convpair(b.w, c0.w, h0.w, c1.w, h1.w, c2.w, h2.w, w0b.z, w0b.w, w1b.z, w1b.w, w2b.z, w2b.w);
;                       *(u32x4*)(CC + (size_t)r * 1024 + c) = o; } }
	v_lshlrev_b32_e32 v69, 16, v74
	v_and_b32_e32 v73, 0xffff0000, v74
	v_lshlrev_b32_e32 v101, 16, v75
	v_lshlrev_b32_e32 v100, 16, v79
	v_and_b32_e32 v75, 0xffff0000, v75
	v_lshlrev_b32_e32 v103, 16, v76
	v_and_b32_e32 v105, 0xffff0000, v76
	v_and_b32_e32 v74, 0xffff0000, v79
	v_lshlrev_b32_e32 v102, 16, v80
	v_and_b32_e32 v104, 0xffff0000, v80
	v_lshlrev_b32_e32 v116, 16, v42
	v_and_b32_e32 v117, 0xffff0000, v42
	v_lshlrev_b32_e32 v118, 16, v43
	v_and_b32_e32 v119, 0xffff0000, v43
	v_mov_b32_e32 v42, v0
	v_mov_b32_e32 v43, v64
	v_mov_b32_e32 v64, v1
	v_mov_b32_e32 v0, v2
	v_mov_b32_e32 v1, v62
	v_mov_b32_e32 v62, v3
	v_mov_b32_e32 v2, v38
	v_mov_b32_e32 v3, v46
	v_mov_b32_e32 v46, v39
	v_lshlrev_b32_e32 v68, 16, v78
	v_lshlrev_b32_e32 v71, 16, v52
	v_and_b32_e32 v72, 0xffff0000, v78
	v_and_b32_e32 v99, 0xffff0000, v52
	v_lshlrev_b32_e32 v107, 16, v77
	v_and_b32_e32 v77, 0xffff0000, v77
	v_lshlrev_b32_e32 v109, 16, v53
	v_lshlrev_b32_e32 v106, 16, v81
	v_and_b32_e32 v76, 0xffff0000, v81
	v_and_b32_e32 v53, 0xffff0000, v53
	v_lshlrev_b32_e32 v79, 16, v54
	v_and_b32_e32 v81, 0xffff0000, v54
	v_lshlrev_b32_e32 v70, 16, v48
	v_and_b32_e32 v98, 0xffff0000, v48
	v_lshlrev_b32_e32 v108, 16, v49
	v_and_b32_e32 v52, 0xffff0000, v49
	v_lshlrev_b32_e32 v78, 16, v50
	v_and_b32_e32 v80, 0xffff0000, v50
	v_lshlrev_b32_e32 v110, 16, v51
	v_and_b32_e32 v54, 0xffff0000, v51
	v_lshlrev_b32_e32 v48, 16, v82
	v_and_b32_e32 v49, 0xffff0000, v82
	v_lshlrev_b32_e32 v50, 16, v83
	v_and_b32_e32 v51, 0xffff0000, v83
	v_lshlrev_b32_e32 v82, 16, v84
	v_and_b32_e32 v83, 0xffff0000, v84
	v_lshlrev_b32_e32 v120, 16, v44
	v_and_b32_e32 v121, 0xffff0000, v44
	v_lshlrev_b32_e32 v122, 16, v45
	v_and_b32_e32 v123, 0xffff0000, v45
	v_mov_b32_e32 v38, v36
	v_mov_b32_e32 v39, v66
	v_mov_b32_e32 v66, v37
	v_pk_mul_f32 v[0:1], v[0:1], v[100:101]
	v_pk_mul_f32 v[44:45], v[62:63], v[74:75]
	v_pk_mul_f32 v[2:3], v[2:3], v[102:103]
	v_pk_mul_f32 v[46:47], v[46:47], v[104:105]
	v_lshlrev_b32_e32 v111, 16, v55
	v_and_b32_e32 v55, 0xffff0000, v55
	v_lshlrev_b32_e32 v84, 16, v85
	v_and_b32_e32 v85, 0xffff0000, v85
	v_mul_f32_e32 v90, v90, v48
	v_mul_f32_e32 v91, v91, v49
	v_mul_f32_e32 v50, v92, v50
	v_mul_f32_e32 v51, v93, v51
	v_mul_f32_e32 v82, v94, v82
	v_mul_f32_e32 v83, v95, v83
	v_pk_mul_f32 v[36:37], v[42:43], v[68:69]
	v_pk_mul_f32 v[42:43], v[64:65], v[72:73]
	v_pk_mul_f32 v[38:39], v[38:39], v[106:107]
	v_pk_mul_f32 v[48:49], v[66:67], v[76:77]
	v_pk_mul_f32 v[0:1], v[0:1], v[108:109]
	v_pk_mul_f32 v[44:45], v[44:45], v[52:53]
	v_pk_mul_f32 v[2:3], v[2:3], v[78:79]
	v_pk_mul_f32 v[46:47], v[46:47], v[80:81]
	v_mul_f32_e32 v84, v96, v84
	v_mul_f32_e32 v85, v97, v85
	v_pk_mul_f32 v[36:37], v[36:37], v[70:71]
	v_pk_mul_f32 v[42:43], v[42:43], v[98:99]
	v_pk_mul_f32 v[38:39], v[38:39], v[110:111]
	v_pk_mul_f32 v[48:49], v[48:49], v[54:55]
	v_fma_f32 v0, v50, v118, v0
	v_fma_f32 v44, v51, v119, v44
	v_fma_f32 v2, v82, v120, v2
	v_fma_f32 v46, v83, v121, v46
	v_lshlrev_b32_e32 v113, 16, v87
	v_and_b32_e32 v87, 0xffff0000, v87
	v_lshlrev_b32_e32 v114, 16, v88
	v_and_b32_e32 v88, 0xffff0000, v88
	v_fma_f32 v36, v90, v116, v36
	v_fma_f32 v42, v91, v117, v42
	v_fma_f32 v38, v84, v122, v38
	v_fma_f32 v48, v85, v123, v48
	v_add_f32_e32 v0, v0, v1
	v_add_f32_e32 v1, v44, v45
	v_add_f32_e32 v2, v2, v3
	v_add_f32_e32 v3, v46, v47
	v_lshlrev_b32_e32 v112, 16, v86
	v_and_b32_e32 v86, 0xffff0000, v86
	v_lshlrev_b32_e32 v115, 16, v89
	v_and_b32_e32 v89, 0xffff0000, v89
	v_add_f32_e32 v36, v36, v37
	v_add_f32_e32 v37, v42, v43
	v_add_f32_e32 v38, v38, v39
	v_add_f32_e32 v39, v48, v49
	v_mul_f32_e32 v1, v1, v87
	v_mul_f32_e32 v2, v2, v114
	v_mul_f32_e32 v3, v3, v88
	v_mul_f32_e32 v36, v36, v112
	v_mul_f32_e32 v37, v37, v86
	v_mul_f32_e32 v42, v0, v113
	v_mul_f32_e32 v38, v38, v115
	v_mul_f32_e32 v39, v39, v89
	v_cvt_pk_bf16_f32 v0, v36, v37
	v_cvt_pk_bf16_f32 v1, v42, v1
	v_cvt_pk_bf16_f32 v2, v2, v3
	v_cvt_pk_bf16_f32 v3, v38, v39
	global_store_dwordx4 v[40:41], v[0:3], off offset:1024
	s_cbranch_scc0 .LBB0_239

; __device__ __forceinline__ unsigned addpair(unsigned x, unsigned y, float sg) { return cvt_pk_bf16(bf_lo(x) + sg * bf_lo(y), bf_hi(x) + sg * bf_hi(y)); }
; __global__ void __launch_bounds__(512, 2) mk_fwd(Args a) {
;     ...
;             for (int lf = gw; lf < MH; lf += NGW) {
;                 const bool v = lf <= HF, pr2 = lf > 0 && lf < HF;
;                 const bf16_t* p1 = PA + (size_t)(v ? phys_of(lf) : 0) * NPA; const bf16_t* p2 = PA + (size_t)(pr2 ? phys_of(LSEQ - lf) : 0) * NPA;
; #pragma unroll
;                 for (int j = 0; j < 2; ++j) { const int c = (lane + 64 * j) * 8; u32x4 e = {0u, 0u, 0u, 0u}, o = {0u, 0u, 0u, 0u};
;                     if (v) { const u32x4 x = *(const u32x4*)(p1 + c); e = x;
;                         if (pr2) { const u32x4 y = *(const u32x4*)(p2 + c);
;                             e.x = addpair(x.x, y.x, 1.f); e.y = addpair(x.y, y.y, 1.f); e.z = addpair(x.z, y.z, 1.f); e.w = addpair(x.w, y.w, 1.f);
;                             o.x = addpair(x.x, y.x, -1.f); o.y = addpair(x.y, y.y, -1.f); o.z = addpair(x.z, y.z, -1.f); o.w = addpair(x.w, y.w, -1.f); } }
;                     *(u32x4*)(EO + (size_t)lf * 1024 + c) = e; *(u32x4*)(EO + (size_t)MH * 1024 + (size_t)lf * 1024 + c) = o; }
.LBB0_242:
	global_load_dwordx4 v[0:3], v[22:23], off offset:1024
	s_waitcnt vmcnt(0) lgkmcnt(0)
	v_lshlrev_b32_e32 v8, 16, v4
	v_and_b32_e32 v4, 0xffff0000, v4
	v_lshlrev_b32_e32 v9, 16, v5
	v_and_b32_e32 v5, 0xffff0000, v5
	v_lshlrev_b32_e32 v10, 16, v6
	v_and_b32_e32 v6, 0xffff0000, v6
	v_lshlrev_b32_e32 v11, 16, v7
	v_and_b32_e32 v7, 0xffff0000, v7
	v_lshlrev_b32_e32 v20, 16, v0
	v_and_b32_e32 v0, 0xffff0000, v0
	v_lshlrev_b32_e32 v21, 16, v1
	v_and_b32_e32 v1, 0xffff0000, v1
	v_lshlrev_b32_e32 v22, 16, v2
	v_and_b32_e32 v2, 0xffff0000, v2
	v_lshlrev_b32_e32 v23, 16, v3
	v_and_b32_e32 v3, 0xffff0000, v3
	v_add_f32_e32 v25, v0, v4
	v_add_f32_e32 v27, v1, v5
	v_add_f32_e32 v29, v2, v6
	v_add_f32_e32 v31, v3, v7
	v_sub_f32_e32 v0, v4, v0
	v_sub_f32_e32 v1, v5, v1
	v_sub_f32_e32 v2, v6, v2
	v_sub_f32_e32 v3, v7, v3
	v_add_f32_e32 v24, v20, v8
	v_add_f32_e32 v26, v21, v9
	v_add_f32_e32 v28, v22, v10
	v_add_f32_e32 v30, v23, v11
	v_sub_f32_e32 v8, v8, v20
	v_sub_f32_e32 v9, v9, v21
	v_sub_f32_e32 v10, v10, v22
	v_sub_f32_e32 v11, v11, v23
	v_cvt_pk_bf16_f32 v4, v24, v25
	v_cvt_pk_bf16_f32 v5, v26, v27
	v_cvt_pk_bf16_f32 v6, v28, v29
	v_cvt_pk_bf16_f32 v7, v30, v31
	v_cvt_pk_bf16_f32 v0, v8, v0
	v_cvt_pk_bf16_f32 v1, v9, v1
	v_cvt_pk_bf16_f32 v2, v10, v2
	v_cvt_pk_bf16_f32 v3, v11, v3
.LBB0_243:
	v_lshl_add_u64 v[8:9], s[0:1], 0, v[18:19]
	v_add_co_u32_e32 v10, vcc, 0x23dc1000, v8
	s_add_i32 s6, s6, s72
	s_nop 0
	v_addc_co_u32_e32 v11, vcc, 0, v9, vcc
	s_add_u32 s0, s0, s80
	s_mul_i32 s3, s16, 0xa800
	s_waitcnt vmcnt(0) lgkmcnt(0)
	global_store_dwordx4 v[10:11], v[4:7], off
	s_addc_u32 s1, s1, s81
	s_sub_i32 s2, s2, s3
	v_add_co_u32_e32 v4, vcc, 0x24641000, v8
	s_cmpk_gt_i32 s6, 0x10ff
	s_nop 0
	v_addc_co_u32_e32 v5, vcc, 0, v9, vcc
	global_store_dwordx4 v[4:5], v[0:3], off
	s_cbranch_scc1 .LBB0_257

; __device__ __forceinline__ unsigned addpair(unsigned x, unsigned y, float sg) { return cvt_pk_bf16(bf_lo(x) + sg * bf_lo(y), bf_hi(x) + sg * bf_hi(y)); }
; __global__ void __launch_bounds__(512, 2) mk_fwd(Args a) {
;     ...
;                 for (int j = 0; j < 2; ++j) { const int c = (lane + 64 * j) * 8; u32x4 e = {0u, 0u, 0u, 0u}, o = {0u, 0u, 0u, 0u};
;                     if (v) { const u32x4 x = *(const u32x4*)(p1 + c); e = x;
;                         if (pr2) { const u32x4 y = *(const u32x4*)(p2 + c);
;                             e.x = addpair(x.x, y.x, 1.f); e.y = addpair(x.y, y.y, 1.f); e.z = addpair(x.z, y.z, 1.f); e.w = addpair(x.w, y.w, 1.f);
;                             o.x = addpair(x.x, y.x, -1.f); o.y = addpair(x.y, y.y, -1.f); o.z = addpair(x.z, y.z, -1.f); o.w = addpair(x.w, y.w, -1.f); } }
;                     *(u32x4*)(EO + (size_t)lf * 1024 + c) = e; *(u32x4*)(EO + (size_t)MH * 1024 + (size_t)lf * 1024 + c) = o; }
.LBB0_248:
	s_mov_b64 s[40:41], -1
	s_and_b64 vcc, exec, s[14:15]
	v_lshl_add_u64 v[20:21], s[0:1], 0, v[14:15]
	s_cbranch_vccz .LBB0_250
	s_mov_b32 s13, s12
	v_add_co_u32_e32 v0, vcc, 0x23dc1000, v20
	s_mov_b32 s14, s12
	s_mov_b32 s15, s12
	s_waitcnt lgkmcnt(0)
	v_mov_b64_e32 v[2:3], s[12:13]
	v_addc_co_u32_e32 v1, vcc, 0, v21, vcc
	v_mov_b64_e32 v[4:5], s[14:15]
	global_store_dwordx4 v[0:1], v[2:5], off
	v_add_co_u32_e32 v0, vcc, 0x24641000, v20
	s_mov_b64 s[40:41], 0
	s_nop 0
	v_addc_co_u32_e32 v1, vcc, 0, v21, vcc
	global_store_dwordx4 v[0:1], v[2:5], off

; __device__ __forceinline__ unsigned addpair(unsigned x, unsigned y, float sg) { return cvt_pk_bf16(bf_lo(x) + sg * bf_lo(y), bf_hi(x) + sg * bf_hi(y)); }
; __global__ void __launch_bounds__(512, 2) mk_fwd(Args a) {
;     ...
;                 for (int j = 0; j < 2; ++j) { const int c = (lane + 64 * j) * 8; u32x4 e = {0u, 0u, 0u, 0u}, o = {0u, 0u, 0u, 0u};
;                     if (v) { const u32x4 x = *(const u32x4*)(p1 + c); e = x;
;                         if (pr2) { const u32x4 y = *(const u32x4*)(p2 + c);
;                             e.x = addpair(x.x, y.x, 1.f); e.y = addpair(x.y, y.y, 1.f); e.z = addpair(x.z, y.z, 1.f); e.w = addpair(x.w, y.w, 1.f);
;                             o.x = addpair(x.x, y.x, -1.f); o.y = addpair(x.y, y.y, -1.f); o.z = addpair(x.z, y.z, -1.f); o.w = addpair(x.w, y.w, -1.f); } }
;                     *(u32x4*)(EO + (size_t)lf * 1024 + c) = e; *(u32x4*)(EO + (size_t)MH * 1024 + (size_t)lf * 1024 + c) = o; }
.LBB0_253:
	v_mov_b32_e32 v3, 0
	s_andn2_b64 vcc, exec, s[34:35]
	v_lshl_add_u64 v[22:23], v[12:13], 1, s[14:15]
	v_mov_b32_e32 v8, 0
	v_mov_b32_e32 v9, 0
	v_mov_b32_e32 v10, 0
	v_mov_b32_e32 v11, 0
	s_cbranch_vccnz .LBB0_255
	global_load_dwordx4 v[8:11], v[22:23], off
	s_waitcnt vmcnt(0) lgkmcnt(0)
	v_lshlrev_b32_e32 v2, 16, v4
	v_and_b32_e32 v4, 0xffff0000, v4
	v_lshlrev_b32_e32 v24, 16, v5
	v_and_b32_e32 v5, 0xffff0000, v5
	v_lshlrev_b32_e32 v25, 16, v6
	v_and_b32_e32 v6, 0xffff0000, v6
	v_lshlrev_b32_e32 v26, 16, v7
	v_and_b32_e32 v7, 0xffff0000, v7
	v_lshlrev_b32_e32 v27, 16, v8
	v_and_b32_e32 v8, 0xffff0000, v8
	v_lshlrev_b32_e32 v28, 16, v9
	v_and_b32_e32 v9, 0xffff0000, v9
	v_lshlrev_b32_e32 v29, 16, v10
	v_and_b32_e32 v10, 0xffff0000, v10
	v_lshlrev_b32_e32 v30, 16, v11
	v_and_b32_e32 v11, 0xffff0000, v11
	v_add_f32_e32 v32, v8, v4
	v_add_f32_e32 v34, v9, v5
	v_add_f32_e32 v36, v10, v6
	v_add_f32_e32 v38, v11, v7
	v_sub_f32_e32 v8, v4, v8
	v_sub_f32_e32 v9, v5, v9
	v_sub_f32_e32 v10, v6, v10
	v_sub_f32_e32 v11, v7, v11
	v_add_f32_e32 v31, v27, v2
	v_add_f32_e32 v33, v28, v24
	v_add_f32_e32 v35, v29, v25
	v_add_f32_e32 v37, v30, v26
	v_sub_f32_e32 v2, v2, v27
	v_sub_f32_e32 v24, v24, v28
	v_sub_f32_e32 v25, v25, v29
	v_sub_f32_e32 v26, v26, v30
	v_cvt_pk_bf16_f32 v4, v31, v32
	v_cvt_pk_bf16_f32 v5, v33, v34
	v_cvt_pk_bf16_f32 v6, v35, v36
	v_cvt_pk_bf16_f32 v7, v37, v38
	v_cvt_pk_bf16_f32 v8, v2, v8
	v_cvt_pk_bf16_f32 v9, v24, v9
	v_cvt_pk_bf16_f32 v10, v25, v10
	v_cvt_pk_bf16_f32 v11, v26, v11
.LBB0_255:
	v_add_co_u32_e32 v24, vcc, 0x23dc1000, v20
	s_nop 1
	v_addc_co_u32_e32 v25, vcc, 0, v21, vcc
	s_waitcnt vmcnt(0) lgkmcnt(0)
	global_store_dwordx4 v[24:25], v[4:7], off
	s_nop 1
	v_add_co_u32_e32 v4, vcc, 0x24641000, v20
	s_nop 1
	v_addc_co_u32_e32 v5, vcc, 0, v21, vcc
	global_store_dwordx4 v[4:5], v[8:11], off
	flat_load_dwordx4 v[4:7], v[0:1] offset:1024
	s_and_b64 vcc, exec, s[8:9]
	s_cbranch_vccnz .LBB0_242
	v_mov_b32_e32 v2, 0
	v_mov_b32_e32 v1, 0
	v_mov_b32_e32 v0, 0
	s_branch .LBB0_243

; __device__ __forceinline__ void epi8(const Desc& d, int pb, int row, int col, f32x4 v0, f32x4 v1) {
;     ...
;         float* hp = (float*)d.o0 + (size_t)row * DM + col;
;         const float* rp = (row < LREAL ? (const float*)d.o2 + (size_t)row * DM : (const float*)d.gate + (size_t)(row - LREAL) * DM) + col;
;         v0 += *(const f32x4*)rp; v1 += *(const f32x4*)(rp + 4);
;         if (d.epi == EPI_RESID) { *(f32x4*)hp = v0; *(f32x4*)(hp + 4) = v1; }
;         else if (row < LREAL) { float* op = (float*)d.o1 + (size_t)row * DM + col; *(f32x4*)op = v0; *(f32x4*)(op + 4) = v1; }
.LBB0_317:
	s_cmp_lt_i32 s26, 2
	s_cbranch_scc1 .LBB0_332
	s_cmp_gt_i32 s26, 4
	s_cbranch_scc0 .LBB0_326
	v_lshl_add_u64 v[128:129], v[162:163], 2, s[86:87]
	v_lshl_add_u64 v[130:131], s[82:83], 0, v[164:165]
	v_ashrrev_i32_e32 v167, 31, v144
	v_mov_b32_e32 v166, v144
	v_cndmask_b32_e64 v129, v131, v129, s[0:1]
	v_cndmask_b32_e64 v128, v130, v128, s[0:1]
	v_lshl_add_u64 v[132:133], v[166:167], 2, v[128:129]
	global_load_dwordx4 v[128:131], v[132:133], off
	s_nop 0
	global_load_dwordx4 v[132:135], v[132:133], off offset:16
	s_and_b64 vcc, exec, s[64:65]
	s_waitcnt vmcnt(0) lgkmcnt(0)
	v_pk_add_f32 v[130:131], v[126:127], v[130:131]
	v_pk_add_f32 v[128:129], v[124:125], v[128:129]
	v_pk_add_f32 v[134:135], v[122:123], v[134:135]
	v_pk_add_f32 v[132:133], v[120:121], v[132:133]
	s_cbranch_vccz .LBB0_323
	s_and_saveexec_b64 s[74:75], s[0:1]
	s_cbranch_execz .LBB0_322
	v_lshl_add_u64 v[146:147], v[162:163], 2, s[84:85]
	v_lshl_add_u64 v[146:147], v[166:167], 2, v[146:147]
	global_store_dwordx4 v[146:147], v[128:131], off
	global_store_dwordx4 v[146:147], v[132:135], off offset:16

; __device__ __forceinline__ void epi8(const Desc& d, int pb, int row, int col, f32x4 v0, f32x4 v1) {
;     ...
;         float* hp = (float*)d.o0 + (size_t)row * DM + col;
;         const float* rp = (row < LREAL ? (const float*)d.o2 + (size_t)row * DM : (const float*)d.gate + (size_t)(row - LREAL) * DM) + col;
;         v0 += *(const f32x4*)rp; v1 += *(const f32x4*)(rp + 4);
;         if (d.epi == EPI_RESID) { *(f32x4*)hp = v0; *(f32x4*)(hp + 4) = v1; }
;         else if (row < LREAL) { float* op = (float*)d.o1 + (size_t)row * DM + col; *(f32x4*)op = v0; *(f32x4*)(op + 4) = v1; }
.LBB0_323:
	s_andn2_b64 vcc, exec, s[74:75]
	s_cbranch_vccnz .LBB0_325
	v_lshl_add_u64 v[146:147], v[162:163], 2, s[50:51]
	v_lshl_add_u64 v[146:147], v[166:167], 2, v[146:147]
	global_store_dwordx4 v[146:147], v[128:131], off
	global_store_dwordx4 v[146:147], v[132:135], off offset:16

; __device__ __forceinline__ float bf_lo(unsigned w) { return __uint_as_float(w << 16); }
; __device__ __forceinline__ float bf_hi(unsigned w) { return __uint_as_float(w & 0xffff0000u); }
; __device__ __forceinline__ float sigm(float x) { return __builtin_amdgcn_rcpf(1.f + __builtin_amdgcn_exp2f(-1.4426950408889634f * x)); }
; __device__ __forceinline__ f32x4 sigm4(unsigned lo, unsigned hi) { f32x4 r; r[0] = sigm(bf_lo(lo)); r[1] = sigm(bf_hi(lo)); r[2] = sigm(bf_lo(hi)); r[3] = sigm(bf_hi(hi)); return r; }
; __device__ __forceinline__ void epi8(const Desc& d, int pb, int row, int col, f32x4 v0, f32x4 v1) {
;     ...
;     } else if (d.epi == EPI_MERGE0 || d.epi == EPI_MERGE1 || d.epi == EPI_MERGE2) {
;         const u32x4 gw = *(const u32x4*)(d.gate + (size_t)row * NPG + col);
;         v0 *= sigm4(gw.x, gw.y); v1 *= sigm4(gw.z, gw.w);
;         bf16_t* mp = (bf16_t*)d.o0 + (size_t)row * DM + col;
.LBB0_326:
	s_andn2_b64 vcc, exec, s[74:75]
	s_cbranch_vccnz .LBB0_331
	v_ashrrev_i32_e32 v129, 31, v144
	v_mov_b32_e32 v128, v144
	v_lshl_add_u64 v[130:131], s[82:83], 0, v[160:161]
	v_lshlrev_b64 v[146:147], 1, v[128:129]
	v_lshl_add_u64 v[130:131], v[130:131], 0, v[146:147]
	global_load_dwordx4 v[130:133], v[130:131], off
	v_lshl_add_u64 v[148:149], v[162:163], 1, s[50:51]
	s_andn2_b64 vcc, exec, s[80:81]
	s_waitcnt vmcnt(0) lgkmcnt(0)
	v_lshlrev_b32_e32 v134, 16, v130
	v_and_b32_e32 v130, 0xffff0000, v130
	v_lshlrev_b32_e32 v135, 16, v131
	v_and_b32_e32 v131, 0xffff0000, v131
	v_lshlrev_b32_e32 v166, 16, v132
	v_and_b32_e32 v132, 0xffff0000, v132
	v_lshlrev_b32_e32 v167, 16, v133
	v_and_b32_e32 v133, 0xffff0000, v133
	v_mul_f32_e32 v134, 0xbfb8aa3b, v134
	v_mul_f32_e32 v130, 0xbfb8aa3b, v130
	v_mul_f32_e32 v135, 0xbfb8aa3b, v135
	v_mul_f32_e32 v131, 0xbfb8aa3b, v131
	v_mul_f32_e32 v166, 0xbfb8aa3b, v166
	v_mul_f32_e32 v132, 0xbfb8aa3b, v132
	v_mul_f32_e32 v167, 0xbfb8aa3b, v167
	v_mul_f32_e32 v133, 0xbfb8aa3b, v133
	v_exp_f32_e32 v134, v134
	v_exp_f32_e32 v130, v130
	v_exp_f32_e32 v135, v135
	v_exp_f32_e32 v131, v131
	v_exp_f32_e32 v166, v166
	v_exp_f32_e32 v132, v132
	v_exp_f32_e32 v167, v167
	v_exp_f32_e32 v133, v133
	v_add_f32_e32 v134, 1.0, v134
	v_add_f32_e32 v168, 1.0, v130
	v_add_f32_e32 v135, 1.0, v135
	v_add_f32_e32 v169, 1.0, v131
	v_add_f32_e32 v166, 1.0, v166
	v_add_f32_e32 v173, 1.0, v132
	v_add_f32_e32 v167, 1.0, v167
	v_add_f32_e32 v175, 1.0, v133
	v_rcp_f32_e32 v130, v134
	v_rcp_f32_e32 v131, v168
	v_rcp_f32_e32 v132, v135
	v_rcp_f32_e32 v133, v169
	v_rcp_f32_e32 v168, v166
	v_rcp_f32_e32 v174, v167
	v_rcp_f32_e32 v175, v175
	v_rcp_f32_e32 v169, v173
	v_pk_mul_f32 v[134:135], v[126:127], v[132:133]
	v_pk_mul_f32 v[166:167], v[124:125], v[130:131]
	v_pk_mul_f32 v[130:131], v[122:123], v[174:175]
	v_pk_mul_f32 v[132:133], v[120:121], v[168:169]
	v_lshl_add_u64 v[168:169], v[148:149], 0, v[146:147]
	s_cbranch_vccz .LBB0_781
	s_andn2_b64 vcc, exec, s[52:53]
	s_mov_b64 s[74:75], -1
	s_cbranch_vccz .LBB0_782

; __device__ __forceinline__ u32x4 pack8(f32x4 v0, f32x4 v1) { u32x4 w; w.x = cvt_pk_bf16(v0[0], v0[1]); w.y = cvt_pk_bf16(v0[2], v0[3]); w.z = cvt_pk_bf16(v1[0], v1[1]); w.w = cvt_pk_bf16(v1[2], v1[3]); return w; }
; __device__ __forceinline__ void epi8(const Desc& d, int pb, int row, int col, f32x4 v0, f32x4 v1) {
;     ...
;         if (d.epi != EPI_MERGE2) *(u32x4*)mp = pack8(v0, v1);
;         else *(u32x4*)((bf16_t*)d.o1 + (size_t)row * DM + col) = pack8(v0, v1);
.LBB0_330:
	v_cvt_pk_bf16_f32 v146, v166, v167
	v_cvt_pk_bf16_f32 v147, v134, v135
	v_cvt_pk_bf16_f32 v148, v132, v133
	v_cvt_pk_bf16_f32 v149, v130, v131
	v_lshl_add_u64 v[130:131], v[162:163], 1, s[84:85]
	v_lshl_add_u64 v[128:129], v[128:129], 1, v[130:131]
	global_store_dwordx4 v[128:129], v[146:149], off

; __device__ __forceinline__ u32x4 pack8(f32x4 v0, f32x4 v1) { u32x4 w; w.x = cvt_pk_bf16(v0[0], v0[1]); w.y = cvt_pk_bf16(v0[2], v0[3]); w.z = cvt_pk_bf16(v1[0], v1[1]); w.w = cvt_pk_bf16(v1[2], v1[3]); return w; }
; __device__ __forceinline__ void epi8(const Desc& d, int pb, int row, int col, f32x4 v0, f32x4 v1) {
;     ...
;     } else if (d.epi == EPI_BF16) {
;         *(u32x4*)((bf16_t*)d.o0 + (size_t)pb * d.sO + (size_t)row * d.ldc + col) = pack8(v0 * d.scale, v1 * d.scale);
.LBB0_332:
	s_andn2_b64 vcc, exec, s[74:75]
	s_cbranch_vccnz .LBB0_334
	s_mul_hi_i32 s43, s56, s93
	s_mul_i32 s42, s56, s93
	s_lshl_b64 s[42:43], s[42:43], 1
	s_add_u32 s42, s50, s42
	s_addc_u32 s43, s51, s43
	v_mad_i64_i32 v[132:133], s[74:75], s14, v158, 0
	v_lshl_add_u64 v[132:133], v[132:133], 1, s[42:43]
	v_ashrrev_i32_e32 v135, 31, v144
	v_mov_b32_e32 v134, v144
	v_lshl_add_u64 v[132:133], v[134:135], 1, v[132:133]
	v_cvt_pk_bf16_f32 v128, v124, v125
	v_cvt_pk_bf16_f32 v129, v126, v127
	v_cvt_pk_bf16_f32 v130, v120, v121
	v_cvt_pk_bf16_f32 v131, v122, v123
	global_store_dwordx4 v[132:133], v[128:131], off

; __device__ __forceinline__ u32x4 pack8(f32x4 v0, f32x4 v1) { u32x4 w; w.x = cvt_pk_bf16(v0[0], v0[1]); w.y = cvt_pk_bf16(v0[2], v0[3]); w.z = cvt_pk_bf16(v1[0], v1[1]); w.w = cvt_pk_bf16(v1[2], v1[3]); return w; }
; __device__ __forceinline__ void epi8(const Desc& d, int pb, int row, int col, f32x4 v0, f32x4 v1) {
;     if (d.epi == EPI_PIN) {
;         const int pn = col >> 8; bf16_t* p;
;         if (pn < 21) p = (bf16_t*)d.o0 + (size_t)row * NPA + col;
;         else if (pn == 21) p = (bf16_t*)d.o1 + (size_t)row * NKR + (col - 21 * 256);
;         else p = (bf16_t*)d.o2 + (size_t)row * NPG + (col - 22 * 256);
;         *(u32x4*)p = pack8(v0, v1);
;     ...
;         float* hp = (float*)d.o0 + (size_t)row * DM + col;
;         const float* rp = (row < LREAL ? (const float*)d.o2 + (size_t)row * DM : (const float*)d.gate + (size_t)(row - LREAL) * DM) + col;
;         v0 += *(const f32x4*)rp; v1 += *(const f32x4*)(rp + 4);
;         if (d.epi == EPI_RESID) { *(f32x4*)hp = v0; *(f32x4*)(hp + 4) = v1; }
;         else if (row < LREAL) { float* op = (float*)d.o1 + (size_t)row * DM + col; *(f32x4*)op = v0; *(f32x4*)(op + 4) = v1; }
.LBB0_343:
	v_cvt_pk_bf16_f32 v124, v124, v125
	v_cvt_pk_bf16_f32 v125, v126, v127
	v_cvt_pk_bf16_f32 v126, v120, v121
	v_cvt_pk_bf16_f32 v127, v122, v123
	global_store_dwordx4 v[132:133], v[124:127], off
	s_cmp_lt_i32 s26, 1
	s_mov_b64 s[74:75], -1
	s_cbranch_scc1 .LBB0_316
.LBB0_344:
	s_cmp_lt_i32 s26, 2
	s_cbranch_scc1 .LBB0_359
	s_cmp_gt_i32 s26, 4
	s_cbranch_scc0 .LBB0_353
	v_lshl_add_u64 v[120:121], v[162:163], 2, s[86:87]
	v_lshl_add_u64 v[122:123], s[82:83], 0, v[164:165]
	v_cndmask_b32_e64 v121, v123, v121, s[0:1]
	v_cndmask_b32_e64 v120, v122, v120, s[0:1]
	v_ashrrev_i32_e32 v133, 31, v144
	v_mov_b32_e32 v132, v144
	v_lshl_add_u64 v[124:125], v[132:133], 2, v[120:121]
	global_load_dwordx4 v[120:123], v[124:125], off offset:512
	s_nop 0
	global_load_dwordx4 v[124:127], v[124:125], off offset:528
	s_andn2_b64 vcc, exec, s[64:65]
	s_waitcnt vmcnt(0) lgkmcnt(0)
	v_pk_add_f32 v[122:123], v[118:119], v[122:123]
	v_pk_add_f32 v[120:121], v[116:117], v[120:121]
	v_pk_add_f32 v[126:127], v[114:115], v[126:127]
	v_pk_add_f32 v[124:125], v[112:113], v[124:125]
	s_cbranch_vccnz .LBB0_350
	s_and_saveexec_b64 s[74:75], s[0:1]
	s_cbranch_execz .LBB0_349
	v_lshl_add_u64 v[134:135], v[162:163], 2, s[84:85]
	v_lshl_add_u64 v[134:135], v[132:133], 2, v[134:135]
	global_store_dwordx4 v[134:135], v[120:123], off offset:512
	global_store_dwordx4 v[134:135], v[124:127], off offset:528

; __device__ __forceinline__ void epi8(const Desc& d, int pb, int row, int col, f32x4 v0, f32x4 v1) {
;     ...
;         float* hp = (float*)d.o0 + (size_t)row * DM + col;
;         const float* rp = (row < LREAL ? (const float*)d.o2 + (size_t)row * DM : (const float*)d.gate + (size_t)(row - LREAL) * DM) + col;
;         v0 += *(const f32x4*)rp; v1 += *(const f32x4*)(rp + 4);
;         if (d.epi == EPI_RESID) { *(f32x4*)hp = v0; *(f32x4*)(hp + 4) = v1; }
;         else if (row < LREAL) { float* op = (float*)d.o1 + (size_t)row * DM + col; *(f32x4*)op = v0; *(f32x4*)(op + 4) = v1; }
.LBB0_350:
	s_andn2_b64 vcc, exec, s[74:75]
	s_cbranch_vccnz .LBB0_352
	v_lshl_add_u64 v[134:135], v[162:163], 2, s[50:51]
	v_lshl_add_u64 v[132:133], v[132:133], 2, v[134:135]
	global_store_dwordx4 v[132:133], v[120:123], off offset:512
	global_store_dwordx4 v[132:133], v[124:127], off offset:528

; __device__ __forceinline__ float bf_lo(unsigned w) { return __uint_as_float(w << 16); }
; __device__ __forceinline__ float bf_hi(unsigned w) { return __uint_as_float(w & 0xffff0000u); }
; __device__ __forceinline__ float sigm(float x) { return __builtin_amdgcn_rcpf(1.f + __builtin_amdgcn_exp2f(-1.4426950408889634f * x)); }
; __device__ __forceinline__ f32x4 sigm4(unsigned lo, unsigned hi) { f32x4 r; r[0] = sigm(bf_lo(lo)); r[1] = sigm(bf_hi(lo)); r[2] = sigm(bf_lo(hi)); r[3] = sigm(bf_hi(hi)); return r; }
; __device__ __forceinline__ void epi8(const Desc& d, int pb, int row, int col, f32x4 v0, f32x4 v1) {
;     ...
;     } else if (d.epi == EPI_MERGE0 || d.epi == EPI_MERGE1 || d.epi == EPI_MERGE2) {
;         const u32x4 gw = *(const u32x4*)(d.gate + (size_t)row * NPG + col);
;         v0 *= sigm4(gw.x, gw.y); v1 *= sigm4(gw.z, gw.w);
;         bf16_t* mp = (bf16_t*)d.o0 + (size_t)row * DM + col;
.LBB0_353:
	s_andn2_b64 vcc, exec, s[74:75]
	s_cbranch_vccnz .LBB0_358
	v_ashrrev_i32_e32 v121, 31, v144
	v_mov_b32_e32 v120, v144
	v_lshl_add_u64 v[122:123], s[82:83], 0, v[160:161]
	v_lshlrev_b64 v[134:135], 1, v[120:121]
	v_lshl_add_u64 v[122:123], v[122:123], 0, v[134:135]
	global_load_dwordx4 v[122:125], v[122:123], off offset:256
	v_lshl_add_u64 v[146:147], v[162:163], 1, s[50:51]
	s_andn2_b64 vcc, exec, s[80:81]
	v_lshl_add_u64 v[134:135], v[146:147], 0, v[134:135]
	s_waitcnt vmcnt(0) lgkmcnt(0)
	v_lshlrev_b32_e32 v126, 16, v122
	v_and_b32_e32 v122, 0xffff0000, v122
	v_lshlrev_b32_e32 v127, 16, v123
	v_and_b32_e32 v123, 0xffff0000, v123
	v_lshlrev_b32_e32 v132, 16, v124
	v_and_b32_e32 v124, 0xffff0000, v124
	v_lshlrev_b32_e32 v133, 16, v125
	v_and_b32_e32 v125, 0xffff0000, v125
	v_mul_f32_e32 v126, 0xbfb8aa3b, v126
	v_mul_f32_e32 v122, 0xbfb8aa3b, v122
	v_mul_f32_e32 v127, 0xbfb8aa3b, v127
	v_mul_f32_e32 v123, 0xbfb8aa3b, v123
	v_mul_f32_e32 v132, 0xbfb8aa3b, v132
	v_mul_f32_e32 v124, 0xbfb8aa3b, v124
	v_mul_f32_e32 v133, 0xbfb8aa3b, v133
	v_mul_f32_e32 v125, 0xbfb8aa3b, v125
	v_exp_f32_e32 v126, v126
	v_exp_f32_e32 v122, v122
	v_exp_f32_e32 v127, v127
	v_exp_f32_e32 v123, v123
	v_exp_f32_e32 v132, v132
	v_exp_f32_e32 v124, v124
	v_exp_f32_e32 v133, v133
	v_exp_f32_e32 v125, v125
	v_add_f32_e32 v126, 1.0, v126
	v_add_f32_e32 v148, 1.0, v122
	v_add_f32_e32 v127, 1.0, v127
	v_add_f32_e32 v149, 1.0, v123
	v_add_f32_e32 v132, 1.0, v132
	v_add_f32_e32 v159, 1.0, v124
	v_add_f32_e32 v133, 1.0, v133
	v_add_f32_e32 v165, 1.0, v125
	v_rcp_f32_e32 v122, v126
	v_rcp_f32_e32 v123, v148
	v_rcp_f32_e32 v124, v127
	v_rcp_f32_e32 v125, v149
	v_rcp_f32_e32 v148, v132
	v_rcp_f32_e32 v164, v133
	v_rcp_f32_e32 v165, v165
	v_rcp_f32_e32 v149, v159
	v_pk_mul_f32 v[126:127], v[118:119], v[124:125]
	v_pk_mul_f32 v[132:133], v[116:117], v[122:123]
	v_pk_mul_f32 v[122:123], v[114:115], v[164:165]
	v_pk_mul_f32 v[124:125], v[112:113], v[148:149]
	s_cbranch_vccz .LBB0_783
	s_andn2_b64 vcc, exec, s[52:53]
	s_mov_b64 s[0:1], -1
	s_cbranch_vccz .LBB0_784

; __device__ __forceinline__ u32x4 pack8(f32x4 v0, f32x4 v1) { u32x4 w; w.x = cvt_pk_bf16(v0[0], v0[1]); w.y = cvt_pk_bf16(v0[2], v0[3]); w.z = cvt_pk_bf16(v1[0], v1[1]); w.w = cvt_pk_bf16(v1[2], v1[3]); return w; }
; __device__ __forceinline__ void epi8(const Desc& d, int pb, int row, int col, f32x4 v0, f32x4 v1) {
;     ...
;         if (d.epi != EPI_MERGE2) *(u32x4*)mp = pack8(v0, v1);
;         else *(u32x4*)((bf16_t*)d.o1 + (size_t)row * DM + col) = pack8(v0, v1);
.LBB0_357:
	v_cvt_pk_bf16_f32 v132, v132, v133
	v_cvt_pk_bf16_f32 v133, v126, v127
	v_cvt_pk_bf16_f32 v134, v124, v125
	v_cvt_pk_bf16_f32 v135, v122, v123
	v_lshl_add_u64 v[122:123], v[162:163], 1, s[84:85]
	v_lshl_add_u64 v[120:121], v[120:121], 1, v[122:123]
	global_store_dwordx4 v[120:121], v[132:135], off offset:256

; __device__ __forceinline__ u32x4 pack8(f32x4 v0, f32x4 v1) { u32x4 w; w.x = cvt_pk_bf16(v0[0], v0[1]); w.y = cvt_pk_bf16(v0[2], v0[3]); w.z = cvt_pk_bf16(v1[0], v1[1]); w.w = cvt_pk_bf16(v1[2], v1[3]); return w; }
; __device__ __forceinline__ void epi8(const Desc& d, int pb, int row, int col, f32x4 v0, f32x4 v1) {
;     ...
;     } else if (d.epi == EPI_BF16) {
;         *(u32x4*)((bf16_t*)d.o0 + (size_t)pb * d.sO + (size_t)row * d.ldc + col) = pack8(v0 * d.scale, v1 * d.scale);
.LBB0_359:
	s_andn2_b64 vcc, exec, s[74:75]
	s_cbranch_vccnz .LBB0_361
	s_mul_hi_i32 s1, s56, s93
	s_mul_i32 s0, s56, s93
	s_lshl_b64 s[0:1], s[0:1], 1
	s_add_u32 s0, s50, s0
	s_addc_u32 s1, s51, s1
	v_mad_i64_i32 v[124:125], s[42:43], s14, v158, 0
	v_lshl_add_u64 v[124:125], v[124:125], 1, s[0:1]
	v_ashrrev_i32_e32 v127, 31, v144
	v_mov_b32_e32 v126, v144
	v_lshl_add_u64 v[124:125], v[126:127], 1, v[124:125]
	v_cvt_pk_bf16_f32 v120, v116, v117
	v_cvt_pk_bf16_f32 v121, v118, v119
	v_cvt_pk_bf16_f32 v122, v112, v113
	v_cvt_pk_bf16_f32 v123, v114, v115
	global_store_dwordx4 v[124:125], v[120:123], off offset:256

; __device__ __forceinline__ u32x4 pack8(f32x4 v0, f32x4 v1) { u32x4 w; w.x = cvt_pk_bf16(v0[0], v0[1]); w.y = cvt_pk_bf16(v0[2], v0[3]); w.z = cvt_pk_bf16(v1[0], v1[1]); w.w = cvt_pk_bf16(v1[2], v1[3]); return w; }
; __device__ __forceinline__ void epi8(const Desc& d, int pb, int row, int col, f32x4 v0, f32x4 v1) {
;     if (d.epi == EPI_PIN) {
;         const int pn = col >> 8; bf16_t* p;
;         if (pn < 21) p = (bf16_t*)d.o0 + (size_t)row * NPA + col;
;         else if (pn == 21) p = (bf16_t*)d.o1 + (size_t)row * NKR + (col - 21 * 256);
;         else p = (bf16_t*)d.o2 + (size_t)row * NPG + (col - 22 * 256);
;         *(u32x4*)p = pack8(v0, v1);
.LBB0_370:
	v_cvt_pk_bf16_f32 v116, v116, v117
	v_cvt_pk_bf16_f32 v117, v118, v119
	v_cvt_pk_bf16_f32 v118, v112, v113
	v_cvt_pk_bf16_f32 v119, v114, v115
	global_store_dwordx4 v[120:121], v[116:119], off

; __device__ __forceinline__ void epi8(const Desc& d, int pb, int row, int col, f32x4 v0, f32x4 v1) {
;     ...
;         float* hp = (float*)d.o0 + (size_t)row * DM + col;
;         const float* rp = (row < LREAL ? (const float*)d.o2 + (size_t)row * DM : (const float*)d.gate + (size_t)(row - LREAL) * DM) + col;
;         v0 += *(const f32x4*)rp; v1 += *(const f32x4*)(rp + 4);
;         if (d.epi == EPI_RESID) { *(f32x4*)hp = v0; *(f32x4*)(hp + 4) = v1; }
;         else if (row < LREAL) { float* op = (float*)d.o1 + (size_t)row * DM + col; *(f32x4*)op = v0; *(f32x4*)(op + 4) = v1; }
.LBB0_375:
	s_cmp_lt_i32 s26, 2
	s_cbranch_scc1 .LBB0_390
	s_cmp_gt_i32 s26, 4
	s_cbranch_scc0 .LBB0_384
	v_lshl_add_u64 v[112:113], v[124:125], 2, s[86:87]
	v_lshl_add_u64 v[114:115], s[82:83], 0, v[126:127]
	v_ashrrev_i32_e32 v129, 31, v144
	v_mov_b32_e32 v128, v144
	v_cndmask_b32_e64 v113, v115, v113, s[0:1]
	v_cndmask_b32_e64 v112, v114, v112, s[0:1]
	v_lshl_add_u64 v[116:117], v[128:129], 2, v[112:113]
	global_load_dwordx4 v[112:115], v[116:117], off
	s_nop 0
	global_load_dwordx4 v[116:119], v[116:117], off offset:16
	s_andn2_b64 vcc, exec, s[64:65]
	s_waitcnt vmcnt(0) lgkmcnt(0)
	v_pk_add_f32 v[114:115], v[110:111], v[114:115]
	v_pk_add_f32 v[112:113], v[108:109], v[112:113]
	v_pk_add_f32 v[118:119], v[106:107], v[118:119]
	v_pk_add_f32 v[116:117], v[104:105], v[116:117]
	s_cbranch_vccnz .LBB0_381
	s_and_saveexec_b64 s[74:75], s[0:1]
	s_cbranch_execz .LBB0_380
	v_lshl_add_u64 v[130:131], v[124:125], 2, s[84:85]
	v_lshl_add_u64 v[130:131], v[128:129], 2, v[130:131]
	global_store_dwordx4 v[130:131], v[112:115], off
	global_store_dwordx4 v[130:131], v[116:119], off offset:16

; __device__ __forceinline__ void epi8(const Desc& d, int pb, int row, int col, f32x4 v0, f32x4 v1) {
;     ...
;         float* hp = (float*)d.o0 + (size_t)row * DM + col;
;         const float* rp = (row < LREAL ? (const float*)d.o2 + (size_t)row * DM : (const float*)d.gate + (size_t)(row - LREAL) * DM) + col;
;         v0 += *(const f32x4*)rp; v1 += *(const f32x4*)(rp + 4);
;         if (d.epi == EPI_RESID) { *(f32x4*)hp = v0; *(f32x4*)(hp + 4) = v1; }
;         else if (row < LREAL) { float* op = (float*)d.o1 + (size_t)row * DM + col; *(f32x4*)op = v0; *(f32x4*)(op + 4) = v1; }
.LBB0_381:
	s_andn2_b64 vcc, exec, s[74:75]
	s_cbranch_vccnz .LBB0_383
	v_lshl_add_u64 v[130:131], v[124:125], 2, s[50:51]
	v_lshl_add_u64 v[128:129], v[128:129], 2, v[130:131]
	global_store_dwordx4 v[128:129], v[112:115], off
	global_store_dwordx4 v[128:129], v[116:119], off offset:16

; __device__ __forceinline__ float bf_lo(unsigned w) { return __uint_as_float(w << 16); }
; __device__ __forceinline__ float bf_hi(unsigned w) { return __uint_as_float(w & 0xffff0000u); }
; __device__ __forceinline__ float sigm(float x) { return __builtin_amdgcn_rcpf(1.f + __builtin_amdgcn_exp2f(-1.4426950408889634f * x)); }
; __device__ __forceinline__ f32x4 sigm4(unsigned lo, unsigned hi) { f32x4 r; r[0] = sigm(bf_lo(lo)); r[1] = sigm(bf_hi(lo)); r[2] = sigm(bf_lo(hi)); r[3] = sigm(bf_hi(hi)); return r; }
; __device__ __forceinline__ void epi8(const Desc& d, int pb, int row, int col, f32x4 v0, f32x4 v1) {
;     ...
;     } else if (d.epi == EPI_MERGE0 || d.epi == EPI_MERGE1 || d.epi == EPI_MERGE2) {
;         const u32x4 gw = *(const u32x4*)(d.gate + (size_t)row * NPG + col);
;         v0 *= sigm4(gw.x, gw.y); v1 *= sigm4(gw.z, gw.w);
;         bf16_t* mp = (bf16_t*)d.o0 + (size_t)row * DM + col;
.LBB0_384:
	s_andn2_b64 vcc, exec, s[74:75]
	s_cbranch_vccnz .LBB0_389
	v_ashrrev_i32_e32 v113, 31, v144
	v_mov_b32_e32 v112, v144
	v_lshl_add_u64 v[114:115], s[82:83], 0, v[120:121]
	v_lshlrev_b64 v[130:131], 1, v[112:113]
	v_lshl_add_u64 v[114:115], v[114:115], 0, v[130:131]
	global_load_dwordx4 v[114:117], v[114:115], off
	v_lshl_add_u64 v[132:133], v[124:125], 1, s[50:51]
	s_andn2_b64 vcc, exec, s[80:81]
	v_lshl_add_u64 v[130:131], v[132:133], 0, v[130:131]
	s_waitcnt vmcnt(0) lgkmcnt(0)
	v_lshlrev_b32_e32 v118, 16, v114
	v_and_b32_e32 v114, 0xffff0000, v114
	v_lshlrev_b32_e32 v119, 16, v115
	v_and_b32_e32 v115, 0xffff0000, v115
	v_lshlrev_b32_e32 v128, 16, v116
	v_and_b32_e32 v116, 0xffff0000, v116
	v_lshlrev_b32_e32 v129, 16, v117
	v_and_b32_e32 v117, 0xffff0000, v117
	v_mul_f32_e32 v118, 0xbfb8aa3b, v118
	v_mul_f32_e32 v114, 0xbfb8aa3b, v114
	v_mul_f32_e32 v119, 0xbfb8aa3b, v119
	v_mul_f32_e32 v115, 0xbfb8aa3b, v115
	v_mul_f32_e32 v128, 0xbfb8aa3b, v128
	v_mul_f32_e32 v116, 0xbfb8aa3b, v116
	v_mul_f32_e32 v129, 0xbfb8aa3b, v129
	v_mul_f32_e32 v117, 0xbfb8aa3b, v117
	v_exp_f32_e32 v118, v118
	v_exp_f32_e32 v114, v114
	v_exp_f32_e32 v119, v119
	v_exp_f32_e32 v115, v115
	v_exp_f32_e32 v128, v128
	v_exp_f32_e32 v116, v116
	v_exp_f32_e32 v129, v129
	v_exp_f32_e32 v117, v117
	v_add_f32_e32 v118, 1.0, v118
	v_add_f32_e32 v134, 1.0, v114
	v_add_f32_e32 v119, 1.0, v119
	v_add_f32_e32 v135, 1.0, v115
	v_add_f32_e32 v128, 1.0, v128
	v_add_f32_e32 v148, 1.0, v116
	v_add_f32_e32 v129, 1.0, v129
	v_add_f32_e32 v147, 1.0, v117
	v_rcp_f32_e32 v114, v118
	v_rcp_f32_e32 v115, v134
	v_rcp_f32_e32 v116, v119
	v_rcp_f32_e32 v117, v135
	v_rcp_f32_e32 v134, v128
	v_rcp_f32_e32 v146, v129
	v_rcp_f32_e32 v147, v147
	v_rcp_f32_e32 v135, v148
	v_pk_mul_f32 v[118:119], v[110:111], v[116:117]
	v_pk_mul_f32 v[128:129], v[108:109], v[114:115]
	v_pk_mul_f32 v[114:115], v[106:107], v[146:147]
	v_pk_mul_f32 v[116:117], v[104:105], v[134:135]
	s_cbranch_vccz .LBB0_785
	s_andn2_b64 vcc, exec, s[52:53]
	s_mov_b64 s[74:75], -1
	s_cbranch_vccz .LBB0_786

; __device__ __forceinline__ u32x4 pack8(f32x4 v0, f32x4 v1) { u32x4 w; w.x = cvt_pk_bf16(v0[0], v0[1]); w.y = cvt_pk_bf16(v0[2], v0[3]); w.z = cvt_pk_bf16(v1[0], v1[1]); w.w = cvt_pk_bf16(v1[2], v1[3]); return w; }
; __device__ __forceinline__ void epi8(const Desc& d, int pb, int row, int col, f32x4 v0, f32x4 v1) {
;     ...
;         if (d.epi != EPI_MERGE2) *(u32x4*)mp = pack8(v0, v1);
;         else *(u32x4*)((bf16_t*)d.o1 + (size_t)row * DM + col) = pack8(v0, v1);
.LBB0_388:
	v_cvt_pk_bf16_f32 v128, v128, v129
	v_cvt_pk_bf16_f32 v129, v118, v119
	v_cvt_pk_bf16_f32 v130, v116, v117
	v_cvt_pk_bf16_f32 v131, v114, v115
	v_lshl_add_u64 v[114:115], v[124:125], 1, s[84:85]
	v_lshl_add_u64 v[112:113], v[112:113], 1, v[114:115]
	global_store_dwordx4 v[112:113], v[128:131], off

; __device__ __forceinline__ u32x4 pack8(f32x4 v0, f32x4 v1) { u32x4 w; w.x = cvt_pk_bf16(v0[0], v0[1]); w.y = cvt_pk_bf16(v0[2], v0[3]); w.z = cvt_pk_bf16(v1[0], v1[1]); w.w = cvt_pk_bf16(v1[2], v1[3]); return w; }
; __device__ __forceinline__ void epi8(const Desc& d, int pb, int row, int col, f32x4 v0, f32x4 v1) {
;     ...
;     } else if (d.epi == EPI_BF16) {
;         *(u32x4*)((bf16_t*)d.o0 + (size_t)pb * d.sO + (size_t)row * d.ldc + col) = pack8(v0 * d.scale, v1 * d.scale);
.LBB0_390:
	s_andn2_b64 vcc, exec, s[74:75]
	s_cbranch_vccnz .LBB0_392
	s_mul_hi_i32 s43, s56, s93
	s_mul_i32 s42, s56, s93
	s_lshl_b64 s[42:43], s[42:43], 1
	s_add_u32 s42, s50, s42
	s_addc_u32 s43, s51, s43
	v_mad_i64_i32 v[116:117], s[74:75], s14, v122, 0
	v_lshl_add_u64 v[116:117], v[116:117], 1, s[42:43]
	v_ashrrev_i32_e32 v119, 31, v144
	v_mov_b32_e32 v118, v144
	v_lshl_add_u64 v[116:117], v[118:119], 1, v[116:117]
	v_cvt_pk_bf16_f32 v112, v108, v109
	v_cvt_pk_bf16_f32 v113, v110, v111
	v_cvt_pk_bf16_f32 v114, v104, v105
	v_cvt_pk_bf16_f32 v115, v106, v107
	global_store_dwordx4 v[116:117], v[112:115], off

; __device__ __forceinline__ u32x4 pack8(f32x4 v0, f32x4 v1) { u32x4 w; w.x = cvt_pk_bf16(v0[0], v0[1]); w.y = cvt_pk_bf16(v0[2], v0[3]); w.z = cvt_pk_bf16(v1[0], v1[1]); w.w = cvt_pk_bf16(v1[2], v1[3]); return w; }
; __device__ __forceinline__ void epi8(const Desc& d, int pb, int row, int col, f32x4 v0, f32x4 v1) {
;     if (d.epi == EPI_PIN) {
;         const int pn = col >> 8; bf16_t* p;
;         if (pn < 21) p = (bf16_t*)d.o0 + (size_t)row * NPA + col;
;         else if (pn == 21) p = (bf16_t*)d.o1 + (size_t)row * NKR + (col - 21 * 256);
;         else p = (bf16_t*)d.o2 + (size_t)row * NPG + (col - 22 * 256);
;         *(u32x4*)p = pack8(v0, v1);
;     ...
;         float* hp = (float*)d.o0 + (size_t)row * DM + col;
;         const float* rp = (row < LREAL ? (const float*)d.o2 + (size_t)row * DM : (const float*)d.gate + (size_t)(row - LREAL) * DM) + col;
;         v0 += *(const f32x4*)rp; v1 += *(const f32x4*)(rp + 4);
;         if (d.epi == EPI_RESID) { *(f32x4*)hp = v0; *(f32x4*)(hp + 4) = v1; }
;         else if (row < LREAL) { float* op = (float*)d.o1 + (size_t)row * DM + col; *(f32x4*)op = v0; *(f32x4*)(op + 4) = v1; }
.LBB0_401:
	v_cvt_pk_bf16_f32 v108, v108, v109
	v_cvt_pk_bf16_f32 v109, v110, v111
	v_cvt_pk_bf16_f32 v110, v104, v105
	v_cvt_pk_bf16_f32 v111, v106, v107
	global_store_dwordx4 v[116:117], v[108:111], off
	s_cmp_lt_i32 s26, 1
	s_mov_b64 s[74:75], -1
	s_cbranch_scc1 .LBB0_374
.LBB0_402:
	s_cmp_lt_i32 s26, 2
	s_cbranch_scc1 .LBB0_417
	s_cmp_gt_i32 s26, 4
	s_cbranch_scc0 .LBB0_411
	v_lshl_add_u64 v[104:105], v[124:125], 2, s[86:87]
	v_lshl_add_u64 v[106:107], s[82:83], 0, v[126:127]
	v_cndmask_b32_e64 v105, v107, v105, s[0:1]
	v_cndmask_b32_e64 v104, v106, v104, s[0:1]
	v_ashrrev_i32_e32 v117, 31, v144
	v_mov_b32_e32 v116, v144
	v_lshl_add_u64 v[108:109], v[116:117], 2, v[104:105]
	global_load_dwordx4 v[104:107], v[108:109], off offset:512
	s_nop 0
	global_load_dwordx4 v[108:111], v[108:109], off offset:528
	s_andn2_b64 vcc, exec, s[64:65]
	s_waitcnt vmcnt(0) lgkmcnt(0)
	v_pk_add_f32 v[106:107], v[102:103], v[106:107]
	v_pk_add_f32 v[104:105], v[100:101], v[104:105]
	v_pk_add_f32 v[110:111], v[98:99], v[110:111]
	v_pk_add_f32 v[108:109], v[96:97], v[108:109]
	s_cbranch_vccnz .LBB0_408
	s_and_saveexec_b64 s[74:75], s[0:1]
	s_cbranch_execz .LBB0_407
	v_lshl_add_u64 v[118:119], v[124:125], 2, s[84:85]
	v_lshl_add_u64 v[118:119], v[116:117], 2, v[118:119]
	global_store_dwordx4 v[118:119], v[104:107], off offset:512
	global_store_dwordx4 v[118:119], v[108:111], off offset:528

; __device__ __forceinline__ void epi8(const Desc& d, int pb, int row, int col, f32x4 v0, f32x4 v1) {
;     ...
;         float* hp = (float*)d.o0 + (size_t)row * DM + col;
;         const float* rp = (row < LREAL ? (const float*)d.o2 + (size_t)row * DM : (const float*)d.gate + (size_t)(row - LREAL) * DM) + col;
;         v0 += *(const f32x4*)rp; v1 += *(const f32x4*)(rp + 4);
;         if (d.epi == EPI_RESID) { *(f32x4*)hp = v0; *(f32x4*)(hp + 4) = v1; }
;         else if (row < LREAL) { float* op = (float*)d.o1 + (size_t)row * DM + col; *(f32x4*)op = v0; *(f32x4*)(op + 4) = v1; }
.LBB0_408:
	s_andn2_b64 vcc, exec, s[74:75]
	s_cbranch_vccnz .LBB0_410
	v_lshl_add_u64 v[118:119], v[124:125], 2, s[50:51]
	v_lshl_add_u64 v[116:117], v[116:117], 2, v[118:119]
	global_store_dwordx4 v[116:117], v[104:107], off offset:512
	global_store_dwordx4 v[116:117], v[108:111], off offset:528

; __device__ __forceinline__ float bf_lo(unsigned w) { return __uint_as_float(w << 16); }
; __device__ __forceinline__ float bf_hi(unsigned w) { return __uint_as_float(w & 0xffff0000u); }
; __device__ __forceinline__ float sigm(float x) { return __builtin_amdgcn_rcpf(1.f + __builtin_amdgcn_exp2f(-1.4426950408889634f * x)); }
; __device__ __forceinline__ f32x4 sigm4(unsigned lo, unsigned hi) { f32x4 r; r[0] = sigm(bf_lo(lo)); r[1] = sigm(bf_hi(lo)); r[2] = sigm(bf_lo(hi)); r[3] = sigm(bf_hi(hi)); return r; }
; __device__ __forceinline__ void epi8(const Desc& d, int pb, int row, int col, f32x4 v0, f32x4 v1) {
;     ...
;     } else if (d.epi == EPI_MERGE0 || d.epi == EPI_MERGE1 || d.epi == EPI_MERGE2) {
;         const u32x4 gw = *(const u32x4*)(d.gate + (size_t)row * NPG + col);
;         v0 *= sigm4(gw.x, gw.y); v1 *= sigm4(gw.z, gw.w);
;         bf16_t* mp = (bf16_t*)d.o0 + (size_t)row * DM + col;
.LBB0_411:
	s_andn2_b64 vcc, exec, s[74:75]
	s_cbranch_vccnz .LBB0_416
	v_ashrrev_i32_e32 v105, 31, v144
	v_mov_b32_e32 v104, v144
	v_lshl_add_u64 v[106:107], s[82:83], 0, v[120:121]
	v_lshlrev_b64 v[118:119], 1, v[104:105]
	v_lshl_add_u64 v[106:107], v[106:107], 0, v[118:119]
	global_load_dwordx4 v[106:109], v[106:107], off offset:256
	v_lshl_add_u64 v[126:127], v[124:125], 1, s[50:51]
	s_andn2_b64 vcc, exec, s[80:81]
	v_lshl_add_u64 v[118:119], v[126:127], 0, v[118:119]
	s_waitcnt vmcnt(0) lgkmcnt(0)
	v_lshlrev_b32_e32 v110, 16, v106
	v_and_b32_e32 v106, 0xffff0000, v106
	v_lshlrev_b32_e32 v111, 16, v107
	v_and_b32_e32 v107, 0xffff0000, v107
	v_lshlrev_b32_e32 v116, 16, v108
	v_and_b32_e32 v108, 0xffff0000, v108
	v_lshlrev_b32_e32 v117, 16, v109
	v_and_b32_e32 v109, 0xffff0000, v109
	v_mul_f32_e32 v110, 0xbfb8aa3b, v110
	v_mul_f32_e32 v106, 0xbfb8aa3b, v106
	v_mul_f32_e32 v111, 0xbfb8aa3b, v111
	v_mul_f32_e32 v107, 0xbfb8aa3b, v107
	v_mul_f32_e32 v116, 0xbfb8aa3b, v116
	v_mul_f32_e32 v108, 0xbfb8aa3b, v108
	v_mul_f32_e32 v117, 0xbfb8aa3b, v117
	v_mul_f32_e32 v109, 0xbfb8aa3b, v109
	v_exp_f32_e32 v110, v110
	v_exp_f32_e32 v106, v106
	v_exp_f32_e32 v111, v111
	v_exp_f32_e32 v107, v107
	v_exp_f32_e32 v116, v116
	v_exp_f32_e32 v108, v108
	v_exp_f32_e32 v117, v117
	v_exp_f32_e32 v109, v109
	v_add_f32_e32 v110, 1.0, v110
	v_add_f32_e32 v123, 1.0, v106
	v_add_f32_e32 v111, 1.0, v111
	v_add_f32_e32 v128, 1.0, v107
	v_add_f32_e32 v116, 1.0, v116
	v_add_f32_e32 v129, 1.0, v108
	v_add_f32_e32 v117, 1.0, v117
	v_add_f32_e32 v131, 1.0, v109
	v_rcp_f32_e32 v106, v110
	v_rcp_f32_e32 v107, v123
	v_rcp_f32_e32 v108, v111
	v_rcp_f32_e32 v109, v128
	v_rcp_f32_e32 v128, v116
	v_rcp_f32_e32 v130, v117
	v_rcp_f32_e32 v131, v131
	v_rcp_f32_e32 v129, v129
	v_pk_mul_f32 v[110:111], v[102:103], v[108:109]
	v_pk_mul_f32 v[116:117], v[100:101], v[106:107]
	v_pk_mul_f32 v[106:107], v[98:99], v[130:131]
	v_pk_mul_f32 v[108:109], v[96:97], v[128:129]
	s_cbranch_vccz .LBB0_787
	s_andn2_b64 vcc, exec, s[52:53]
	s_mov_b64 s[0:1], -1
	s_cbranch_vccz .LBB0_788

; __device__ __forceinline__ u32x4 pack8(f32x4 v0, f32x4 v1) { u32x4 w; w.x = cvt_pk_bf16(v0[0], v0[1]); w.y = cvt_pk_bf16(v0[2], v0[3]); w.z = cvt_pk_bf16(v1[0], v1[1]); w.w = cvt_pk_bf16(v1[2], v1[3]); return w; }
; __device__ __forceinline__ void epi8(const Desc& d, int pb, int row, int col, f32x4 v0, f32x4 v1) {
;     ...
;         if (d.epi != EPI_MERGE2) *(u32x4*)mp = pack8(v0, v1);
;         else *(u32x4*)((bf16_t*)d.o1 + (size_t)row * DM + col) = pack8(v0, v1);
.LBB0_415:
	v_cvt_pk_bf16_f32 v116, v116, v117
	v_cvt_pk_bf16_f32 v117, v110, v111
	v_cvt_pk_bf16_f32 v118, v108, v109
	v_cvt_pk_bf16_f32 v119, v106, v107
	v_lshl_add_u64 v[106:107], v[124:125], 1, s[84:85]
	v_lshl_add_u64 v[104:105], v[104:105], 1, v[106:107]
	global_store_dwordx4 v[104:105], v[116:119], off offset:256

; __device__ __forceinline__ u32x4 pack8(f32x4 v0, f32x4 v1) { u32x4 w; w.x = cvt_pk_bf16(v0[0], v0[1]); w.y = cvt_pk_bf16(v0[2], v0[3]); w.z = cvt_pk_bf16(v1[0], v1[1]); w.w = cvt_pk_bf16(v1[2], v1[3]); return w; }
; __device__ __forceinline__ void epi8(const Desc& d, int pb, int row, int col, f32x4 v0, f32x4 v1) {
;     ...
;     } else if (d.epi == EPI_BF16) {
;         *(u32x4*)((bf16_t*)d.o0 + (size_t)pb * d.sO + (size_t)row * d.ldc + col) = pack8(v0 * d.scale, v1 * d.scale);
.LBB0_417:
	s_andn2_b64 vcc, exec, s[74:75]
	s_cbranch_vccnz .LBB0_419
	s_mul_hi_i32 s1, s56, s93
	s_mul_i32 s0, s56, s93
	s_lshl_b64 s[0:1], s[0:1], 1
	s_add_u32 s0, s50, s0
	s_addc_u32 s1, s51, s1
	v_mad_i64_i32 v[108:109], s[42:43], s14, v122, 0
	v_lshl_add_u64 v[108:109], v[108:109], 1, s[0:1]
	v_ashrrev_i32_e32 v111, 31, v144
	v_mov_b32_e32 v110, v144
	v_lshl_add_u64 v[108:109], v[110:111], 1, v[108:109]
	v_cvt_pk_bf16_f32 v104, v100, v101
	v_cvt_pk_bf16_f32 v105, v102, v103
	v_cvt_pk_bf16_f32 v106, v96, v97
	v_cvt_pk_bf16_f32 v107, v98, v99
	global_store_dwordx4 v[108:109], v[104:107], off offset:256

; __device__ __forceinline__ u32x4 pack8(f32x4 v0, f32x4 v1) { u32x4 w; w.x = cvt_pk_bf16(v0[0], v0[1]); w.y = cvt_pk_bf16(v0[2], v0[3]); w.z = cvt_pk_bf16(v1[0], v1[1]); w.w = cvt_pk_bf16(v1[2], v1[3]); return w; }
; __device__ __forceinline__ void epi8(const Desc& d, int pb, int row, int col, f32x4 v0, f32x4 v1) {
;     if (d.epi == EPI_PIN) {
;         const int pn = col >> 8; bf16_t* p;
;         if (pn < 21) p = (bf16_t*)d.o0 + (size_t)row * NPA + col;
;         else if (pn == 21) p = (bf16_t*)d.o1 + (size_t)row * NKR + (col - 21 * 256);
;         else p = (bf16_t*)d.o2 + (size_t)row * NPG + (col - 22 * 256);
;         *(u32x4*)p = pack8(v0, v1);
.LBB0_428:
	v_cvt_pk_bf16_f32 v100, v100, v101
	v_cvt_pk_bf16_f32 v101, v102, v103
	v_cvt_pk_bf16_f32 v102, v96, v97
	v_cvt_pk_bf16_f32 v103, v98, v99
	global_store_dwordx4 v[104:105], v[100:103], off

; __device__ __forceinline__ void epi8(const Desc& d, int pb, int row, int col, f32x4 v0, f32x4 v1) {
;     ...
;         float* hp = (float*)d.o0 + (size_t)row * DM + col;
;         const float* rp = (row < LREAL ? (const float*)d.o2 + (size_t)row * DM : (const float*)d.gate + (size_t)(row - LREAL) * DM) + col;
;         v0 += *(const f32x4*)rp; v1 += *(const f32x4*)(rp + 4);
;         if (d.epi == EPI_RESID) { *(f32x4*)hp = v0; *(f32x4*)(hp + 4) = v1; }
;         else if (row < LREAL) { float* op = (float*)d.o1 + (size_t)row * DM + col; *(f32x4*)op = v0; *(f32x4*)(op + 4) = v1; }
.LBB0_433:
	s_cmp_lt_i32 s26, 2
	s_cbranch_scc1 .LBB0_448
	s_cmp_gt_i32 s26, 4
	s_cbranch_scc0 .LBB0_442
	v_lshl_add_u64 v[96:97], v[108:109], 2, s[86:87]
	v_lshl_add_u64 v[98:99], s[82:83], 0, v[110:111]
	v_ashrrev_i32_e32 v113, 31, v144
	v_mov_b32_e32 v112, v144
	v_cndmask_b32_e64 v97, v99, v97, s[0:1]
	v_cndmask_b32_e64 v96, v98, v96, s[0:1]
	v_lshl_add_u64 v[100:101], v[112:113], 2, v[96:97]
	global_load_dwordx4 v[96:99], v[100:101], off
	s_nop 0
	global_load_dwordx4 v[100:103], v[100:101], off offset:16
	s_andn2_b64 vcc, exec, s[64:65]
	s_waitcnt vmcnt(0) lgkmcnt(0)
	v_pk_add_f32 v[98:99], v[94:95], v[98:99]
	v_pk_add_f32 v[96:97], v[92:93], v[96:97]
	v_pk_add_f32 v[102:103], v[90:91], v[102:103]
	v_pk_add_f32 v[100:101], v[88:89], v[100:101]
	s_cbranch_vccnz .LBB0_439
	s_and_saveexec_b64 s[74:75], s[0:1]
	s_cbranch_execz .LBB0_438
	v_lshl_add_u64 v[114:115], v[108:109], 2, s[84:85]
	v_lshl_add_u64 v[114:115], v[112:113], 2, v[114:115]
	global_store_dwordx4 v[114:115], v[96:99], off
	global_store_dwordx4 v[114:115], v[100:103], off offset:16

; __device__ __forceinline__ void epi8(const Desc& d, int pb, int row, int col, f32x4 v0, f32x4 v1) {
;     ...
;         float* hp = (float*)d.o0 + (size_t)row * DM + col;
;         const float* rp = (row < LREAL ? (const float*)d.o2 + (size_t)row * DM : (const float*)d.gate + (size_t)(row - LREAL) * DM) + col;
;         v0 += *(const f32x4*)rp; v1 += *(const f32x4*)(rp + 4);
;         if (d.epi == EPI_RESID) { *(f32x4*)hp = v0; *(f32x4*)(hp + 4) = v1; }
;         else if (row < LREAL) { float* op = (float*)d.o1 + (size_t)row * DM + col; *(f32x4*)op = v0; *(f32x4*)(op + 4) = v1; }
.LBB0_439:
	s_andn2_b64 vcc, exec, s[74:75]
	s_cbranch_vccnz .LBB0_441
	v_lshl_add_u64 v[114:115], v[108:109], 2, s[50:51]
	v_lshl_add_u64 v[112:113], v[112:113], 2, v[114:115]
	global_store_dwordx4 v[112:113], v[96:99], off
	global_store_dwordx4 v[112:113], v[100:103], off offset:16

; __device__ __forceinline__ float bf_lo(unsigned w) { return __uint_as_float(w << 16); }
; __device__ __forceinline__ float bf_hi(unsigned w) { return __uint_as_float(w & 0xffff0000u); }
; __device__ __forceinline__ float sigm(float x) { return __builtin_amdgcn_rcpf(1.f + __builtin_amdgcn_exp2f(-1.4426950408889634f * x)); }
; __device__ __forceinline__ f32x4 sigm4(unsigned lo, unsigned hi) { f32x4 r; r[0] = sigm(bf_lo(lo)); r[1] = sigm(bf_hi(lo)); r[2] = sigm(bf_lo(hi)); r[3] = sigm(bf_hi(hi)); return r; }
; __device__ __forceinline__ void epi8(const Desc& d, int pb, int row, int col, f32x4 v0, f32x4 v1) {
;     ...
;     } else if (d.epi == EPI_MERGE0 || d.epi == EPI_MERGE1 || d.epi == EPI_MERGE2) {
;         const u32x4 gw = *(const u32x4*)(d.gate + (size_t)row * NPG + col);
;         v0 *= sigm4(gw.x, gw.y); v1 *= sigm4(gw.z, gw.w);
;         bf16_t* mp = (bf16_t*)d.o0 + (size_t)row * DM + col;
.LBB0_442:
	s_andn2_b64 vcc, exec, s[74:75]
	s_cbranch_vccnz .LBB0_447
	v_ashrrev_i32_e32 v97, 31, v144
	v_mov_b32_e32 v96, v144
	v_lshl_add_u64 v[98:99], s[82:83], 0, v[104:105]
	v_lshlrev_b64 v[114:115], 1, v[96:97]
	v_lshl_add_u64 v[98:99], v[98:99], 0, v[114:115]
	global_load_dwordx4 v[98:101], v[98:99], off
	v_lshl_add_u64 v[116:117], v[108:109], 1, s[50:51]
	s_andn2_b64 vcc, exec, s[80:81]
	v_lshl_add_u64 v[114:115], v[116:117], 0, v[114:115]
	s_waitcnt vmcnt(0) lgkmcnt(0)
	v_lshlrev_b32_e32 v102, 16, v98
	v_and_b32_e32 v98, 0xffff0000, v98
	v_lshlrev_b32_e32 v103, 16, v99
	v_and_b32_e32 v99, 0xffff0000, v99
	v_lshlrev_b32_e32 v112, 16, v100
	v_and_b32_e32 v100, 0xffff0000, v100
	v_lshlrev_b32_e32 v113, 16, v101
	v_and_b32_e32 v101, 0xffff0000, v101
	v_mul_f32_e32 v102, 0xbfb8aa3b, v102
	v_mul_f32_e32 v98, 0xbfb8aa3b, v98
	v_mul_f32_e32 v103, 0xbfb8aa3b, v103
	v_mul_f32_e32 v99, 0xbfb8aa3b, v99
	v_mul_f32_e32 v112, 0xbfb8aa3b, v112
	v_mul_f32_e32 v100, 0xbfb8aa3b, v100
	v_mul_f32_e32 v113, 0xbfb8aa3b, v113
	v_mul_f32_e32 v101, 0xbfb8aa3b, v101
	v_exp_f32_e32 v102, v102
	v_exp_f32_e32 v98, v98
	v_exp_f32_e32 v103, v103
	v_exp_f32_e32 v99, v99
	v_exp_f32_e32 v112, v112
	v_exp_f32_e32 v100, v100
	v_exp_f32_e32 v113, v113
	v_exp_f32_e32 v101, v101
	v_add_f32_e32 v102, 1.0, v102
	v_add_f32_e32 v118, 1.0, v98
	v_add_f32_e32 v103, 1.0, v103
	v_add_f32_e32 v119, 1.0, v99
	v_add_f32_e32 v112, 1.0, v112
	v_add_f32_e32 v122, 1.0, v100
	v_add_f32_e32 v113, 1.0, v113
	v_add_f32_e32 v121, 1.0, v101
	v_rcp_f32_e32 v98, v102
	v_rcp_f32_e32 v99, v118
	v_rcp_f32_e32 v100, v103
	v_rcp_f32_e32 v101, v119
	v_rcp_f32_e32 v118, v112
	v_rcp_f32_e32 v120, v113
	v_rcp_f32_e32 v121, v121
	v_rcp_f32_e32 v119, v122
	v_pk_mul_f32 v[102:103], v[94:95], v[100:101]
	v_pk_mul_f32 v[112:113], v[92:93], v[98:99]
	v_pk_mul_f32 v[98:99], v[90:91], v[120:121]
	v_pk_mul_f32 v[100:101], v[88:89], v[118:119]
	s_cbranch_vccz .LBB0_789
	s_andn2_b64 vcc, exec, s[52:53]
	s_mov_b64 s[74:75], -1
	s_cbranch_vccz .LBB0_790

; __device__ __forceinline__ u32x4 pack8(f32x4 v0, f32x4 v1) { u32x4 w; w.x = cvt_pk_bf16(v0[0], v0[1]); w.y = cvt_pk_bf16(v0[2], v0[3]); w.z = cvt_pk_bf16(v1[0], v1[1]); w.w = cvt_pk_bf16(v1[2], v1[3]); return w; }
; __device__ __forceinline__ void epi8(const Desc& d, int pb, int row, int col, f32x4 v0, f32x4 v1) {
;     ...
;         if (d.epi != EPI_MERGE2) *(u32x4*)mp = pack8(v0, v1);
;         else *(u32x4*)((bf16_t*)d.o1 + (size_t)row * DM + col) = pack8(v0, v1);
.LBB0_446:
	v_cvt_pk_bf16_f32 v112, v112, v113
	v_cvt_pk_bf16_f32 v113, v102, v103
	v_cvt_pk_bf16_f32 v114, v100, v101
	v_cvt_pk_bf16_f32 v115, v98, v99
	v_lshl_add_u64 v[98:99], v[108:109], 1, s[84:85]
	v_lshl_add_u64 v[96:97], v[96:97], 1, v[98:99]
	global_store_dwordx4 v[96:97], v[112:115], off

; __device__ __forceinline__ u32x4 pack8(f32x4 v0, f32x4 v1) { u32x4 w; w.x = cvt_pk_bf16(v0[0], v0[1]); w.y = cvt_pk_bf16(v0[2], v0[3]); w.z = cvt_pk_bf16(v1[0], v1[1]); w.w = cvt_pk_bf16(v1[2], v1[3]); return w; }
; __device__ __forceinline__ void epi8(const Desc& d, int pb, int row, int col, f32x4 v0, f32x4 v1) {
;     ...
;     } else if (d.epi == EPI_BF16) {
;         *(u32x4*)((bf16_t*)d.o0 + (size_t)pb * d.sO + (size_t)row * d.ldc + col) = pack8(v0 * d.scale, v1 * d.scale);
.LBB0_448:
	s_andn2_b64 vcc, exec, s[74:75]
	s_cbranch_vccnz .LBB0_450
	s_mul_hi_i32 s43, s56, s93
	s_mul_i32 s42, s56, s93
	s_lshl_b64 s[42:43], s[42:43], 1
	s_add_u32 s42, s50, s42
	s_addc_u32 s43, s51, s43
	v_mad_i64_i32 v[100:101], s[74:75], s14, v106, 0
	v_lshl_add_u64 v[100:101], v[100:101], 1, s[42:43]
	v_ashrrev_i32_e32 v103, 31, v144
	v_mov_b32_e32 v102, v144
	v_lshl_add_u64 v[100:101], v[102:103], 1, v[100:101]
	v_cvt_pk_bf16_f32 v96, v92, v93
	v_cvt_pk_bf16_f32 v97, v94, v95
	v_cvt_pk_bf16_f32 v98, v88, v89
	v_cvt_pk_bf16_f32 v99, v90, v91
	global_store_dwordx4 v[100:101], v[96:99], off

; __device__ __forceinline__ u32x4 pack8(f32x4 v0, f32x4 v1) { u32x4 w; w.x = cvt_pk_bf16(v0[0], v0[1]); w.y = cvt_pk_bf16(v0[2], v0[3]); w.z = cvt_pk_bf16(v1[0], v1[1]); w.w = cvt_pk_bf16(v1[2], v1[3]); return w; }
; __device__ __forceinline__ void epi8(const Desc& d, int pb, int row, int col, f32x4 v0, f32x4 v1) {
;     if (d.epi == EPI_PIN) {
;         const int pn = col >> 8; bf16_t* p;
;         if (pn < 21) p = (bf16_t*)d.o0 + (size_t)row * NPA + col;
;         else if (pn == 21) p = (bf16_t*)d.o1 + (size_t)row * NKR + (col - 21 * 256);
;         else p = (bf16_t*)d.o2 + (size_t)row * NPG + (col - 22 * 256);
;         *(u32x4*)p = pack8(v0, v1);
;     ...
;         float* hp = (float*)d.o0 + (size_t)row * DM + col;
;         const float* rp = (row < LREAL ? (const float*)d.o2 + (size_t)row * DM : (const float*)d.gate + (size_t)(row - LREAL) * DM) + col;
;         v0 += *(const f32x4*)rp; v1 += *(const f32x4*)(rp + 4);
;         if (d.epi == EPI_RESID) { *(f32x4*)hp = v0; *(f32x4*)(hp + 4) = v1; }
;         else if (row < LREAL) { float* op = (float*)d.o1 + (size_t)row * DM + col; *(f32x4*)op = v0; *(f32x4*)(op + 4) = v1; }
.LBB0_459:
	v_cvt_pk_bf16_f32 v92, v92, v93
	v_cvt_pk_bf16_f32 v93, v94, v95
	v_cvt_pk_bf16_f32 v94, v88, v89
	v_cvt_pk_bf16_f32 v95, v90, v91
	global_store_dwordx4 v[100:101], v[92:95], off
	s_cmp_lt_i32 s26, 1
	s_mov_b64 s[74:75], -1
	s_cbranch_scc1 .LBB0_432
.LBB0_460:
	s_cmp_lt_i32 s26, 2
	s_cbranch_scc1 .LBB0_475
	s_cmp_gt_i32 s26, 4
	s_cbranch_scc0 .LBB0_469
	v_lshl_add_u64 v[88:89], v[108:109], 2, s[86:87]
	v_lshl_add_u64 v[90:91], s[82:83], 0, v[110:111]
	v_cndmask_b32_e64 v89, v91, v89, s[0:1]
	v_cndmask_b32_e64 v88, v90, v88, s[0:1]
	v_ashrrev_i32_e32 v101, 31, v144
	v_mov_b32_e32 v100, v144
	v_lshl_add_u64 v[92:93], v[100:101], 2, v[88:89]
	global_load_dwordx4 v[88:91], v[92:93], off offset:512
	s_nop 0
	global_load_dwordx4 v[92:95], v[92:93], off offset:528
	s_andn2_b64 vcc, exec, s[64:65]
	s_waitcnt vmcnt(0) lgkmcnt(0)
	v_pk_add_f32 v[90:91], v[86:87], v[90:91]
	v_pk_add_f32 v[88:89], v[84:85], v[88:89]
	v_pk_add_f32 v[94:95], v[82:83], v[94:95]
	v_pk_add_f32 v[92:93], v[80:81], v[92:93]
	s_cbranch_vccnz .LBB0_466
	s_and_saveexec_b64 s[74:75], s[0:1]
	s_cbranch_execz .LBB0_465
	v_lshl_add_u64 v[102:103], v[108:109], 2, s[84:85]
	v_lshl_add_u64 v[102:103], v[100:101], 2, v[102:103]
	global_store_dwordx4 v[102:103], v[88:91], off offset:512
	global_store_dwordx4 v[102:103], v[92:95], off offset:528

; __device__ __forceinline__ void epi8(const Desc& d, int pb, int row, int col, f32x4 v0, f32x4 v1) {
;     ...
;         float* hp = (float*)d.o0 + (size_t)row * DM + col;
;         const float* rp = (row < LREAL ? (const float*)d.o2 + (size_t)row * DM : (const float*)d.gate + (size_t)(row - LREAL) * DM) + col;
;         v0 += *(const f32x4*)rp; v1 += *(const f32x4*)(rp + 4);
;         if (d.epi == EPI_RESID) { *(f32x4*)hp = v0; *(f32x4*)(hp + 4) = v1; }
;         else if (row < LREAL) { float* op = (float*)d.o1 + (size_t)row * DM + col; *(f32x4*)op = v0; *(f32x4*)(op + 4) = v1; }
.LBB0_466:
	s_andn2_b64 vcc, exec, s[74:75]
	s_cbranch_vccnz .LBB0_468
	v_lshl_add_u64 v[102:103], v[108:109], 2, s[50:51]
	v_lshl_add_u64 v[100:101], v[100:101], 2, v[102:103]
	global_store_dwordx4 v[100:101], v[88:91], off offset:512
	global_store_dwordx4 v[100:101], v[92:95], off offset:528

; __device__ __forceinline__ float bf_lo(unsigned w) { return __uint_as_float(w << 16); }
; __device__ __forceinline__ float bf_hi(unsigned w) { return __uint_as_float(w & 0xffff0000u); }
; __device__ __forceinline__ float sigm(float x) { return __builtin_amdgcn_rcpf(1.f + __builtin_amdgcn_exp2f(-1.4426950408889634f * x)); }
; __device__ __forceinline__ f32x4 sigm4(unsigned lo, unsigned hi) { f32x4 r; r[0] = sigm(bf_lo(lo)); r[1] = sigm(bf_hi(lo)); r[2] = sigm(bf_lo(hi)); r[3] = sigm(bf_hi(hi)); return r; }
; __device__ __forceinline__ void epi8(const Desc& d, int pb, int row, int col, f32x4 v0, f32x4 v1) {
;     ...
;     } else if (d.epi == EPI_MERGE0 || d.epi == EPI_MERGE1 || d.epi == EPI_MERGE2) {
;         const u32x4 gw = *(const u32x4*)(d.gate + (size_t)row * NPG + col);
;         v0 *= sigm4(gw.x, gw.y); v1 *= sigm4(gw.z, gw.w);
;         bf16_t* mp = (bf16_t*)d.o0 + (size_t)row * DM + col;
.LBB0_469:
	s_andn2_b64 vcc, exec, s[74:75]
	s_cbranch_vccnz .LBB0_474
	v_ashrrev_i32_e32 v89, 31, v144
	v_mov_b32_e32 v88, v144
	v_lshl_add_u64 v[90:91], s[82:83], 0, v[104:105]
	v_lshlrev_b64 v[102:103], 1, v[88:89]
	v_lshl_add_u64 v[90:91], v[90:91], 0, v[102:103]
	global_load_dwordx4 v[90:93], v[90:91], off offset:256
	v_lshl_add_u64 v[110:111], v[108:109], 1, s[50:51]
	s_andn2_b64 vcc, exec, s[80:81]
	v_lshl_add_u64 v[102:103], v[110:111], 0, v[102:103]
	s_waitcnt vmcnt(0) lgkmcnt(0)
	v_lshlrev_b32_e32 v94, 16, v90
	v_and_b32_e32 v90, 0xffff0000, v90
	v_lshlrev_b32_e32 v95, 16, v91
	v_and_b32_e32 v91, 0xffff0000, v91
	v_lshlrev_b32_e32 v100, 16, v92
	v_and_b32_e32 v92, 0xffff0000, v92
	v_lshlrev_b32_e32 v101, 16, v93
	v_and_b32_e32 v93, 0xffff0000, v93
	v_mul_f32_e32 v94, 0xbfb8aa3b, v94
	v_mul_f32_e32 v90, 0xbfb8aa3b, v90
	v_mul_f32_e32 v95, 0xbfb8aa3b, v95
	v_mul_f32_e32 v91, 0xbfb8aa3b, v91
	v_mul_f32_e32 v100, 0xbfb8aa3b, v100
	v_mul_f32_e32 v92, 0xbfb8aa3b, v92
	v_mul_f32_e32 v101, 0xbfb8aa3b, v101
	v_mul_f32_e32 v93, 0xbfb8aa3b, v93
	v_exp_f32_e32 v94, v94
	v_exp_f32_e32 v90, v90
	v_exp_f32_e32 v95, v95
	v_exp_f32_e32 v91, v91
	v_exp_f32_e32 v100, v100
	v_exp_f32_e32 v92, v92
	v_exp_f32_e32 v101, v101
	v_exp_f32_e32 v93, v93
	v_add_f32_e32 v94, 1.0, v94
	v_add_f32_e32 v107, 1.0, v90
	v_add_f32_e32 v95, 1.0, v95
	v_add_f32_e32 v112, 1.0, v91
	v_add_f32_e32 v100, 1.0, v100
	v_add_f32_e32 v113, 1.0, v92
	v_add_f32_e32 v101, 1.0, v101
	v_add_f32_e32 v115, 1.0, v93
	v_rcp_f32_e32 v90, v94
	v_rcp_f32_e32 v91, v107
	v_rcp_f32_e32 v92, v95
	v_rcp_f32_e32 v93, v112
	v_rcp_f32_e32 v112, v100
	v_rcp_f32_e32 v114, v101
	v_rcp_f32_e32 v115, v115
	v_rcp_f32_e32 v113, v113
	v_pk_mul_f32 v[94:95], v[86:87], v[92:93]
	v_pk_mul_f32 v[100:101], v[84:85], v[90:91]
	v_pk_mul_f32 v[90:91], v[82:83], v[114:115]
	v_pk_mul_f32 v[92:93], v[80:81], v[112:113]
	s_cbranch_vccz .LBB0_791
	s_andn2_b64 vcc, exec, s[52:53]
	s_mov_b64 s[0:1], -1
	s_cbranch_vccz .LBB0_792

; __device__ __forceinline__ u32x4 pack8(f32x4 v0, f32x4 v1) { u32x4 w; w.x = cvt_pk_bf16(v0[0], v0[1]); w.y = cvt_pk_bf16(v0[2], v0[3]); w.z = cvt_pk_bf16(v1[0], v1[1]); w.w = cvt_pk_bf16(v1[2], v1[3]); return w; }
; __device__ __forceinline__ void epi8(const Desc& d, int pb, int row, int col, f32x4 v0, f32x4 v1) {
;     ...
;         if (d.epi != EPI_MERGE2) *(u32x4*)mp = pack8(v0, v1);
;         else *(u32x4*)((bf16_t*)d.o1 + (size_t)row * DM + col) = pack8(v0, v1);
.LBB0_473:
	v_cvt_pk_bf16_f32 v100, v100, v101
	v_cvt_pk_bf16_f32 v101, v94, v95
	v_cvt_pk_bf16_f32 v102, v92, v93
	v_cvt_pk_bf16_f32 v103, v90, v91
	v_lshl_add_u64 v[90:91], v[108:109], 1, s[84:85]
	v_lshl_add_u64 v[88:89], v[88:89], 1, v[90:91]
	global_store_dwordx4 v[88:89], v[100:103], off offset:256

; __device__ __forceinline__ u32x4 pack8(f32x4 v0, f32x4 v1) { u32x4 w; w.x = cvt_pk_bf16(v0[0], v0[1]); w.y = cvt_pk_bf16(v0[2], v0[3]); w.z = cvt_pk_bf16(v1[0], v1[1]); w.w = cvt_pk_bf16(v1[2], v1[3]); return w; }
; __device__ __forceinline__ void epi8(const Desc& d, int pb, int row, int col, f32x4 v0, f32x4 v1) {
;     ...
;     } else if (d.epi == EPI_BF16) {
;         *(u32x4*)((bf16_t*)d.o0 + (size_t)pb * d.sO + (size_t)row * d.ldc + col) = pack8(v0 * d.scale, v1 * d.scale);
.LBB0_475:
	s_andn2_b64 vcc, exec, s[74:75]
	s_cbranch_vccnz .LBB0_477
	s_mul_hi_i32 s1, s56, s93
	s_mul_i32 s0, s56, s93
	s_lshl_b64 s[0:1], s[0:1], 1
	s_add_u32 s0, s50, s0
	s_addc_u32 s1, s51, s1
	v_mad_i64_i32 v[92:93], s[42:43], s14, v106, 0
	v_lshl_add_u64 v[92:93], v[92:93], 1, s[0:1]
	v_ashrrev_i32_e32 v95, 31, v144
	v_mov_b32_e32 v94, v144
	v_lshl_add_u64 v[92:93], v[94:95], 1, v[92:93]
	v_cvt_pk_bf16_f32 v88, v84, v85
	v_cvt_pk_bf16_f32 v89, v86, v87
	v_cvt_pk_bf16_f32 v90, v80, v81
	v_cvt_pk_bf16_f32 v91, v82, v83
	global_store_dwordx4 v[92:93], v[88:91], off offset:256

; __device__ __forceinline__ u32x4 pack8(f32x4 v0, f32x4 v1) { u32x4 w; w.x = cvt_pk_bf16(v0[0], v0[1]); w.y = cvt_pk_bf16(v0[2], v0[3]); w.z = cvt_pk_bf16(v1[0], v1[1]); w.w = cvt_pk_bf16(v1[2], v1[3]); return w; }
; __device__ __forceinline__ void epi8(const Desc& d, int pb, int row, int col, f32x4 v0, f32x4 v1) {
;     if (d.epi == EPI_PIN) {
;         const int pn = col >> 8; bf16_t* p;
;         if (pn < 21) p = (bf16_t*)d.o0 + (size_t)row * NPA + col;
;         else if (pn == 21) p = (bf16_t*)d.o1 + (size_t)row * NKR + (col - 21 * 256);
;         else p = (bf16_t*)d.o2 + (size_t)row * NPG + (col - 22 * 256);
;         *(u32x4*)p = pack8(v0, v1);
.LBB0_486:
	v_cvt_pk_bf16_f32 v84, v84, v85
	v_cvt_pk_bf16_f32 v85, v86, v87
	v_cvt_pk_bf16_f32 v86, v80, v81
	v_cvt_pk_bf16_f32 v87, v82, v83
	global_store_dwordx4 v[88:89], v[84:87], off

; __device__ __forceinline__ void epi8(const Desc& d, int pb, int row, int col, f32x4 v0, f32x4 v1) {
;     ...
;         float* hp = (float*)d.o0 + (size_t)row * DM + col;
;         const float* rp = (row < LREAL ? (const float*)d.o2 + (size_t)row * DM : (const float*)d.gate + (size_t)(row - LREAL) * DM) + col;
;         v0 += *(const f32x4*)rp; v1 += *(const f32x4*)(rp + 4);
;         if (d.epi == EPI_RESID) { *(f32x4*)hp = v0; *(f32x4*)(hp + 4) = v1; }
;         else if (row < LREAL) { float* op = (float*)d.o1 + (size_t)row * DM + col; *(f32x4*)op = v0; *(f32x4*)(op + 4) = v1; }
.LBB0_491:
	s_cmp_lt_i32 s26, 2
	s_cbranch_scc1 .LBB0_506
	s_cmp_gt_i32 s26, 4
	s_cbranch_scc0 .LBB0_500
	v_lshl_add_u64 v[80:81], v[92:93], 2, s[86:87]
	v_lshl_add_u64 v[82:83], s[82:83], 0, v[94:95]
	v_ashrrev_i32_e32 v97, 31, v144
	v_mov_b32_e32 v96, v144
	v_cndmask_b32_e64 v81, v83, v81, s[0:1]
	v_cndmask_b32_e64 v80, v82, v80, s[0:1]
	v_lshl_add_u64 v[84:85], v[96:97], 2, v[80:81]
	global_load_dwordx4 v[80:83], v[84:85], off
	s_nop 0
	global_load_dwordx4 v[84:87], v[84:85], off offset:16
	s_andn2_b64 vcc, exec, s[64:65]
	s_waitcnt vmcnt(0) lgkmcnt(0)
	v_pk_add_f32 v[82:83], v[78:79], v[82:83]
	v_pk_add_f32 v[80:81], v[76:77], v[80:81]
	v_pk_add_f32 v[86:87], v[74:75], v[86:87]
	v_pk_add_f32 v[84:85], v[72:73], v[84:85]
	s_cbranch_vccnz .LBB0_497
	s_and_saveexec_b64 s[74:75], s[0:1]
	s_cbranch_execz .LBB0_496
	v_lshl_add_u64 v[98:99], v[92:93], 2, s[84:85]
	v_lshl_add_u64 v[98:99], v[96:97], 2, v[98:99]
	global_store_dwordx4 v[98:99], v[80:83], off
	global_store_dwordx4 v[98:99], v[84:87], off offset:16

; __device__ __forceinline__ void epi8(const Desc& d, int pb, int row, int col, f32x4 v0, f32x4 v1) {
;     ...
;         float* hp = (float*)d.o0 + (size_t)row * DM + col;
;         const float* rp = (row < LREAL ? (const float*)d.o2 + (size_t)row * DM : (const float*)d.gate + (size_t)(row - LREAL) * DM) + col;
;         v0 += *(const f32x4*)rp; v1 += *(const f32x4*)(rp + 4);
;         if (d.epi == EPI_RESID) { *(f32x4*)hp = v0; *(f32x4*)(hp + 4) = v1; }
;         else if (row < LREAL) { float* op = (float*)d.o1 + (size_t)row * DM + col; *(f32x4*)op = v0; *(f32x4*)(op + 4) = v1; }
.LBB0_497:
	s_andn2_b64 vcc, exec, s[74:75]
	s_cbranch_vccnz .LBB0_499
	v_lshl_add_u64 v[98:99], v[92:93], 2, s[50:51]
	v_lshl_add_u64 v[96:97], v[96:97], 2, v[98:99]
	global_store_dwordx4 v[96:97], v[80:83], off
	global_store_dwordx4 v[96:97], v[84:87], off offset:16

; __device__ __forceinline__ float bf_lo(unsigned w) { return __uint_as_float(w << 16); }
; __device__ __forceinline__ float bf_hi(unsigned w) { return __uint_as_float(w & 0xffff0000u); }
; __device__ __forceinline__ float sigm(float x) { return __builtin_amdgcn_rcpf(1.f + __builtin_amdgcn_exp2f(-1.4426950408889634f * x)); }
; __device__ __forceinline__ f32x4 sigm4(unsigned lo, unsigned hi) { f32x4 r; r[0] = sigm(bf_lo(lo)); r[1] = sigm(bf_hi(lo)); r[2] = sigm(bf_lo(hi)); r[3] = sigm(bf_hi(hi)); return r; }
; __device__ __forceinline__ void epi8(const Desc& d, int pb, int row, int col, f32x4 v0, f32x4 v1) {
;     ...
;     } else if (d.epi == EPI_MERGE0 || d.epi == EPI_MERGE1 || d.epi == EPI_MERGE2) {
;         const u32x4 gw = *(const u32x4*)(d.gate + (size_t)row * NPG + col);
;         v0 *= sigm4(gw.x, gw.y); v1 *= sigm4(gw.z, gw.w);
;         bf16_t* mp = (bf16_t*)d.o0 + (size_t)row * DM + col;
.LBB0_500:
	s_andn2_b64 vcc, exec, s[74:75]
	s_cbranch_vccnz .LBB0_505
	v_ashrrev_i32_e32 v81, 31, v144
	v_mov_b32_e32 v80, v144
	v_lshl_add_u64 v[82:83], s[82:83], 0, v[88:89]
	v_lshlrev_b64 v[98:99], 1, v[80:81]
	v_lshl_add_u64 v[82:83], v[82:83], 0, v[98:99]
	global_load_dwordx4 v[82:85], v[82:83], off
	v_lshl_add_u64 v[100:101], v[92:93], 1, s[50:51]
	s_andn2_b64 vcc, exec, s[80:81]
	v_lshl_add_u64 v[98:99], v[100:101], 0, v[98:99]
	s_waitcnt vmcnt(0) lgkmcnt(0)
	v_lshlrev_b32_e32 v86, 16, v82
	v_and_b32_e32 v82, 0xffff0000, v82
	v_lshlrev_b32_e32 v87, 16, v83
	v_and_b32_e32 v83, 0xffff0000, v83
	v_lshlrev_b32_e32 v96, 16, v84
	v_and_b32_e32 v84, 0xffff0000, v84
	v_lshlrev_b32_e32 v97, 16, v85
	v_and_b32_e32 v85, 0xffff0000, v85
	v_mul_f32_e32 v86, 0xbfb8aa3b, v86
	v_mul_f32_e32 v82, 0xbfb8aa3b, v82
	v_mul_f32_e32 v87, 0xbfb8aa3b, v87
	v_mul_f32_e32 v83, 0xbfb8aa3b, v83
	v_mul_f32_e32 v96, 0xbfb8aa3b, v96
	v_mul_f32_e32 v84, 0xbfb8aa3b, v84
	v_mul_f32_e32 v97, 0xbfb8aa3b, v97
	v_mul_f32_e32 v85, 0xbfb8aa3b, v85
	v_exp_f32_e32 v86, v86
	v_exp_f32_e32 v82, v82
	v_exp_f32_e32 v87, v87
	v_exp_f32_e32 v83, v83
	v_exp_f32_e32 v96, v96
	v_exp_f32_e32 v84, v84
	v_exp_f32_e32 v97, v97
	v_exp_f32_e32 v85, v85
	v_add_f32_e32 v86, 1.0, v86
	v_add_f32_e32 v102, 1.0, v82
	v_add_f32_e32 v87, 1.0, v87
	v_add_f32_e32 v103, 1.0, v83
	v_add_f32_e32 v96, 1.0, v96
	v_add_f32_e32 v106, 1.0, v84
	v_add_f32_e32 v97, 1.0, v97
	v_add_f32_e32 v105, 1.0, v85
	v_rcp_f32_e32 v82, v86
	v_rcp_f32_e32 v83, v102
	v_rcp_f32_e32 v84, v87
	v_rcp_f32_e32 v85, v103
	v_rcp_f32_e32 v102, v96
	v_rcp_f32_e32 v104, v97
	v_rcp_f32_e32 v105, v105
	v_rcp_f32_e32 v103, v106
	v_pk_mul_f32 v[86:87], v[78:79], v[84:85]
	v_pk_mul_f32 v[96:97], v[76:77], v[82:83]
	v_pk_mul_f32 v[82:83], v[74:75], v[104:105]
	v_pk_mul_f32 v[84:85], v[72:73], v[102:103]
	s_cbranch_vccz .LBB0_793
	s_andn2_b64 vcc, exec, s[52:53]
	s_mov_b64 s[74:75], -1
	s_cbranch_vccz .LBB0_794

; __device__ __forceinline__ u32x4 pack8(f32x4 v0, f32x4 v1) { u32x4 w; w.x = cvt_pk_bf16(v0[0], v0[1]); w.y = cvt_pk_bf16(v0[2], v0[3]); w.z = cvt_pk_bf16(v1[0], v1[1]); w.w = cvt_pk_bf16(v1[2], v1[3]); return w; }
; __device__ __forceinline__ void epi8(const Desc& d, int pb, int row, int col, f32x4 v0, f32x4 v1) {
;     ...
;         if (d.epi != EPI_MERGE2) *(u32x4*)mp = pack8(v0, v1);
;         else *(u32x4*)((bf16_t*)d.o1 + (size_t)row * DM + col) = pack8(v0, v1);
.LBB0_504:
	v_cvt_pk_bf16_f32 v96, v96, v97
	v_cvt_pk_bf16_f32 v97, v86, v87
	v_cvt_pk_bf16_f32 v98, v84, v85
	v_cvt_pk_bf16_f32 v99, v82, v83
	v_lshl_add_u64 v[82:83], v[92:93], 1, s[84:85]
	v_lshl_add_u64 v[80:81], v[80:81], 1, v[82:83]
	global_store_dwordx4 v[80:81], v[96:99], off

; __device__ __forceinline__ u32x4 pack8(f32x4 v0, f32x4 v1) { u32x4 w; w.x = cvt_pk_bf16(v0[0], v0[1]); w.y = cvt_pk_bf16(v0[2], v0[3]); w.z = cvt_pk_bf16(v1[0], v1[1]); w.w = cvt_pk_bf16(v1[2], v1[3]); return w; }
; __device__ __forceinline__ void epi8(const Desc& d, int pb, int row, int col, f32x4 v0, f32x4 v1) {
;     ...
;     } else if (d.epi == EPI_BF16) {
;         *(u32x4*)((bf16_t*)d.o0 + (size_t)pb * d.sO + (size_t)row * d.ldc + col) = pack8(v0 * d.scale, v1 * d.scale);
.LBB0_506:
	s_andn2_b64 vcc, exec, s[74:75]
	s_cbranch_vccnz .LBB0_508
	s_mul_hi_i32 s43, s56, s93
	s_mul_i32 s42, s56, s93
	s_lshl_b64 s[42:43], s[42:43], 1
	s_add_u32 s42, s50, s42
	s_addc_u32 s43, s51, s43
	v_mad_i64_i32 v[84:85], s[74:75], s14, v90, 0
	v_lshl_add_u64 v[84:85], v[84:85], 1, s[42:43]
	v_ashrrev_i32_e32 v87, 31, v144
	v_mov_b32_e32 v86, v144
	v_lshl_add_u64 v[84:85], v[86:87], 1, v[84:85]
	v_cvt_pk_bf16_f32 v80, v76, v77
	v_cvt_pk_bf16_f32 v81, v78, v79
	v_cvt_pk_bf16_f32 v82, v72, v73
	v_cvt_pk_bf16_f32 v83, v74, v75
	global_store_dwordx4 v[84:85], v[80:83], off

; __device__ __forceinline__ u32x4 pack8(f32x4 v0, f32x4 v1) { u32x4 w; w.x = cvt_pk_bf16(v0[0], v0[1]); w.y = cvt_pk_bf16(v0[2], v0[3]); w.z = cvt_pk_bf16(v1[0], v1[1]); w.w = cvt_pk_bf16(v1[2], v1[3]); return w; }
; __device__ __forceinline__ void epi8(const Desc& d, int pb, int row, int col, f32x4 v0, f32x4 v1) {
;     if (d.epi == EPI_PIN) {
;         const int pn = col >> 8; bf16_t* p;
;         if (pn < 21) p = (bf16_t*)d.o0 + (size_t)row * NPA + col;
;         else if (pn == 21) p = (bf16_t*)d.o1 + (size_t)row * NKR + (col - 21 * 256);
;         else p = (bf16_t*)d.o2 + (size_t)row * NPG + (col - 22 * 256);
;         *(u32x4*)p = pack8(v0, v1);
;     ...
;         float* hp = (float*)d.o0 + (size_t)row * DM + col;
;         const float* rp = (row < LREAL ? (const float*)d.o2 + (size_t)row * DM : (const float*)d.gate + (size_t)(row - LREAL) * DM) + col;
;         v0 += *(const f32x4*)rp; v1 += *(const f32x4*)(rp + 4);
;         if (d.epi == EPI_RESID) { *(f32x4*)hp = v0; *(f32x4*)(hp + 4) = v1; }
;         else if (row < LREAL) { float* op = (float*)d.o1 + (size_t)row * DM + col; *(f32x4*)op = v0; *(f32x4*)(op + 4) = v1; }
.LBB0_517:
	v_cvt_pk_bf16_f32 v76, v76, v77
	v_cvt_pk_bf16_f32 v77, v78, v79
	v_cvt_pk_bf16_f32 v78, v72, v73
	v_cvt_pk_bf16_f32 v79, v74, v75
	global_store_dwordx4 v[84:85], v[76:79], off
	s_cmp_lt_i32 s26, 1
	s_mov_b64 s[74:75], -1
	s_cbranch_scc1 .LBB0_490
.LBB0_518:
	s_cmp_lt_i32 s26, 2
	s_cbranch_scc1 .LBB0_533
	s_cmp_gt_i32 s26, 4
	s_cbranch_scc0 .LBB0_527
	v_lshl_add_u64 v[72:73], v[92:93], 2, s[86:87]
	v_lshl_add_u64 v[74:75], s[82:83], 0, v[94:95]
	v_cndmask_b32_e64 v73, v75, v73, s[0:1]
	v_cndmask_b32_e64 v72, v74, v72, s[0:1]
	v_ashrrev_i32_e32 v85, 31, v144
	v_mov_b32_e32 v84, v144
	v_lshl_add_u64 v[76:77], v[84:85], 2, v[72:73]
	global_load_dwordx4 v[72:75], v[76:77], off offset:512
	s_nop 0
	global_load_dwordx4 v[76:79], v[76:77], off offset:528
	s_andn2_b64 vcc, exec, s[64:65]
	s_waitcnt vmcnt(0) lgkmcnt(0)
	v_pk_add_f32 v[74:75], v[70:71], v[74:75]
	v_pk_add_f32 v[72:73], v[68:69], v[72:73]
	v_pk_add_f32 v[78:79], v[66:67], v[78:79]
	v_pk_add_f32 v[76:77], v[64:65], v[76:77]
	s_cbranch_vccnz .LBB0_524
	s_and_saveexec_b64 s[74:75], s[0:1]
	s_cbranch_execz .LBB0_523
	v_lshl_add_u64 v[86:87], v[92:93], 2, s[84:85]
	v_lshl_add_u64 v[86:87], v[84:85], 2, v[86:87]
	global_store_dwordx4 v[86:87], v[72:75], off offset:512
	global_store_dwordx4 v[86:87], v[76:79], off offset:528

; __device__ __forceinline__ void epi8(const Desc& d, int pb, int row, int col, f32x4 v0, f32x4 v1) {
;     ...
;         float* hp = (float*)d.o0 + (size_t)row * DM + col;
;         const float* rp = (row < LREAL ? (const float*)d.o2 + (size_t)row * DM : (const float*)d.gate + (size_t)(row - LREAL) * DM) + col;
;         v0 += *(const f32x4*)rp; v1 += *(const f32x4*)(rp + 4);
;         if (d.epi == EPI_RESID) { *(f32x4*)hp = v0; *(f32x4*)(hp + 4) = v1; }
;         else if (row < LREAL) { float* op = (float*)d.o1 + (size_t)row * DM + col; *(f32x4*)op = v0; *(f32x4*)(op + 4) = v1; }
.LBB0_524:
	s_andn2_b64 vcc, exec, s[74:75]
	s_cbranch_vccnz .LBB0_526
	v_lshl_add_u64 v[86:87], v[92:93], 2, s[50:51]
	v_lshl_add_u64 v[84:85], v[84:85], 2, v[86:87]
	global_store_dwordx4 v[84:85], v[72:75], off offset:512
	global_store_dwordx4 v[84:85], v[76:79], off offset:528

; __device__ __forceinline__ float bf_lo(unsigned w) { return __uint_as_float(w << 16); }
; __device__ __forceinline__ float bf_hi(unsigned w) { return __uint_as_float(w & 0xffff0000u); }
; __device__ __forceinline__ float sigm(float x) { return __builtin_amdgcn_rcpf(1.f + __builtin_amdgcn_exp2f(-1.4426950408889634f * x)); }
; __device__ __forceinline__ f32x4 sigm4(unsigned lo, unsigned hi) { f32x4 r; r[0] = sigm(bf_lo(lo)); r[1] = sigm(bf_hi(lo)); r[2] = sigm(bf_lo(hi)); r[3] = sigm(bf_hi(hi)); return r; }
; __device__ __forceinline__ void epi8(const Desc& d, int pb, int row, int col, f32x4 v0, f32x4 v1) {
;     ...
;     } else if (d.epi == EPI_MERGE0 || d.epi == EPI_MERGE1 || d.epi == EPI_MERGE2) {
;         const u32x4 gw = *(const u32x4*)(d.gate + (size_t)row * NPG + col);
;         v0 *= sigm4(gw.x, gw.y); v1 *= sigm4(gw.z, gw.w);
;         bf16_t* mp = (bf16_t*)d.o0 + (size_t)row * DM + col;
.LBB0_527:
	s_andn2_b64 vcc, exec, s[74:75]
	s_cbranch_vccnz .LBB0_532
	v_ashrrev_i32_e32 v73, 31, v144
	v_mov_b32_e32 v72, v144
	v_lshl_add_u64 v[74:75], s[82:83], 0, v[88:89]
	v_lshlrev_b64 v[86:87], 1, v[72:73]
	v_lshl_add_u64 v[74:75], v[74:75], 0, v[86:87]
	global_load_dwordx4 v[74:77], v[74:75], off offset:256
	v_lshl_add_u64 v[94:95], v[92:93], 1, s[50:51]
	s_andn2_b64 vcc, exec, s[80:81]
	v_lshl_add_u64 v[86:87], v[94:95], 0, v[86:87]
	s_waitcnt vmcnt(0) lgkmcnt(0)
	v_lshlrev_b32_e32 v78, 16, v74
	v_and_b32_e32 v74, 0xffff0000, v74
	v_lshlrev_b32_e32 v79, 16, v75
	v_and_b32_e32 v75, 0xffff0000, v75
	v_lshlrev_b32_e32 v84, 16, v76
	v_and_b32_e32 v76, 0xffff0000, v76
	v_lshlrev_b32_e32 v85, 16, v77
	v_and_b32_e32 v77, 0xffff0000, v77
	v_mul_f32_e32 v78, 0xbfb8aa3b, v78
	v_mul_f32_e32 v74, 0xbfb8aa3b, v74
	v_mul_f32_e32 v79, 0xbfb8aa3b, v79
	v_mul_f32_e32 v75, 0xbfb8aa3b, v75
	v_mul_f32_e32 v84, 0xbfb8aa3b, v84
	v_mul_f32_e32 v76, 0xbfb8aa3b, v76
	v_mul_f32_e32 v85, 0xbfb8aa3b, v85
	v_mul_f32_e32 v77, 0xbfb8aa3b, v77
	v_exp_f32_e32 v78, v78
	v_exp_f32_e32 v74, v74
	v_exp_f32_e32 v79, v79
	v_exp_f32_e32 v75, v75
	v_exp_f32_e32 v84, v84
	v_exp_f32_e32 v76, v76
	v_exp_f32_e32 v85, v85
	v_exp_f32_e32 v77, v77
	v_add_f32_e32 v78, 1.0, v78
	v_add_f32_e32 v91, 1.0, v74
	v_add_f32_e32 v79, 1.0, v79
	v_add_f32_e32 v96, 1.0, v75
	v_add_f32_e32 v84, 1.0, v84
	v_add_f32_e32 v97, 1.0, v76
	v_add_f32_e32 v85, 1.0, v85
	v_add_f32_e32 v99, 1.0, v77
	v_rcp_f32_e32 v74, v78
	v_rcp_f32_e32 v75, v91
	v_rcp_f32_e32 v76, v79
	v_rcp_f32_e32 v77, v96
	v_rcp_f32_e32 v96, v84
	v_rcp_f32_e32 v98, v85
	v_rcp_f32_e32 v99, v99
	v_rcp_f32_e32 v97, v97
	v_pk_mul_f32 v[78:79], v[70:71], v[76:77]
	v_pk_mul_f32 v[84:85], v[68:69], v[74:75]
	v_pk_mul_f32 v[74:75], v[66:67], v[98:99]
	v_pk_mul_f32 v[76:77], v[64:65], v[96:97]
	s_cbranch_vccz .LBB0_795
	s_andn2_b64 vcc, exec, s[52:53]
	s_mov_b64 s[0:1], -1
	s_cbranch_vccz .LBB0_796

; __device__ __forceinline__ u32x4 pack8(f32x4 v0, f32x4 v1) { u32x4 w; w.x = cvt_pk_bf16(v0[0], v0[1]); w.y = cvt_pk_bf16(v0[2], v0[3]); w.z = cvt_pk_bf16(v1[0], v1[1]); w.w = cvt_pk_bf16(v1[2], v1[3]); return w; }
; __device__ __forceinline__ void epi8(const Desc& d, int pb, int row, int col, f32x4 v0, f32x4 v1) {
;     ...
;         if (d.epi != EPI_MERGE2) *(u32x4*)mp = pack8(v0, v1);
;         else *(u32x4*)((bf16_t*)d.o1 + (size_t)row * DM + col) = pack8(v0, v1);
.LBB0_531:
	v_cvt_pk_bf16_f32 v84, v84, v85
	v_cvt_pk_bf16_f32 v85, v78, v79
	v_cvt_pk_bf16_f32 v86, v76, v77
	v_cvt_pk_bf16_f32 v87, v74, v75
	v_lshl_add_u64 v[74:75], v[92:93], 1, s[84:85]
	v_lshl_add_u64 v[72:73], v[72:73], 1, v[74:75]
	global_store_dwordx4 v[72:73], v[84:87], off offset:256

; __device__ __forceinline__ u32x4 pack8(f32x4 v0, f32x4 v1) { u32x4 w; w.x = cvt_pk_bf16(v0[0], v0[1]); w.y = cvt_pk_bf16(v0[2], v0[3]); w.z = cvt_pk_bf16(v1[0], v1[1]); w.w = cvt_pk_bf16(v1[2], v1[3]); return w; }
; __device__ __forceinline__ void epi8(const Desc& d, int pb, int row, int col, f32x4 v0, f32x4 v1) {
;     ...
;     } else if (d.epi == EPI_BF16) {
;         *(u32x4*)((bf16_t*)d.o0 + (size_t)pb * d.sO + (size_t)row * d.ldc + col) = pack8(v0 * d.scale, v1 * d.scale);
.LBB0_533:
	s_andn2_b64 vcc, exec, s[74:75]
	s_cbranch_vccnz .LBB0_535
	s_mul_hi_i32 s1, s56, s93
	s_mul_i32 s0, s56, s93
	s_lshl_b64 s[0:1], s[0:1], 1
	s_add_u32 s0, s50, s0
	s_addc_u32 s1, s51, s1
	v_mad_i64_i32 v[76:77], s[42:43], s14, v90, 0
	v_lshl_add_u64 v[76:77], v[76:77], 1, s[0:1]
	v_ashrrev_i32_e32 v79, 31, v144
	v_mov_b32_e32 v78, v144
	v_lshl_add_u64 v[76:77], v[78:79], 1, v[76:77]
	v_cvt_pk_bf16_f32 v72, v68, v69
	v_cvt_pk_bf16_f32 v73, v70, v71
	v_cvt_pk_bf16_f32 v74, v64, v65
	v_cvt_pk_bf16_f32 v75, v66, v67
	global_store_dwordx4 v[76:77], v[72:75], off offset:256

; __device__ __forceinline__ u32x4 pack8(f32x4 v0, f32x4 v1) { u32x4 w; w.x = cvt_pk_bf16(v0[0], v0[1]); w.y = cvt_pk_bf16(v0[2], v0[3]); w.z = cvt_pk_bf16(v1[0], v1[1]); w.w = cvt_pk_bf16(v1[2], v1[3]); return w; }
; __device__ __forceinline__ void epi8(const Desc& d, int pb, int row, int col, f32x4 v0, f32x4 v1) {
;     if (d.epi == EPI_PIN) {
;         const int pn = col >> 8; bf16_t* p;
;         if (pn < 21) p = (bf16_t*)d.o0 + (size_t)row * NPA + col;
;         else if (pn == 21) p = (bf16_t*)d.o1 + (size_t)row * NKR + (col - 21 * 256);
;         else p = (bf16_t*)d.o2 + (size_t)row * NPG + (col - 22 * 256);
;         *(u32x4*)p = pack8(v0, v1);
.LBB0_544:
	v_cvt_pk_bf16_f32 v68, v68, v69
	v_cvt_pk_bf16_f32 v69, v70, v71
	v_cvt_pk_bf16_f32 v70, v64, v65
	v_cvt_pk_bf16_f32 v71, v66, v67
	global_store_dwordx4 v[72:73], v[68:71], off

; __device__ __forceinline__ void epi8(const Desc& d, int pb, int row, int col, f32x4 v0, f32x4 v1) {
;     ...
;         float* hp = (float*)d.o0 + (size_t)row * DM + col;
;         const float* rp = (row < LREAL ? (const float*)d.o2 + (size_t)row * DM : (const float*)d.gate + (size_t)(row - LREAL) * DM) + col;
;         v0 += *(const f32x4*)rp; v1 += *(const f32x4*)(rp + 4);
;         if (d.epi == EPI_RESID) { *(f32x4*)hp = v0; *(f32x4*)(hp + 4) = v1; }
;         else if (row < LREAL) { float* op = (float*)d.o1 + (size_t)row * DM + col; *(f32x4*)op = v0; *(f32x4*)(op + 4) = v1; }
.LBB0_549:
	s_cmp_lt_i32 s26, 2
	s_cbranch_scc1 .LBB0_564
	s_cmp_gt_i32 s26, 4
	s_cbranch_scc0 .LBB0_558
	v_lshl_add_u64 v[64:65], v[76:77], 2, s[86:87]
	v_lshl_add_u64 v[66:67], s[82:83], 0, v[78:79]
	v_ashrrev_i32_e32 v81, 31, v144
	v_mov_b32_e32 v80, v144
	v_cndmask_b32_e64 v65, v67, v65, s[0:1]
	v_cndmask_b32_e64 v64, v66, v64, s[0:1]
	v_lshl_add_u64 v[68:69], v[80:81], 2, v[64:65]
	global_load_dwordx4 v[64:67], v[68:69], off
	s_nop 0
	global_load_dwordx4 v[68:71], v[68:69], off offset:16
	s_andn2_b64 vcc, exec, s[64:65]
	s_waitcnt vmcnt(0) lgkmcnt(0)
	v_pk_add_f32 v[66:67], v[62:63], v[66:67]
	v_pk_add_f32 v[64:65], v[60:61], v[64:65]
	v_pk_add_f32 v[70:71], v[58:59], v[70:71]
	v_pk_add_f32 v[68:69], v[56:57], v[68:69]
	s_cbranch_vccnz .LBB0_555
	s_and_saveexec_b64 s[74:75], s[0:1]
	s_cbranch_execz .LBB0_554
	v_lshl_add_u64 v[82:83], v[76:77], 2, s[84:85]
	v_lshl_add_u64 v[82:83], v[80:81], 2, v[82:83]
	global_store_dwordx4 v[82:83], v[64:67], off
	global_store_dwordx4 v[82:83], v[68:71], off offset:16

; __device__ __forceinline__ void epi8(const Desc& d, int pb, int row, int col, f32x4 v0, f32x4 v1) {
;     ...
;         float* hp = (float*)d.o0 + (size_t)row * DM + col;
;         const float* rp = (row < LREAL ? (const float*)d.o2 + (size_t)row * DM : (const float*)d.gate + (size_t)(row - LREAL) * DM) + col;
;         v0 += *(const f32x4*)rp; v1 += *(const f32x4*)(rp + 4);
;         if (d.epi == EPI_RESID) { *(f32x4*)hp = v0; *(f32x4*)(hp + 4) = v1; }
;         else if (row < LREAL) { float* op = (float*)d.o1 + (size_t)row * DM + col; *(f32x4*)op = v0; *(f32x4*)(op + 4) = v1; }
.LBB0_555:
	s_andn2_b64 vcc, exec, s[74:75]
	s_cbranch_vccnz .LBB0_557
	v_lshl_add_u64 v[82:83], v[76:77], 2, s[50:51]
	v_lshl_add_u64 v[80:81], v[80:81], 2, v[82:83]
	global_store_dwordx4 v[80:81], v[64:67], off
	global_store_dwordx4 v[80:81], v[68:71], off offset:16

; __device__ __forceinline__ float bf_lo(unsigned w) { return __uint_as_float(w << 16); }
; __device__ __forceinline__ float bf_hi(unsigned w) { return __uint_as_float(w & 0xffff0000u); }
; __device__ __forceinline__ float sigm(float x) { return __builtin_amdgcn_rcpf(1.f + __builtin_amdgcn_exp2f(-1.4426950408889634f * x)); }
; __device__ __forceinline__ f32x4 sigm4(unsigned lo, unsigned hi) { f32x4 r; r[0] = sigm(bf_lo(lo)); r[1] = sigm(bf_hi(lo)); r[2] = sigm(bf_lo(hi)); r[3] = sigm(bf_hi(hi)); return r; }
; __device__ __forceinline__ void epi8(const Desc& d, int pb, int row, int col, f32x4 v0, f32x4 v1) {
;     ...
;     } else if (d.epi == EPI_MERGE0 || d.epi == EPI_MERGE1 || d.epi == EPI_MERGE2) {
;         const u32x4 gw = *(const u32x4*)(d.gate + (size_t)row * NPG + col);
;         v0 *= sigm4(gw.x, gw.y); v1 *= sigm4(gw.z, gw.w);
;         bf16_t* mp = (bf16_t*)d.o0 + (size_t)row * DM + col;
.LBB0_558:
	s_andn2_b64 vcc, exec, s[74:75]
	s_cbranch_vccnz .LBB0_563
	v_ashrrev_i32_e32 v65, 31, v144
	v_mov_b32_e32 v64, v144
	v_lshl_add_u64 v[66:67], s[82:83], 0, v[72:73]
	v_lshlrev_b64 v[82:83], 1, v[64:65]
	v_lshl_add_u64 v[66:67], v[66:67], 0, v[82:83]
	global_load_dwordx4 v[66:69], v[66:67], off
	v_lshl_add_u64 v[84:85], v[76:77], 1, s[50:51]
	s_andn2_b64 vcc, exec, s[80:81]
	v_lshl_add_u64 v[82:83], v[84:85], 0, v[82:83]
	s_waitcnt vmcnt(0) lgkmcnt(0)
	v_lshlrev_b32_e32 v70, 16, v66
	v_and_b32_e32 v66, 0xffff0000, v66
	v_lshlrev_b32_e32 v71, 16, v67
	v_and_b32_e32 v67, 0xffff0000, v67
	v_lshlrev_b32_e32 v80, 16, v68
	v_and_b32_e32 v68, 0xffff0000, v68
	v_lshlrev_b32_e32 v81, 16, v69
	v_and_b32_e32 v69, 0xffff0000, v69
	v_mul_f32_e32 v70, 0xbfb8aa3b, v70
	v_mul_f32_e32 v66, 0xbfb8aa3b, v66
	v_mul_f32_e32 v71, 0xbfb8aa3b, v71
	v_mul_f32_e32 v67, 0xbfb8aa3b, v67
	v_mul_f32_e32 v80, 0xbfb8aa3b, v80
	v_mul_f32_e32 v68, 0xbfb8aa3b, v68
	v_mul_f32_e32 v81, 0xbfb8aa3b, v81
	v_mul_f32_e32 v69, 0xbfb8aa3b, v69
	v_exp_f32_e32 v70, v70
	v_exp_f32_e32 v66, v66
	v_exp_f32_e32 v71, v71
	v_exp_f32_e32 v67, v67
	v_exp_f32_e32 v80, v80
	v_exp_f32_e32 v68, v68
	v_exp_f32_e32 v81, v81
	v_exp_f32_e32 v69, v69
	v_add_f32_e32 v70, 1.0, v70
	v_add_f32_e32 v86, 1.0, v66
	v_add_f32_e32 v71, 1.0, v71
	v_add_f32_e32 v87, 1.0, v67
	v_add_f32_e32 v80, 1.0, v80
	v_add_f32_e32 v90, 1.0, v68
	v_add_f32_e32 v81, 1.0, v81
	v_add_f32_e32 v89, 1.0, v69
	v_rcp_f32_e32 v66, v70
	v_rcp_f32_e32 v67, v86
	v_rcp_f32_e32 v68, v71
	v_rcp_f32_e32 v69, v87
	v_rcp_f32_e32 v86, v80
	v_rcp_f32_e32 v88, v81
	v_rcp_f32_e32 v89, v89
	v_rcp_f32_e32 v87, v90
	v_pk_mul_f32 v[70:71], v[62:63], v[68:69]
	v_pk_mul_f32 v[80:81], v[60:61], v[66:67]
	v_pk_mul_f32 v[66:67], v[58:59], v[88:89]
	v_pk_mul_f32 v[68:69], v[56:57], v[86:87]
	s_cbranch_vccz .LBB0_797
	s_andn2_b64 vcc, exec, s[52:53]
	s_mov_b64 s[74:75], -1
	s_cbranch_vccz .LBB0_798

; __device__ __forceinline__ u32x4 pack8(f32x4 v0, f32x4 v1) { u32x4 w; w.x = cvt_pk_bf16(v0[0], v0[1]); w.y = cvt_pk_bf16(v0[2], v0[3]); w.z = cvt_pk_bf16(v1[0], v1[1]); w.w = cvt_pk_bf16(v1[2], v1[3]); return w; }
; __device__ __forceinline__ void epi8(const Desc& d, int pb, int row, int col, f32x4 v0, f32x4 v1) {
;     ...
;         if (d.epi != EPI_MERGE2) *(u32x4*)mp = pack8(v0, v1);
;         else *(u32x4*)((bf16_t*)d.o1 + (size_t)row * DM + col) = pack8(v0, v1);
.LBB0_562:
	v_cvt_pk_bf16_f32 v80, v80, v81
	v_cvt_pk_bf16_f32 v81, v70, v71
	v_cvt_pk_bf16_f32 v82, v68, v69
	v_cvt_pk_bf16_f32 v83, v66, v67
	v_lshl_add_u64 v[66:67], v[76:77], 1, s[84:85]
	v_lshl_add_u64 v[64:65], v[64:65], 1, v[66:67]
	global_store_dwordx4 v[64:65], v[80:83], off

; __device__ __forceinline__ u32x4 pack8(f32x4 v0, f32x4 v1) { u32x4 w; w.x = cvt_pk_bf16(v0[0], v0[1]); w.y = cvt_pk_bf16(v0[2], v0[3]); w.z = cvt_pk_bf16(v1[0], v1[1]); w.w = cvt_pk_bf16(v1[2], v1[3]); return w; }
; __device__ __forceinline__ void epi8(const Desc& d, int pb, int row, int col, f32x4 v0, f32x4 v1) {
;     ...
;     } else if (d.epi == EPI_BF16) {
;         *(u32x4*)((bf16_t*)d.o0 + (size_t)pb * d.sO + (size_t)row * d.ldc + col) = pack8(v0 * d.scale, v1 * d.scale);
.LBB0_564:
	s_andn2_b64 vcc, exec, s[74:75]
	s_cbranch_vccnz .LBB0_566
	s_mul_hi_i32 s43, s56, s93
	s_mul_i32 s42, s56, s93
	s_lshl_b64 s[42:43], s[42:43], 1
	s_add_u32 s42, s50, s42
	s_addc_u32 s43, s51, s43
	v_mad_i64_i32 v[68:69], s[74:75], s14, v74, 0
	v_lshl_add_u64 v[68:69], v[68:69], 1, s[42:43]
	v_ashrrev_i32_e32 v71, 31, v144
	v_mov_b32_e32 v70, v144
	v_lshl_add_u64 v[68:69], v[70:71], 1, v[68:69]
	v_cvt_pk_bf16_f32 v64, v60, v61
	v_cvt_pk_bf16_f32 v65, v62, v63
	v_cvt_pk_bf16_f32 v66, v56, v57
	v_cvt_pk_bf16_f32 v67, v58, v59
	global_store_dwordx4 v[68:69], v[64:67], off

; __device__ __forceinline__ u32x4 pack8(f32x4 v0, f32x4 v1) { u32x4 w; w.x = cvt_pk_bf16(v0[0], v0[1]); w.y = cvt_pk_bf16(v0[2], v0[3]); w.z = cvt_pk_bf16(v1[0], v1[1]); w.w = cvt_pk_bf16(v1[2], v1[3]); return w; }
; __device__ __forceinline__ void epi8(const Desc& d, int pb, int row, int col, f32x4 v0, f32x4 v1) {
;     if (d.epi == EPI_PIN) {
;         const int pn = col >> 8; bf16_t* p;
;         if (pn < 21) p = (bf16_t*)d.o0 + (size_t)row * NPA + col;
;         else if (pn == 21) p = (bf16_t*)d.o1 + (size_t)row * NKR + (col - 21 * 256);
;         else p = (bf16_t*)d.o2 + (size_t)row * NPG + (col - 22 * 256);
;         *(u32x4*)p = pack8(v0, v1);
;     ...
;         float* hp = (float*)d.o0 + (size_t)row * DM + col;
;         const float* rp = (row < LREAL ? (const float*)d.o2 + (size_t)row * DM : (const float*)d.gate + (size_t)(row - LREAL) * DM) + col;
;         v0 += *(const f32x4*)rp; v1 += *(const f32x4*)(rp + 4);
;         if (d.epi == EPI_RESID) { *(f32x4*)hp = v0; *(f32x4*)(hp + 4) = v1; }
;         else if (row < LREAL) { float* op = (float*)d.o1 + (size_t)row * DM + col; *(f32x4*)op = v0; *(f32x4*)(op + 4) = v1; }
.LBB0_575:
	v_cvt_pk_bf16_f32 v60, v60, v61
	v_cvt_pk_bf16_f32 v61, v62, v63
	v_cvt_pk_bf16_f32 v62, v56, v57
	v_cvt_pk_bf16_f32 v63, v58, v59
	global_store_dwordx4 v[68:69], v[60:63], off
	s_cmp_lt_i32 s26, 1
	s_mov_b64 s[74:75], -1
	s_cbranch_scc1 .LBB0_548
.LBB0_576:
	s_cmp_lt_i32 s26, 2
	s_cbranch_scc1 .LBB0_591
	s_cmp_gt_i32 s26, 4
	s_cbranch_scc0 .LBB0_585
	v_lshl_add_u64 v[56:57], v[76:77], 2, s[86:87]
	v_lshl_add_u64 v[58:59], s[82:83], 0, v[78:79]
	v_cndmask_b32_e64 v57, v59, v57, s[0:1]
	v_cndmask_b32_e64 v56, v58, v56, s[0:1]
	v_ashrrev_i32_e32 v69, 31, v144
	v_mov_b32_e32 v68, v144
	v_lshl_add_u64 v[60:61], v[68:69], 2, v[56:57]
	global_load_dwordx4 v[56:59], v[60:61], off offset:512
	s_nop 0
	global_load_dwordx4 v[60:63], v[60:61], off offset:528
	s_andn2_b64 vcc, exec, s[64:65]
	s_waitcnt vmcnt(0) lgkmcnt(0)
	v_pk_add_f32 v[58:59], v[54:55], v[58:59]
	v_pk_add_f32 v[56:57], v[52:53], v[56:57]
	v_pk_add_f32 v[62:63], v[50:51], v[62:63]
	v_pk_add_f32 v[60:61], v[48:49], v[60:61]
	s_cbranch_vccnz .LBB0_582
	s_and_saveexec_b64 s[74:75], s[0:1]
	s_cbranch_execz .LBB0_581
	v_lshl_add_u64 v[70:71], v[76:77], 2, s[84:85]
	v_lshl_add_u64 v[70:71], v[68:69], 2, v[70:71]
	global_store_dwordx4 v[70:71], v[56:59], off offset:512
	global_store_dwordx4 v[70:71], v[60:63], off offset:528

; __device__ __forceinline__ void epi8(const Desc& d, int pb, int row, int col, f32x4 v0, f32x4 v1) {
;     ...
;         float* hp = (float*)d.o0 + (size_t)row * DM + col;
;         const float* rp = (row < LREAL ? (const float*)d.o2 + (size_t)row * DM : (const float*)d.gate + (size_t)(row - LREAL) * DM) + col;
;         v0 += *(const f32x4*)rp; v1 += *(const f32x4*)(rp + 4);
;         if (d.epi == EPI_RESID) { *(f32x4*)hp = v0; *(f32x4*)(hp + 4) = v1; }
;         else if (row < LREAL) { float* op = (float*)d.o1 + (size_t)row * DM + col; *(f32x4*)op = v0; *(f32x4*)(op + 4) = v1; }
.LBB0_582:
	s_andn2_b64 vcc, exec, s[74:75]
	s_cbranch_vccnz .LBB0_584
	v_lshl_add_u64 v[70:71], v[76:77], 2, s[50:51]
	v_lshl_add_u64 v[68:69], v[68:69], 2, v[70:71]
	global_store_dwordx4 v[68:69], v[56:59], off offset:512
	global_store_dwordx4 v[68:69], v[60:63], off offset:528

; __device__ __forceinline__ float bf_lo(unsigned w) { return __uint_as_float(w << 16); }
; __device__ __forceinline__ float bf_hi(unsigned w) { return __uint_as_float(w & 0xffff0000u); }
; __device__ __forceinline__ float sigm(float x) { return __builtin_amdgcn_rcpf(1.f + __builtin_amdgcn_exp2f(-1.4426950408889634f * x)); }
; __device__ __forceinline__ f32x4 sigm4(unsigned lo, unsigned hi) { f32x4 r; r[0] = sigm(bf_lo(lo)); r[1] = sigm(bf_hi(lo)); r[2] = sigm(bf_lo(hi)); r[3] = sigm(bf_hi(hi)); return r; }
; __device__ __forceinline__ void epi8(const Desc& d, int pb, int row, int col, f32x4 v0, f32x4 v1) {
;     ...
;     } else if (d.epi == EPI_MERGE0 || d.epi == EPI_MERGE1 || d.epi == EPI_MERGE2) {
;         const u32x4 gw = *(const u32x4*)(d.gate + (size_t)row * NPG + col);
;         v0 *= sigm4(gw.x, gw.y); v1 *= sigm4(gw.z, gw.w);
;         bf16_t* mp = (bf16_t*)d.o0 + (size_t)row * DM + col;
.LBB0_585:
	s_andn2_b64 vcc, exec, s[74:75]
	s_cbranch_vccnz .LBB0_590
	v_ashrrev_i32_e32 v57, 31, v144
	v_mov_b32_e32 v56, v144
	v_lshl_add_u64 v[58:59], s[82:83], 0, v[72:73]
	v_lshlrev_b64 v[70:71], 1, v[56:57]
	v_lshl_add_u64 v[58:59], v[58:59], 0, v[70:71]
	global_load_dwordx4 v[58:61], v[58:59], off offset:256
	v_lshl_add_u64 v[78:79], v[76:77], 1, s[50:51]
	s_andn2_b64 vcc, exec, s[80:81]
	v_lshl_add_u64 v[70:71], v[78:79], 0, v[70:71]
	s_waitcnt vmcnt(0) lgkmcnt(0)
	v_lshlrev_b32_e32 v62, 16, v58
	v_and_b32_e32 v58, 0xffff0000, v58
	v_lshlrev_b32_e32 v63, 16, v59
	v_and_b32_e32 v59, 0xffff0000, v59
	v_lshlrev_b32_e32 v68, 16, v60
	v_and_b32_e32 v60, 0xffff0000, v60
	v_lshlrev_b32_e32 v69, 16, v61
	v_and_b32_e32 v61, 0xffff0000, v61
	v_mul_f32_e32 v62, 0xbfb8aa3b, v62
	v_mul_f32_e32 v58, 0xbfb8aa3b, v58
	v_mul_f32_e32 v63, 0xbfb8aa3b, v63
	v_mul_f32_e32 v59, 0xbfb8aa3b, v59
	v_mul_f32_e32 v68, 0xbfb8aa3b, v68
	v_mul_f32_e32 v60, 0xbfb8aa3b, v60
	v_mul_f32_e32 v69, 0xbfb8aa3b, v69
	v_mul_f32_e32 v61, 0xbfb8aa3b, v61
	v_exp_f32_e32 v62, v62
	v_exp_f32_e32 v58, v58
	v_exp_f32_e32 v63, v63
	v_exp_f32_e32 v59, v59
	v_exp_f32_e32 v68, v68
	v_exp_f32_e32 v60, v60
	v_exp_f32_e32 v69, v69
	v_exp_f32_e32 v61, v61
	v_add_f32_e32 v62, 1.0, v62
	v_add_f32_e32 v75, 1.0, v58
	v_add_f32_e32 v63, 1.0, v63
	v_add_f32_e32 v80, 1.0, v59
	v_add_f32_e32 v68, 1.0, v68
	v_add_f32_e32 v81, 1.0, v60
	v_add_f32_e32 v69, 1.0, v69
	v_add_f32_e32 v83, 1.0, v61
	v_rcp_f32_e32 v58, v62
	v_rcp_f32_e32 v59, v75
	v_rcp_f32_e32 v60, v63
	v_rcp_f32_e32 v61, v80
	v_rcp_f32_e32 v80, v68
	v_rcp_f32_e32 v82, v69
	v_rcp_f32_e32 v83, v83
	v_rcp_f32_e32 v81, v81
	v_pk_mul_f32 v[62:63], v[54:55], v[60:61]
	v_pk_mul_f32 v[68:69], v[52:53], v[58:59]
	v_pk_mul_f32 v[58:59], v[50:51], v[82:83]
	v_pk_mul_f32 v[60:61], v[48:49], v[80:81]
	s_cbranch_vccz .LBB0_799
	s_andn2_b64 vcc, exec, s[52:53]
	s_mov_b64 s[0:1], -1
	s_cbranch_vccz .LBB0_800

; __device__ __forceinline__ float bf_lo(unsigned w) { return __uint_as_float(w << 16); }
; __device__ __forceinline__ float bf_hi(unsigned w) { return __uint_as_float(w & 0xffff0000u); }
; __device__ __forceinline__ f32x4 sigm4(unsigned lo, unsigned hi) { f32x4 r; r[0] = sigm(bf_lo(lo)); r[1] = sigm(bf_hi(lo)); r[2] = sigm(bf_lo(hi)); r[3] = sigm(bf_hi(hi)); return r; }
; __device__ __forceinline__ u32x4 pack8(f32x4 v0, f32x4 v1) { u32x4 w; w.x = cvt_pk_bf16(v0[0], v0[1]); w.y = cvt_pk_bf16(v0[2], v0[3]); w.z = cvt_pk_bf16(v1[0], v1[1]); w.w = cvt_pk_bf16(v1[2], v1[3]); return w; }
; __device__ __forceinline__ void epi8(const Desc& d, int pb, int row, int col, f32x4 v0, f32x4 v1) {
;     ...
;     } else if (d.epi == EPI_MERGE0 || d.epi == EPI_MERGE1 || d.epi == EPI_MERGE2) {
;         const u32x4 gw = *(const u32x4*)(d.gate + (size_t)row * NPG + col);
;         v0 *= sigm4(gw.x, gw.y); v1 *= sigm4(gw.z, gw.w);
;         bf16_t* mp = (bf16_t*)d.o0 + (size_t)row * DM + col;
;         if (d.epi != EPI_MERGE0) { const u32x4 m = *(const u32x4*)mp;
;             v0 += (f32x4){bf_lo(m.x), bf_hi(m.x), bf_lo(m.y), bf_hi(m.y)}; v1 += (f32x4){bf_lo(m.z), bf_hi(m.z), bf_lo(m.w), bf_hi(m.w)}; }
;         if (d.epi != EPI_MERGE2) *(u32x4*)mp = pack8(v0, v1);
;         else *(u32x4*)((bf16_t*)d.o1 + (size_t)row * DM + col) = pack8(v0, v1);
.LBB0_589:
	v_cvt_pk_bf16_f32 v68, v68, v69
	v_cvt_pk_bf16_f32 v69, v62, v63
	v_cvt_pk_bf16_f32 v70, v60, v61
	v_cvt_pk_bf16_f32 v71, v58, v59
	v_lshl_add_u64 v[58:59], v[76:77], 1, s[84:85]
	v_lshl_add_u64 v[56:57], v[56:57], 1, v[58:59]
	global_store_dwordx4 v[56:57], v[68:71], off offset:256

; __device__ __forceinline__ u32x4 pack8(f32x4 v0, f32x4 v1) { u32x4 w; w.x = cvt_pk_bf16(v0[0], v0[1]); w.y = cvt_pk_bf16(v0[2], v0[3]); w.z = cvt_pk_bf16(v1[0], v1[1]); w.w = cvt_pk_bf16(v1[2], v1[3]); return w; }
; __device__ __forceinline__ void epi8(const Desc& d, int pb, int row, int col, f32x4 v0, f32x4 v1) {
;     ...
;     } else if (d.epi == EPI_BF16) {
;         *(u32x4*)((bf16_t*)d.o0 + (size_t)pb * d.sO + (size_t)row * d.ldc + col) = pack8(v0 * d.scale, v1 * d.scale);
.LBB0_591:
	s_andn2_b64 vcc, exec, s[74:75]
	s_cbranch_vccnz .LBB0_593
	s_mul_hi_i32 s1, s56, s93
	s_mul_i32 s0, s56, s93
	s_lshl_b64 s[0:1], s[0:1], 1
	s_add_u32 s0, s50, s0
	s_addc_u32 s1, s51, s1
	v_mad_i64_i32 v[60:61], s[42:43], s14, v74, 0
	v_lshl_add_u64 v[60:61], v[60:61], 1, s[0:1]
	v_ashrrev_i32_e32 v63, 31, v144
	v_mov_b32_e32 v62, v144
	v_lshl_add_u64 v[60:61], v[62:63], 1, v[60:61]
	v_cvt_pk_bf16_f32 v56, v52, v53
	v_cvt_pk_bf16_f32 v57, v54, v55
	v_cvt_pk_bf16_f32 v58, v48, v49
	v_cvt_pk_bf16_f32 v59, v50, v51
	global_store_dwordx4 v[60:61], v[56:59], off offset:256

; __device__ __forceinline__ u32x4 pack8(f32x4 v0, f32x4 v1) { u32x4 w; w.x = cvt_pk_bf16(v0[0], v0[1]); w.y = cvt_pk_bf16(v0[2], v0[3]); w.z = cvt_pk_bf16(v1[0], v1[1]); w.w = cvt_pk_bf16(v1[2], v1[3]); return w; }
; __device__ __forceinline__ void epi8(const Desc& d, int pb, int row, int col, f32x4 v0, f32x4 v1) {
;     if (d.epi == EPI_PIN) {
;         const int pn = col >> 8; bf16_t* p;
;         if (pn < 21) p = (bf16_t*)d.o0 + (size_t)row * NPA + col;
;         else if (pn == 21) p = (bf16_t*)d.o1 + (size_t)row * NKR + (col - 21 * 256);
;         else p = (bf16_t*)d.o2 + (size_t)row * NPG + (col - 22 * 256);
;         *(u32x4*)p = pack8(v0, v1);
.LBB0_602:
	v_cvt_pk_bf16_f32 v52, v52, v53
	v_cvt_pk_bf16_f32 v53, v54, v55
	v_cvt_pk_bf16_f32 v54, v48, v49
	v_cvt_pk_bf16_f32 v55, v50, v51
	global_store_dwordx4 v[56:57], v[52:55], off

; __device__ __forceinline__ void epi8(const Desc& d, int pb, int row, int col, f32x4 v0, f32x4 v1) {
;     ...
;     } else {
;         float* hp = (float*)d.o0 + (size_t)row * DM + col;
;         const float* rp = (row < LREAL ? (const float*)d.o2 + (size_t)row * DM : (const float*)d.gate + (size_t)(row - LREAL) * DM) + col;
;         v0 += *(const f32x4*)rp; v1 += *(const f32x4*)(rp + 4);
;         if (d.epi == EPI_RESID) { *(f32x4*)hp = v0; *(f32x4*)(hp + 4) = v1; }
;         else if (row < LREAL) { float* op = (float*)d.o1 + (size_t)row * DM + col; *(f32x4*)op = v0; *(f32x4*)(op + 4) = v1; }
.LBB0_607:
	s_cmp_lt_i32 s26, 2
	s_cbranch_scc1 .LBB0_622
	s_cmp_gt_i32 s26, 4
	s_cbranch_scc0 .LBB0_616
	v_lshl_add_u64 v[48:49], v[60:61], 2, s[86:87]
	v_lshl_add_u64 v[50:51], s[82:83], 0, v[62:63]
	v_ashrrev_i32_e32 v65, 31, v144
	v_mov_b32_e32 v64, v144
	v_cndmask_b32_e64 v49, v51, v49, s[0:1]
	v_cndmask_b32_e64 v48, v50, v48, s[0:1]
	v_lshl_add_u64 v[52:53], v[64:65], 2, v[48:49]
	global_load_dwordx4 v[48:51], v[52:53], off
	s_nop 0
	global_load_dwordx4 v[52:55], v[52:53], off offset:16
	s_andn2_b64 vcc, exec, s[64:65]
	s_waitcnt vmcnt(0) lgkmcnt(0)
	v_pk_add_f32 v[50:51], v[46:47], v[50:51]
	v_pk_add_f32 v[48:49], v[44:45], v[48:49]
	v_pk_add_f32 v[54:55], v[42:43], v[54:55]
	v_pk_add_f32 v[52:53], v[40:41], v[52:53]
	s_cbranch_vccnz .LBB0_613
	s_and_saveexec_b64 s[74:75], s[0:1]
	s_cbranch_execz .LBB0_612
	v_lshl_add_u64 v[66:67], v[60:61], 2, s[84:85]
	v_lshl_add_u64 v[66:67], v[64:65], 2, v[66:67]
	global_store_dwordx4 v[66:67], v[48:51], off
	global_store_dwordx4 v[66:67], v[52:55], off offset:16

; __device__ __forceinline__ void epi8(const Desc& d, int pb, int row, int col, f32x4 v0, f32x4 v1) {
;     ...
;     } else {
;         float* hp = (float*)d.o0 + (size_t)row * DM + col;
;         const float* rp = (row < LREAL ? (const float*)d.o2 + (size_t)row * DM : (const float*)d.gate + (size_t)(row - LREAL) * DM) + col;
;         v0 += *(const f32x4*)rp; v1 += *(const f32x4*)(rp + 4);
;         if (d.epi == EPI_RESID) { *(f32x4*)hp = v0; *(f32x4*)(hp + 4) = v1; }
;         else if (row < LREAL) { float* op = (float*)d.o1 + (size_t)row * DM + col; *(f32x4*)op = v0; *(f32x4*)(op + 4) = v1; }
.LBB0_613:
	s_andn2_b64 vcc, exec, s[74:75]
	s_cbranch_vccnz .LBB0_615
	v_lshl_add_u64 v[66:67], v[60:61], 2, s[50:51]
	v_lshl_add_u64 v[64:65], v[64:65], 2, v[66:67]
	global_store_dwordx4 v[64:65], v[48:51], off
	global_store_dwordx4 v[64:65], v[52:55], off offset:16

; __device__ __forceinline__ float bf_lo(unsigned w) { return __uint_as_float(w << 16); }
; __device__ __forceinline__ float bf_hi(unsigned w) { return __uint_as_float(w & 0xffff0000u); }
; __device__ __forceinline__ float sigm(float x) { return __builtin_amdgcn_rcpf(1.f + __builtin_amdgcn_exp2f(-1.4426950408889634f * x)); }
; __device__ __forceinline__ f32x4 sigm4(unsigned lo, unsigned hi) { f32x4 r; r[0] = sigm(bf_lo(lo)); r[1] = sigm(bf_hi(lo)); r[2] = sigm(bf_lo(hi)); r[3] = sigm(bf_hi(hi)); return r; }
; __device__ __forceinline__ void epi8(const Desc& d, int pb, int row, int col, f32x4 v0, f32x4 v1) {
;     ...
;     } else if (d.epi == EPI_MERGE0 || d.epi == EPI_MERGE1 || d.epi == EPI_MERGE2) {
;         const u32x4 gw = *(const u32x4*)(d.gate + (size_t)row * NPG + col);
;         v0 *= sigm4(gw.x, gw.y); v1 *= sigm4(gw.z, gw.w);
;         bf16_t* mp = (bf16_t*)d.o0 + (size_t)row * DM + col;
;         if (d.epi != EPI_MERGE0) { const u32x4 m = *(const u32x4*)mp;
;             v0 += (f32x4){bf_lo(m.x), bf_hi(m.x), bf_lo(m.y), bf_hi(m.y)}; v1 += (f32x4){bf_lo(m.z), bf_hi(m.z), bf_lo(m.w), bf_hi(m.w)}; }
.LBB0_616:
	s_andn2_b64 vcc, exec, s[74:75]
	s_cbranch_vccnz .LBB0_621
	v_ashrrev_i32_e32 v49, 31, v144
	v_mov_b32_e32 v48, v144
	v_lshl_add_u64 v[50:51], s[82:83], 0, v[56:57]
	v_lshlrev_b64 v[66:67], 1, v[48:49]
	v_lshl_add_u64 v[50:51], v[50:51], 0, v[66:67]
	global_load_dwordx4 v[50:53], v[50:51], off
	v_lshl_add_u64 v[68:69], v[60:61], 1, s[50:51]
	s_andn2_b64 vcc, exec, s[80:81]
	v_lshl_add_u64 v[66:67], v[68:69], 0, v[66:67]
	s_waitcnt vmcnt(0) lgkmcnt(0)
	v_lshlrev_b32_e32 v54, 16, v50
	v_and_b32_e32 v50, 0xffff0000, v50
	v_lshlrev_b32_e32 v55, 16, v51
	v_and_b32_e32 v51, 0xffff0000, v51
	v_lshlrev_b32_e32 v64, 16, v52
	v_and_b32_e32 v52, 0xffff0000, v52
	v_lshlrev_b32_e32 v65, 16, v53
	v_and_b32_e32 v53, 0xffff0000, v53
	v_mul_f32_e32 v54, 0xbfb8aa3b, v54
	v_mul_f32_e32 v50, 0xbfb8aa3b, v50
	v_mul_f32_e32 v55, 0xbfb8aa3b, v55
	v_mul_f32_e32 v51, 0xbfb8aa3b, v51
	v_mul_f32_e32 v64, 0xbfb8aa3b, v64
	v_mul_f32_e32 v52, 0xbfb8aa3b, v52
	v_mul_f32_e32 v65, 0xbfb8aa3b, v65
	v_mul_f32_e32 v53, 0xbfb8aa3b, v53
	v_exp_f32_e32 v54, v54
	v_exp_f32_e32 v50, v50
	v_exp_f32_e32 v55, v55
	v_exp_f32_e32 v51, v51
	v_exp_f32_e32 v64, v64
	v_exp_f32_e32 v52, v52
	v_exp_f32_e32 v65, v65
	v_exp_f32_e32 v53, v53
	v_add_f32_e32 v54, 1.0, v54
	v_add_f32_e32 v70, 1.0, v50
	v_add_f32_e32 v55, 1.0, v55
	v_add_f32_e32 v71, 1.0, v51
	v_add_f32_e32 v64, 1.0, v64
	v_add_f32_e32 v74, 1.0, v52
	v_add_f32_e32 v65, 1.0, v65
	v_add_f32_e32 v73, 1.0, v53
	v_rcp_f32_e32 v50, v54
	v_rcp_f32_e32 v51, v70
	v_rcp_f32_e32 v52, v55
	v_rcp_f32_e32 v53, v71
	v_rcp_f32_e32 v70, v64
	v_rcp_f32_e32 v72, v65
	v_rcp_f32_e32 v73, v73
	v_rcp_f32_e32 v71, v74
	v_pk_mul_f32 v[54:55], v[46:47], v[52:53]
	v_pk_mul_f32 v[64:65], v[44:45], v[50:51]
	v_pk_mul_f32 v[50:51], v[42:43], v[72:73]
	v_pk_mul_f32 v[52:53], v[40:41], v[70:71]
	s_cbranch_vccz .LBB0_801
	s_andn2_b64 vcc, exec, s[52:53]
	s_mov_b64 s[74:75], -1
	s_cbranch_vccz .LBB0_802

; __device__ __forceinline__ u32x4 pack8(f32x4 v0, f32x4 v1) { u32x4 w; w.x = cvt_pk_bf16(v0[0], v0[1]); w.y = cvt_pk_bf16(v0[2], v0[3]); w.z = cvt_pk_bf16(v1[0], v1[1]); w.w = cvt_pk_bf16(v1[2], v1[3]); return w; }
; __device__ __forceinline__ void epi8(const Desc& d, int pb, int row, int col, f32x4 v0, f32x4 v1) {
;     ...
;         if (d.epi != EPI_MERGE2) *(u32x4*)mp = pack8(v0, v1);
;         else *(u32x4*)((bf16_t*)d.o1 + (size_t)row * DM + col) = pack8(v0, v1);
.LBB0_620:
	v_cvt_pk_bf16_f32 v64, v64, v65
	v_cvt_pk_bf16_f32 v65, v54, v55
	v_cvt_pk_bf16_f32 v66, v52, v53
	v_cvt_pk_bf16_f32 v67, v50, v51
	v_lshl_add_u64 v[50:51], v[60:61], 1, s[84:85]
	v_lshl_add_u64 v[48:49], v[48:49], 1, v[50:51]
	global_store_dwordx4 v[48:49], v[64:67], off

; __device__ __forceinline__ u32x4 pack8(f32x4 v0, f32x4 v1) { u32x4 w; w.x = cvt_pk_bf16(v0[0], v0[1]); w.y = cvt_pk_bf16(v0[2], v0[3]); w.z = cvt_pk_bf16(v1[0], v1[1]); w.w = cvt_pk_bf16(v1[2], v1[3]); return w; }
; __device__ __forceinline__ void epi8(const Desc& d, int pb, int row, int col, f32x4 v0, f32x4 v1) {
;     ...
;     } else if (d.epi == EPI_BF16) {
;         *(u32x4*)((bf16_t*)d.o0 + (size_t)pb * d.sO + (size_t)row * d.ldc + col) = pack8(v0 * d.scale, v1 * d.scale);
.LBB0_622:
	s_andn2_b64 vcc, exec, s[74:75]
	s_cbranch_vccnz .LBB0_624
	s_mul_hi_i32 s43, s56, s93
	s_mul_i32 s42, s56, s93
	s_lshl_b64 s[42:43], s[42:43], 1
	s_add_u32 s42, s50, s42
	s_addc_u32 s43, s51, s43
	v_mad_i64_i32 v[52:53], s[74:75], s14, v58, 0
	v_lshl_add_u64 v[52:53], v[52:53], 1, s[42:43]
	v_ashrrev_i32_e32 v55, 31, v144
	v_mov_b32_e32 v54, v144
	v_lshl_add_u64 v[52:53], v[54:55], 1, v[52:53]
	v_cvt_pk_bf16_f32 v48, v44, v45
	v_cvt_pk_bf16_f32 v49, v46, v47
	v_cvt_pk_bf16_f32 v50, v40, v41
	v_cvt_pk_bf16_f32 v51, v42, v43
	global_store_dwordx4 v[52:53], v[48:51], off

; __device__ __forceinline__ u32x4 pack8(f32x4 v0, f32x4 v1) { u32x4 w; w.x = cvt_pk_bf16(v0[0], v0[1]); w.y = cvt_pk_bf16(v0[2], v0[3]); w.z = cvt_pk_bf16(v1[0], v1[1]); w.w = cvt_pk_bf16(v1[2], v1[3]); return w; }
; __device__ __forceinline__ void epi8(const Desc& d, int pb, int row, int col, f32x4 v0, f32x4 v1) {
;     if (d.epi == EPI_PIN) {
;         const int pn = col >> 8; bf16_t* p;
;         if (pn < 21) p = (bf16_t*)d.o0 + (size_t)row * NPA + col;
;         else if (pn == 21) p = (bf16_t*)d.o1 + (size_t)row * NKR + (col - 21 * 256);
;         else p = (bf16_t*)d.o2 + (size_t)row * NPG + (col - 22 * 256);
;         *(u32x4*)p = pack8(v0, v1);
;     ...
;     } else {
;         float* hp = (float*)d.o0 + (size_t)row * DM + col;
;         const float* rp = (row < LREAL ? (const float*)d.o2 + (size_t)row * DM : (const float*)d.gate + (size_t)(row - LREAL) * DM) + col;
;         v0 += *(const f32x4*)rp; v1 += *(const f32x4*)(rp + 4);
;         if (d.epi == EPI_RESID) { *(f32x4*)hp = v0; *(f32x4*)(hp + 4) = v1; }
;         else if (row < LREAL) { float* op = (float*)d.o1 + (size_t)row * DM + col; *(f32x4*)op = v0; *(f32x4*)(op + 4) = v1; }
.LBB0_633:
	v_cvt_pk_bf16_f32 v44, v44, v45
	v_cvt_pk_bf16_f32 v45, v46, v47
	v_cvt_pk_bf16_f32 v46, v40, v41
	v_cvt_pk_bf16_f32 v47, v42, v43
	global_store_dwordx4 v[52:53], v[44:47], off
	s_cmp_lt_i32 s26, 1
	s_mov_b64 s[74:75], -1
	s_cbranch_scc1 .LBB0_606
.LBB0_634:
	s_cmp_lt_i32 s26, 2
	s_cbranch_scc1 .LBB0_649
	s_cmp_gt_i32 s26, 4
	s_cbranch_scc0 .LBB0_643
	v_lshl_add_u64 v[40:41], v[60:61], 2, s[86:87]
	v_lshl_add_u64 v[42:43], s[82:83], 0, v[62:63]
	v_cndmask_b32_e64 v41, v43, v41, s[0:1]
	v_cndmask_b32_e64 v40, v42, v40, s[0:1]
	v_ashrrev_i32_e32 v53, 31, v144
	v_mov_b32_e32 v52, v144
	v_lshl_add_u64 v[44:45], v[52:53], 2, v[40:41]
	global_load_dwordx4 v[40:43], v[44:45], off offset:512
	s_nop 0
	global_load_dwordx4 v[44:47], v[44:45], off offset:528
	s_andn2_b64 vcc, exec, s[64:65]
	s_waitcnt vmcnt(0) lgkmcnt(0)
	v_pk_add_f32 v[42:43], v[38:39], v[42:43]
	v_pk_add_f32 v[40:41], v[36:37], v[40:41]
	v_pk_add_f32 v[46:47], v[34:35], v[46:47]
	v_pk_add_f32 v[44:45], v[32:33], v[44:45]
	s_cbranch_vccnz .LBB0_640
	s_and_saveexec_b64 s[74:75], s[0:1]
	s_cbranch_execz .LBB0_639
	v_lshl_add_u64 v[54:55], v[60:61], 2, s[84:85]
	v_lshl_add_u64 v[54:55], v[52:53], 2, v[54:55]
	global_store_dwordx4 v[54:55], v[40:43], off offset:512
	global_store_dwordx4 v[54:55], v[44:47], off offset:528

; __device__ __forceinline__ void epi8(const Desc& d, int pb, int row, int col, f32x4 v0, f32x4 v1) {
;     ...
;     } else {
;         float* hp = (float*)d.o0 + (size_t)row * DM + col;
;         const float* rp = (row < LREAL ? (const float*)d.o2 + (size_t)row * DM : (const float*)d.gate + (size_t)(row - LREAL) * DM) + col;
;         v0 += *(const f32x4*)rp; v1 += *(const f32x4*)(rp + 4);
;         if (d.epi == EPI_RESID) { *(f32x4*)hp = v0; *(f32x4*)(hp + 4) = v1; }
;         else if (row < LREAL) { float* op = (float*)d.o1 + (size_t)row * DM + col; *(f32x4*)op = v0; *(f32x4*)(op + 4) = v1; }
.LBB0_640:
	s_andn2_b64 vcc, exec, s[74:75]
	s_cbranch_vccnz .LBB0_642
	v_lshl_add_u64 v[54:55], v[60:61], 2, s[50:51]
	v_lshl_add_u64 v[52:53], v[52:53], 2, v[54:55]
	global_store_dwordx4 v[52:53], v[40:43], off offset:512
	global_store_dwordx4 v[52:53], v[44:47], off offset:528

; __device__ __forceinline__ float bf_lo(unsigned w) { return __uint_as_float(w << 16); }
; __device__ __forceinline__ float bf_hi(unsigned w) { return __uint_as_float(w & 0xffff0000u); }
; __device__ __forceinline__ float sigm(float x) { return __builtin_amdgcn_rcpf(1.f + __builtin_amdgcn_exp2f(-1.4426950408889634f * x)); }
; __device__ __forceinline__ f32x4 sigm4(unsigned lo, unsigned hi) { f32x4 r; r[0] = sigm(bf_lo(lo)); r[1] = sigm(bf_hi(lo)); r[2] = sigm(bf_lo(hi)); r[3] = sigm(bf_hi(hi)); return r; }
; __device__ __forceinline__ void epi8(const Desc& d, int pb, int row, int col, f32x4 v0, f32x4 v1) {
;     ...
;     } else if (d.epi == EPI_MERGE0 || d.epi == EPI_MERGE1 || d.epi == EPI_MERGE2) {
;         const u32x4 gw = *(const u32x4*)(d.gate + (size_t)row * NPG + col);
;         v0 *= sigm4(gw.x, gw.y); v1 *= sigm4(gw.z, gw.w);
;         bf16_t* mp = (bf16_t*)d.o0 + (size_t)row * DM + col;
;         if (d.epi != EPI_MERGE0) { const u32x4 m = *(const u32x4*)mp;
;             v0 += (f32x4){bf_lo(m.x), bf_hi(m.x), bf_lo(m.y), bf_hi(m.y)}; v1 += (f32x4){bf_lo(m.z), bf_hi(m.z), bf_lo(m.w), bf_hi(m.w)}; }
.LBB0_643:
	s_andn2_b64 vcc, exec, s[74:75]
	s_cbranch_vccnz .LBB0_648
	v_ashrrev_i32_e32 v41, 31, v144
	v_mov_b32_e32 v40, v144
	v_lshl_add_u64 v[42:43], s[82:83], 0, v[56:57]
	v_lshlrev_b64 v[54:55], 1, v[40:41]
	v_lshl_add_u64 v[42:43], v[42:43], 0, v[54:55]
	global_load_dwordx4 v[42:45], v[42:43], off offset:256
	v_lshl_add_u64 v[62:63], v[60:61], 1, s[50:51]
	s_andn2_b64 vcc, exec, s[80:81]
	v_lshl_add_u64 v[54:55], v[62:63], 0, v[54:55]
	s_waitcnt vmcnt(0) lgkmcnt(0)
	v_lshlrev_b32_e32 v46, 16, v42
	v_and_b32_e32 v42, 0xffff0000, v42
	v_lshlrev_b32_e32 v47, 16, v43
	v_and_b32_e32 v43, 0xffff0000, v43
	v_lshlrev_b32_e32 v52, 16, v44
	v_and_b32_e32 v44, 0xffff0000, v44
	v_lshlrev_b32_e32 v53, 16, v45
	v_and_b32_e32 v45, 0xffff0000, v45
	v_mul_f32_e32 v46, 0xbfb8aa3b, v46
	v_mul_f32_e32 v42, 0xbfb8aa3b, v42
	v_mul_f32_e32 v47, 0xbfb8aa3b, v47
	v_mul_f32_e32 v43, 0xbfb8aa3b, v43
	v_mul_f32_e32 v52, 0xbfb8aa3b, v52
	v_mul_f32_e32 v44, 0xbfb8aa3b, v44
	v_mul_f32_e32 v53, 0xbfb8aa3b, v53
	v_mul_f32_e32 v45, 0xbfb8aa3b, v45
	v_exp_f32_e32 v46, v46
	v_exp_f32_e32 v42, v42
	v_exp_f32_e32 v47, v47
	v_exp_f32_e32 v43, v43
	v_exp_f32_e32 v52, v52
	v_exp_f32_e32 v44, v44
	v_exp_f32_e32 v53, v53
	v_exp_f32_e32 v45, v45
	v_add_f32_e32 v46, 1.0, v46
	v_add_f32_e32 v59, 1.0, v42
	v_add_f32_e32 v47, 1.0, v47
	v_add_f32_e32 v64, 1.0, v43
	v_add_f32_e32 v52, 1.0, v52
	v_add_f32_e32 v65, 1.0, v44
	v_add_f32_e32 v53, 1.0, v53
	v_add_f32_e32 v67, 1.0, v45
	v_rcp_f32_e32 v42, v46
	v_rcp_f32_e32 v43, v59
	v_rcp_f32_e32 v44, v47
	v_rcp_f32_e32 v45, v64
	v_rcp_f32_e32 v64, v52
	v_rcp_f32_e32 v66, v53
	v_rcp_f32_e32 v67, v67
	v_rcp_f32_e32 v65, v65
	v_pk_mul_f32 v[46:47], v[38:39], v[44:45]
	v_pk_mul_f32 v[52:53], v[36:37], v[42:43]
	v_pk_mul_f32 v[42:43], v[34:35], v[66:67]
	v_pk_mul_f32 v[44:45], v[32:33], v[64:65]
	s_cbranch_vccz .LBB0_803
	s_andn2_b64 vcc, exec, s[52:53]
	s_mov_b64 s[0:1], -1
	s_cbranch_vccz .LBB0_804

; __device__ __forceinline__ u32x4 pack8(f32x4 v0, f32x4 v1) { u32x4 w; w.x = cvt_pk_bf16(v0[0], v0[1]); w.y = cvt_pk_bf16(v0[2], v0[3]); w.z = cvt_pk_bf16(v1[0], v1[1]); w.w = cvt_pk_bf16(v1[2], v1[3]); return w; }
; __device__ __forceinline__ void epi8(const Desc& d, int pb, int row, int col, f32x4 v0, f32x4 v1) {
;     ...
;         if (d.epi != EPI_MERGE2) *(u32x4*)mp = pack8(v0, v1);
;         else *(u32x4*)((bf16_t*)d.o1 + (size_t)row * DM + col) = pack8(v0, v1);
.LBB0_647:
	v_cvt_pk_bf16_f32 v52, v52, v53
	v_cvt_pk_bf16_f32 v53, v46, v47
	v_cvt_pk_bf16_f32 v54, v44, v45
	v_cvt_pk_bf16_f32 v55, v42, v43
	v_lshl_add_u64 v[42:43], v[60:61], 1, s[84:85]
	v_lshl_add_u64 v[40:41], v[40:41], 1, v[42:43]
	global_store_dwordx4 v[40:41], v[52:55], off offset:256

; __device__ __forceinline__ u32x4 pack8(f32x4 v0, f32x4 v1) { u32x4 w; w.x = cvt_pk_bf16(v0[0], v0[1]); w.y = cvt_pk_bf16(v0[2], v0[3]); w.z = cvt_pk_bf16(v1[0], v1[1]); w.w = cvt_pk_bf16(v1[2], v1[3]); return w; }
; __device__ __forceinline__ void epi8(const Desc& d, int pb, int row, int col, f32x4 v0, f32x4 v1) {
;     ...
;     } else if (d.epi == EPI_BF16) {
;         *(u32x4*)((bf16_t*)d.o0 + (size_t)pb * d.sO + (size_t)row * d.ldc + col) = pack8(v0 * d.scale, v1 * d.scale);
.LBB0_649:
	s_andn2_b64 vcc, exec, s[74:75]
	s_cbranch_vccnz .LBB0_651
	s_mul_hi_i32 s1, s56, s93
	s_mul_i32 s0, s56, s93
	s_lshl_b64 s[0:1], s[0:1], 1
	s_add_u32 s0, s50, s0
	s_addc_u32 s1, s51, s1
	v_mad_i64_i32 v[44:45], s[42:43], s14, v58, 0
	v_lshl_add_u64 v[44:45], v[44:45], 1, s[0:1]
	v_ashrrev_i32_e32 v47, 31, v144
	v_mov_b32_e32 v46, v144
	v_lshl_add_u64 v[44:45], v[46:47], 1, v[44:45]
	v_cvt_pk_bf16_f32 v40, v36, v37
	v_cvt_pk_bf16_f32 v41, v38, v39
	v_cvt_pk_bf16_f32 v42, v32, v33
	v_cvt_pk_bf16_f32 v43, v34, v35
	global_store_dwordx4 v[44:45], v[40:43], off offset:256

; __device__ __forceinline__ u32x4 pack8(f32x4 v0, f32x4 v1) { u32x4 w; w.x = cvt_pk_bf16(v0[0], v0[1]); w.y = cvt_pk_bf16(v0[2], v0[3]); w.z = cvt_pk_bf16(v1[0], v1[1]); w.w = cvt_pk_bf16(v1[2], v1[3]); return w; }
; __device__ __forceinline__ void epi8(const Desc& d, int pb, int row, int col, f32x4 v0, f32x4 v1) {
;     if (d.epi == EPI_PIN) {
;         const int pn = col >> 8; bf16_t* p;
;         if (pn < 21) p = (bf16_t*)d.o0 + (size_t)row * NPA + col;
;         else if (pn == 21) p = (bf16_t*)d.o1 + (size_t)row * NKR + (col - 21 * 256);
;         else p = (bf16_t*)d.o2 + (size_t)row * NPG + (col - 22 * 256);
;         *(u32x4*)p = pack8(v0, v1);
.LBB0_660:
	v_cvt_pk_bf16_f32 v36, v36, v37
	v_cvt_pk_bf16_f32 v37, v38, v39
	v_cvt_pk_bf16_f32 v38, v32, v33
	v_cvt_pk_bf16_f32 v39, v34, v35
	global_store_dwordx4 v[40:41], v[36:39], off

; __device__ __forceinline__ void epi8(const Desc& d, int pb, int row, int col, f32x4 v0, f32x4 v1) {
;     ...
;     } else {
;         float* hp = (float*)d.o0 + (size_t)row * DM + col;
;         const float* rp = (row < LREAL ? (const float*)d.o2 + (size_t)row * DM : (const float*)d.gate + (size_t)(row - LREAL) * DM) + col;
;         v0 += *(const f32x4*)rp; v1 += *(const f32x4*)(rp + 4);
;         if (d.epi == EPI_RESID) { *(f32x4*)hp = v0; *(f32x4*)(hp + 4) = v1; }
;         else if (row < LREAL) { float* op = (float*)d.o1 + (size_t)row * DM + col; *(f32x4*)op = v0; *(f32x4*)(op + 4) = v1; }
.LBB0_665:
	s_cmp_lt_i32 s26, 2
	s_cbranch_scc1 .LBB0_680
	s_cmp_gt_i32 s26, 4
	s_cbranch_scc0 .LBB0_674
	v_lshl_add_u64 v[32:33], v[44:45], 2, s[86:87]
	v_lshl_add_u64 v[34:35], s[82:83], 0, v[46:47]
	v_ashrrev_i32_e32 v49, 31, v144
	v_mov_b32_e32 v48, v144
	v_cndmask_b32_e64 v33, v35, v33, s[0:1]
	v_cndmask_b32_e64 v32, v34, v32, s[0:1]
	v_lshl_add_u64 v[36:37], v[48:49], 2, v[32:33]
	global_load_dwordx4 v[32:35], v[36:37], off
	s_nop 0
	global_load_dwordx4 v[36:39], v[36:37], off offset:16
	s_andn2_b64 vcc, exec, s[64:65]
	s_waitcnt vmcnt(0) lgkmcnt(0)
	v_pk_add_f32 v[34:35], v[30:31], v[34:35]
	v_pk_add_f32 v[32:33], v[28:29], v[32:33]
	v_pk_add_f32 v[38:39], v[26:27], v[38:39]
	v_pk_add_f32 v[36:37], v[24:25], v[36:37]
	s_cbranch_vccnz .LBB0_671
	s_and_saveexec_b64 s[74:75], s[0:1]
	s_cbranch_execz .LBB0_670
	v_lshl_add_u64 v[50:51], v[44:45], 2, s[84:85]
	v_lshl_add_u64 v[50:51], v[48:49], 2, v[50:51]
	global_store_dwordx4 v[50:51], v[32:35], off
	global_store_dwordx4 v[50:51], v[36:39], off offset:16

; __device__ __forceinline__ void epi8(const Desc& d, int pb, int row, int col, f32x4 v0, f32x4 v1) {
;     ...
;     } else {
;         float* hp = (float*)d.o0 + (size_t)row * DM + col;
;         const float* rp = (row < LREAL ? (const float*)d.o2 + (size_t)row * DM : (const float*)d.gate + (size_t)(row - LREAL) * DM) + col;
;         v0 += *(const f32x4*)rp; v1 += *(const f32x4*)(rp + 4);
;         if (d.epi == EPI_RESID) { *(f32x4*)hp = v0; *(f32x4*)(hp + 4) = v1; }
;         else if (row < LREAL) { float* op = (float*)d.o1 + (size_t)row * DM + col; *(f32x4*)op = v0; *(f32x4*)(op + 4) = v1; }
.LBB0_671:
	s_andn2_b64 vcc, exec, s[74:75]
	s_cbranch_vccnz .LBB0_673
	v_lshl_add_u64 v[50:51], v[44:45], 2, s[50:51]
	v_lshl_add_u64 v[48:49], v[48:49], 2, v[50:51]
	global_store_dwordx4 v[48:49], v[32:35], off
	global_store_dwordx4 v[48:49], v[36:39], off offset:16

; __device__ __forceinline__ float bf_lo(unsigned w) { return __uint_as_float(w << 16); }
; __device__ __forceinline__ float bf_hi(unsigned w) { return __uint_as_float(w & 0xffff0000u); }
; __device__ __forceinline__ float sigm(float x) { return __builtin_amdgcn_rcpf(1.f + __builtin_amdgcn_exp2f(-1.4426950408889634f * x)); }
; __device__ __forceinline__ f32x4 sigm4(unsigned lo, unsigned hi) { f32x4 r; r[0] = sigm(bf_lo(lo)); r[1] = sigm(bf_hi(lo)); r[2] = sigm(bf_lo(hi)); r[3] = sigm(bf_hi(hi)); return r; }
; __device__ __forceinline__ void epi8(const Desc& d, int pb, int row, int col, f32x4 v0, f32x4 v1) {
;     ...
;     } else if (d.epi == EPI_MERGE0 || d.epi == EPI_MERGE1 || d.epi == EPI_MERGE2) {
;         const u32x4 gw = *(const u32x4*)(d.gate + (size_t)row * NPG + col);
;         v0 *= sigm4(gw.x, gw.y); v1 *= sigm4(gw.z, gw.w);
;         bf16_t* mp = (bf16_t*)d.o0 + (size_t)row * DM + col;
;         if (d.epi != EPI_MERGE0) { const u32x4 m = *(const u32x4*)mp;
;             v0 += (f32x4){bf_lo(m.x), bf_hi(m.x), bf_lo(m.y), bf_hi(m.y)}; v1 += (f32x4){bf_lo(m.z), bf_hi(m.z), bf_lo(m.w), bf_hi(m.w)}; }
.LBB0_674:
	s_andn2_b64 vcc, exec, s[74:75]
	s_cbranch_vccnz .LBB0_679
	v_ashrrev_i32_e32 v33, 31, v144
	v_mov_b32_e32 v32, v144
	v_lshl_add_u64 v[34:35], s[82:83], 0, v[40:41]
	v_lshlrev_b64 v[50:51], 1, v[32:33]
	v_lshl_add_u64 v[34:35], v[34:35], 0, v[50:51]
	global_load_dwordx4 v[34:37], v[34:35], off
	v_lshl_add_u64 v[52:53], v[44:45], 1, s[50:51]
	s_andn2_b64 vcc, exec, s[80:81]
	v_lshl_add_u64 v[50:51], v[52:53], 0, v[50:51]
	s_waitcnt vmcnt(0) lgkmcnt(0)
	v_lshlrev_b32_e32 v38, 16, v34
	v_and_b32_e32 v34, 0xffff0000, v34
	v_lshlrev_b32_e32 v39, 16, v35
	v_and_b32_e32 v35, 0xffff0000, v35
	v_lshlrev_b32_e32 v48, 16, v36
	v_and_b32_e32 v36, 0xffff0000, v36
	v_lshlrev_b32_e32 v49, 16, v37
	v_and_b32_e32 v37, 0xffff0000, v37
	v_mul_f32_e32 v38, 0xbfb8aa3b, v38
	v_mul_f32_e32 v34, 0xbfb8aa3b, v34
	v_mul_f32_e32 v39, 0xbfb8aa3b, v39
	v_mul_f32_e32 v35, 0xbfb8aa3b, v35
	v_mul_f32_e32 v48, 0xbfb8aa3b, v48
	v_mul_f32_e32 v36, 0xbfb8aa3b, v36
	v_mul_f32_e32 v49, 0xbfb8aa3b, v49
	v_mul_f32_e32 v37, 0xbfb8aa3b, v37
	v_exp_f32_e32 v38, v38
	v_exp_f32_e32 v34, v34
	v_exp_f32_e32 v39, v39
	v_exp_f32_e32 v35, v35
	v_exp_f32_e32 v48, v48
	v_exp_f32_e32 v36, v36
	v_exp_f32_e32 v49, v49
	v_exp_f32_e32 v37, v37
	v_add_f32_e32 v38, 1.0, v38
	v_add_f32_e32 v54, 1.0, v34
	v_add_f32_e32 v39, 1.0, v39
	v_add_f32_e32 v55, 1.0, v35
	v_add_f32_e32 v48, 1.0, v48
	v_add_f32_e32 v58, 1.0, v36
	v_add_f32_e32 v49, 1.0, v49
	v_add_f32_e32 v57, 1.0, v37
	v_rcp_f32_e32 v34, v38
	v_rcp_f32_e32 v35, v54
	v_rcp_f32_e32 v36, v39
	v_rcp_f32_e32 v37, v55
	v_rcp_f32_e32 v54, v48
	v_rcp_f32_e32 v56, v49
	v_rcp_f32_e32 v57, v57
	v_rcp_f32_e32 v55, v58
	v_pk_mul_f32 v[38:39], v[30:31], v[36:37]
	v_pk_mul_f32 v[48:49], v[28:29], v[34:35]
	v_pk_mul_f32 v[34:35], v[26:27], v[56:57]
	v_pk_mul_f32 v[36:37], v[24:25], v[54:55]
	s_cbranch_vccz .LBB0_805
	s_andn2_b64 vcc, exec, s[52:53]
	s_mov_b64 s[74:75], -1
	s_cbranch_vccz .LBB0_806

; __device__ __forceinline__ u32x4 pack8(f32x4 v0, f32x4 v1) { u32x4 w; w.x = cvt_pk_bf16(v0[0], v0[1]); w.y = cvt_pk_bf16(v0[2], v0[3]); w.z = cvt_pk_bf16(v1[0], v1[1]); w.w = cvt_pk_bf16(v1[2], v1[3]); return w; }
; __device__ __forceinline__ void epi8(const Desc& d, int pb, int row, int col, f32x4 v0, f32x4 v1) {
;     ...
;         if (d.epi != EPI_MERGE2) *(u32x4*)mp = pack8(v0, v1);
;         else *(u32x4*)((bf16_t*)d.o1 + (size_t)row * DM + col) = pack8(v0, v1);
.LBB0_678:
	v_cvt_pk_bf16_f32 v48, v48, v49
	v_cvt_pk_bf16_f32 v49, v38, v39
	v_cvt_pk_bf16_f32 v50, v36, v37
	v_cvt_pk_bf16_f32 v51, v34, v35
	v_lshl_add_u64 v[34:35], v[44:45], 1, s[84:85]
	v_lshl_add_u64 v[32:33], v[32:33], 1, v[34:35]
	global_store_dwordx4 v[32:33], v[48:51], off

; __device__ __forceinline__ u32x4 pack8(f32x4 v0, f32x4 v1) { u32x4 w; w.x = cvt_pk_bf16(v0[0], v0[1]); w.y = cvt_pk_bf16(v0[2], v0[3]); w.z = cvt_pk_bf16(v1[0], v1[1]); w.w = cvt_pk_bf16(v1[2], v1[3]); return w; }
; __device__ __forceinline__ void epi8(const Desc& d, int pb, int row, int col, f32x4 v0, f32x4 v1) {
;     ...
;     } else if (d.epi == EPI_BF16) {
;         *(u32x4*)((bf16_t*)d.o0 + (size_t)pb * d.sO + (size_t)row * d.ldc + col) = pack8(v0 * d.scale, v1 * d.scale);
.LBB0_680:
	s_andn2_b64 vcc, exec, s[74:75]
	s_cbranch_vccnz .LBB0_682
	s_mul_hi_i32 s43, s56, s93
	s_mul_i32 s42, s56, s93
	s_lshl_b64 s[42:43], s[42:43], 1
	s_add_u32 s42, s50, s42
	s_addc_u32 s43, s51, s43
	v_mad_i64_i32 v[36:37], s[74:75], s14, v42, 0
	v_lshl_add_u64 v[36:37], v[36:37], 1, s[42:43]
	v_ashrrev_i32_e32 v39, 31, v144
	v_mov_b32_e32 v38, v144
	v_lshl_add_u64 v[36:37], v[38:39], 1, v[36:37]
	v_cvt_pk_bf16_f32 v32, v28, v29
	v_cvt_pk_bf16_f32 v33, v30, v31
	v_cvt_pk_bf16_f32 v34, v24, v25
	v_cvt_pk_bf16_f32 v35, v26, v27
	global_store_dwordx4 v[36:37], v[32:35], off

; __device__ __forceinline__ u32x4 pack8(f32x4 v0, f32x4 v1) { u32x4 w; w.x = cvt_pk_bf16(v0[0], v0[1]); w.y = cvt_pk_bf16(v0[2], v0[3]); w.z = cvt_pk_bf16(v1[0], v1[1]); w.w = cvt_pk_bf16(v1[2], v1[3]); return w; }
; __device__ __forceinline__ void epi8(const Desc& d, int pb, int row, int col, f32x4 v0, f32x4 v1) {
;     if (d.epi == EPI_PIN) {
;         const int pn = col >> 8; bf16_t* p;
;         if (pn < 21) p = (bf16_t*)d.o0 + (size_t)row * NPA + col;
;         else if (pn == 21) p = (bf16_t*)d.o1 + (size_t)row * NKR + (col - 21 * 256);
;         else p = (bf16_t*)d.o2 + (size_t)row * NPG + (col - 22 * 256);
;         *(u32x4*)p = pack8(v0, v1);
;     ...
;     } else {
;         float* hp = (float*)d.o0 + (size_t)row * DM + col;
;         const float* rp = (row < LREAL ? (const float*)d.o2 + (size_t)row * DM : (const float*)d.gate + (size_t)(row - LREAL) * DM) + col;
;         v0 += *(const f32x4*)rp; v1 += *(const f32x4*)(rp + 4);
;         if (d.epi == EPI_RESID) { *(f32x4*)hp = v0; *(f32x4*)(hp + 4) = v1; }
;         else if (row < LREAL) { float* op = (float*)d.o1 + (size_t)row * DM + col; *(f32x4*)op = v0; *(f32x4*)(op + 4) = v1; }
.LBB0_691:
	v_cvt_pk_bf16_f32 v28, v28, v29
	v_cvt_pk_bf16_f32 v29, v30, v31
	v_cvt_pk_bf16_f32 v30, v24, v25
	v_cvt_pk_bf16_f32 v31, v26, v27
	global_store_dwordx4 v[36:37], v[28:31], off
	s_cmp_lt_i32 s26, 1
	s_mov_b64 s[74:75], -1
	s_cbranch_scc1 .LBB0_664
.LBB0_692:
	s_cmp_lt_i32 s26, 2
	s_cbranch_scc1 .LBB0_707
	s_cmp_gt_i32 s26, 4
	s_cbranch_scc0 .LBB0_701
	v_lshl_add_u64 v[24:25], v[44:45], 2, s[86:87]
	v_lshl_add_u64 v[26:27], s[82:83], 0, v[46:47]
	v_cndmask_b32_e64 v25, v27, v25, s[0:1]
	v_cndmask_b32_e64 v24, v26, v24, s[0:1]
	v_ashrrev_i32_e32 v37, 31, v144
	v_mov_b32_e32 v36, v144
	v_lshl_add_u64 v[28:29], v[36:37], 2, v[24:25]
	global_load_dwordx4 v[24:27], v[28:29], off offset:512
	s_nop 0
	global_load_dwordx4 v[28:31], v[28:29], off offset:528
	s_andn2_b64 vcc, exec, s[64:65]
	s_waitcnt vmcnt(0) lgkmcnt(0)
	v_pk_add_f32 v[26:27], v[22:23], v[26:27]
	v_pk_add_f32 v[24:25], v[20:21], v[24:25]
	v_pk_add_f32 v[30:31], v[18:19], v[30:31]
	v_pk_add_f32 v[28:29], v[16:17], v[28:29]
	s_cbranch_vccnz .LBB0_698
	s_and_saveexec_b64 s[74:75], s[0:1]
	s_cbranch_execz .LBB0_697
	v_lshl_add_u64 v[38:39], v[44:45], 2, s[84:85]
	v_lshl_add_u64 v[38:39], v[36:37], 2, v[38:39]
	global_store_dwordx4 v[38:39], v[24:27], off offset:512
	global_store_dwordx4 v[38:39], v[28:31], off offset:528

; __device__ __forceinline__ void epi8(const Desc& d, int pb, int row, int col, f32x4 v0, f32x4 v1) {
;     ...
;     } else {
;         float* hp = (float*)d.o0 + (size_t)row * DM + col;
;         const float* rp = (row < LREAL ? (const float*)d.o2 + (size_t)row * DM : (const float*)d.gate + (size_t)(row - LREAL) * DM) + col;
;         v0 += *(const f32x4*)rp; v1 += *(const f32x4*)(rp + 4);
;         if (d.epi == EPI_RESID) { *(f32x4*)hp = v0; *(f32x4*)(hp + 4) = v1; }
;         else if (row < LREAL) { float* op = (float*)d.o1 + (size_t)row * DM + col; *(f32x4*)op = v0; *(f32x4*)(op + 4) = v1; }
.LBB0_698:
	s_andn2_b64 vcc, exec, s[74:75]
	s_cbranch_vccnz .LBB0_700
	v_lshl_add_u64 v[38:39], v[44:45], 2, s[50:51]
	v_lshl_add_u64 v[36:37], v[36:37], 2, v[38:39]
	global_store_dwordx4 v[36:37], v[24:27], off offset:512
	global_store_dwordx4 v[36:37], v[28:31], off offset:528

; __device__ __forceinline__ float bf_lo(unsigned w) { return __uint_as_float(w << 16); }
; __device__ __forceinline__ float bf_hi(unsigned w) { return __uint_as_float(w & 0xffff0000u); }
; __device__ __forceinline__ float sigm(float x) { return __builtin_amdgcn_rcpf(1.f + __builtin_amdgcn_exp2f(-1.4426950408889634f * x)); }
; __device__ __forceinline__ f32x4 sigm4(unsigned lo, unsigned hi) { f32x4 r; r[0] = sigm(bf_lo(lo)); r[1] = sigm(bf_hi(lo)); r[2] = sigm(bf_lo(hi)); r[3] = sigm(bf_hi(hi)); return r; }
; __device__ __forceinline__ void epi8(const Desc& d, int pb, int row, int col, f32x4 v0, f32x4 v1) {
;     ...
;     } else if (d.epi == EPI_MERGE0 || d.epi == EPI_MERGE1 || d.epi == EPI_MERGE2) {
;         const u32x4 gw = *(const u32x4*)(d.gate + (size_t)row * NPG + col);
;         v0 *= sigm4(gw.x, gw.y); v1 *= sigm4(gw.z, gw.w);
;         bf16_t* mp = (bf16_t*)d.o0 + (size_t)row * DM + col;
;         if (d.epi != EPI_MERGE0) { const u32x4 m = *(const u32x4*)mp;
;             v0 += (f32x4){bf_lo(m.x), bf_hi(m.x), bf_lo(m.y), bf_hi(m.y)}; v1 += (f32x4){bf_lo(m.z), bf_hi(m.z), bf_lo(m.w), bf_hi(m.w)}; }
.LBB0_701:
	s_andn2_b64 vcc, exec, s[74:75]
	s_cbranch_vccnz .LBB0_706
	v_ashrrev_i32_e32 v25, 31, v144
	v_mov_b32_e32 v24, v144
	v_lshl_add_u64 v[26:27], s[82:83], 0, v[40:41]
	v_lshlrev_b64 v[38:39], 1, v[24:25]
	v_lshl_add_u64 v[26:27], v[26:27], 0, v[38:39]
	global_load_dwordx4 v[26:29], v[26:27], off offset:256
	v_lshl_add_u64 v[46:47], v[44:45], 1, s[50:51]
	s_andn2_b64 vcc, exec, s[80:81]
	v_lshl_add_u64 v[38:39], v[46:47], 0, v[38:39]
	s_waitcnt vmcnt(0) lgkmcnt(0)
	v_lshlrev_b32_e32 v30, 16, v26
	v_and_b32_e32 v26, 0xffff0000, v26
	v_lshlrev_b32_e32 v31, 16, v27
	v_and_b32_e32 v27, 0xffff0000, v27
	v_lshlrev_b32_e32 v36, 16, v28
	v_and_b32_e32 v28, 0xffff0000, v28
	v_lshlrev_b32_e32 v37, 16, v29
	v_and_b32_e32 v29, 0xffff0000, v29
	v_mul_f32_e32 v30, 0xbfb8aa3b, v30
	v_mul_f32_e32 v26, 0xbfb8aa3b, v26
	v_mul_f32_e32 v31, 0xbfb8aa3b, v31
	v_mul_f32_e32 v27, 0xbfb8aa3b, v27
	v_mul_f32_e32 v36, 0xbfb8aa3b, v36
	v_mul_f32_e32 v28, 0xbfb8aa3b, v28
	v_mul_f32_e32 v37, 0xbfb8aa3b, v37
	v_mul_f32_e32 v29, 0xbfb8aa3b, v29
	v_exp_f32_e32 v30, v30
	v_exp_f32_e32 v26, v26
	v_exp_f32_e32 v31, v31
	v_exp_f32_e32 v27, v27
	v_exp_f32_e32 v36, v36
	v_exp_f32_e32 v28, v28
	v_exp_f32_e32 v37, v37
	v_exp_f32_e32 v29, v29
	v_add_f32_e32 v30, 1.0, v30
	v_add_f32_e32 v43, 1.0, v26
	v_add_f32_e32 v31, 1.0, v31
	v_add_f32_e32 v48, 1.0, v27
	v_add_f32_e32 v36, 1.0, v36
	v_add_f32_e32 v49, 1.0, v28
	v_add_f32_e32 v37, 1.0, v37
	v_add_f32_e32 v51, 1.0, v29
	v_rcp_f32_e32 v26, v30
	v_rcp_f32_e32 v27, v43
	v_rcp_f32_e32 v28, v31
	v_rcp_f32_e32 v29, v48
	v_rcp_f32_e32 v48, v36
	v_rcp_f32_e32 v50, v37
	v_rcp_f32_e32 v51, v51
	v_rcp_f32_e32 v49, v49
	v_pk_mul_f32 v[30:31], v[22:23], v[28:29]
	v_pk_mul_f32 v[36:37], v[20:21], v[26:27]
	v_pk_mul_f32 v[26:27], v[18:19], v[50:51]
	v_pk_mul_f32 v[28:29], v[16:17], v[48:49]
	s_cbranch_vccz .LBB0_807
	s_andn2_b64 vcc, exec, s[52:53]
	s_mov_b64 s[0:1], -1
	s_cbranch_vccz .LBB0_808

; __device__ __forceinline__ u32x4 pack8(f32x4 v0, f32x4 v1) { u32x4 w; w.x = cvt_pk_bf16(v0[0], v0[1]); w.y = cvt_pk_bf16(v0[2], v0[3]); w.z = cvt_pk_bf16(v1[0], v1[1]); w.w = cvt_pk_bf16(v1[2], v1[3]); return w; }
; __device__ __forceinline__ void epi8(const Desc& d, int pb, int row, int col, f32x4 v0, f32x4 v1) {
;     ...
;         if (d.epi != EPI_MERGE2) *(u32x4*)mp = pack8(v0, v1);
;         else *(u32x4*)((bf16_t*)d.o1 + (size_t)row * DM + col) = pack8(v0, v1);
.LBB0_705:
	v_cvt_pk_bf16_f32 v36, v36, v37
	v_cvt_pk_bf16_f32 v37, v30, v31
	v_cvt_pk_bf16_f32 v38, v28, v29
	v_cvt_pk_bf16_f32 v39, v26, v27
	v_lshl_add_u64 v[26:27], v[44:45], 1, s[84:85]
	v_lshl_add_u64 v[24:25], v[24:25], 1, v[26:27]
	global_store_dwordx4 v[24:25], v[36:39], off offset:256

; __device__ __forceinline__ u32x4 pack8(f32x4 v0, f32x4 v1) { u32x4 w; w.x = cvt_pk_bf16(v0[0], v0[1]); w.y = cvt_pk_bf16(v0[2], v0[3]); w.z = cvt_pk_bf16(v1[0], v1[1]); w.w = cvt_pk_bf16(v1[2], v1[3]); return w; }
; __device__ __forceinline__ void epi8(const Desc& d, int pb, int row, int col, f32x4 v0, f32x4 v1) {
;     ...
;     } else if (d.epi == EPI_BF16) {
;         *(u32x4*)((bf16_t*)d.o0 + (size_t)pb * d.sO + (size_t)row * d.ldc + col) = pack8(v0 * d.scale, v1 * d.scale);
.LBB0_707:
	s_andn2_b64 vcc, exec, s[74:75]
	s_cbranch_vccnz .LBB0_709
	s_mul_hi_i32 s1, s56, s93
	s_mul_i32 s0, s56, s93
	s_lshl_b64 s[0:1], s[0:1], 1
	s_add_u32 s0, s50, s0
	s_addc_u32 s1, s51, s1
	v_mad_i64_i32 v[28:29], s[42:43], s14, v42, 0
	v_lshl_add_u64 v[28:29], v[28:29], 1, s[0:1]
	v_ashrrev_i32_e32 v31, 31, v144
	v_mov_b32_e32 v30, v144
	v_lshl_add_u64 v[28:29], v[30:31], 1, v[28:29]
	v_cvt_pk_bf16_f32 v24, v20, v21
	v_cvt_pk_bf16_f32 v25, v22, v23
	v_cvt_pk_bf16_f32 v26, v16, v17
	v_cvt_pk_bf16_f32 v27, v18, v19
	global_store_dwordx4 v[28:29], v[24:27], off offset:256

; __device__ __forceinline__ u32x4 pack8(f32x4 v0, f32x4 v1) { u32x4 w; w.x = cvt_pk_bf16(v0[0], v0[1]); w.y = cvt_pk_bf16(v0[2], v0[3]); w.z = cvt_pk_bf16(v1[0], v1[1]); w.w = cvt_pk_bf16(v1[2], v1[3]); return w; }
; __device__ __forceinline__ void epi8(const Desc& d, int pb, int row, int col, f32x4 v0, f32x4 v1) {
;     if (d.epi == EPI_PIN) {
;         const int pn = col >> 8; bf16_t* p;
;         if (pn < 21) p = (bf16_t*)d.o0 + (size_t)row * NPA + col;
;         else if (pn == 21) p = (bf16_t*)d.o1 + (size_t)row * NKR + (col - 21 * 256);
;         else p = (bf16_t*)d.o2 + (size_t)row * NPG + (col - 22 * 256);
;         *(u32x4*)p = pack8(v0, v1);
.LBB0_718:
	v_cvt_pk_bf16_f32 v20, v20, v21
	v_cvt_pk_bf16_f32 v21, v22, v23
	v_cvt_pk_bf16_f32 v22, v16, v17
	v_cvt_pk_bf16_f32 v23, v18, v19
	global_store_dwordx4 v[24:25], v[20:23], off

; __device__ __forceinline__ void epi8(const Desc& d, int pb, int row, int col, f32x4 v0, f32x4 v1) {
;     ...
;     } else {
;         float* hp = (float*)d.o0 + (size_t)row * DM + col;
;         const float* rp = (row < LREAL ? (const float*)d.o2 + (size_t)row * DM : (const float*)d.gate + (size_t)(row - LREAL) * DM) + col;
;         v0 += *(const f32x4*)rp; v1 += *(const f32x4*)(rp + 4);
;         if (d.epi == EPI_RESID) { *(f32x4*)hp = v0; *(f32x4*)(hp + 4) = v1; }
;         else if (row < LREAL) { float* op = (float*)d.o1 + (size_t)row * DM + col; *(f32x4*)op = v0; *(f32x4*)(op + 4) = v1; }
.LBB0_723:
	s_cmp_lt_i32 s26, 2
	s_cbranch_scc1 .LBB0_738
	s_cmp_gt_i32 s26, 4
	s_cbranch_scc0 .LBB0_732
	v_lshl_add_u64 v[16:17], v[28:29], 2, s[86:87]
	v_lshl_add_u64 v[18:19], s[82:83], 0, v[30:31]
	v_ashrrev_i32_e32 v33, 31, v144
	v_mov_b32_e32 v32, v144
	v_cndmask_b32_e64 v17, v19, v17, s[0:1]
	v_cndmask_b32_e64 v16, v18, v16, s[0:1]
	v_lshl_add_u64 v[20:21], v[32:33], 2, v[16:17]
	global_load_dwordx4 v[16:19], v[20:21], off
	s_nop 0
	global_load_dwordx4 v[20:23], v[20:21], off offset:16
	s_andn2_b64 vcc, exec, s[64:65]
	s_waitcnt vmcnt(0) lgkmcnt(0)
	v_pk_add_f32 v[18:19], v[14:15], v[18:19]
	v_pk_add_f32 v[16:17], v[12:13], v[16:17]
	v_pk_add_f32 v[22:23], v[10:11], v[22:23]
	v_pk_add_f32 v[20:21], v[8:9], v[20:21]
	s_cbranch_vccnz .LBB0_729
	s_and_saveexec_b64 s[74:75], s[0:1]
	s_cbranch_execz .LBB0_728
	v_lshl_add_u64 v[34:35], v[28:29], 2, s[84:85]
	v_lshl_add_u64 v[34:35], v[32:33], 2, v[34:35]
	global_store_dwordx4 v[34:35], v[16:19], off
	global_store_dwordx4 v[34:35], v[20:23], off offset:16

; __device__ __forceinline__ void epi8(const Desc& d, int pb, int row, int col, f32x4 v0, f32x4 v1) {
;     ...
;     } else {
;         float* hp = (float*)d.o0 + (size_t)row * DM + col;
;         const float* rp = (row < LREAL ? (const float*)d.o2 + (size_t)row * DM : (const float*)d.gate + (size_t)(row - LREAL) * DM) + col;
;         v0 += *(const f32x4*)rp; v1 += *(const f32x4*)(rp + 4);
;         if (d.epi == EPI_RESID) { *(f32x4*)hp = v0; *(f32x4*)(hp + 4) = v1; }
;         else if (row < LREAL) { float* op = (float*)d.o1 + (size_t)row * DM + col; *(f32x4*)op = v0; *(f32x4*)(op + 4) = v1; }
.LBB0_729:
	s_andn2_b64 vcc, exec, s[74:75]
	s_cbranch_vccnz .LBB0_731
	v_lshl_add_u64 v[34:35], v[28:29], 2, s[50:51]
	v_lshl_add_u64 v[32:33], v[32:33], 2, v[34:35]
	global_store_dwordx4 v[32:33], v[16:19], off
	global_store_dwordx4 v[32:33], v[20:23], off offset:16

; __device__ __forceinline__ float bf_lo(unsigned w) { return __uint_as_float(w << 16); }
; __device__ __forceinline__ float bf_hi(unsigned w) { return __uint_as_float(w & 0xffff0000u); }
; __device__ __forceinline__ float sigm(float x) { return __builtin_amdgcn_rcpf(1.f + __builtin_amdgcn_exp2f(-1.4426950408889634f * x)); }
; __device__ __forceinline__ f32x4 sigm4(unsigned lo, unsigned hi) { f32x4 r; r[0] = sigm(bf_lo(lo)); r[1] = sigm(bf_hi(lo)); r[2] = sigm(bf_lo(hi)); r[3] = sigm(bf_hi(hi)); return r; }
; __device__ __forceinline__ void epi8(const Desc& d, int pb, int row, int col, f32x4 v0, f32x4 v1) {
;     ...
;     } else if (d.epi == EPI_MERGE0 || d.epi == EPI_MERGE1 || d.epi == EPI_MERGE2) {
;         const u32x4 gw = *(const u32x4*)(d.gate + (size_t)row * NPG + col);
;         v0 *= sigm4(gw.x, gw.y); v1 *= sigm4(gw.z, gw.w);
;         bf16_t* mp = (bf16_t*)d.o0 + (size_t)row * DM + col;
;         if (d.epi != EPI_MERGE0) { const u32x4 m = *(const u32x4*)mp;
;             v0 += (f32x4){bf_lo(m.x), bf_hi(m.x), bf_lo(m.y), bf_hi(m.y)}; v1 += (f32x4){bf_lo(m.z), bf_hi(m.z), bf_lo(m.w), bf_hi(m.w)}; }
.LBB0_732:
	s_andn2_b64 vcc, exec, s[74:75]
	s_cbranch_vccnz .LBB0_737
	v_ashrrev_i32_e32 v17, 31, v144
	v_mov_b32_e32 v16, v144
	v_lshl_add_u64 v[18:19], s[82:83], 0, v[24:25]
	v_lshlrev_b64 v[34:35], 1, v[16:17]
	v_lshl_add_u64 v[18:19], v[18:19], 0, v[34:35]
	global_load_dwordx4 v[18:21], v[18:19], off
	v_lshl_add_u64 v[36:37], v[28:29], 1, s[50:51]
	s_andn2_b64 vcc, exec, s[80:81]
	v_lshl_add_u64 v[34:35], v[36:37], 0, v[34:35]
	s_waitcnt vmcnt(0) lgkmcnt(0)
	v_lshlrev_b32_e32 v22, 16, v18
	v_and_b32_e32 v18, 0xffff0000, v18
	v_lshlrev_b32_e32 v23, 16, v19
	v_and_b32_e32 v19, 0xffff0000, v19
	v_lshlrev_b32_e32 v32, 16, v20
	v_and_b32_e32 v20, 0xffff0000, v20
	v_lshlrev_b32_e32 v33, 16, v21
	v_and_b32_e32 v21, 0xffff0000, v21
	v_mul_f32_e32 v22, 0xbfb8aa3b, v22
	v_mul_f32_e32 v18, 0xbfb8aa3b, v18
	v_mul_f32_e32 v23, 0xbfb8aa3b, v23
	v_mul_f32_e32 v19, 0xbfb8aa3b, v19
	v_mul_f32_e32 v32, 0xbfb8aa3b, v32
	v_mul_f32_e32 v20, 0xbfb8aa3b, v20
	v_mul_f32_e32 v33, 0xbfb8aa3b, v33
	v_mul_f32_e32 v21, 0xbfb8aa3b, v21
	v_exp_f32_e32 v22, v22
	v_exp_f32_e32 v18, v18
	v_exp_f32_e32 v23, v23
	v_exp_f32_e32 v19, v19
	v_exp_f32_e32 v32, v32
	v_exp_f32_e32 v20, v20
	v_exp_f32_e32 v33, v33
	v_exp_f32_e32 v21, v21
	v_add_f32_e32 v22, 1.0, v22
	v_add_f32_e32 v38, 1.0, v18
	v_add_f32_e32 v23, 1.0, v23
	v_add_f32_e32 v39, 1.0, v19
	v_add_f32_e32 v32, 1.0, v32
	v_add_f32_e32 v42, 1.0, v20
	v_add_f32_e32 v33, 1.0, v33
	v_add_f32_e32 v41, 1.0, v21
	v_rcp_f32_e32 v18, v22
	v_rcp_f32_e32 v19, v38
	v_rcp_f32_e32 v20, v23
	v_rcp_f32_e32 v21, v39
	v_rcp_f32_e32 v38, v32
	v_rcp_f32_e32 v40, v33
	v_rcp_f32_e32 v41, v41
	v_rcp_f32_e32 v39, v42
	v_pk_mul_f32 v[22:23], v[14:15], v[20:21]
	v_pk_mul_f32 v[32:33], v[12:13], v[18:19]
	v_pk_mul_f32 v[18:19], v[10:11], v[40:41]
	v_pk_mul_f32 v[20:21], v[8:9], v[38:39]
	s_cbranch_vccz .LBB0_809
	s_andn2_b64 vcc, exec, s[52:53]
	s_mov_b64 s[74:75], -1
	s_cbranch_vccz .LBB0_810

; __device__ __forceinline__ u32x4 pack8(f32x4 v0, f32x4 v1) { u32x4 w; w.x = cvt_pk_bf16(v0[0], v0[1]); w.y = cvt_pk_bf16(v0[2], v0[3]); w.z = cvt_pk_bf16(v1[0], v1[1]); w.w = cvt_pk_bf16(v1[2], v1[3]); return w; }
; __device__ __forceinline__ void epi8(const Desc& d, int pb, int row, int col, f32x4 v0, f32x4 v1) {
;     ...
;         if (d.epi != EPI_MERGE2) *(u32x4*)mp = pack8(v0, v1);
;         else *(u32x4*)((bf16_t*)d.o1 + (size_t)row * DM + col) = pack8(v0, v1);
.LBB0_736:
	v_cvt_pk_bf16_f32 v32, v32, v33
	v_cvt_pk_bf16_f32 v33, v22, v23
	v_cvt_pk_bf16_f32 v34, v20, v21
	v_cvt_pk_bf16_f32 v35, v18, v19
	v_lshl_add_u64 v[18:19], v[28:29], 1, s[84:85]
	v_lshl_add_u64 v[16:17], v[16:17], 1, v[18:19]
	global_store_dwordx4 v[16:17], v[32:35], off

; __device__ __forceinline__ u32x4 pack8(f32x4 v0, f32x4 v1) { u32x4 w; w.x = cvt_pk_bf16(v0[0], v0[1]); w.y = cvt_pk_bf16(v0[2], v0[3]); w.z = cvt_pk_bf16(v1[0], v1[1]); w.w = cvt_pk_bf16(v1[2], v1[3]); return w; }
; __device__ __forceinline__ void epi8(const Desc& d, int pb, int row, int col, f32x4 v0, f32x4 v1) {
;     ...
;     } else if (d.epi == EPI_BF16) {
;         *(u32x4*)((bf16_t*)d.o0 + (size_t)pb * d.sO + (size_t)row * d.ldc + col) = pack8(v0 * d.scale, v1 * d.scale);
.LBB0_738:
	s_andn2_b64 vcc, exec, s[74:75]
	s_cbranch_vccnz .LBB0_740
	s_mul_hi_i32 s43, s56, s93
	s_mul_i32 s42, s56, s93
	s_lshl_b64 s[42:43], s[42:43], 1
	s_add_u32 s42, s50, s42
	s_addc_u32 s43, s51, s43
	v_mad_i64_i32 v[20:21], s[74:75], s14, v26, 0
	v_lshl_add_u64 v[20:21], v[20:21], 1, s[42:43]
	v_ashrrev_i32_e32 v23, 31, v144
	v_mov_b32_e32 v22, v144
	v_lshl_add_u64 v[20:21], v[22:23], 1, v[20:21]
	v_cvt_pk_bf16_f32 v16, v12, v13
	v_cvt_pk_bf16_f32 v17, v14, v15
	v_cvt_pk_bf16_f32 v18, v8, v9
	v_cvt_pk_bf16_f32 v19, v10, v11
	global_store_dwordx4 v[20:21], v[16:19], off

; __device__ __forceinline__ u32x4 pack8(f32x4 v0, f32x4 v1) { u32x4 w; w.x = cvt_pk_bf16(v0[0], v0[1]); w.y = cvt_pk_bf16(v0[2], v0[3]); w.z = cvt_pk_bf16(v1[0], v1[1]); w.w = cvt_pk_bf16(v1[2], v1[3]); return w; }
; __device__ __forceinline__ void epi8(const Desc& d, int pb, int row, int col, f32x4 v0, f32x4 v1) {
;     if (d.epi == EPI_PIN) {
;         const int pn = col >> 8; bf16_t* p;
;         if (pn < 21) p = (bf16_t*)d.o0 + (size_t)row * NPA + col;
;         else if (pn == 21) p = (bf16_t*)d.o1 + (size_t)row * NKR + (col - 21 * 256);
;         else p = (bf16_t*)d.o2 + (size_t)row * NPG + (col - 22 * 256);
;         *(u32x4*)p = pack8(v0, v1);
;     ...
;     } else {
;         float* hp = (float*)d.o0 + (size_t)row * DM + col;
;         const float* rp = (row < LREAL ? (const float*)d.o2 + (size_t)row * DM : (const float*)d.gate + (size_t)(row - LREAL) * DM) + col;
;         v0 += *(const f32x4*)rp; v1 += *(const f32x4*)(rp + 4);
;         if (d.epi == EPI_RESID) { *(f32x4*)hp = v0; *(f32x4*)(hp + 4) = v1; }
;         else if (row < LREAL) { float* op = (float*)d.o1 + (size_t)row * DM + col; *(f32x4*)op = v0; *(f32x4*)(op + 4) = v1; }
.LBB0_749:
	v_cvt_pk_bf16_f32 v12, v12, v13
	v_cvt_pk_bf16_f32 v13, v14, v15
	v_cvt_pk_bf16_f32 v14, v8, v9
	v_cvt_pk_bf16_f32 v15, v10, v11
	global_store_dwordx4 v[20:21], v[12:15], off
	s_cmp_lt_i32 s26, 1
	s_mov_b64 s[74:75], -1
	s_cbranch_scc1 .LBB0_722
.LBB0_750:
	s_cmp_lt_i32 s26, 2
	s_cbranch_scc1 .LBB0_765
	s_cmp_gt_i32 s26, 4
	s_cbranch_scc0 .LBB0_759
	v_lshl_add_u64 v[8:9], v[28:29], 2, s[86:87]
	v_lshl_add_u64 v[10:11], s[82:83], 0, v[30:31]
	v_cndmask_b32_e64 v9, v11, v9, s[0:1]
	v_cndmask_b32_e64 v8, v10, v8, s[0:1]
	v_ashrrev_i32_e32 v21, 31, v144
	v_mov_b32_e32 v20, v144
	v_lshl_add_u64 v[12:13], v[20:21], 2, v[8:9]
	global_load_dwordx4 v[8:11], v[12:13], off offset:512
	s_nop 0
	global_load_dwordx4 v[12:15], v[12:13], off offset:528
	s_andn2_b64 vcc, exec, s[64:65]
	s_waitcnt vmcnt(0) lgkmcnt(0)
	v_pk_add_f32 v[10:11], v[2:3], v[10:11]
	v_pk_add_f32 v[8:9], v[0:1], v[8:9]
	v_pk_add_f32 v[14:15], v[6:7], v[14:15]
	v_pk_add_f32 v[12:13], v[4:5], v[12:13]
	s_cbranch_vccnz .LBB0_756
	s_and_saveexec_b64 s[74:75], s[0:1]
	s_cbranch_execz .LBB0_755
	v_lshl_add_u64 v[22:23], v[28:29], 2, s[84:85]
	v_lshl_add_u64 v[22:23], v[20:21], 2, v[22:23]
	global_store_dwordx4 v[22:23], v[8:11], off offset:512
	global_store_dwordx4 v[22:23], v[12:15], off offset:528

; __device__ __forceinline__ void epi8(const Desc& d, int pb, int row, int col, f32x4 v0, f32x4 v1) {
;     ...
;     } else {
;         float* hp = (float*)d.o0 + (size_t)row * DM + col;
;         const float* rp = (row < LREAL ? (const float*)d.o2 + (size_t)row * DM : (const float*)d.gate + (size_t)(row - LREAL) * DM) + col;
;         v0 += *(const f32x4*)rp; v1 += *(const f32x4*)(rp + 4);
;         if (d.epi == EPI_RESID) { *(f32x4*)hp = v0; *(f32x4*)(hp + 4) = v1; }
;         else if (row < LREAL) { float* op = (float*)d.o1 + (size_t)row * DM + col; *(f32x4*)op = v0; *(f32x4*)(op + 4) = v1; }
.LBB0_756:
	s_andn2_b64 vcc, exec, s[74:75]
	s_cbranch_vccnz .LBB0_758
	v_lshl_add_u64 v[22:23], v[28:29], 2, s[50:51]
	v_lshl_add_u64 v[20:21], v[20:21], 2, v[22:23]
	global_store_dwordx4 v[20:21], v[8:11], off offset:512
	global_store_dwordx4 v[20:21], v[12:15], off offset:528

; __device__ __forceinline__ float bf_lo(unsigned w) { return __uint_as_float(w << 16); }
; __device__ __forceinline__ float bf_hi(unsigned w) { return __uint_as_float(w & 0xffff0000u); }
; __device__ __forceinline__ float sigm(float x) { return __builtin_amdgcn_rcpf(1.f + __builtin_amdgcn_exp2f(-1.4426950408889634f * x)); }
; __device__ __forceinline__ f32x4 sigm4(unsigned lo, unsigned hi) { f32x4 r; r[0] = sigm(bf_lo(lo)); r[1] = sigm(bf_hi(lo)); r[2] = sigm(bf_lo(hi)); r[3] = sigm(bf_hi(hi)); return r; }
; __device__ __forceinline__ void epi8(const Desc& d, int pb, int row, int col, f32x4 v0, f32x4 v1) {
;     ...
;     } else if (d.epi == EPI_MERGE0 || d.epi == EPI_MERGE1 || d.epi == EPI_MERGE2) {
;         const u32x4 gw = *(const u32x4*)(d.gate + (size_t)row * NPG + col);
;         v0 *= sigm4(gw.x, gw.y); v1 *= sigm4(gw.z, gw.w);
;         bf16_t* mp = (bf16_t*)d.o0 + (size_t)row * DM + col;
;         if (d.epi != EPI_MERGE0) { const u32x4 m = *(const u32x4*)mp;
;             v0 += (f32x4){bf_lo(m.x), bf_hi(m.x), bf_lo(m.y), bf_hi(m.y)}; v1 += (f32x4){bf_lo(m.z), bf_hi(m.z), bf_lo(m.w), bf_hi(m.w)}; }
.LBB0_759:
	s_andn2_b64 vcc, exec, s[74:75]
	s_cbranch_vccnz .LBB0_764
	v_ashrrev_i32_e32 v9, 31, v144
	v_mov_b32_e32 v8, v144
	v_lshl_add_u64 v[10:11], s[82:83], 0, v[24:25]
	v_lshlrev_b64 v[22:23], 1, v[8:9]
	v_lshl_add_u64 v[10:11], v[10:11], 0, v[22:23]
	global_load_dwordx4 v[10:13], v[10:11], off offset:256
	v_lshl_add_u64 v[30:31], v[28:29], 1, s[50:51]
	s_andn2_b64 vcc, exec, s[80:81]
	v_lshl_add_u64 v[22:23], v[30:31], 0, v[22:23]
	s_waitcnt vmcnt(0) lgkmcnt(0)
	v_lshlrev_b32_e32 v14, 16, v10
	v_and_b32_e32 v10, 0xffff0000, v10
	v_lshlrev_b32_e32 v15, 16, v11
	v_and_b32_e32 v11, 0xffff0000, v11
	v_lshlrev_b32_e32 v20, 16, v12
	v_and_b32_e32 v12, 0xffff0000, v12
	v_lshlrev_b32_e32 v21, 16, v13
	v_and_b32_e32 v13, 0xffff0000, v13
	v_mul_f32_e32 v14, 0xbfb8aa3b, v14
	v_mul_f32_e32 v10, 0xbfb8aa3b, v10
	v_mul_f32_e32 v15, 0xbfb8aa3b, v15
	v_mul_f32_e32 v11, 0xbfb8aa3b, v11
	v_mul_f32_e32 v20, 0xbfb8aa3b, v20
	v_mul_f32_e32 v12, 0xbfb8aa3b, v12
	v_mul_f32_e32 v21, 0xbfb8aa3b, v21
	v_mul_f32_e32 v13, 0xbfb8aa3b, v13
	v_exp_f32_e32 v14, v14
	v_exp_f32_e32 v10, v10
	v_exp_f32_e32 v15, v15
	v_exp_f32_e32 v11, v11
	v_exp_f32_e32 v20, v20
	v_exp_f32_e32 v12, v12
	v_exp_f32_e32 v21, v21
	v_exp_f32_e32 v13, v13
	v_add_f32_e32 v14, 1.0, v14
	v_add_f32_e32 v27, 1.0, v10
	v_add_f32_e32 v15, 1.0, v15
	v_add_f32_e32 v32, 1.0, v11
	v_add_f32_e32 v20, 1.0, v20
	v_add_f32_e32 v33, 1.0, v12
	v_add_f32_e32 v21, 1.0, v21
	v_add_f32_e32 v35, 1.0, v13
	v_rcp_f32_e32 v10, v14
	v_rcp_f32_e32 v11, v27
	v_rcp_f32_e32 v12, v15
	v_rcp_f32_e32 v13, v32
	v_rcp_f32_e32 v32, v20
	v_rcp_f32_e32 v34, v21
	v_rcp_f32_e32 v35, v35
	v_rcp_f32_e32 v33, v33
	v_pk_mul_f32 v[14:15], v[2:3], v[12:13]
	v_pk_mul_f32 v[20:21], v[0:1], v[10:11]
	v_pk_mul_f32 v[10:11], v[6:7], v[34:35]
	v_pk_mul_f32 v[12:13], v[4:5], v[32:33]
	s_cbranch_vccz .LBB0_811
	s_andn2_b64 vcc, exec, s[52:53]
	s_mov_b64 s[0:1], -1
	s_cbranch_vccz .LBB0_812

; __device__ __forceinline__ u32x4 pack8(f32x4 v0, f32x4 v1) { u32x4 w; w.x = cvt_pk_bf16(v0[0], v0[1]); w.y = cvt_pk_bf16(v0[2], v0[3]); w.z = cvt_pk_bf16(v1[0], v1[1]); w.w = cvt_pk_bf16(v1[2], v1[3]); return w; }
; __device__ __forceinline__ void epi8(const Desc& d, int pb, int row, int col, f32x4 v0, f32x4 v1) {
;     ...
;         if (d.epi != EPI_MERGE2) *(u32x4*)mp = pack8(v0, v1);
;         else *(u32x4*)((bf16_t*)d.o1 + (size_t)row * DM + col) = pack8(v0, v1);
.LBB0_763:
	v_cvt_pk_bf16_f32 v20, v20, v21
	v_cvt_pk_bf16_f32 v21, v14, v15
	v_cvt_pk_bf16_f32 v22, v12, v13
	v_cvt_pk_bf16_f32 v23, v10, v11
	v_lshl_add_u64 v[10:11], v[28:29], 1, s[84:85]
	v_lshl_add_u64 v[8:9], v[8:9], 1, v[10:11]
	global_store_dwordx4 v[8:9], v[20:23], off offset:256

; __device__ __forceinline__ u32x4 pack8(f32x4 v0, f32x4 v1) { u32x4 w; w.x = cvt_pk_bf16(v0[0], v0[1]); w.y = cvt_pk_bf16(v0[2], v0[3]); w.z = cvt_pk_bf16(v1[0], v1[1]); w.w = cvt_pk_bf16(v1[2], v1[3]); return w; }
; __device__ __forceinline__ void epi8(const Desc& d, int pb, int row, int col, f32x4 v0, f32x4 v1) {
;     ...
;     } else if (d.epi == EPI_BF16) {
;         *(u32x4*)((bf16_t*)d.o0 + (size_t)pb * d.sO + (size_t)row * d.ldc + col) = pack8(v0 * d.scale, v1 * d.scale);
.LBB0_765:
	s_andn2_b64 vcc, exec, s[74:75]
	s_cbranch_vccnz .LBB0_767
	s_mul_hi_i32 s1, s56, s93
	s_mul_i32 s0, s56, s93
	s_lshl_b64 s[0:1], s[0:1], 1
	s_add_u32 s0, s50, s0
	s_addc_u32 s1, s51, s1
	v_mad_i64_i32 v[12:13], s[42:43], s14, v26, 0
	v_lshl_add_u64 v[12:13], v[12:13], 1, s[0:1]
	v_ashrrev_i32_e32 v15, 31, v144
	v_mov_b32_e32 v14, v144
	v_lshl_add_u64 v[12:13], v[14:15], 1, v[12:13]
	v_cvt_pk_bf16_f32 v8, v0, v1
	v_cvt_pk_bf16_f32 v9, v2, v3
	v_cvt_pk_bf16_f32 v10, v4, v5
	v_cvt_pk_bf16_f32 v11, v6, v7
	global_store_dwordx4 v[12:13], v[8:11], off offset:256

; __device__ __forceinline__ u32x4 pack8(f32x4 v0, f32x4 v1) { u32x4 w; w.x = cvt_pk_bf16(v0[0], v0[1]); w.y = cvt_pk_bf16(v0[2], v0[3]); w.z = cvt_pk_bf16(v1[0], v1[1]); w.w = cvt_pk_bf16(v1[2], v1[3]); return w; }
; __device__ __forceinline__ void epi8(const Desc& d, int pb, int row, int col, f32x4 v0, f32x4 v1) {
;     if (d.epi == EPI_PIN) {
;         const int pn = col >> 8; bf16_t* p;
;         if (pn < 21) p = (bf16_t*)d.o0 + (size_t)row * NPA + col;
;         else if (pn == 21) p = (bf16_t*)d.o1 + (size_t)row * NKR + (col - 21 * 256);
;         else p = (bf16_t*)d.o2 + (size_t)row * NPG + (col - 22 * 256);
;         *(u32x4*)p = pack8(v0, v1);
.LBB0_776:
	v_cvt_pk_bf16_f32 v0, v0, v1
	v_cvt_pk_bf16_f32 v1, v2, v3
	v_cvt_pk_bf16_f32 v2, v4, v5
	v_cvt_pk_bf16_f32 v3, v6, v7
	global_store_dwordx4 v[8:9], v[0:3], off

; __device__ __forceinline__ float bf_lo(unsigned w) { return __uint_as_float(w << 16); }
; __device__ __forceinline__ float bf_hi(unsigned w) { return __uint_as_float(w & 0xffff0000u); }
; __device__ __forceinline__ u32x4 pack8(f32x4 v0, f32x4 v1) { u32x4 w; w.x = cvt_pk_bf16(v0[0], v0[1]); w.y = cvt_pk_bf16(v0[2], v0[3]); w.z = cvt_pk_bf16(v1[0], v1[1]); w.w = cvt_pk_bf16(v1[2], v1[3]); return w; }
; __device__ __forceinline__ void epi8(const Desc& d, int pb, int row, int col, f32x4 v0, f32x4 v1) {
;     ...
;         if (d.epi != EPI_MERGE0) { const u32x4 m = *(const u32x4*)mp;
;             v0 += (f32x4){bf_lo(m.x), bf_hi(m.x), bf_lo(m.y), bf_hi(m.y)}; v1 += (f32x4){bf_lo(m.z), bf_hi(m.z), bf_lo(m.w), bf_hi(m.w)}; }
;         if (d.epi != EPI_MERGE2) *(u32x4*)mp = pack8(v0, v1);
.LBB0_781:
	global_load_dwordx4 v[146:149], v[168:169], off
	s_waitcnt vmcnt(0) lgkmcnt(0)
	v_lshlrev_b32_e32 v174, 16, v146
	v_and_b32_e32 v175, 0xffff0000, v146
	v_lshlrev_b32_e32 v146, 16, v147
	v_and_b32_e32 v147, 0xffff0000, v147
	v_pk_add_f32 v[134:135], v[134:135], v[146:147]
	v_lshlrev_b32_e32 v146, 16, v148
	v_and_b32_e32 v147, 0xffff0000, v148
	v_lshlrev_b32_e32 v148, 16, v149
	v_and_b32_e32 v149, 0xffff0000, v149
	v_pk_add_f32 v[166:167], v[166:167], v[174:175]
	v_pk_add_f32 v[130:131], v[130:131], v[148:149]
	v_pk_add_f32 v[132:133], v[132:133], v[146:147]
	s_andn2_b64 vcc, exec, s[52:53]
	s_mov_b64 s[74:75], -1
	s_cbranch_vccnz .LBB0_329
.LBB0_782:
	v_cvt_pk_bf16_f32 v146, v166, v167
	v_cvt_pk_bf16_f32 v147, v134, v135
	v_cvt_pk_bf16_f32 v148, v132, v133
	v_cvt_pk_bf16_f32 v149, v130, v131
	global_store_dwordx4 v[168:169], v[146:149], off
	s_cbranch_execz .LBB0_330
	s_branch .LBB0_331
.LBB0_783:
	global_load_dwordx4 v[146:149], v[134:135], off offset:256
	s_waitcnt vmcnt(0) lgkmcnt(0)
	v_lshlrev_b32_e32 v164, 16, v146
	v_and_b32_e32 v165, 0xffff0000, v146
	v_lshlrev_b32_e32 v146, 16, v147
	v_and_b32_e32 v147, 0xffff0000, v147
	v_pk_add_f32 v[126:127], v[126:127], v[146:147]
	v_lshlrev_b32_e32 v146, 16, v148
	v_and_b32_e32 v147, 0xffff0000, v148
	v_lshlrev_b32_e32 v148, 16, v149
	v_and_b32_e32 v149, 0xffff0000, v149
	v_pk_add_f32 v[132:133], v[132:133], v[164:165]
	v_pk_add_f32 v[122:123], v[122:123], v[148:149]
	v_pk_add_f32 v[124:125], v[124:125], v[146:147]
	s_andn2_b64 vcc, exec, s[52:53]
	s_mov_b64 s[0:1], -1
	s_cbranch_vccnz .LBB0_356
.LBB0_784:
	v_cvt_pk_bf16_f32 v146, v132, v133
	v_cvt_pk_bf16_f32 v147, v126, v127
	v_cvt_pk_bf16_f32 v148, v124, v125
	v_cvt_pk_bf16_f32 v149, v122, v123
	global_store_dwordx4 v[134:135], v[146:149], off offset:256
	s_cbranch_execz .LBB0_357
	s_branch .LBB0_358
.LBB0_785:
	global_load_dwordx4 v[132:135], v[130:131], off
	s_waitcnt vmcnt(0) lgkmcnt(0)
	v_lshlrev_b32_e32 v146, 16, v132
	v_and_b32_e32 v147, 0xffff0000, v132
	v_lshlrev_b32_e32 v132, 16, v133
	v_and_b32_e32 v133, 0xffff0000, v133
	v_pk_add_f32 v[118:119], v[118:119], v[132:133]
	v_lshlrev_b32_e32 v132, 16, v134
	v_and_b32_e32 v133, 0xffff0000, v134
	v_lshlrev_b32_e32 v134, 16, v135
	v_and_b32_e32 v135, 0xffff0000, v135
	v_pk_add_f32 v[128:129], v[128:129], v[146:147]
	v_pk_add_f32 v[114:115], v[114:115], v[134:135]
	v_pk_add_f32 v[116:117], v[116:117], v[132:133]
	s_andn2_b64 vcc, exec, s[52:53]
	s_mov_b64 s[74:75], -1
	s_cbranch_vccnz .LBB0_387
.LBB0_786:
	v_cvt_pk_bf16_f32 v132, v128, v129
	v_cvt_pk_bf16_f32 v133, v118, v119
	v_cvt_pk_bf16_f32 v134, v116, v117
	v_cvt_pk_bf16_f32 v135, v114, v115
	global_store_dwordx4 v[130:131], v[132:135], off
	s_cbranch_execz .LBB0_388
	s_branch .LBB0_389
.LBB0_787:
	global_load_dwordx4 v[126:129], v[118:119], off offset:256
	s_waitcnt vmcnt(0) lgkmcnt(0)
	v_lshlrev_b32_e32 v130, 16, v126
	v_and_b32_e32 v131, 0xffff0000, v126
	v_lshlrev_b32_e32 v126, 16, v127
	v_and_b32_e32 v127, 0xffff0000, v127
	v_pk_add_f32 v[110:111], v[110:111], v[126:127]
	v_lshlrev_b32_e32 v126, 16, v128
	v_and_b32_e32 v127, 0xffff0000, v128
	v_lshlrev_b32_e32 v128, 16, v129
	v_and_b32_e32 v129, 0xffff0000, v129
	v_pk_add_f32 v[116:117], v[116:117], v[130:131]
	v_pk_add_f32 v[106:107], v[106:107], v[128:129]
	v_pk_add_f32 v[108:109], v[108:109], v[126:127]
	s_andn2_b64 vcc, exec, s[52:53]
	s_mov_b64 s[0:1], -1
	s_cbranch_vccnz .LBB0_414
.LBB0_788:
	v_cvt_pk_bf16_f32 v126, v116, v117
	v_cvt_pk_bf16_f32 v127, v110, v111
	v_cvt_pk_bf16_f32 v128, v108, v109
	v_cvt_pk_bf16_f32 v129, v106, v107
	global_store_dwordx4 v[118:119], v[126:129], off offset:256
	s_cbranch_execz .LBB0_415
	s_branch .LBB0_416
.LBB0_789:
	global_load_dwordx4 v[116:119], v[114:115], off
	s_waitcnt vmcnt(0) lgkmcnt(0)
	v_lshlrev_b32_e32 v120, 16, v116
	v_and_b32_e32 v121, 0xffff0000, v116
	v_lshlrev_b32_e32 v116, 16, v117
	v_and_b32_e32 v117, 0xffff0000, v117
	v_pk_add_f32 v[102:103], v[102:103], v[116:117]
	v_lshlrev_b32_e32 v116, 16, v118
	v_and_b32_e32 v117, 0xffff0000, v118
	v_lshlrev_b32_e32 v118, 16, v119
	v_and_b32_e32 v119, 0xffff0000, v119
	v_pk_add_f32 v[112:113], v[112:113], v[120:121]
	v_pk_add_f32 v[98:99], v[98:99], v[118:119]
	v_pk_add_f32 v[100:101], v[100:101], v[116:117]
	s_andn2_b64 vcc, exec, s[52:53]
	s_mov_b64 s[74:75], -1
	s_cbranch_vccnz .LBB0_445
.LBB0_790:
	v_cvt_pk_bf16_f32 v116, v112, v113
	v_cvt_pk_bf16_f32 v117, v102, v103
	v_cvt_pk_bf16_f32 v118, v100, v101
	v_cvt_pk_bf16_f32 v119, v98, v99
	global_store_dwordx4 v[114:115], v[116:119], off
	s_cbranch_execz .LBB0_446
	s_branch .LBB0_447
.LBB0_791:
	global_load_dwordx4 v[110:113], v[102:103], off offset:256
	s_waitcnt vmcnt(0) lgkmcnt(0)
	v_lshlrev_b32_e32 v114, 16, v110
	v_and_b32_e32 v115, 0xffff0000, v110
	v_lshlrev_b32_e32 v110, 16, v111
	v_and_b32_e32 v111, 0xffff0000, v111
	v_pk_add_f32 v[94:95], v[94:95], v[110:111]
	v_lshlrev_b32_e32 v110, 16, v112
	v_and_b32_e32 v111, 0xffff0000, v112
	v_lshlrev_b32_e32 v112, 16, v113
	v_and_b32_e32 v113, 0xffff0000, v113
	v_pk_add_f32 v[100:101], v[100:101], v[114:115]
	v_pk_add_f32 v[90:91], v[90:91], v[112:113]
	v_pk_add_f32 v[92:93], v[92:93], v[110:111]
	s_andn2_b64 vcc, exec, s[52:53]
	s_mov_b64 s[0:1], -1
	s_cbranch_vccnz .LBB0_472
.LBB0_792:
	v_cvt_pk_bf16_f32 v110, v100, v101
	v_cvt_pk_bf16_f32 v111, v94, v95
	v_cvt_pk_bf16_f32 v112, v92, v93
	v_cvt_pk_bf16_f32 v113, v90, v91
	global_store_dwordx4 v[102:103], v[110:113], off offset:256
	s_cbranch_execz .LBB0_473
	s_branch .LBB0_474
; __device__ __forceinline__ float bf_lo(unsigned w) { return __uint_as_float(w << 16); }
; __device__ __forceinline__ float bf_hi(unsigned w) { return __uint_as_float(w & 0xffff0000u); }
; __device__ __forceinline__ u32x4 pack8(f32x4 v0, f32x4 v1) { u32x4 w; w.x = cvt_pk_bf16(v0[0], v0[1]); w.y = cvt_pk_bf16(v0[2], v0[3]); w.z = cvt_pk_bf16(v1[0], v1[1]); w.w = cvt_pk_bf16(v1[2], v1[3]); return w; }
; __device__ __forceinline__ void epi8(const Desc& d, int pb, int row, int col, f32x4 v0, f32x4 v1) {
;     ...
;         if (d.epi != EPI_MERGE0) { const u32x4 m = *(const u32x4*)mp;
;             v0 += (f32x4){bf_lo(m.x), bf_hi(m.x), bf_lo(m.y), bf_hi(m.y)}; v1 += (f32x4){bf_lo(m.z), bf_hi(m.z), bf_lo(m.w), bf_hi(m.w)}; }
;         if (d.epi != EPI_MERGE2) *(u32x4*)mp = pack8(v0, v1);
.LBB0_793:
	global_load_dwordx4 v[100:103], v[98:99], off
	s_waitcnt vmcnt(0) lgkmcnt(0)
	v_lshlrev_b32_e32 v104, 16, v100
	v_and_b32_e32 v105, 0xffff0000, v100
	v_lshlrev_b32_e32 v100, 16, v101
	v_and_b32_e32 v101, 0xffff0000, v101
	v_pk_add_f32 v[86:87], v[86:87], v[100:101]
	v_lshlrev_b32_e32 v100, 16, v102
	v_and_b32_e32 v101, 0xffff0000, v102
	v_lshlrev_b32_e32 v102, 16, v103
	v_and_b32_e32 v103, 0xffff0000, v103
	v_pk_add_f32 v[96:97], v[96:97], v[104:105]
	v_pk_add_f32 v[82:83], v[82:83], v[102:103]
	v_pk_add_f32 v[84:85], v[84:85], v[100:101]
	s_andn2_b64 vcc, exec, s[52:53]
	s_mov_b64 s[74:75], -1
	s_cbranch_vccnz .LBB0_503
.LBB0_794:
	v_cvt_pk_bf16_f32 v100, v96, v97
	v_cvt_pk_bf16_f32 v101, v86, v87
	v_cvt_pk_bf16_f32 v102, v84, v85
	v_cvt_pk_bf16_f32 v103, v82, v83
	global_store_dwordx4 v[98:99], v[100:103], off
	s_cbranch_execz .LBB0_504
	s_branch .LBB0_505
.LBB0_795:
	global_load_dwordx4 v[94:97], v[86:87], off offset:256
	s_waitcnt vmcnt(0) lgkmcnt(0)
	v_lshlrev_b32_e32 v98, 16, v94
	v_and_b32_e32 v99, 0xffff0000, v94
	v_lshlrev_b32_e32 v94, 16, v95
	v_and_b32_e32 v95, 0xffff0000, v95
	v_pk_add_f32 v[78:79], v[78:79], v[94:95]
	v_lshlrev_b32_e32 v94, 16, v96
	v_and_b32_e32 v95, 0xffff0000, v96
	v_lshlrev_b32_e32 v96, 16, v97
	v_and_b32_e32 v97, 0xffff0000, v97
	v_pk_add_f32 v[84:85], v[84:85], v[98:99]
	v_pk_add_f32 v[74:75], v[74:75], v[96:97]
	v_pk_add_f32 v[76:77], v[76:77], v[94:95]
	s_andn2_b64 vcc, exec, s[52:53]
	s_mov_b64 s[0:1], -1
	s_cbranch_vccnz .LBB0_530
.LBB0_796:
	v_cvt_pk_bf16_f32 v94, v84, v85
	v_cvt_pk_bf16_f32 v95, v78, v79
	v_cvt_pk_bf16_f32 v96, v76, v77
	v_cvt_pk_bf16_f32 v97, v74, v75
	global_store_dwordx4 v[86:87], v[94:97], off offset:256
	s_cbranch_execz .LBB0_531
	s_branch .LBB0_532
.LBB0_797:
	global_load_dwordx4 v[84:87], v[82:83], off
	s_waitcnt vmcnt(0) lgkmcnt(0)
	v_lshlrev_b32_e32 v88, 16, v84
	v_and_b32_e32 v89, 0xffff0000, v84
	v_lshlrev_b32_e32 v84, 16, v85
	v_and_b32_e32 v85, 0xffff0000, v85
	v_pk_add_f32 v[70:71], v[70:71], v[84:85]
	v_lshlrev_b32_e32 v84, 16, v86
	v_and_b32_e32 v85, 0xffff0000, v86
	v_lshlrev_b32_e32 v86, 16, v87
	v_and_b32_e32 v87, 0xffff0000, v87
	v_pk_add_f32 v[80:81], v[80:81], v[88:89]
	v_pk_add_f32 v[66:67], v[66:67], v[86:87]
	v_pk_add_f32 v[68:69], v[68:69], v[84:85]
	s_andn2_b64 vcc, exec, s[52:53]
	s_mov_b64 s[74:75], -1
	s_cbranch_vccnz .LBB0_561
.LBB0_798:
	v_cvt_pk_bf16_f32 v84, v80, v81
	v_cvt_pk_bf16_f32 v85, v70, v71
	v_cvt_pk_bf16_f32 v86, v68, v69
	v_cvt_pk_bf16_f32 v87, v66, v67
	global_store_dwordx4 v[82:83], v[84:87], off
	s_cbranch_execz .LBB0_562
	s_branch .LBB0_563
.LBB0_799:
	global_load_dwordx4 v[78:81], v[70:71], off offset:256
	s_waitcnt vmcnt(0) lgkmcnt(0)
	v_lshlrev_b32_e32 v82, 16, v78
	v_and_b32_e32 v83, 0xffff0000, v78
	v_lshlrev_b32_e32 v78, 16, v79
	v_and_b32_e32 v79, 0xffff0000, v79
	v_pk_add_f32 v[62:63], v[62:63], v[78:79]
	v_lshlrev_b32_e32 v78, 16, v80
	v_and_b32_e32 v79, 0xffff0000, v80
	v_lshlrev_b32_e32 v80, 16, v81
	v_and_b32_e32 v81, 0xffff0000, v81
	v_pk_add_f32 v[68:69], v[68:69], v[82:83]
	v_pk_add_f32 v[58:59], v[58:59], v[80:81]
	v_pk_add_f32 v[60:61], v[60:61], v[78:79]
	s_andn2_b64 vcc, exec, s[52:53]
	s_mov_b64 s[0:1], -1
	s_cbranch_vccnz .LBB0_588
.LBB0_800:
	v_cvt_pk_bf16_f32 v78, v68, v69
	v_cvt_pk_bf16_f32 v79, v62, v63
	v_cvt_pk_bf16_f32 v80, v60, v61
	v_cvt_pk_bf16_f32 v81, v58, v59
	global_store_dwordx4 v[70:71], v[78:81], off offset:256
	s_cbranch_execz .LBB0_589
	s_branch .LBB0_590
.LBB0_801:
	global_load_dwordx4 v[68:71], v[66:67], off
	s_waitcnt vmcnt(0) lgkmcnt(0)
	v_lshlrev_b32_e32 v72, 16, v68
	v_and_b32_e32 v73, 0xffff0000, v68
	v_lshlrev_b32_e32 v68, 16, v69
	v_and_b32_e32 v69, 0xffff0000, v69
	v_pk_add_f32 v[54:55], v[54:55], v[68:69]
	v_lshlrev_b32_e32 v68, 16, v70
	v_and_b32_e32 v69, 0xffff0000, v70
	v_lshlrev_b32_e32 v70, 16, v71
	v_and_b32_e32 v71, 0xffff0000, v71
	v_pk_add_f32 v[64:65], v[64:65], v[72:73]
	v_pk_add_f32 v[50:51], v[50:51], v[70:71]
	v_pk_add_f32 v[52:53], v[52:53], v[68:69]
	s_andn2_b64 vcc, exec, s[52:53]
	s_mov_b64 s[74:75], -1
	s_cbranch_vccnz .LBB0_619
.LBB0_802:
	v_cvt_pk_bf16_f32 v68, v64, v65
	v_cvt_pk_bf16_f32 v69, v54, v55
	v_cvt_pk_bf16_f32 v70, v52, v53
	v_cvt_pk_bf16_f32 v71, v50, v51
	global_store_dwordx4 v[66:67], v[68:71], off
	s_cbranch_execz .LBB0_620
	s_branch .LBB0_621
; __device__ __forceinline__ float bf_lo(unsigned w) { return __uint_as_float(w << 16); }
; __device__ __forceinline__ float bf_hi(unsigned w) { return __uint_as_float(w & 0xffff0000u); }
; __device__ __forceinline__ u32x4 pack8(f32x4 v0, f32x4 v1) { u32x4 w; w.x = cvt_pk_bf16(v0[0], v0[1]); w.y = cvt_pk_bf16(v0[2], v0[3]); w.z = cvt_pk_bf16(v1[0], v1[1]); w.w = cvt_pk_bf16(v1[2], v1[3]); return w; }
; __device__ __forceinline__ void epi8(const Desc& d, int pb, int row, int col, f32x4 v0, f32x4 v1) {
;     ...
;         if (d.epi != EPI_MERGE0) { const u32x4 m = *(const u32x4*)mp;
;             v0 += (f32x4){bf_lo(m.x), bf_hi(m.x), bf_lo(m.y), bf_hi(m.y)}; v1 += (f32x4){bf_lo(m.z), bf_hi(m.z), bf_lo(m.w), bf_hi(m.w)}; }
;         if (d.epi != EPI_MERGE2) *(u32x4*)mp = pack8(v0, v1);
.LBB0_803:
	global_load_dwordx4 v[62:65], v[54:55], off offset:256
	s_waitcnt vmcnt(0) lgkmcnt(0)
	v_lshlrev_b32_e32 v66, 16, v62
	v_and_b32_e32 v67, 0xffff0000, v62
	v_lshlrev_b32_e32 v62, 16, v63
	v_and_b32_e32 v63, 0xffff0000, v63
	v_pk_add_f32 v[46:47], v[46:47], v[62:63]
	v_lshlrev_b32_e32 v62, 16, v64
	v_and_b32_e32 v63, 0xffff0000, v64
	v_lshlrev_b32_e32 v64, 16, v65
	v_and_b32_e32 v65, 0xffff0000, v65
	v_pk_add_f32 v[52:53], v[52:53], v[66:67]
	v_pk_add_f32 v[42:43], v[42:43], v[64:65]
	v_pk_add_f32 v[44:45], v[44:45], v[62:63]
	s_andn2_b64 vcc, exec, s[52:53]
	s_mov_b64 s[0:1], -1
	s_cbranch_vccnz .LBB0_646
.LBB0_804:
	v_cvt_pk_bf16_f32 v62, v52, v53
	v_cvt_pk_bf16_f32 v63, v46, v47
	v_cvt_pk_bf16_f32 v64, v44, v45
	v_cvt_pk_bf16_f32 v65, v42, v43
	global_store_dwordx4 v[54:55], v[62:65], off offset:256
	s_cbranch_execz .LBB0_647
	s_branch .LBB0_648
.LBB0_805:
	global_load_dwordx4 v[52:55], v[50:51], off
	s_waitcnt vmcnt(0) lgkmcnt(0)
	v_lshlrev_b32_e32 v56, 16, v52
	v_and_b32_e32 v57, 0xffff0000, v52
	v_lshlrev_b32_e32 v52, 16, v53
	v_and_b32_e32 v53, 0xffff0000, v53
	v_pk_add_f32 v[38:39], v[38:39], v[52:53]
	v_lshlrev_b32_e32 v52, 16, v54
	v_and_b32_e32 v53, 0xffff0000, v54
	v_lshlrev_b32_e32 v54, 16, v55
	v_and_b32_e32 v55, 0xffff0000, v55
	v_pk_add_f32 v[48:49], v[48:49], v[56:57]
	v_pk_add_f32 v[34:35], v[34:35], v[54:55]
	v_pk_add_f32 v[36:37], v[36:37], v[52:53]
	s_andn2_b64 vcc, exec, s[52:53]
	s_mov_b64 s[74:75], -1
	s_cbranch_vccnz .LBB0_677
.LBB0_806:
	v_cvt_pk_bf16_f32 v52, v48, v49
	v_cvt_pk_bf16_f32 v53, v38, v39
	v_cvt_pk_bf16_f32 v54, v36, v37
	v_cvt_pk_bf16_f32 v55, v34, v35
	global_store_dwordx4 v[50:51], v[52:55], off
	s_cbranch_execz .LBB0_678
	s_branch .LBB0_679
.LBB0_807:
	global_load_dwordx4 v[46:49], v[38:39], off offset:256
	s_waitcnt vmcnt(0) lgkmcnt(0)
	v_lshlrev_b32_e32 v50, 16, v46
	v_and_b32_e32 v51, 0xffff0000, v46
	v_lshlrev_b32_e32 v46, 16, v47
	v_and_b32_e32 v47, 0xffff0000, v47
	v_pk_add_f32 v[30:31], v[30:31], v[46:47]
	v_lshlrev_b32_e32 v46, 16, v48
	v_and_b32_e32 v47, 0xffff0000, v48
	v_lshlrev_b32_e32 v48, 16, v49
	v_and_b32_e32 v49, 0xffff0000, v49
	v_pk_add_f32 v[36:37], v[36:37], v[50:51]
	v_pk_add_f32 v[26:27], v[26:27], v[48:49]
	v_pk_add_f32 v[28:29], v[28:29], v[46:47]
	s_andn2_b64 vcc, exec, s[52:53]
	s_mov_b64 s[0:1], -1
	s_cbranch_vccnz .LBB0_704
.LBB0_808:
	v_cvt_pk_bf16_f32 v46, v36, v37
	v_cvt_pk_bf16_f32 v47, v30, v31
	v_cvt_pk_bf16_f32 v48, v28, v29
	v_cvt_pk_bf16_f32 v49, v26, v27
	global_store_dwordx4 v[38:39], v[46:49], off offset:256
	s_cbranch_execz .LBB0_705
	s_branch .LBB0_706
.LBB0_809:
	global_load_dwordx4 v[36:39], v[34:35], off
	s_waitcnt vmcnt(0) lgkmcnt(0)
	v_lshlrev_b32_e32 v40, 16, v36
	v_and_b32_e32 v41, 0xffff0000, v36
	v_lshlrev_b32_e32 v36, 16, v37
	v_and_b32_e32 v37, 0xffff0000, v37
	v_pk_add_f32 v[22:23], v[22:23], v[36:37]
	v_lshlrev_b32_e32 v36, 16, v38
	v_and_b32_e32 v37, 0xffff0000, v38
	v_lshlrev_b32_e32 v38, 16, v39
	v_and_b32_e32 v39, 0xffff0000, v39
	v_pk_add_f32 v[32:33], v[32:33], v[40:41]
	v_pk_add_f32 v[18:19], v[18:19], v[38:39]
	v_pk_add_f32 v[20:21], v[20:21], v[36:37]
	s_andn2_b64 vcc, exec, s[52:53]
	s_mov_b64 s[74:75], -1
	s_cbranch_vccnz .LBB0_735
.LBB0_810:
	v_cvt_pk_bf16_f32 v36, v32, v33
	v_cvt_pk_bf16_f32 v37, v22, v23
	v_cvt_pk_bf16_f32 v38, v20, v21
	v_cvt_pk_bf16_f32 v39, v18, v19
	global_store_dwordx4 v[34:35], v[36:39], off
	s_cbranch_execz .LBB0_736
	s_branch .LBB0_737
.LBB0_811:
	global_load_dwordx4 v[30:33], v[22:23], off offset:256
	s_waitcnt vmcnt(0) lgkmcnt(0)
	v_lshlrev_b32_e32 v34, 16, v30
	v_and_b32_e32 v35, 0xffff0000, v30
	v_lshlrev_b32_e32 v30, 16, v31
	v_and_b32_e32 v31, 0xffff0000, v31
	v_pk_add_f32 v[14:15], v[14:15], v[30:31]
	v_lshlrev_b32_e32 v30, 16, v32
	v_and_b32_e32 v31, 0xffff0000, v32
	v_lshlrev_b32_e32 v32, 16, v33
	v_and_b32_e32 v33, 0xffff0000, v33
	v_pk_add_f32 v[20:21], v[20:21], v[34:35]
	v_pk_add_f32 v[10:11], v[10:11], v[32:33]
	v_pk_add_f32 v[12:13], v[12:13], v[30:31]
	s_andn2_b64 vcc, exec, s[52:53]
	s_mov_b64 s[0:1], -1
	s_cbranch_vccnz .LBB0_762
.LBB0_812:
	v_cvt_pk_bf16_f32 v30, v20, v21
	v_cvt_pk_bf16_f32 v31, v14, v15
	v_cvt_pk_bf16_f32 v32, v12, v13
	v_cvt_pk_bf16_f32 v33, v10, v11
	global_store_dwordx4 v[22:23], v[30:33], off offset:256
	s_cbranch_execz .LBB0_763
	s_branch .LBB0_764

; __device__ __forceinline__ float bf_lo(unsigned w) { return __uint_as_float(w << 16); }
; __device__ __forceinline__ float bf_hi(unsigned w) { return __uint_as_float(w & 0xffff0000u); }
; __device__ __forceinline__ f32x4 sigm4(unsigned lo, unsigned hi) { f32x4 r; r[0] = sigm(bf_lo(lo)); r[1] = sigm(bf_hi(lo)); r[2] = sigm(bf_lo(hi)); r[3] = sigm(bf_hi(hi)); return r; }
; __device__ __forceinline__ u32x4 pack8(f32x4 v0, f32x4 v1) { u32x4 w; w.x = cvt_pk_bf16(v0[0], v0[1]); w.y = cvt_pk_bf16(v0[2], v0[3]); w.z = cvt_pk_bf16(v1[0], v1[1]); w.w = cvt_pk_bf16(v1[2], v1[3]); return w; }
; __device__ __forceinline__ void epi8(const Desc& d, int pb, int row, int col, f32x4 v0, f32x4 v1) {
;     if (d.epi == EPI_PIN) {
;         const int pn = col >> 8; bf16_t* p;
;         if (pn < 21) p = (bf16_t*)d.o0 + (size_t)row * NPA + col;
;         else if (pn == 21) p = (bf16_t*)d.o1 + (size_t)row * NKR + (col - 21 * 256);
;         else p = (bf16_t*)d.o2 + (size_t)row * NPG + (col - 22 * 256);
;         *(u32x4*)p = pack8(v0, v1);
;     } else if (d.epi == EPI_BF16) {
;         *(u32x4*)((bf16_t*)d.o0 + (size_t)pb * d.sO + (size_t)row * d.ldc + col) = pack8(v0 * d.scale, v1 * d.scale);
;     } else if (d.epi == EPI_MERGE0 || d.epi == EPI_MERGE1 || d.epi == EPI_MERGE2) {
;         const u32x4 gw = *(const u32x4*)(d.gate + (size_t)row * NPG + col);
;         v0 *= sigm4(gw.x, gw.y); v1 *= sigm4(gw.z, gw.w);
;         bf16_t* mp = (bf16_t*)d.o0 + (size_t)row * DM + col;
;         if (d.epi != EPI_MERGE0) { const u32x4 m = *(const u32x4*)mp;
;             v0 += (f32x4){bf_lo(m.x), bf_hi(m.x), bf_lo(m.y), bf_hi(m.y)}; v1 += (f32x4){bf_lo(m.z), bf_hi(m.z), bf_lo(m.w), bf_hi(m.w)}; }
;         if (d.epi != EPI_MERGE2) *(u32x4*)mp = pack8(v0, v1);
;         else *(u32x4*)((bf16_t*)d.o1 + (size_t)row * DM + col) = pack8(v0, v1);
; __device__ __forceinline__ void skinny_phase(LAS unsigned char* lds, const Desc& g, int G, int bx, int wave, int lane) {
;     ...
;         red[(wave * 64 + lane) * 2] = a0; red[(wave * 64 + lane) * 2 + 1] = a1;
;         __syncthreads();
;         if (wave == 0) {
; #pragma unroll
;             for (int w = 1; w < 8; ++w) { a0 += red[(w * 64 + lane) * 2]; a1 += red[(w * 64 + lane) * 2 + 1]; }
;             epi8(g, 0, LREAL + fr, c0 + 8 * fq, a0, a1);
;         }
.LBB0_820:
	s_or_b64 exec, exec, s[8:9]
	v_cvt_pk_bf16_f32 v34, v2, v3
	v_cvt_pk_bf16_f32 v35, v0, v1
	v_cvt_pk_bf16_f32 v36, v6, v7
	v_cvt_pk_bf16_f32 v37, v4, v5
	global_store_dwordx4 v[32:33], v[34:37], off

; __device__ __forceinline__ void epi8(const Desc& d, int pb, int row, int col, f32x4 v0, f32x4 v1) {
;     ...
;     } else {
;         float* hp = (float*)d.o0 + (size_t)row * DM + col;
;         const float* rp = (row < LREAL ? (const float*)d.o2 + (size_t)row * DM : (const float*)d.gate + (size_t)(row - LREAL) * DM) + col;
;         v0 += *(const f32x4*)rp; v1 += *(const f32x4*)(rp + 4);
;         if (d.epi == EPI_RESID) { *(f32x4*)hp = v0; *(f32x4*)(hp + 4) = v1; }
;         else if (row < LREAL) { float* op = (float*)d.o1 + (size_t)row * DM + col; *(f32x4*)op = v0; *(f32x4*)(op + 4) = v1; }
; __device__ __forceinline__ void skinny_phase(LAS unsigned char* lds, const Desc& g, int G, int bx, int wave, int lane) {
;     ...
;         red[(wave * 64 + lane) * 2] = a0; red[(wave * 64 + lane) * 2 + 1] = a1;
;         __syncthreads();
;         if (wave == 0) {
; #pragma unroll
;             for (int w = 1; w < 8; ++w) { a0 += red[(w * 64 + lane) * 2]; a1 += red[(w * 64 + lane) * 2 + 1]; }
;             epi8(g, 0, LREAL + fr, c0 + 8 * fq, a0, a1);
;         }
.Lsk_done:
	s_nop 7
	s_andn2_b64 vcc, exec, s[4:5]
	s_nop 1
	ds_write_b128 v9, v[0:3]
	s_nop 2
	ds_write_b128 v9, v[4:7] offset:16
	s_waitcnt lgkmcnt(0)
	s_barrier
	s_cbranch_vccnz .LBB0_821
	ds_read_b128 v[32:35], v44 offset:2048
	ds_read_b128 v[36:39], v44 offset:2064
	v_lshl_add_u32 v144, s6, 5, v8
	s_mov_b64 s[8:9], -1
	s_cmp_lt_i32 s26, 2
	s_waitcnt lgkmcnt(1)
	v_pk_add_f32 v[34:35], v[2:3], v[34:35]
	v_pk_add_f32 v[32:33], v[0:1], v[32:33]
	ds_read_b128 v[0:3], v44 offset:4096
	s_waitcnt lgkmcnt(1)
	v_pk_add_f32 v[6:7], v[6:7], v[38:39]
	v_pk_add_f32 v[4:5], v[4:5], v[36:37]
	s_waitcnt lgkmcnt(0)
	v_pk_add_f32 v[34:35], v[34:35], v[2:3]
	v_pk_add_f32 v[32:33], v[32:33], v[0:1]
	ds_read_b128 v[0:3], v44 offset:4112
	s_waitcnt lgkmcnt(0)
	v_pk_add_f32 v[6:7], v[6:7], v[2:3]
	v_pk_add_f32 v[4:5], v[4:5], v[0:1]
	ds_read_b128 v[0:3], v44 offset:6144
	s_waitcnt lgkmcnt(0)
	v_pk_add_f32 v[34:35], v[34:35], v[2:3]
	v_pk_add_f32 v[32:33], v[32:33], v[0:1]
	ds_read_b128 v[0:3], v44 offset:6160
	s_waitcnt lgkmcnt(0)
	v_pk_add_f32 v[6:7], v[6:7], v[2:3]
	v_pk_add_f32 v[4:5], v[4:5], v[0:1]
	ds_read_b128 v[0:3], v44 offset:8192
	s_waitcnt lgkmcnt(0)
	v_pk_add_f32 v[34:35], v[34:35], v[2:3]
	v_pk_add_f32 v[32:33], v[32:33], v[0:1]
	ds_read_b128 v[0:3], v44 offset:8208
	s_waitcnt lgkmcnt(0)
	v_pk_add_f32 v[6:7], v[6:7], v[2:3]
	v_pk_add_f32 v[4:5], v[4:5], v[0:1]
	ds_read_b128 v[0:3], v44 offset:10240
	s_waitcnt lgkmcnt(0)
	v_pk_add_f32 v[34:35], v[34:35], v[2:3]
	v_pk_add_f32 v[32:33], v[32:33], v[0:1]
	ds_read_b128 v[0:3], v44 offset:10256
	s_waitcnt lgkmcnt(0)
	v_pk_add_f32 v[6:7], v[6:7], v[2:3]
	v_pk_add_f32 v[4:5], v[4:5], v[0:1]
	ds_read_b128 v[0:3], v44 offset:12288
	s_waitcnt lgkmcnt(0)
	v_pk_add_f32 v[34:35], v[34:35], v[2:3]
	v_pk_add_f32 v[32:33], v[32:33], v[0:1]
	ds_read_b128 v[0:3], v44 offset:12304
	s_waitcnt lgkmcnt(0)
	v_pk_add_f32 v[6:7], v[6:7], v[2:3]
	v_pk_add_f32 v[36:37], v[4:5], v[0:1]
	ds_read_b128 v[2:5], v44 offset:14336
	s_waitcnt lgkmcnt(0)
	v_pk_add_f32 v[0:1], v[34:35], v[4:5]
	v_pk_add_f32 v[2:3], v[32:33], v[2:3]
	ds_read_b128 v[32:35], v44 offset:14352
	s_waitcnt lgkmcnt(0)
	v_pk_add_f32 v[4:5], v[6:7], v[34:35]
	v_pk_add_f32 v[6:7], v[36:37], v[32:33]
	s_cbranch_scc1 .LBB0_836
	s_cmp_lt_i32 s26, 5
	s_cbranch_scc1 .LBB0_830
	s_cmp_eq_u32 s26, 5
	s_cbranch_scc0 .LBB0_829
	v_ashrrev_i32_e32 v33, 31, v144
	v_mov_b32_e32 v32, v144
	v_lshlrev_b64 v[40:41], 2, v[32:33]
	v_lshl_add_u64 v[36:37], v[14:15], 0, v[40:41]
	global_load_dwordx4 v[32:35], v[36:37], off offset:16
	s_nop 0
	global_load_dwordx4 v[36:39], v[36:37], off
	v_lshl_add_u64 v[40:41], v[12:13], 0, v[40:41]
	s_waitcnt vmcnt(0) lgkmcnt(0)
	v_pk_add_f32 v[34:35], v[4:5], v[34:35]
	v_pk_add_f32 v[38:39], v[0:1], v[38:39]
	v_pk_add_f32 v[36:37], v[2:3], v[36:37]
	v_pk_add_f32 v[32:33], v[6:7], v[32:33]
	global_store_dwordx4 v[40:41], v[36:39], off
	global_store_dwordx4 v[40:41], v[32:35], off offset:16

; __device__ __forceinline__ float bf_lo(unsigned w) { return __uint_as_float(w << 16); }
; __device__ __forceinline__ float bf_hi(unsigned w) { return __uint_as_float(w & 0xffff0000u); }
; __device__ __forceinline__ float sigm(float x) { return __builtin_amdgcn_rcpf(1.f + __builtin_amdgcn_exp2f(-1.4426950408889634f * x)); }
; __device__ __forceinline__ f32x4 sigm4(unsigned lo, unsigned hi) { f32x4 r; r[0] = sigm(bf_lo(lo)); r[1] = sigm(bf_hi(lo)); r[2] = sigm(bf_lo(hi)); r[3] = sigm(bf_hi(hi)); return r; }
; __device__ __forceinline__ void epi8(const Desc& d, int pb, int row, int col, f32x4 v0, f32x4 v1) {
;     ...
;     } else if (d.epi == EPI_MERGE0 || d.epi == EPI_MERGE1 || d.epi == EPI_MERGE2) {
;         const u32x4 gw = *(const u32x4*)(d.gate + (size_t)row * NPG + col);
;         v0 *= sigm4(gw.x, gw.y); v1 *= sigm4(gw.z, gw.w);
;         bf16_t* mp = (bf16_t*)d.o0 + (size_t)row * DM + col;
;         if (d.epi != EPI_MERGE0) { const u32x4 m = *(const u32x4*)mp;
;             v0 += (f32x4){bf_lo(m.x), bf_hi(m.x), bf_lo(m.y), bf_hi(m.y)}; v1 += (f32x4){bf_lo(m.z), bf_hi(m.z), bf_lo(m.w), bf_hi(m.w)}; }
.LBB0_830:
	s_andn2_b64 vcc, exec, s[8:9]
	s_cbranch_vccnz .LBB0_835
	v_ashrrev_i32_e32 v33, 31, v144
	v_mov_b32_e32 v32, v144
	v_lshlrev_b64 v[42:43], 1, v[32:33]
	v_lshl_add_u64 v[34:35], v[16:17], 0, v[42:43]
	global_load_dwordx4 v[34:37], v[34:35], off
	s_andn2_b64 vcc, exec, s[0:1]
	v_lshl_add_u64 v[42:43], v[18:19], 0, v[42:43]
	s_waitcnt vmcnt(0) lgkmcnt(0)
	v_lshlrev_b32_e32 v38, 16, v34
	v_and_b32_e32 v34, 0xffff0000, v34
	v_lshlrev_b32_e32 v39, 16, v35
	v_and_b32_e32 v35, 0xffff0000, v35
	v_lshlrev_b32_e32 v40, 16, v36
	v_and_b32_e32 v36, 0xffff0000, v36
	v_lshlrev_b32_e32 v41, 16, v37
	v_and_b32_e32 v37, 0xffff0000, v37
	v_mul_f32_e32 v38, 0xbfb8aa3b, v38
	v_mul_f32_e32 v34, 0xbfb8aa3b, v34
	v_mul_f32_e32 v39, 0xbfb8aa3b, v39
	v_mul_f32_e32 v35, 0xbfb8aa3b, v35
	v_mul_f32_e32 v40, 0xbfb8aa3b, v40
	v_mul_f32_e32 v36, 0xbfb8aa3b, v36
	v_mul_f32_e32 v41, 0xbfb8aa3b, v41
	v_mul_f32_e32 v37, 0xbfb8aa3b, v37
	v_exp_f32_e32 v38, v38
	v_exp_f32_e32 v34, v34
	v_exp_f32_e32 v39, v39
	v_exp_f32_e32 v35, v35
	v_exp_f32_e32 v40, v40
	v_exp_f32_e32 v36, v36
	v_exp_f32_e32 v41, v41
	v_exp_f32_e32 v37, v37
	v_add_f32_e32 v38, 1.0, v38
	v_add_f32_e32 v47, 1.0, v34
	v_add_f32_e32 v39, 1.0, v39
	v_add_f32_e32 v48, 1.0, v35
	v_add_f32_e32 v40, 1.0, v40
	v_add_f32_e32 v49, 1.0, v36
	v_add_f32_e32 v41, 1.0, v41
	v_add_f32_e32 v51, 1.0, v37
	v_rcp_f32_e32 v34, v38
	v_rcp_f32_e32 v35, v47
	v_rcp_f32_e32 v36, v39
	v_rcp_f32_e32 v37, v48
	v_rcp_f32_e32 v48, v40
	v_rcp_f32_e32 v50, v41
	v_rcp_f32_e32 v51, v51
	v_rcp_f32_e32 v49, v49
	v_pk_mul_f32 v[38:39], v[0:1], v[36:37]
	v_pk_mul_f32 v[40:41], v[2:3], v[34:35]
	v_pk_mul_f32 v[34:35], v[4:5], v[50:51]
	v_pk_mul_f32 v[36:37], v[6:7], v[48:49]
	s_cbranch_vccz .LBB0_848
	s_andn2_b64 vcc, exec, s[2:3]
	s_mov_b64 s[8:9], -1
	s_cbranch_vccz .LBB0_849

; __device__ __forceinline__ u32x4 pack8(f32x4 v0, f32x4 v1) { u32x4 w; w.x = cvt_pk_bf16(v0[0], v0[1]); w.y = cvt_pk_bf16(v0[2], v0[3]); w.z = cvt_pk_bf16(v1[0], v1[1]); w.w = cvt_pk_bf16(v1[2], v1[3]); return w; }
; __device__ __forceinline__ void epi8(const Desc& d, int pb, int row, int col, f32x4 v0, f32x4 v1) {
;     ...
;         if (d.epi != EPI_MERGE2) *(u32x4*)mp = pack8(v0, v1);
;         else *(u32x4*)((bf16_t*)d.o1 + (size_t)row * DM + col) = pack8(v0, v1);
.LBB0_834:
	v_lshl_add_u64 v[32:33], v[32:33], 1, v[20:21]
	v_cvt_pk_bf16_f32 v40, v40, v41
	v_cvt_pk_bf16_f32 v41, v38, v39
	v_cvt_pk_bf16_f32 v42, v36, v37
	v_cvt_pk_bf16_f32 v43, v34, v35
	global_store_dwordx4 v[32:33], v[40:43], off

; __device__ __forceinline__ u32x4 pack8(f32x4 v0, f32x4 v1) { u32x4 w; w.x = cvt_pk_bf16(v0[0], v0[1]); w.y = cvt_pk_bf16(v0[2], v0[3]); w.z = cvt_pk_bf16(v1[0], v1[1]); w.w = cvt_pk_bf16(v1[2], v1[3]); return w; }
; __device__ __forceinline__ void epi8(const Desc& d, int pb, int row, int col, f32x4 v0, f32x4 v1) {
;     if (d.epi == EPI_PIN) {
;         const int pn = col >> 8; bf16_t* p;
;         if (pn < 21) p = (bf16_t*)d.o0 + (size_t)row * NPA + col;
;         else if (pn == 21) p = (bf16_t*)d.o1 + (size_t)row * NKR + (col - 21 * 256);
;         else p = (bf16_t*)d.o2 + (size_t)row * NPG + (col - 22 * 256);
;         *(u32x4*)p = pack8(v0, v1);
;     } else if (d.epi == EPI_BF16) {
;         *(u32x4*)((bf16_t*)d.o0 + (size_t)pb * d.sO + (size_t)row * d.ldc + col) = pack8(v0 * d.scale, v1 * d.scale);
.LBB0_836:
	s_andn2_b64 vcc, exec, s[8:9]
	s_cbranch_vccnz .LBB0_821
	s_cmp_gt_i32 s26, 0
	s_mov_b64 s[8:9], -1
	s_cbranch_scc0 .LBB0_839
	v_ashrrev_i32_e32 v37, 31, v144
	v_mov_b32_e32 v36, v144
	v_lshl_add_u64 v[36:37], v[36:37], 1, v[22:23]
	v_cvt_pk_bf16_f32 v32, v2, v3
	v_cvt_pk_bf16_f32 v33, v0, v1
	v_cvt_pk_bf16_f32 v34, v6, v7
	v_cvt_pk_bf16_f32 v35, v4, v5
	global_store_dwordx4 v[36:37], v[32:35], off
	s_mov_b64 s[8:9], 0

; __device__ __forceinline__ float bf_lo(unsigned w) { return __uint_as_float(w << 16); }
; __device__ __forceinline__ float bf_hi(unsigned w) { return __uint_as_float(w & 0xffff0000u); }
; __device__ __forceinline__ u32x4 pack8(f32x4 v0, f32x4 v1) { u32x4 w; w.x = cvt_pk_bf16(v0[0], v0[1]); w.y = cvt_pk_bf16(v0[2], v0[3]); w.z = cvt_pk_bf16(v1[0], v1[1]); w.w = cvt_pk_bf16(v1[2], v1[3]); return w; }
; __device__ __forceinline__ void epi8(const Desc& d, int pb, int row, int col, f32x4 v0, f32x4 v1) {
;     ...
;         if (d.epi != EPI_MERGE0) { const u32x4 m = *(const u32x4*)mp;
;             v0 += (f32x4){bf_lo(m.x), bf_hi(m.x), bf_lo(m.y), bf_hi(m.y)}; v1 += (f32x4){bf_lo(m.z), bf_hi(m.z), bf_lo(m.w), bf_hi(m.w)}; }
;         if (d.epi != EPI_MERGE2) *(u32x4*)mp = pack8(v0, v1);
.LBB0_848:
	global_load_dwordx4 v[48:51], v[42:43], off
	s_waitcnt vmcnt(0) lgkmcnt(0)
	v_lshlrev_b32_e32 v52, 16, v48
	v_and_b32_e32 v53, 0xffff0000, v48
	v_lshlrev_b32_e32 v48, 16, v49
	v_and_b32_e32 v49, 0xffff0000, v49
	v_pk_add_f32 v[38:39], v[38:39], v[48:49]
	v_lshlrev_b32_e32 v48, 16, v50
	v_and_b32_e32 v49, 0xffff0000, v50
	v_lshlrev_b32_e32 v50, 16, v51
	v_and_b32_e32 v51, 0xffff0000, v51
	v_pk_add_f32 v[40:41], v[40:41], v[52:53]
	v_pk_add_f32 v[34:35], v[34:35], v[50:51]
	v_pk_add_f32 v[36:37], v[36:37], v[48:49]
	s_andn2_b64 vcc, exec, s[2:3]
	s_mov_b64 s[8:9], -1
	s_cbranch_vccnz .LBB0_833
.LBB0_849:
	v_cvt_pk_bf16_f32 v48, v40, v41
	v_cvt_pk_bf16_f32 v49, v38, v39
	v_cvt_pk_bf16_f32 v50, v36, v37
	v_cvt_pk_bf16_f32 v51, v34, v35
	global_store_dwordx4 v[42:43], v[48:51], off
	s_cbranch_execz .LBB0_834
	s_branch .LBB0_835

; __device__ __forceinline__ f32x4 zero4() { float a, b, c, e; asm volatile("v_mov_b32 %0, 0\n\tv_mov_b32 %1, 0\n\tv_mov_b32 %2, 0\n\tv_mov_b32 %3, 0" : "=v"(a), "=v"(b), "=v"(c), "=v"(e)); return (f32x4){a, b, c, e}; }
; __global__ void __launch_bounds__(512, 2) mk_fwd(Args a) {
;     ...
;                 { const f32x4 zf = pg8::zero4(); const u32x4 z4 = {__float_as_uint(zf[0]), __float_as_uint(zf[1]), __float_as_uint(zf[2]), __float_as_uint(zf[3])};
;                 for (int idx = gt; idx < 48 * (NKV / 8); idx += NTH) *(u32x4*)(KV + (size_t)LSEQ * NKV + (size_t)idx * 8) = z4;
.LBB0_861:
	v_add_u32_e32 v8, s4, v8
	s_movk_i32 s6, 0x5fff
	v_cmp_lt_i32_e32 vcc, s6, v8
	global_store_dwordx4 v[6:7], v[0:3], off
	s_or_b64 s[2:3], vcc, s[2:3]
	v_lshl_add_u64 v[6:7], v[6:7], 0, s[8:9]
	s_andn2_b64 exec, exec, s[2:3]
	s_cbranch_execnz .LBB0_861

; __global__ void __launch_bounds__(512, 2) mk_fwd(Args a) {
;     ...
;                 for (int idx = gt; idx < 48 * (NQ / 8); idx += NTH) *(u32x4*)(KP + (size_t)LSEQ * NQ + (size_t)idx * 8) = z4; }
.LBB0_864:
	v_add_u32_e32 v8, s4, v8
	s_movk_i32 s6, 0x47ff
	v_cmp_lt_i32_e32 vcc, s6, v8
	global_store_dwordx4 v[6:7], v[0:3], off
	s_or_b64 s[2:3], vcc, s[2:3]
	v_lshl_add_u64 v[6:7], v[6:7], 0, s[8:9]
	s_andn2_b64 exec, exec, s[2:3]
	s_cbranch_execnz .LBB0_864

; __global__ void __launch_bounds__(512, 2) mk_fwd(Args a) {
;     ...
;                 for (int idx = gt; idx < LSEQ * 32; idx += NTH) { const int pos = idx >> 5, i = idx & 31;
;                     const float inv = __builtin_amdgcn_exp2f(-(float)i * (13.287712379549449f / 32.f)); const float ang = (float)pos * inv;
;                     double rv = (double)ang * 0.15915494309189535; rv -= __builtin_floor(rv); const float rf = (float)rv;
;                     ROPE[pos * 64 + i] = __builtin_amdgcn_cosf(rf); ROPE[pos * 64 + 32 + i] = __builtin_amdgcn_sinf(rf); }
.LBB0_867:
	v_ashrrev_i32_e32 v3, 5, v2
	v_cvt_f32_i32_e32 v8, v3
	v_lshl_or_b32 v6, v3, 6, v0
	v_add_u32_e32 v2, s4, v2
	s_mov_b32 s6, 0x401ff
	v_mul_f32_e32 v3, v1, v8
	v_cvt_f64_f32_e32 v[8:9], v3
	v_mul_f64 v[10:11], v[8:9], s[28:29]
	v_floor_f64_e32 v[10:11], v[10:11]
	v_fma_f64 v[8:9], v[8:9], s[28:29], -v[10:11]
	v_cvt_f32_f64_e32 v3, v[8:9]
	v_cos_f32_e32 v8, v3
	v_sin_f32_e32 v3, v3
	v_cmp_lt_i32_e32 vcc, s6, v2
	v_ashrrev_i32_e32 v7, 31, v6
	s_or_b64 s[2:3], vcc, s[2:3]
	v_lshl_add_u64 v[6:7], v[6:7], 2, s[34:35]
	global_store_dword v[6:7], v8, off
	global_store_dword v[6:7], v3, off offset:128
	s_andn2_b64 exec, exec, s[2:3]
	s_cbranch_execnz .LBB0_867

; __device__ __forceinline__ bf16_t to_bf1(float f) { return (bf16_t)(cvt_pk_bf16(f, 0.f) & 0xffffu); }
; __global__ void __launch_bounds__(512, 2) mk_fwd(Args a) {
;     ...
;                 for (int idx = gt; idx < 2 * 65536; idx += NTH) { const int cs = idx >> 16, m = (idx >> 8) & 255, c = idx & 255; const float rf = (float)((m * c) & 255) * (1.f / 256.f);
;                     CS[idx] = to_bf1(cs ? __builtin_amdgcn_sinf(rf) : __builtin_amdgcn_cosf(rf)); }
.LBB0_870:
	v_lshrrev_b32_e32 v3, 8, v2
	v_mul_lo_u32 v3, v3, v2
	v_cvt_f32_ubyte0_e32 v3, v3
	v_mul_f32_e32 v3, 0x3b800000, v3
	v_sin_f32_e32 v5, v3
	v_cos_f32_e32 v3, v3
	v_cmp_gt_u32_e32 vcc, s7, v2
	v_add_u32_e32 v2, s4, v2
	s_mov_b32 s0, 0x1ffff
	v_cmp_lt_i32_e64 s[0:1], s0, v2
	v_cndmask_b32_e32 v3, v5, v3, vcc
	s_or_b64 s[8:9], s[0:1], s[8:9]
	v_cvt_pk_bf16_f32 v3, v3, v145
	global_store_short v[0:1], v3, off
	v_lshl_add_u64 v[0:1], v[0:1], 0, s[14:15]
	s_andn2_b64 exec, exec, s[8:9]
	s_cbranch_execnz .LBB0_870

; __device__ __forceinline__ unsigned cvt_pk_bf16(float lo, float hi) { unsigned r; asm volatile("v_cvt_pk_bf16_f32 %0, %1, %2" : "=v"(r) : "v"(lo), "v"(hi)); return r; }
; __global__ void __launch_bounds__(512, 2) mk_fwd(Args a) {
;     ...
;                 for (int idx = gt; idx < MH * (MH / 8); idx += NTH) { const int kf = idx / (MH / 8), lf0 = (idx - kf * (MH / 8)) * 8;
;                     int t = (int)(((long)kf * lf0) % LSEQ); float cv[8], sv[8];
; #pragma unroll
;                     for (int j = 0; j < 8; ++j) { const bool ok = (kf <= HF) && (lf0 + j <= HF); const float rf = (float)t * (1.f / (float)LSEQ);
;                         cv[j] = ok ? __builtin_amdgcn_cosf(rf) : 0.f; sv[j] = ok ? __builtin_amdgcn_sinf(rf) : 0.f; t += kf; if (t >= LSEQ) t -= LSEQ; }
;                     u32x4 wc_, ws_; wc_.x = cvt_pk_bf16(cv[0], cv[1]); wc_.y = cvt_pk_bf16(cv[2], cv[3]); wc_.z = cvt_pk_bf16(cv[4], cv[5]); wc_.w = cvt_pk_bf16(cv[6], cv[7]);
;                     ws_.x = cvt_pk_bf16(sv[0], sv[1]); ws_.y = cvt_pk_bf16(sv[2], sv[3]); ws_.z = cvt_pk_bf16(sv[4], sv[5]); ws_.w = cvt_pk_bf16(sv[6], sv[7]);
;                     *(u32x4*)(CH + (size_t)kf * MH + lf0) = wc_; *(u32x4*)(SH + (size_t)kf * MH + lf0) = ws_; }
.LBB0_873:
	s_mov_b32 s0, 0x78787879
	v_mul_hi_i32 v0, v4, s0
	v_lshrrev_b32_e32 v2, 31, v0
	v_ashrrev_i32_e32 v0, 8, v0
	v_add_u32_e32 v5, v0, v2
	v_mul_i32_i24_e32 v0, 0xfffffde0, v5
	s_mov_b32 s0, 0x221320
	v_mul_hi_i32_i24_e32 v3, 0x1100, v5
	v_mul_i32_i24_e32 v2, 0x1100, v5
	v_add_u32_e32 v0, v0, v4
	v_cmp_gt_i32_e32 vcc, s0, v4
	v_lshlrev_b64 v[6:7], 1, v[2:3]
	v_add_u32_e32 v4, s4, v4
	v_lshlrev_b32_e32 v2, 3, v0
	s_mov_b32 s6, 0x241fff
	v_cmp_lt_i32_e64 s[50:51], s6, v4
	v_mad_i64_i32 v[10:11], s[6:7], v2, v5, 0
	v_or_b32_e32 v12, 2, v2
	v_or_b32_e32 v13, 3, v2
	v_mul_hi_u32 v144, v10, s18
	s_movk_i32 s0, 0x202
	v_ashrrev_i32_e32 v3, 31, v2
	v_cmp_gt_i32_e64 s[40:41], s26, v12
	v_cmp_gt_i32_e64 s[44:45], s26, v13
	v_mad_u64_u32 v[12:13], s[6:7], v11, s18, v[144:145]
	v_cmp_gt_i32_e64 s[0:1], s0, v0
	v_lshl_add_u64 v[8:9], s[28:29], 0, v[6:7]
	v_lshl_add_u64 v[6:7], s[8:9], 0, v[6:7]
	v_or_b32_e32 v0, 1, v2
	v_or_b32_e32 v14, 4, v2
	v_or_b32_e32 v15, 5, v2
	v_or_b32_e32 v16, 6, v2
	v_or_b32_e32 v17, 7, v2
	v_lshlrev_b64 v[2:3], 1, v[2:3]
	v_mov_b32_e32 v144, v13
	v_mov_b32_e32 v13, v145
	v_cmp_gt_i32_e64 s[56:57], s26, v14
	v_cmp_gt_i32_e64 s[58:59], s26, v15
	v_cmp_gt_i32_e64 s[60:61], s26, v16
	v_cmp_gt_i32_e64 s[62:63], s26, v17
	v_lshl_add_u64 v[14:15], v[8:9], 0, v[2:3]
	v_lshl_add_u64 v[16:17], v[6:7], 0, v[2:3]
	v_mad_u64_u32 v[2:3], s[6:7], v10, s24, v[12:13]
	v_mov_b32_e32 v1, v145
	v_cmp_gt_i32_e64 s[38:39], s26, v0
	v_mov_b32_e32 v0, v3
	v_lshl_add_u64 v[0:1], v[144:145], 0, v[0:1]
	v_ashrrev_i32_e32 v18, 31, v11
	v_mad_u64_u32 v[0:1], s[6:7], v11, s24, v[0:1]
	v_mad_u64_u32 v[0:1], s[6:7], v18, s18, v[0:1]
	v_mov_b32_e32 v2, v1
	v_mad_u64_u32 v[2:3], s[6:7], v18, s18, v[2:3]
	v_mad_i32_i24 v1, v18, s24, v2
	v_lshrrev_b64 v[2:3], 3, v[0:1]
	v_lshrrev_b32_e32 v144, 31, v1
	v_lshl_add_u64 v[0:1], v[2:3], 0, v[144:145]
	v_mad_u64_u32 v[2:3], s[6:7], v0, s5, 0
	s_and_b64 s[0:1], vcc, s[0:1]
	s_and_b64 s[52:53], vcc, s[38:39]
	s_and_b64 s[48:49], vcc, s[40:41]
	s_and_b64 s[46:47], vcc, s[44:45]
	s_and_b64 s[44:45], vcc, s[56:57]
	s_and_b64 s[40:41], vcc, s[58:59]
	s_and_b64 s[38:39], vcc, s[60:61]
	s_and_b64 vcc, vcc, s[62:63]
	v_mov_b32_e32 v0, v3
	s_or_b64 s[14:15], s[50:51], s[14:15]
	v_sub_co_u32_e64 v2, s[50:51], v10, v2
	v_mad_u64_u32 v[0:1], s[6:7], v1, s5, v[0:1]
	v_add_u32_e32 v1, v5, v2
	v_subb_co_u32_e64 v3, s[50:51], v11, v0, s[50:51]
	v_add_u32_e32 v0, 0xffffdff0, v1
	v_cmp_lt_i32_e64 s[50:51], s13, v1
	v_xor_b32_e32 v6, v2, v3
	v_ffbh_i32_e32 v7, v3
	v_cndmask_b32_e64 v0, v1, v0, s[50:51]
	v_ashrrev_i32_e32 v1, 31, v6
	v_add_u32_e32 v6, -1, v7
	v_cvt_f32_i32_e32 v7, v0
	v_add_u32_e32 v0, v0, v5
	v_add_u32_e32 v1, 32, v1
	v_add_u32_e32 v8, 0xffffdff0, v0
	v_cmp_lt_i32_e64 s[50:51], s13, v0
	v_min_u32_e32 v6, v6, v1
	v_mul_f32_e32 v7, 0x38ff8040, v7
	v_cndmask_b32_e64 v8, v0, v8, s[50:51]
	v_lshlrev_b64 v[0:1], v6, v[2:3]
	v_sub_u32_e32 v2, 32, v6
	v_cvt_f32_i32_e32 v3, v8
	v_add_u32_e32 v6, v8, v5
	v_min_u32_e32 v0, 1, v0
	v_add_u32_e32 v8, 0xffffdff0, v6
	v_cmp_lt_i32_e64 s[50:51], s13, v6
	v_or_b32_e32 v0, v1, v0
	v_cvt_f32_i32_e32 v0, v0
	v_cndmask_b32_e64 v6, v6, v8, s[50:51]
	v_cvt_f32_i32_e32 v8, v6
	v_add_u32_e32 v6, v6, v5
	v_mul_f32_e32 v3, 0x38ff8040, v3
	v_add_u32_e32 v9, 0xffffdff0, v6
	v_cmp_lt_i32_e64 s[50:51], s13, v6
	v_cos_f32_e32 v10, v3
	v_sin_f32_e32 v3, v3
	v_cndmask_b32_e64 v6, v6, v9, s[50:51]
	v_cvt_f32_i32_e32 v9, v6
	v_add_u32_e32 v6, v6, v5
	v_ldexp_f32 v0, v0, v2
	v_mul_f32_e32 v2, 0x38ff8040, v8
	v_add_u32_e32 v8, 0xffffdff0, v6
	v_cmp_lt_i32_e64 s[50:51], s13, v6
	v_mul_f32_e32 v0, 0x38ff8040, v0
	v_cos_f32_e32 v11, v2
	v_cndmask_b32_e64 v6, v6, v8, s[50:51]
	v_sin_f32_e32 v2, v2
	v_cos_f32_e32 v8, v0
	v_sin_f32_e32 v0, v0
	v_cndmask_b32_e64 v12, 0, v3, s[48:49]
	v_cvt_f32_i32_e32 v3, v6
	v_add_u32_e32 v6, v6, v5
	v_cndmask_b32_e64 v10, 0, v10, s[48:49]
	v_add_u32_e32 v13, 0xffffdff0, v6
	v_cmp_lt_i32_e64 s[48:49], s13, v6
	v_cos_f32_e32 v1, v7
	v_mul_f32_e32 v3, 0x38ff8040, v3
	v_cndmask_b32_e64 v6, v6, v13, s[48:49]
	v_add_u32_e32 v5, v6, v5
	v_cndmask_b32_e64 v13, 0, v2, s[46:47]
	v_cvt_f32_i32_e32 v2, v6
	v_cndmask_b32_e64 v6, 0, v8, s[0:1]
	v_cndmask_b32_e64 v8, 0, v0, s[0:1]
	v_add_u32_e32 v19, 0xffffdff0, v5
	v_cmp_lt_i32_e64 s[0:1], s13, v5
	v_cndmask_b32_e64 v1, 0, v1, s[52:53]
	v_cvt_pk_bf16_f32 v0, v6, v1
	v_cos_f32_e32 v6, v3
	v_cndmask_b32_e64 v5, v5, v19, s[0:1]
	v_sin_f32_e32 v3, v3
	v_cvt_f32_i32_e32 v5, v5
	v_mul_f32_e32 v9, 0x38ff8040, v9
	v_cos_f32_e32 v18, v9
	v_cndmask_b32_e64 v11, 0, v11, s[46:47]
	v_mul_f32_e32 v2, 0x38ff8040, v2
	v_cndmask_b32_e64 v19, 0, v3, s[40:41]
	v_mul_f32_e32 v3, 0x38ff8040, v5
	v_sin_f32_e32 v7, v7
	v_sin_f32_e32 v9, v9
	v_cvt_pk_bf16_f32 v1, v10, v11
	v_cos_f32_e32 v11, v2
	v_cos_f32_e32 v5, v3
	v_sin_f32_e32 v3, v3
	v_cndmask_b32_e64 v10, 0, v18, s[44:45]
	v_sin_f32_e32 v18, v2
	v_cndmask_b32_e64 v2, 0, v6, s[40:41]
	v_cndmask_b32_e64 v7, 0, v7, s[52:53]
	v_cndmask_b32_e64 v9, 0, v9, s[44:45]
	v_cvt_pk_bf16_f32 v2, v10, v2
	v_cndmask_b32_e64 v6, 0, v11, s[38:39]
	v_cndmask_b32_e32 v5, 0, v5, vcc
	v_cndmask_b32_e32 v11, 0, v3, vcc
	v_cvt_pk_bf16_f32 v3, v6, v5
	v_cndmask_b32_e64 v10, 0, v18, s[38:39]
	v_cvt_pk_bf16_f32 v6, v8, v7
	v_cvt_pk_bf16_f32 v7, v12, v13
	v_cvt_pk_bf16_f32 v8, v9, v19
	v_cvt_pk_bf16_f32 v9, v10, v11
	global_store_dwordx4 v[14:15], v[0:3], off
	global_store_dwordx4 v[16:17], v[6:9], off
	s_andn2_b64 exec, exec, s[14:15]
	s_cbranch_execnz .LBB0_873

; __device__ __forceinline__ u32x4 pack8(f32x4 v0, f32x4 v1) { u32x4 w; w.x = cvt_pk_bf16(v0[0], v0[1]); w.y = cvt_pk_bf16(v0[2], v0[3]); w.z = cvt_pk_bf16(v1[0], v1[1]); w.w = cvt_pk_bf16(v1[2], v1[3]); return w; }
; __global__ void __launch_bounds__(512, 2) mk_fwd(Args a) {
;     ...
; #pragma unroll
;                     for (int j = 0; j < 8; ++j) s += (v[j].x * v[j].x + v[j].y * v[j].y) + (v[j].z * v[j].z + v[j].w * v[j].w);
;                     const float rs = __builtin_amdgcn_rsqf(wave_sum(s, lane) * (1.f / DM) + EPS);
; #pragma unroll
;                     for (int j = 0; j < 4; ++j) { const int c = (lane + 64 * j) * 8; const f32x4 g0 = *(const f32x4*)(gm + c), g1 = *(const f32x4*)(gm + c + 4);
;                         *(u32x4*)(X + (size_t)r * DM + c) = pg8::pack8(v[2 * j] * rs * g0, v[2 * j + 1] * rs * g1); }
.LBB0_931:
	s_waitcnt lgkmcnt(0)
	v_pk_mul_f32 v[6:7], v[38:39], v[38:39]
	v_pk_mul_f32 v[8:9], v[0:1], v[0:1]
	v_pk_mul_f32 v[4:5], v[2:3], v[2:3]
	v_mov_b32_e32 v10, v8
	v_mov_b32_e32 v11, v6
	v_mov_b32_e32 v6, v9
	v_pk_mul_f32 v[8:9], v[40:41], v[40:41]
	v_pk_add_f32 v[6:7], v[10:11], v[6:7]
	v_mov_b32_e32 v10, v4
	v_mov_b32_e32 v11, v8
	v_mov_b32_e32 v8, v5
	v_pk_add_f32 v[8:9], v[10:11], v[8:9]
	s_waitcnt vmcnt(0)
	v_pk_mul_f32 v[4:5], v[52:53], v[52:53]
	v_pk_mul_f32 v[10:11], v[50:51], v[50:51]
	v_pk_add_f32 v[6:7], v[6:7], v[8:9]
	v_pk_mov_b32 v[8:9], v[10:11], v[4:5] op_sel:[1,0]
	v_mov_b32_e32 v11, v5
	v_mul_f32_e32 v4, v54, v54
	v_pk_add_f32 v[18:19], v[6:7], v[6:7] op_sel:[0,1] op_sel_hi:[1,0]
	v_pk_add_f32 v[16:17], v[8:9], v[10:11]
	v_mov_b32_e32 v19, v4
	global_load_dwordx4 v[4:7], v[60:61], off
	global_load_dwordx4 v[8:11], v[60:61], off offset:16
	v_mul_f32_e32 v20, v55, v55
	v_pk_add_f32 v[16:17], v[16:17], v[16:17] op_sel:[0,1] op_sel_hi:[1,0]
	v_mul_f32_e32 v21, v56, v56
	v_mov_b32_e32 v17, v20
	v_pk_add_f32 v[16:17], v[18:19], v[16:17]
	v_mul_f32_e32 v18, v43, v43
	v_pk_fma_f32 v[18:19], v[42:43], v[42:43], v[18:19] op_sel_hi:[1,1,0]
	v_mul_f32_e32 v20, v45, v45
	v_mul_f32_e32 v22, v57, v57
	v_mov_b32_e32 v19, v21
	v_pk_fma_f32 v[20:21], v[44:45], v[44:45], v[20:21] op_sel_hi:[1,1,0]
	v_pk_mul_f32 v[12:13], v[48:49], v[48:49]
	v_mov_b32_e32 v21, v22
	v_pk_mul_f32 v[14:15], v[46:47], v[46:47]
	v_pk_add_f32 v[18:19], v[18:19], v[20:21]
	v_mul_f32_e32 v20, v32, v32
	v_pk_add_f32 v[16:17], v[16:17], v[18:19]
	v_pk_mov_b32 v[18:19], v[14:15], v[12:13] op_sel:[1,0]
	v_mov_b32_e32 v15, v13
	v_pk_add_f32 v[12:13], v[18:19], v[14:15]
	v_mul_f32_e32 v18, v30, v30
	v_mul_f32_e32 v19, v31, v31
	v_pk_add_f32 v[14:15], v[16:17], v[16:17] op_sel:[0,1] op_sel_hi:[1,0]
	v_pk_add_f32 v[12:13], v[12:13], v[12:13] op_sel:[0,1] op_sel_hi:[1,0]
	v_mov_b32_e32 v15, v18
	v_mov_b32_e32 v13, v19
	v_pk_add_f32 v[12:13], v[14:15], v[12:13]
	v_mul_f32_e32 v14, v35, v35
	v_mul_f32_e32 v16, v37, v37
	v_mul_f32_e32 v21, v33, v33
	v_pk_fma_f32 v[14:15], v[34:35], v[34:35], v[14:15] op_sel_hi:[1,1,0]
	v_pk_fma_f32 v[16:17], v[36:37], v[36:37], v[16:17] op_sel_hi:[1,1,0]
	v_mov_b32_e32 v15, v20
	v_mov_b32_e32 v17, v21
	v_pk_add_f32 v[14:15], v[14:15], v[16:17]
	s_add_i32 s6, s6, s72
	v_pk_add_f32 v[12:13], v[12:13], v[14:15]
	s_add_u32 s2, s2, s28
	v_add_f32_e32 v12, v12, v13
	ds_bpermute_b32 v13, v78, v12
	s_addc_u32 s3, s3, s29
	v_lshl_add_u64 v[72:73], v[72:73], 0, s[28:29]
	v_lshl_add_u64 v[74:75], v[74:75], 0, s[28:29]
	s_cmpk_gt_i32 s6, 0x200f
	s_waitcnt lgkmcnt(0)
	v_add_f32_e32 v12, v12, v13
	ds_bpermute_b32 v13, v79, v12
	v_lshl_add_u64 v[76:77], v[76:77], 0, s[28:29]
	s_waitcnt lgkmcnt(0)
	v_add_f32_e32 v12, v12, v13
	ds_bpermute_b32 v13, v80, v12
	s_waitcnt lgkmcnt(0)
	v_add_f32_e32 v12, v12, v13
	ds_bpermute_b32 v13, v81, v12
	s_waitcnt lgkmcnt(0)
	v_add_f32_e32 v12, v12, v13
	ds_bpermute_b32 v13, v82, v12
	s_waitcnt lgkmcnt(0)
	v_add_f32_e32 v12, v12, v13
	ds_bpermute_b32 v13, v83, v12
	s_waitcnt lgkmcnt(0)
	v_add_f32_e32 v12, v12, v13
	v_fmamk_f32 v12, v12, 0x3a000000, v202
	v_rsq_f32_e32 v12, v12
	s_nop 0
	v_pk_mul_f32 v[0:1], v[12:13], v[0:1] op_sel_hi:[0,1]
	v_pk_mul_f32 v[2:3], v[12:13], v[2:3] op_sel_hi:[0,1]
	v_pk_mul_f32 v[16:17], v[12:13], v[40:41] op_sel_hi:[0,1]
	v_pk_mul_f32 v[14:15], v[12:13], v[38:39] op_sel_hi:[0,1]
	s_waitcnt vmcnt(1)
	v_pk_mul_f32 v[2:3], v[2:3], v[6:7]
	v_pk_mul_f32 v[0:1], v[0:1], v[4:5]
	s_waitcnt vmcnt(0)
	v_pk_mul_f32 v[4:5], v[16:17], v[10:11]
	v_pk_mul_f32 v[6:7], v[14:15], v[8:9]
	v_cvt_pk_bf16_f32 v0, v0, v1
	v_cvt_pk_bf16_f32 v1, v2, v3
	v_pk_mul_f32 v[10:11], v[12:13], v[50:51] op_sel_hi:[0,1]
	v_cvt_pk_bf16_f32 v2, v6, v7
	v_cvt_pk_bf16_f32 v3, v4, v5
	v_lshl_add_u64 v[4:5], s[64:65], 0, v[70:71]
	v_add_co_u32_e32 v8, vcc, s7, v4
	v_pk_mul_f32 v[14:15], v[12:13], v[52:53] op_sel_hi:[0,1]
	s_nop 0
	v_addc_co_u32_e32 v9, vcc, 0, v5, vcc
	global_store_dwordx4 v[8:9], v[0:3], off
	global_load_dwordx4 v[0:3], v[60:61], off offset:2048
	s_nop 0
	global_load_dwordx4 v[4:7], v[60:61], off offset:2064
	v_pk_mul_f32 v[16:17], v[12:13], v[42:43] op_sel_hi:[0,1]
	v_pk_mul_f32 v[18:19], v[12:13], v[44:45] op_sel_hi:[0,1]
	v_lshl_add_u64 v[70:71], v[70:71], 0, s[4:5]
	s_waitcnt vmcnt(0)
	v_pk_mul_f32 v[2:3], v[14:15], v[2:3]
	v_pk_mul_f32 v[0:1], v[10:11], v[0:1]
	v_pk_mul_f32 v[6:7], v[18:19], v[6:7]
	v_pk_mul_f32 v[4:5], v[16:17], v[4:5]
	v_cvt_pk_bf16_f32 v0, v0, v1
	v_cvt_pk_bf16_f32 v1, v2, v3
	v_pk_mul_f32 v[10:11], v[12:13], v[54:55] op_sel_hi:[0,1]
	v_cvt_pk_bf16_f32 v2, v4, v5
	v_cvt_pk_bf16_f32 v3, v6, v7
	global_store_dwordx4 v[8:9], v[0:3], off offset:1024
	global_load_dwordx4 v[0:3], v[66:67], off
	s_nop 0
	global_load_dwordx4 v[4:7], v[66:67], off offset:16
	v_pk_mul_f32 v[14:15], v[12:13], v[56:57] op_sel_hi:[0,1]
	v_pk_mul_f32 v[16:17], v[12:13], v[46:47] op_sel_hi:[0,1]
	v_pk_mul_f32 v[18:19], v[12:13], v[48:49] op_sel_hi:[0,1]
	s_waitcnt vmcnt(0)
	v_pk_mul_f32 v[2:3], v[14:15], v[2:3]
	v_pk_mul_f32 v[0:1], v[10:11], v[0:1]
	v_pk_mul_f32 v[6:7], v[18:19], v[6:7]
	v_pk_mul_f32 v[4:5], v[16:17], v[4:5]
	v_cvt_pk_bf16_f32 v0, v0, v1
	v_cvt_pk_bf16_f32 v1, v2, v3
	v_pk_mul_f32 v[10:11], v[12:13], v[34:35] op_sel_hi:[0,1]
	v_cvt_pk_bf16_f32 v2, v4, v5
	v_cvt_pk_bf16_f32 v3, v6, v7
	global_store_dwordx4 v[8:9], v[0:3], off offset:2048
	global_load_dwordx4 v[0:3], v[68:69], off
	s_nop 0
	global_load_dwordx4 v[4:7], v[68:69], off offset:16
	v_pk_mul_f32 v[14:15], v[12:13], v[36:37] op_sel_hi:[0,1]
	v_pk_mul_f32 v[16:17], v[12:13], v[30:31] op_sel_hi:[0,1]
	v_pk_mul_f32 v[12:13], v[12:13], v[32:33] op_sel_hi:[0,1]
	s_waitcnt vmcnt(0)
	v_pk_mul_f32 v[2:3], v[14:15], v[2:3]
	v_pk_mul_f32 v[0:1], v[10:11], v[0:1]
	v_pk_mul_f32 v[6:7], v[12:13], v[6:7]
	v_pk_mul_f32 v[4:5], v[16:17], v[4:5]
	v_cvt_pk_bf16_f32 v0, v0, v1
	v_cvt_pk_bf16_f32 v1, v2, v3
	s_nop 0
	v_cvt_pk_bf16_f32 v2, v4, v5
	v_cvt_pk_bf16_f32 v3, v6, v7
	global_store_dwordx4 v[8:9], v[0:3], off offset:3072
	s_cbranch_scc1 .LBB0_7
